# d1 + back-edge rotation (7.11) in all GEMM K-loops: loop-back barrier becomes loop head, counter/exit test moved before it
# baseline (speedup 1.0000x reference)
;     __host__ __device__ bool next(int i, Unit& u) const { const bool ok = StaticOrder::next(i >> 1, u); if (i & 1) { u.ka = D_INNER; u.nkt = D_ATT / BK; } else { u.ka = 0; u.nkt = D_INNER / BK; } return ok; }
;     __host__ __device__ bool next(int i, Unit& u) const { const long L = (long)i * G + c; if (L >= (long)nM * nS) return false; u.pm = (int)(L % nM); u.pn = 0; u.ka = (int)(L / nM) * kslab; u.nkt = kslab / BK; return true; }
;     __host__ __device__ bool next(int i, Unit& u) const { if (i > 0) return false; const int x = c & 7, j = c >> 3; u.pm = 16 * s + 4 * (x >> 1) + (j & 3); u.pn = 8 * (x & 1) + (j >> 2); u.ka = 0; u.nkt = nkt; return true; }
; template <class Epi, class Sched, bool ALIGN_EPI, class Hook = NoHook>
; __device__ __forceinline__ void gemm_phase(LAS unsigned char* lds, const Gemm g, const Sched& S, const Epi& E, const Hook& H = Hook()) {
;     ...
;         const bool has_next = S.next(ui + 1, nxt);
;         const char* nA = has_next ? (const char*)g.A + (size_t)nxt.pm * tA + (size_t)nxt.ka * 2 : cA; const char* nB = has_next ? (const char*)g.Bt + (size_t)nxt.pn * 2 * hB + (size_t)nxt.ka * 2 : cB;
;     ...
; #pragma unroll
;         for (int a = 0; a < 2; ++a)
; #pragma unroll
;             for (int b = 0; b < 2; ++b)
; #pragma unroll
;                 for (int m = 0; m < 4; ++m)
; #pragma unroll
;                     for (int n = 0; n < 2; ++n) acc[a][b][m][n] = (f32x4){0.f, 0.f, 0.f, 0.f};
.LBB0_198:
	s_ashr_i32 s25, s24, 31
	s_lshl_b64 s[26:27], s[24:25], 21
	v_readlane_b32 s28, v255, 4
	v_readlane_b32 s29, v255, 5
	s_add_u32 s26, s28, s26
	s_addc_u32 s27, s29, s27
	s_and_b64 s[28:29], s[2:3], exec
	s_cselect_b32 s7, s27, s5
	s_cselect_b32 s8, s26, s4
	s_ashr_i32 s23, s22, 31
	s_lshl_b64 s[28:29], s[22:23], 21
	v_readlane_b32 s23, v254, 42
	s_add_u32 s28, s23, s28
	v_readlane_b32 s23, v254, 43
	s_addc_u32 s29, s23, s29
	s_and_b64 s[36:37], s[2:3], exec
	s_cselect_b32 s23, s29, s35
	s_cselect_b32 s25, s28, s34
	s_add_u32 s31, s34, 0x100
	v_mov_b32_e32 v2, 0
	s_addc_u32 s63, s35, 0
	s_mov_b32 s64, -2
	v_mov_b32_e32 v3, v2
	v_mov_b32_e32 v4, v2
	v_mov_b32_e32 v5, v2
	v_mov_b32_e32 v34, v2
	v_mov_b32_e32 v35, v2
	v_mov_b32_e32 v36, v2
	v_mov_b32_e32 v37, v2
	v_mov_b32_e32 v6, v2
	v_mov_b32_e32 v7, v2
	v_mov_b32_e32 v8, v2
	v_mov_b32_e32 v9, v2
	v_mov_b32_e32 v38, v2
	v_mov_b32_e32 v39, v2
	v_mov_b32_e32 v40, v2
	v_mov_b32_e32 v41, v2
	v_mov_b32_e32 v10, v2
	v_mov_b32_e32 v11, v2
	v_mov_b32_e32 v12, v2
	v_mov_b32_e32 v13, v2
	v_mov_b32_e32 v42, v2
	v_mov_b32_e32 v43, v2
	v_mov_b32_e32 v44, v2
	v_mov_b32_e32 v45, v2
	v_mov_b32_e32 v14, v2
	v_mov_b32_e32 v15, v2
	v_mov_b32_e32 v16, v2
	v_mov_b32_e32 v17, v2
	v_mov_b32_e32 v46, v2
	v_mov_b32_e32 v47, v2
	v_mov_b32_e32 v48, v2
	v_mov_b32_e32 v49, v2
	v_mov_b32_e32 v66, v2
	v_mov_b32_e32 v67, v2
	v_mov_b32_e32 v68, v2
	v_mov_b32_e32 v69, v2
	v_mov_b32_e32 v98, v2
	v_mov_b32_e32 v99, v2
	v_mov_b32_e32 v100, v2
	v_mov_b32_e32 v101, v2
	v_mov_b32_e32 v70, v2
	v_mov_b32_e32 v71, v2
	v_mov_b32_e32 v72, v2
	v_mov_b32_e32 v73, v2
	v_mov_b32_e32 v102, v2
	v_mov_b32_e32 v103, v2
	v_mov_b32_e32 v104, v2
	v_mov_b32_e32 v105, v2
	v_mov_b32_e32 v74, v2
	v_mov_b32_e32 v75, v2
	v_mov_b32_e32 v76, v2
	v_mov_b32_e32 v77, v2
	v_mov_b32_e32 v106, v2
	v_mov_b32_e32 v107, v2
	v_mov_b32_e32 v108, v2
	v_mov_b32_e32 v109, v2
	v_mov_b32_e32 v78, v2
	v_mov_b32_e32 v79, v2
	v_mov_b32_e32 v80, v2
	v_mov_b32_e32 v81, v2
	v_mov_b32_e32 v110, v2
	v_mov_b32_e32 v111, v2
	v_mov_b32_e32 v112, v2
	v_mov_b32_e32 v113, v2
	v_mov_b32_e32 v18, v2
	v_mov_b32_e32 v19, v2
	v_mov_b32_e32 v20, v2
	v_mov_b32_e32 v21, v2
	v_mov_b32_e32 v50, v2
	v_mov_b32_e32 v51, v2
	v_mov_b32_e32 v52, v2
	v_mov_b32_e32 v53, v2
	s_waitcnt vmcnt(0)
	v_mov_b32_e32 v22, v2
	v_mov_b32_e32 v23, v2
	v_mov_b32_e32 v24, v2
	v_mov_b32_e32 v25, v2
	v_mov_b32_e32 v54, v2
	v_mov_b32_e32 v55, v2
	v_mov_b32_e32 v56, v2
	v_mov_b32_e32 v57, v2
	v_mov_b32_e32 v26, v2
	v_mov_b32_e32 v27, v2
	v_mov_b32_e32 v28, v2
	v_mov_b32_e32 v29, v2
	v_mov_b32_e32 v58, v2
	v_mov_b32_e32 v59, v2
	v_mov_b32_e32 v60, v2
	v_mov_b32_e32 v61, v2
	v_mov_b32_e32 v30, v2
	v_mov_b32_e32 v31, v2
	v_mov_b32_e32 v32, v2
	v_mov_b32_e32 v33, v2
	v_mov_b32_e32 v62, v2
	v_mov_b32_e32 v63, v2
	v_mov_b32_e32 v64, v2
	v_mov_b32_e32 v65, v2
	v_mov_b32_e32 v82, v2
	v_mov_b32_e32 v83, v2
	v_mov_b32_e32 v84, v2
	v_mov_b32_e32 v85, v2
	v_mov_b32_e32 v114, v2
	v_mov_b32_e32 v115, v2
	v_mov_b32_e32 v116, v2
	v_mov_b32_e32 v117, v2
	v_mov_b32_e32 v86, v2
	v_mov_b32_e32 v87, v2
	v_mov_b32_e32 v88, v2
	v_mov_b32_e32 v89, v2
	v_mov_b32_e32 v118, v2
	v_mov_b32_e32 v119, v2
	v_mov_b32_e32 v120, v2
	v_mov_b32_e32 v121, v2
	v_mov_b32_e32 v90, v2
	v_mov_b32_e32 v91, v2
	v_mov_b32_e32 v92, v2
	v_mov_b32_e32 v93, v2
	v_mov_b32_e32 v122, v2
	v_mov_b32_e32 v123, v2
	v_mov_b32_e32 v124, v2
	v_mov_b32_e32 v125, v2
	v_mov_b32_e32 v94, v2
	v_mov_b32_e32 v95, v2
	v_mov_b32_e32 v96, v2
	v_mov_b32_e32 v97, v2
	v_mov_b32_e32 v126, v2
	v_mov_b32_e32 v127, v2
	v_mov_b32_e32 v128, v2
	v_mov_b32_e32 v129, v2
	s_and_b64 vcc, exec, s[18:19]
	s_cbranch_vccz .Lmy_rd199BE
	s_branch .Lmy_r199E

; #define PG8_STAGE(bufoff, gbase, voff) do { _Pragma("unroll") for (int _i = 0; _i < 2; ++_i) \
;         __builtin_amdgcn_global_load_lds((const unsigned*)((const char*)(gbase) + (voff)[_i]), (LAS unsigned*)(lds + (bufoff) + ldsw + _i * 8192), 16, 0, 0); } while (0)
; #define PG8_LDA(dst, b, h) do { _Pragma("unroll") for (int m = 0; m < 4; ++m) _Pragma("unroll") for (int k = 0; k < 2; ++k) dst[m][k] = *(const LAS bf16x8*)(lds + PG8_SA(b, h) + aoff + m * 2048 + k * 1024); } while (0)
; #define PG8_LDB(dst, b, h) do { _Pragma("unroll") for (int n = 0; n < 2; ++n) _Pragma("unroll") for (int k = 0; k < 2; ++k) dst[n][k] = *(const LAS bf16x8*)(lds + PG8_SB(b, h) + boff + n * 2048 + k * 1024); } while (0)
; #define PG8_MMA(ai, bj, At, Bt) do { __builtin_amdgcn_s_setprio(1); _Pragma("unroll") for (int m = 0; m < 4; ++m) _Pragma("unroll") for (int n = 0; n < 2; ++n) _Pragma("unroll") for (int k = 0; k < 2; ++k) \
;         acc[ai][bj][m][n] = __builtin_amdgcn_mfma_f32_16x16x32_bf16(Bt[n][k], At[m][k], acc[ai][bj][m][n], 0, 0, 0); __builtin_amdgcn_s_setprio(0); } while (0)
; #define PG8_WAIT_V(n) asm volatile("s_waitcnt vmcnt(" #n ")" ::: "memory")
; #define PG8_WAIT_L(n) asm volatile("s_waitcnt lgkmcnt(" #n ")" ::: "memory")
; template <class Epi, class Sched, bool ALIGN_EPI, class Hook = NoHook>
; __device__ __forceinline__ void gemm_phase(LAS unsigned char* lds, const Gemm g, const Sched& S, const Epi& E, const Hook& H = Hook()) {
;     ...
;         for (int t = tb; t < te; t += 2) {
;             const bool last = (t == nt - 2);
;             const char* a1 = cA + (size_t)(t + 1) * kstep;
;             const char* a2 = last ? nA : cA + (size_t)(t + 2) * kstep; const char* b2 = last ? nB : cB + (size_t)(t + 2) * kstep;
;             const char* a3 = a2 + kstep; const char* b3 = b2 + kstep;
;             if (last && has_next) S.a_ready(nxt);
;             PG8_LDB(B0, 0, 0); PG8_LDB(B1, 0, 1); PG8_SCHED; PG8_LDA(At, 0, 0); PG8_STAGE(PG8_SA(1, 1), a1 + hA, voffA);
;             PG8_WAIT_V(8); PG8_WAIT_L(0); PG8_BAR; PG8_MMA(0, 0, At, B0); PG8_MMA(0, 1, At, B1); PG8_BAR; PG8_SCHED;
;             PG8_LDA(At, 0, 1); PG8_STAGE(PG8_SB(0, 0), b2, voffB); PG8_STAGE(PG8_SB(0, 1), b2 + hB, voffB); PG8_STAGE(PG8_SA(0, 0), a2, voffA);
;             PG8_WAIT_V(8); PG8_WAIT_L(0); PG8_BAR; PG8_MMA(1, 0, At, B0); PG8_MMA(1, 1, At, B1); PG8_BAR; PG8_SCHED;
.Lmy_r199E:
	ds_read_b128 v[130:133], v217
	ds_read_b128 v[134:137], v217 offset:1024
	s_add_u32 s34, s4, 0x100
	s_addc_u32 s35, s5, 0
	s_cmp_eq_u32 s64, 60
	s_cselect_b32 s39, s7, s35
	s_cselect_b32 s38, s8, s34
	s_cselect_b32 s37, s23, s63
	s_cselect_b32 s36, s25, s31
	s_add_i32 m0, s40, 0xc000
	s_nop 0
	global_load_lds_dwordx4 v172, s[4:5]
	ds_read_b128 v[138:141], v217 offset:2048
	ds_read_b128 v[142:145], v217 offset:3072
	ds_read_b128 v[146:149], v218
	ds_read_b128 v[150:153], v218 offset:1024
	ds_read_b128 v[154:157], v218 offset:2048
	ds_read_b128 v[158:161], v218 offset:3072
	ds_read_b128 v[180:183], v219
	s_add_i32 m0, s40, 0xe000
	s_nop 0
	global_load_lds_dwordx4 v174, s[4:5]
	ds_read_b128 v[184:187], v219 offset:1024
	ds_read_b128 v[188:191], v219 offset:2048
	ds_read_b128 v[192:195], v219 offset:3072
	ds_read_b128 v[196:199], v219 offset:4096
	ds_read_b128 v[200:203], v219 offset:5120
	ds_read_b128 v[204:207], v219 offset:6144
	ds_read_b128 v[208:211], v219 offset:7168
	s_waitcnt lgkmcnt(0)
	s_barrier
	s_setprio 1
	s_waitcnt lgkmcnt(0)
	v_mfma_f32_16x16x32_bf16 v[126:129], v[130:133], v[180:183], v[126:129]
	v_mfma_f32_16x16x32_bf16 v[94:97], v[138:141], v[180:183], v[94:97]
	v_mfma_f32_16x16x32_bf16 v[122:125], v[130:133], v[188:191], v[122:125]
	v_mfma_f32_16x16x32_bf16 v[90:93], v[138:141], v[188:191], v[90:93]
	v_mfma_f32_16x16x32_bf16 v[118:121], v[130:133], v[196:199], v[118:121]
	v_mfma_f32_16x16x32_bf16 v[86:89], v[138:141], v[196:199], v[86:89]
	v_mfma_f32_16x16x32_bf16 v[114:117], v[130:133], v[204:207], v[114:117]
	v_mfma_f32_16x16x32_bf16 v[82:85], v[138:141], v[204:207], v[82:85]
	v_mfma_f32_16x16x32_bf16 v[126:129], v[134:137], v[184:187], v[126:129]
	v_mfma_f32_16x16x32_bf16 v[94:97], v[142:145], v[184:187], v[94:97]
	v_mfma_f32_16x16x32_bf16 v[122:125], v[134:137], v[192:195], v[122:125]
	v_mfma_f32_16x16x32_bf16 v[90:93], v[142:145], v[192:195], v[90:93]
	v_mfma_f32_16x16x32_bf16 v[118:121], v[134:137], v[200:203], v[118:121]
	v_mfma_f32_16x16x32_bf16 v[86:89], v[142:145], v[200:203], v[86:89]
	v_mfma_f32_16x16x32_bf16 v[114:117], v[134:137], v[208:211], v[114:117]
	v_mfma_f32_16x16x32_bf16 v[82:85], v[142:145], v[208:211], v[82:85]
	s_setprio 0
	s_setprio 1
	v_mfma_f32_16x16x32_bf16 v[62:65], v[146:149], v[180:183], v[62:65]
	v_mfma_f32_16x16x32_bf16 v[30:33], v[154:157], v[180:183], v[30:33]
	v_mfma_f32_16x16x32_bf16 v[58:61], v[146:149], v[188:191], v[58:61]
	v_mfma_f32_16x16x32_bf16 v[26:29], v[154:157], v[188:191], v[26:29]
	v_mfma_f32_16x16x32_bf16 v[54:57], v[146:149], v[196:199], v[54:57]
	v_mfma_f32_16x16x32_bf16 v[22:25], v[154:157], v[196:199], v[22:25]
	v_mfma_f32_16x16x32_bf16 v[50:53], v[146:149], v[204:207], v[50:53]
	v_mfma_f32_16x16x32_bf16 v[18:21], v[154:157], v[204:207], v[18:21]
	v_mfma_f32_16x16x32_bf16 v[62:65], v[150:153], v[184:187], v[62:65]
	v_mfma_f32_16x16x32_bf16 v[30:33], v[158:161], v[184:187], v[30:33]
	v_mfma_f32_16x16x32_bf16 v[58:61], v[150:153], v[192:195], v[58:61]
	v_mfma_f32_16x16x32_bf16 v[26:29], v[158:161], v[192:195], v[26:29]
	v_mfma_f32_16x16x32_bf16 v[54:57], v[150:153], v[200:203], v[54:57]
	v_mfma_f32_16x16x32_bf16 v[22:25], v[158:161], v[200:203], v[22:25]
	v_mfma_f32_16x16x32_bf16 v[50:53], v[150:153], v[208:211], v[50:53]
	v_mfma_f32_16x16x32_bf16 v[18:21], v[158:161], v[208:211], v[18:21]
	s_setprio 0
	s_waitcnt vmcnt(8)
	s_barrier
	s_add_i32 s4, s59, s21
	s_mov_b32 m0, s4
	ds_read_b128 v[180:183], v219 offset:16384
	ds_read_b128 v[184:187], v219 offset:17408
	global_load_lds_dwordx4 v164, s[36:37]
	ds_read_b128 v[188:191], v219 offset:18432
	s_add_i32 m0, s4, 0x2000
	s_add_u32 s4, s36, 0x100000
	s_addc_u32 s5, s37, 0
	s_add_i32 s65, s60, s21
	global_load_lds_dwordx4 v168, s[36:37]
	ds_read_b128 v[192:195], v219 offset:19456
	s_mov_b32 m0, s65
	s_nop 0
	global_load_lds_dwordx4 v164, s[4:5]
	ds_read_b128 v[196:199], v219 offset:20480
	s_add_i32 m0, s65, 0x2000
	s_nop 0
	global_load_lds_dwordx4 v168, s[4:5]
	ds_read_b128 v[200:203], v219 offset:21504
	s_mov_b32 m0, s40
	s_nop 0
	global_load_lds_dwordx4 v162, s[38:39]
	ds_read_b128 v[204:207], v219 offset:22528
	s_mov_b32 m0, s41
	s_nop 0
	global_load_lds_dwordx4 v166, s[38:39]
	ds_read_b128 v[208:211], v219 offset:23552
	s_waitcnt lgkmcnt(0)
	s_barrier
	s_setprio 1
	s_waitcnt lgkmcnt(0)
	v_mfma_f32_16x16x32_bf16 v[110:113], v[130:133], v[180:183], v[110:113]
	v_mfma_f32_16x16x32_bf16 v[78:81], v[138:141], v[180:183], v[78:81]
	v_mfma_f32_16x16x32_bf16 v[106:109], v[130:133], v[188:191], v[106:109]
	v_mfma_f32_16x16x32_bf16 v[74:77], v[138:141], v[188:191], v[74:77]
	v_mfma_f32_16x16x32_bf16 v[102:105], v[130:133], v[196:199], v[102:105]
	v_mfma_f32_16x16x32_bf16 v[70:73], v[138:141], v[196:199], v[70:73]
	v_mfma_f32_16x16x32_bf16 v[98:101], v[130:133], v[204:207], v[98:101]
	v_mfma_f32_16x16x32_bf16 v[66:69], v[138:141], v[204:207], v[66:69]
	v_mfma_f32_16x16x32_bf16 v[110:113], v[134:137], v[184:187], v[110:113]
	v_mfma_f32_16x16x32_bf16 v[78:81], v[142:145], v[184:187], v[78:81]
	v_mfma_f32_16x16x32_bf16 v[106:109], v[134:137], v[192:195], v[106:109]
	v_mfma_f32_16x16x32_bf16 v[74:77], v[142:145], v[192:195], v[74:77]
	v_mfma_f32_16x16x32_bf16 v[102:105], v[134:137], v[200:203], v[102:105]
	v_mfma_f32_16x16x32_bf16 v[70:73], v[142:145], v[200:203], v[70:73]
	v_mfma_f32_16x16x32_bf16 v[98:101], v[134:137], v[208:211], v[98:101]
	v_mfma_f32_16x16x32_bf16 v[66:69], v[142:145], v[208:211], v[66:69]
	s_setprio 0
	s_setprio 1
	v_mfma_f32_16x16x32_bf16 v[46:49], v[146:149], v[180:183], v[46:49]
	v_mfma_f32_16x16x32_bf16 v[14:17], v[154:157], v[180:183], v[14:17]
	v_mfma_f32_16x16x32_bf16 v[42:45], v[146:149], v[188:191], v[42:45]
	v_mfma_f32_16x16x32_bf16 v[10:13], v[154:157], v[188:191], v[10:13]
	v_mfma_f32_16x16x32_bf16 v[38:41], v[146:149], v[196:199], v[38:41]
	v_mfma_f32_16x16x32_bf16 v[6:9], v[154:157], v[196:199], v[6:9]
	v_mfma_f32_16x16x32_bf16 v[34:37], v[146:149], v[204:207], v[34:37]
	v_mfma_f32_16x16x32_bf16 v[2:5], v[154:157], v[204:207], v[2:5]
	v_mfma_f32_16x16x32_bf16 v[46:49], v[150:153], v[184:187], v[46:49]
	v_mfma_f32_16x16x32_bf16 v[14:17], v[158:161], v[184:187], v[14:17]
	v_mfma_f32_16x16x32_bf16 v[42:45], v[150:153], v[192:195], v[42:45]
	v_mfma_f32_16x16x32_bf16 v[10:13], v[158:161], v[192:195], v[10:13]
	v_mfma_f32_16x16x32_bf16 v[38:41], v[150:153], v[200:203], v[38:41]
	v_mfma_f32_16x16x32_bf16 v[6:9], v[158:161], v[200:203], v[6:9]
	v_mfma_f32_16x16x32_bf16 v[34:37], v[150:153], v[208:211], v[34:37]
	v_mfma_f32_16x16x32_bf16 v[2:5], v[158:161], v[208:211], v[2:5]
	s_setprio 0
	s_waitcnt vmcnt(8)
	s_barrier
; #define PG8_STAGE(bufoff, gbase, voff) do { _Pragma("unroll") for (int _i = 0; _i < 2; ++_i) \
;         __builtin_amdgcn_global_load_lds((const unsigned*)((const char*)(gbase) + (voff)[_i]), (LAS unsigned*)(lds + (bufoff) + ldsw + _i * 8192), 16, 0, 0); } while (0)
; #define PG8_LDA(dst, b, h) do { _Pragma("unroll") for (int m = 0; m < 4; ++m) _Pragma("unroll") for (int k = 0; k < 2; ++k) dst[m][k] = *(const LAS bf16x8*)(lds + PG8_SA(b, h) + aoff + m * 2048 + k * 1024); } while (0)
; #define PG8_LDB(dst, b, h) do { _Pragma("unroll") for (int n = 0; n < 2; ++n) _Pragma("unroll") for (int k = 0; k < 2; ++k) dst[n][k] = *(const LAS bf16x8*)(lds + PG8_SB(b, h) + boff + n * 2048 + k * 1024); } while (0)
; #define PG8_MMA(ai, bj, At, Bt) do { __builtin_amdgcn_s_setprio(1); _Pragma("unroll") for (int m = 0; m < 4; ++m) _Pragma("unroll") for (int n = 0; n < 2; ++n) _Pragma("unroll") for (int k = 0; k < 2; ++k) \
;         acc[ai][bj][m][n] = __builtin_amdgcn_mfma_f32_16x16x32_bf16(Bt[n][k], At[m][k], acc[ai][bj][m][n], 0, 0, 0); __builtin_amdgcn_s_setprio(0); } while (0)
; #define PG8_WAIT_V(n) asm volatile("s_waitcnt vmcnt(" #n ")" ::: "memory")
; #define PG8_WAIT_L(n) asm volatile("s_waitcnt lgkmcnt(" #n ")" ::: "memory")
; #define PG8_BAR __builtin_amdgcn_s_barrier()
; #define PG8_SCHED __builtin_amdgcn_sched_barrier(0)
; template <class Epi, class Sched, bool ALIGN_EPI, class Hook = NoHook>
; __device__ __forceinline__ void gemm_phase(LAS unsigned char* lds, const Gemm g, const Sched& S, const Epi& E, const Hook& H = Hook()) {
;     ...
;             PG8_LDB(B0, 1, 0); PG8_LDB(B1, 1, 1); PG8_SCHED; PG8_LDA(At, 1, 0); PG8_STAGE(PG8_SA(0, 1), a2 + hA, voffA);
;             PG8_WAIT_V(8); PG8_WAIT_L(0); PG8_BAR; PG8_MMA(0, 0, At, B0); PG8_MMA(0, 1, At, B1); PG8_BAR; PG8_SCHED;
;             PG8_LDA(At, 1, 1); PG8_STAGE(PG8_SB(1, 0), b3, voffB); PG8_STAGE(PG8_SB(1, 1), b3 + hB, voffB); PG8_STAGE(PG8_SA(1, 0), a3, voffA);
;             PG8_WAIT_V(8); PG8_WAIT_L(0); PG8_BAR; PG8_MMA(1, 0, At, B0); PG8_MMA(1, 1, At, B1); PG8_BAR; PG8_SCHED;
;         }
	s_add_i32 s65, 0, 0x18000
	s_add_i32 s66, 0, 0x1c000
	v_add_u32_e32 v142, s65, v213
	v_add_u32_e32 v158, s66, v213
	ds_read_b128 v[130:133], v142
	ds_read_b128 v[134:137], v142 offset:1024
	s_add_u32 s4, s38, 0x8000
	s_addc_u32 s5, s39, 0
	s_mov_b32 m0, s42
	s_nop 0
	global_load_lds_dwordx4 v162, s[4:5]
	ds_read_b128 v[138:141], v142 offset:2048
	ds_read_b128 v[142:145], v142 offset:3072
	ds_read_b128 v[146:149], v158
	ds_read_b128 v[150:153], v158 offset:1024
	ds_read_b128 v[154:157], v158 offset:2048
	ds_read_b128 v[158:161], v158 offset:3072
	ds_read_b128 v[180:183], v219 offset:32768
	s_mov_b32 m0, s43
	s_nop 0
	global_load_lds_dwordx4 v166, s[4:5]
	ds_read_b128 v[184:187], v219 offset:33792
	ds_read_b128 v[188:191], v219 offset:34816
	ds_read_b128 v[192:195], v219 offset:35840
	ds_read_b128 v[196:199], v219 offset:36864
	ds_read_b128 v[200:203], v219 offset:37888
	ds_read_b128 v[204:207], v219 offset:38912
	ds_read_b128 v[208:211], v219 offset:39936
	s_waitcnt lgkmcnt(0)
	s_barrier
	s_setprio 1
	s_waitcnt lgkmcnt(0)
	v_mfma_f32_16x16x32_bf16 v[126:129], v[130:133], v[180:183], v[126:129]
	v_mfma_f32_16x16x32_bf16 v[94:97], v[138:141], v[180:183], v[94:97]
	v_mfma_f32_16x16x32_bf16 v[122:125], v[130:133], v[188:191], v[122:125]
	v_mfma_f32_16x16x32_bf16 v[90:93], v[138:141], v[188:191], v[90:93]
	v_mfma_f32_16x16x32_bf16 v[118:121], v[130:133], v[196:199], v[118:121]
	v_mfma_f32_16x16x32_bf16 v[86:89], v[138:141], v[196:199], v[86:89]
	v_mfma_f32_16x16x32_bf16 v[114:117], v[130:133], v[204:207], v[114:117]
	v_mfma_f32_16x16x32_bf16 v[82:85], v[138:141], v[204:207], v[82:85]
	v_mfma_f32_16x16x32_bf16 v[126:129], v[134:137], v[184:187], v[126:129]
	v_mfma_f32_16x16x32_bf16 v[94:97], v[142:145], v[184:187], v[94:97]
	v_mfma_f32_16x16x32_bf16 v[122:125], v[134:137], v[192:195], v[122:125]
	v_mfma_f32_16x16x32_bf16 v[90:93], v[142:145], v[192:195], v[90:93]
	v_mfma_f32_16x16x32_bf16 v[118:121], v[134:137], v[200:203], v[118:121]
	v_mfma_f32_16x16x32_bf16 v[86:89], v[142:145], v[200:203], v[86:89]
	v_mfma_f32_16x16x32_bf16 v[114:117], v[134:137], v[208:211], v[114:117]
	v_mfma_f32_16x16x32_bf16 v[82:85], v[142:145], v[208:211], v[82:85]
	s_setprio 0
	s_setprio 1
	v_mfma_f32_16x16x32_bf16 v[62:65], v[146:149], v[180:183], v[62:65]
	v_mfma_f32_16x16x32_bf16 v[30:33], v[154:157], v[180:183], v[30:33]
	v_mfma_f32_16x16x32_bf16 v[58:61], v[146:149], v[188:191], v[58:61]
	v_mfma_f32_16x16x32_bf16 v[26:29], v[154:157], v[188:191], v[26:29]
	v_mfma_f32_16x16x32_bf16 v[54:57], v[146:149], v[196:199], v[54:57]
	v_mfma_f32_16x16x32_bf16 v[22:25], v[154:157], v[196:199], v[22:25]
	v_mfma_f32_16x16x32_bf16 v[50:53], v[146:149], v[204:207], v[50:53]
	v_mfma_f32_16x16x32_bf16 v[18:21], v[154:157], v[204:207], v[18:21]
	v_mfma_f32_16x16x32_bf16 v[62:65], v[150:153], v[184:187], v[62:65]
	v_mfma_f32_16x16x32_bf16 v[30:33], v[158:161], v[184:187], v[30:33]
	v_mfma_f32_16x16x32_bf16 v[58:61], v[150:153], v[192:195], v[58:61]
	v_mfma_f32_16x16x32_bf16 v[26:29], v[158:161], v[192:195], v[26:29]
	v_mfma_f32_16x16x32_bf16 v[54:57], v[150:153], v[200:203], v[54:57]
	v_mfma_f32_16x16x32_bf16 v[22:25], v[158:161], v[200:203], v[22:25]
	v_mfma_f32_16x16x32_bf16 v[50:53], v[150:153], v[208:211], v[50:53]
	v_mfma_f32_16x16x32_bf16 v[18:21], v[158:161], v[208:211], v[18:21]
	s_setprio 0
	s_waitcnt vmcnt(8)
	s_barrier
	s_add_i32 s4, s65, s21
	s_add_u32 s68, s36, s14
	s_addc_u32 s69, s37, s15
	s_mov_b32 m0, s4
	ds_read_b128 v[180:183], v219 offset:49152
	ds_read_b128 v[184:187], v219 offset:50176
	global_load_lds_dwordx4 v164, s[68:69]
	ds_read_b128 v[188:191], v219 offset:51200
	s_add_i32 m0, s4, 0x2000
	s_add_u32 s4, s36, 0x100080
	s_addc_u32 s5, s37, 0
	s_add_i32 s36, s66, s21
	global_load_lds_dwordx4 v168, s[68:69]
	ds_read_b128 v[192:195], v219 offset:52224
	s_mov_b32 m0, s36
	s_nop 0
	global_load_lds_dwordx4 v164, s[4:5]
	ds_read_b128 v[196:199], v219 offset:53248
	s_add_i32 m0, s36, 0x2000
	s_nop 0
	global_load_lds_dwordx4 v168, s[4:5]
	ds_read_b128 v[200:203], v219 offset:54272
	s_add_u32 s70, s38, s14
	s_addc_u32 s71, s39, s15
	s_mov_b32 m0, s51
	s_nop 0
	global_load_lds_dwordx4 v162, s[70:71]
	ds_read_b128 v[204:207], v219 offset:55296
	s_mov_b32 m0, s52
	s_nop 0
	global_load_lds_dwordx4 v166, s[70:71]
	ds_read_b128 v[208:211], v219 offset:56320
	s_waitcnt lgkmcnt(0)
	s_barrier
	s_setprio 1
	s_waitcnt lgkmcnt(0)
	v_mfma_f32_16x16x32_bf16 v[110:113], v[130:133], v[180:183], v[110:113]
	v_mfma_f32_16x16x32_bf16 v[78:81], v[138:141], v[180:183], v[78:81]
	v_mfma_f32_16x16x32_bf16 v[106:109], v[130:133], v[188:191], v[106:109]
	v_mfma_f32_16x16x32_bf16 v[74:77], v[138:141], v[188:191], v[74:77]
	v_mfma_f32_16x16x32_bf16 v[102:105], v[130:133], v[196:199], v[102:105]
	v_mfma_f32_16x16x32_bf16 v[70:73], v[138:141], v[196:199], v[70:73]
	v_mfma_f32_16x16x32_bf16 v[98:101], v[130:133], v[204:207], v[98:101]
	v_mfma_f32_16x16x32_bf16 v[66:69], v[138:141], v[204:207], v[66:69]
	v_mfma_f32_16x16x32_bf16 v[110:113], v[134:137], v[184:187], v[110:113]
	v_mfma_f32_16x16x32_bf16 v[78:81], v[142:145], v[184:187], v[78:81]
	v_mfma_f32_16x16x32_bf16 v[106:109], v[134:137], v[192:195], v[106:109]
	v_mfma_f32_16x16x32_bf16 v[74:77], v[142:145], v[192:195], v[74:77]
	v_mfma_f32_16x16x32_bf16 v[102:105], v[134:137], v[200:203], v[102:105]
	v_mfma_f32_16x16x32_bf16 v[70:73], v[142:145], v[200:203], v[70:73]
	v_mfma_f32_16x16x32_bf16 v[98:101], v[134:137], v[208:211], v[98:101]
	v_mfma_f32_16x16x32_bf16 v[66:69], v[142:145], v[208:211], v[66:69]
	s_setprio 0
	s_setprio 1
	v_mfma_f32_16x16x32_bf16 v[46:49], v[146:149], v[180:183], v[46:49]
	v_mfma_f32_16x16x32_bf16 v[14:17], v[154:157], v[180:183], v[14:17]
	v_mfma_f32_16x16x32_bf16 v[42:45], v[146:149], v[188:191], v[42:45]
	v_mfma_f32_16x16x32_bf16 v[10:13], v[154:157], v[188:191], v[10:13]
	v_mfma_f32_16x16x32_bf16 v[38:41], v[146:149], v[196:199], v[38:41]
	v_mfma_f32_16x16x32_bf16 v[6:9], v[154:157], v[196:199], v[6:9]
	v_mfma_f32_16x16x32_bf16 v[34:37], v[146:149], v[204:207], v[34:37]
	v_mfma_f32_16x16x32_bf16 v[2:5], v[154:157], v[204:207], v[2:5]
	v_mfma_f32_16x16x32_bf16 v[46:49], v[150:153], v[184:187], v[46:49]
	v_mfma_f32_16x16x32_bf16 v[14:17], v[158:161], v[184:187], v[14:17]
	v_mfma_f32_16x16x32_bf16 v[42:45], v[150:153], v[192:195], v[42:45]
	v_mfma_f32_16x16x32_bf16 v[10:13], v[158:161], v[192:195], v[10:13]
	v_mfma_f32_16x16x32_bf16 v[38:41], v[150:153], v[200:203], v[38:41]
	v_mfma_f32_16x16x32_bf16 v[6:9], v[158:161], v[200:203], v[6:9]
	v_mfma_f32_16x16x32_bf16 v[34:37], v[150:153], v[208:211], v[34:37]
	v_mfma_f32_16x16x32_bf16 v[2:5], v[158:161], v[208:211], v[2:5]
	s_setprio 0
	s_waitcnt vmcnt(8)
	s_add_i32 s64, s64, 2
	s_add_u32 s31, s31, 0x100
	s_addc_u32 s63, s63, 0
	s_cmp_gt_u32 s64, 61
	s_mov_b64 s[4:5], s[34:35]
	s_cbranch_scc0 .LBB0_199
	s_barrier
	s_branch .Lmy_d199X

; #define PG8_STAGE(bufoff, gbase, voff) do { _Pragma("unroll") for (int _i = 0; _i < 2; ++_i) \
;         __builtin_amdgcn_global_load_lds((const unsigned*)((const char*)(gbase) + (voff)[_i]), (LAS unsigned*)(lds + (bufoff) + ldsw + _i * 8192), 16, 0, 0); } while (0)
; #define PG8_LDA(dst, b, h) do { _Pragma("unroll") for (int m = 0; m < 4; ++m) _Pragma("unroll") for (int k = 0; k < 2; ++k) dst[m][k] = *(const LAS bf16x8*)(lds + PG8_SA(b, h) + aoff + m * 2048 + k * 1024); } while (0)
; #define PG8_LDB(dst, b, h) do { _Pragma("unroll") for (int n = 0; n < 2; ++n) _Pragma("unroll") for (int k = 0; k < 2; ++k) dst[n][k] = *(const LAS bf16x8*)(lds + PG8_SB(b, h) + boff + n * 2048 + k * 1024); } while (0)
; #define PG8_MMA(ai, bj, At, Bt) do { __builtin_amdgcn_s_setprio(1); _Pragma("unroll") for (int m = 0; m < 4; ++m) _Pragma("unroll") for (int n = 0; n < 2; ++n) _Pragma("unroll") for (int k = 0; k < 2; ++k) \
;         acc[ai][bj][m][n] = __builtin_amdgcn_mfma_f32_16x16x32_bf16(Bt[n][k], At[m][k], acc[ai][bj][m][n], 0, 0, 0); __builtin_amdgcn_s_setprio(0); } while (0)
; #define PG8_WAIT_V(n) asm volatile("s_waitcnt vmcnt(" #n ")" ::: "memory")
; #define PG8_WAIT_L(n) asm volatile("s_waitcnt lgkmcnt(" #n ")" ::: "memory")
; template <class Epi, class Sched, bool ALIGN_EPI, class Hook = NoHook>
; __device__ __forceinline__ void gemm_phase(LAS unsigned char* lds, const Gemm g, const Sched& S, const Epi& E, const Hook& H = Hook()) {
;     ...
;         for (int t = tb; t < te; t += 2) {
;             const bool last = (t == nt - 2);
;             const char* a1 = cA + (size_t)(t + 1) * kstep;
;             const char* a2 = last ? nA : cA + (size_t)(t + 2) * kstep; const char* b2 = last ? nB : cB + (size_t)(t + 2) * kstep;
;             const char* a3 = a2 + kstep; const char* b3 = b2 + kstep;
;             if (last && has_next) S.a_ready(nxt);
;             PG8_LDB(B0, 0, 0); PG8_LDB(B1, 0, 1); PG8_SCHED; PG8_LDA(At, 0, 0); PG8_STAGE(PG8_SA(1, 1), a1 + hA, voffA);
;             PG8_WAIT_V(8); PG8_WAIT_L(0); PG8_BAR; PG8_MMA(0, 0, At, B0); PG8_MMA(0, 1, At, B1); PG8_BAR; PG8_SCHED;
;             PG8_LDA(At, 0, 1); PG8_STAGE(PG8_SB(0, 0), b2, voffB); PG8_STAGE(PG8_SB(0, 1), b2 + hB, voffB); PG8_STAGE(PG8_SA(0, 0), a2, voffA);
;             PG8_WAIT_V(8); PG8_WAIT_L(0); PG8_BAR; PG8_MMA(1, 0, At, B0); PG8_MMA(1, 1, At, B1); PG8_BAR; PG8_SCHED;
.Lmy_rd199BE:
	ds_read_b128 v[130:133], v217
	ds_read_b128 v[134:137], v217 offset:1024
	s_add_u32 s34, s4, 0x100
	s_addc_u32 s35, s5, 0
	s_cmp_eq_u32 s64, 60
	s_cselect_b32 s39, s7, s35
	s_cselect_b32 s38, s8, s34
	s_cselect_b32 s37, s23, s63
	s_cselect_b32 s36, s25, s31
	s_add_i32 m0, s40, 0xc000
	s_nop 0
	global_load_lds_dwordx4 v172, s[4:5]
	ds_read_b128 v[138:141], v217 offset:2048
	ds_read_b128 v[142:145], v217 offset:3072
	ds_read_b128 v[146:149], v218
	ds_read_b128 v[150:153], v218 offset:1024
	ds_read_b128 v[154:157], v218 offset:2048
	ds_read_b128 v[158:161], v218 offset:3072
	ds_read_b128 v[180:183], v219
	s_add_i32 m0, s40, 0xe000
	s_nop 0
	global_load_lds_dwordx4 v174, s[4:5]
	ds_read_b128 v[184:187], v219 offset:1024
	ds_read_b128 v[188:191], v219 offset:2048
	ds_read_b128 v[192:195], v219 offset:3072
	ds_read_b128 v[196:199], v219 offset:4096
	ds_read_b128 v[200:203], v219 offset:5120
	ds_read_b128 v[204:207], v219 offset:6144
	ds_read_b128 v[208:211], v219 offset:7168
	s_waitcnt vmcnt(8)
	s_waitcnt lgkmcnt(0)
	s_barrier
	s_setprio 1
	s_waitcnt lgkmcnt(0)
	v_mfma_f32_16x16x32_bf16 v[126:129], v[130:133], v[180:183], v[126:129]
	v_mfma_f32_16x16x32_bf16 v[94:97], v[138:141], v[180:183], v[94:97]
	v_mfma_f32_16x16x32_bf16 v[122:125], v[130:133], v[188:191], v[122:125]
	v_mfma_f32_16x16x32_bf16 v[90:93], v[138:141], v[188:191], v[90:93]
	v_mfma_f32_16x16x32_bf16 v[118:121], v[130:133], v[196:199], v[118:121]
	v_mfma_f32_16x16x32_bf16 v[86:89], v[138:141], v[196:199], v[86:89]
	v_mfma_f32_16x16x32_bf16 v[114:117], v[130:133], v[204:207], v[114:117]
	v_mfma_f32_16x16x32_bf16 v[82:85], v[138:141], v[204:207], v[82:85]
	v_mfma_f32_16x16x32_bf16 v[126:129], v[134:137], v[184:187], v[126:129]
	v_mfma_f32_16x16x32_bf16 v[94:97], v[142:145], v[184:187], v[94:97]
	v_mfma_f32_16x16x32_bf16 v[122:125], v[134:137], v[192:195], v[122:125]
	v_mfma_f32_16x16x32_bf16 v[90:93], v[142:145], v[192:195], v[90:93]
	v_mfma_f32_16x16x32_bf16 v[118:121], v[134:137], v[200:203], v[118:121]
	v_mfma_f32_16x16x32_bf16 v[86:89], v[142:145], v[200:203], v[86:89]
	v_mfma_f32_16x16x32_bf16 v[114:117], v[134:137], v[208:211], v[114:117]
	v_mfma_f32_16x16x32_bf16 v[82:85], v[142:145], v[208:211], v[82:85]
	s_setprio 0
	s_setprio 1
	v_mfma_f32_16x16x32_bf16 v[62:65], v[146:149], v[180:183], v[62:65]
	v_mfma_f32_16x16x32_bf16 v[30:33], v[154:157], v[180:183], v[30:33]
	v_mfma_f32_16x16x32_bf16 v[58:61], v[146:149], v[188:191], v[58:61]
	v_mfma_f32_16x16x32_bf16 v[26:29], v[154:157], v[188:191], v[26:29]
	v_mfma_f32_16x16x32_bf16 v[54:57], v[146:149], v[196:199], v[54:57]
	v_mfma_f32_16x16x32_bf16 v[22:25], v[154:157], v[196:199], v[22:25]
	v_mfma_f32_16x16x32_bf16 v[50:53], v[146:149], v[204:207], v[50:53]
	v_mfma_f32_16x16x32_bf16 v[18:21], v[154:157], v[204:207], v[18:21]
	v_mfma_f32_16x16x32_bf16 v[62:65], v[150:153], v[184:187], v[62:65]
	v_mfma_f32_16x16x32_bf16 v[30:33], v[158:161], v[184:187], v[30:33]
	v_mfma_f32_16x16x32_bf16 v[58:61], v[150:153], v[192:195], v[58:61]
	v_mfma_f32_16x16x32_bf16 v[26:29], v[158:161], v[192:195], v[26:29]
	v_mfma_f32_16x16x32_bf16 v[54:57], v[150:153], v[200:203], v[54:57]
	v_mfma_f32_16x16x32_bf16 v[22:25], v[158:161], v[200:203], v[22:25]
	v_mfma_f32_16x16x32_bf16 v[50:53], v[150:153], v[208:211], v[50:53]
	v_mfma_f32_16x16x32_bf16 v[18:21], v[158:161], v[208:211], v[18:21]
	s_setprio 0
	s_barrier
	s_add_i32 s4, s59, s21
	s_mov_b32 m0, s4
	ds_read_b128 v[180:183], v219 offset:16384
	ds_read_b128 v[184:187], v219 offset:17408
	global_load_lds_dwordx4 v164, s[36:37]
	ds_read_b128 v[188:191], v219 offset:18432
	s_add_i32 m0, s4, 0x2000
	s_add_u32 s4, s36, 0x100000
	s_addc_u32 s5, s37, 0
	s_add_i32 s65, s60, s21
	global_load_lds_dwordx4 v168, s[36:37]
	ds_read_b128 v[192:195], v219 offset:19456
	s_mov_b32 m0, s65
	s_nop 0
	global_load_lds_dwordx4 v164, s[4:5]
	ds_read_b128 v[196:199], v219 offset:20480
	s_add_i32 m0, s65, 0x2000
	s_nop 0
	global_load_lds_dwordx4 v168, s[4:5]
	ds_read_b128 v[200:203], v219 offset:21504
	s_mov_b32 m0, s40
	s_nop 0
	global_load_lds_dwordx4 v162, s[38:39]
	ds_read_b128 v[204:207], v219 offset:22528
	s_mov_b32 m0, s41
	s_nop 0
	global_load_lds_dwordx4 v166, s[38:39]
	ds_read_b128 v[208:211], v219 offset:23552
	s_waitcnt vmcnt(8)
	s_waitcnt lgkmcnt(0)
	s_barrier
	s_setprio 1
	s_waitcnt lgkmcnt(0)
	v_mfma_f32_16x16x32_bf16 v[110:113], v[130:133], v[180:183], v[110:113]
	v_mfma_f32_16x16x32_bf16 v[78:81], v[138:141], v[180:183], v[78:81]
	v_mfma_f32_16x16x32_bf16 v[106:109], v[130:133], v[188:191], v[106:109]
	v_mfma_f32_16x16x32_bf16 v[74:77], v[138:141], v[188:191], v[74:77]
	v_mfma_f32_16x16x32_bf16 v[102:105], v[130:133], v[196:199], v[102:105]
	v_mfma_f32_16x16x32_bf16 v[70:73], v[138:141], v[196:199], v[70:73]
	v_mfma_f32_16x16x32_bf16 v[98:101], v[130:133], v[204:207], v[98:101]
	v_mfma_f32_16x16x32_bf16 v[66:69], v[138:141], v[204:207], v[66:69]
	v_mfma_f32_16x16x32_bf16 v[110:113], v[134:137], v[184:187], v[110:113]
	v_mfma_f32_16x16x32_bf16 v[78:81], v[142:145], v[184:187], v[78:81]
	v_mfma_f32_16x16x32_bf16 v[106:109], v[134:137], v[192:195], v[106:109]
	v_mfma_f32_16x16x32_bf16 v[74:77], v[142:145], v[192:195], v[74:77]
	v_mfma_f32_16x16x32_bf16 v[102:105], v[134:137], v[200:203], v[102:105]
	v_mfma_f32_16x16x32_bf16 v[70:73], v[142:145], v[200:203], v[70:73]
	v_mfma_f32_16x16x32_bf16 v[98:101], v[134:137], v[208:211], v[98:101]
	v_mfma_f32_16x16x32_bf16 v[66:69], v[142:145], v[208:211], v[66:69]
	s_setprio 0
	s_setprio 1
	v_mfma_f32_16x16x32_bf16 v[46:49], v[146:149], v[180:183], v[46:49]
	v_mfma_f32_16x16x32_bf16 v[14:17], v[154:157], v[180:183], v[14:17]
	v_mfma_f32_16x16x32_bf16 v[42:45], v[146:149], v[188:191], v[42:45]
	v_mfma_f32_16x16x32_bf16 v[10:13], v[154:157], v[188:191], v[10:13]
	v_mfma_f32_16x16x32_bf16 v[38:41], v[146:149], v[196:199], v[38:41]
	v_mfma_f32_16x16x32_bf16 v[6:9], v[154:157], v[196:199], v[6:9]
	v_mfma_f32_16x16x32_bf16 v[34:37], v[146:149], v[204:207], v[34:37]
	v_mfma_f32_16x16x32_bf16 v[2:5], v[154:157], v[204:207], v[2:5]
	v_mfma_f32_16x16x32_bf16 v[46:49], v[150:153], v[184:187], v[46:49]
	v_mfma_f32_16x16x32_bf16 v[14:17], v[158:161], v[184:187], v[14:17]
	v_mfma_f32_16x16x32_bf16 v[42:45], v[150:153], v[192:195], v[42:45]
	v_mfma_f32_16x16x32_bf16 v[10:13], v[158:161], v[192:195], v[10:13]
	v_mfma_f32_16x16x32_bf16 v[38:41], v[150:153], v[200:203], v[38:41]
	v_mfma_f32_16x16x32_bf16 v[6:9], v[158:161], v[200:203], v[6:9]
	v_mfma_f32_16x16x32_bf16 v[34:37], v[150:153], v[208:211], v[34:37]
	v_mfma_f32_16x16x32_bf16 v[2:5], v[158:161], v[208:211], v[2:5]
	s_setprio 0
	s_barrier
; #define PG8_STAGE(bufoff, gbase, voff) do { _Pragma("unroll") for (int _i = 0; _i < 2; ++_i) \
;         __builtin_amdgcn_global_load_lds((const unsigned*)((const char*)(gbase) + (voff)[_i]), (LAS unsigned*)(lds + (bufoff) + ldsw + _i * 8192), 16, 0, 0); } while (0)
; #define PG8_LDA(dst, b, h) do { _Pragma("unroll") for (int m = 0; m < 4; ++m) _Pragma("unroll") for (int k = 0; k < 2; ++k) dst[m][k] = *(const LAS bf16x8*)(lds + PG8_SA(b, h) + aoff + m * 2048 + k * 1024); } while (0)
; #define PG8_LDB(dst, b, h) do { _Pragma("unroll") for (int n = 0; n < 2; ++n) _Pragma("unroll") for (int k = 0; k < 2; ++k) dst[n][k] = *(const LAS bf16x8*)(lds + PG8_SB(b, h) + boff + n * 2048 + k * 1024); } while (0)
; #define PG8_MMA(ai, bj, At, Bt) do { __builtin_amdgcn_s_setprio(1); _Pragma("unroll") for (int m = 0; m < 4; ++m) _Pragma("unroll") for (int n = 0; n < 2; ++n) _Pragma("unroll") for (int k = 0; k < 2; ++k) \
;         acc[ai][bj][m][n] = __builtin_amdgcn_mfma_f32_16x16x32_bf16(Bt[n][k], At[m][k], acc[ai][bj][m][n], 0, 0, 0); __builtin_amdgcn_s_setprio(0); } while (0)
; #define PG8_WAIT_V(n) asm volatile("s_waitcnt vmcnt(" #n ")" ::: "memory")
; #define PG8_WAIT_L(n) asm volatile("s_waitcnt lgkmcnt(" #n ")" ::: "memory")
; #define PG8_BAR __builtin_amdgcn_s_barrier()
; #define PG8_SCHED __builtin_amdgcn_sched_barrier(0)
; template <class Epi, class Sched, bool ALIGN_EPI, class Hook = NoHook>
; __device__ __forceinline__ void gemm_phase(LAS unsigned char* lds, const Gemm g, const Sched& S, const Epi& E, const Hook& H = Hook()) {
;     ...
;             PG8_LDB(B0, 1, 0); PG8_LDB(B1, 1, 1); PG8_SCHED; PG8_LDA(At, 1, 0); PG8_STAGE(PG8_SA(0, 1), a2 + hA, voffA);
;             PG8_WAIT_V(8); PG8_WAIT_L(0); PG8_BAR; PG8_MMA(0, 0, At, B0); PG8_MMA(0, 1, At, B1); PG8_BAR; PG8_SCHED;
;             PG8_LDA(At, 1, 1); PG8_STAGE(PG8_SB(1, 0), b3, voffB); PG8_STAGE(PG8_SB(1, 1), b3 + hB, voffB); PG8_STAGE(PG8_SA(1, 0), a3, voffA);
;             PG8_WAIT_V(8); PG8_WAIT_L(0); PG8_BAR; PG8_MMA(1, 0, At, B0); PG8_MMA(1, 1, At, B1); PG8_BAR; PG8_SCHED;
;         }
	s_add_i32 s65, 0, 0x18000
	s_add_i32 s66, 0, 0x1c000
	v_add_u32_e32 v142, s65, v213
	v_add_u32_e32 v158, s66, v213
	ds_read_b128 v[130:133], v142
	ds_read_b128 v[134:137], v142 offset:1024
	s_add_u32 s4, s38, 0x8000
	s_addc_u32 s5, s39, 0
	s_mov_b32 m0, s42
	s_nop 0
	global_load_lds_dwordx4 v162, s[4:5]
	ds_read_b128 v[138:141], v142 offset:2048
	ds_read_b128 v[142:145], v142 offset:3072
	ds_read_b128 v[146:149], v158
	ds_read_b128 v[150:153], v158 offset:1024
	ds_read_b128 v[154:157], v158 offset:2048
	ds_read_b128 v[158:161], v158 offset:3072
	ds_read_b128 v[180:183], v219 offset:32768
	s_mov_b32 m0, s43
	s_nop 0
	global_load_lds_dwordx4 v166, s[4:5]
	ds_read_b128 v[184:187], v219 offset:33792
	ds_read_b128 v[188:191], v219 offset:34816
	ds_read_b128 v[192:195], v219 offset:35840
	ds_read_b128 v[196:199], v219 offset:36864
	ds_read_b128 v[200:203], v219 offset:37888
	ds_read_b128 v[204:207], v219 offset:38912
	ds_read_b128 v[208:211], v219 offset:39936
	s_waitcnt vmcnt(8)
	s_waitcnt lgkmcnt(0)
	s_barrier
	s_setprio 1
	s_waitcnt lgkmcnt(0)
	v_mfma_f32_16x16x32_bf16 v[126:129], v[130:133], v[180:183], v[126:129]
	v_mfma_f32_16x16x32_bf16 v[94:97], v[138:141], v[180:183], v[94:97]
	v_mfma_f32_16x16x32_bf16 v[122:125], v[130:133], v[188:191], v[122:125]
	v_mfma_f32_16x16x32_bf16 v[90:93], v[138:141], v[188:191], v[90:93]
	v_mfma_f32_16x16x32_bf16 v[118:121], v[130:133], v[196:199], v[118:121]
	v_mfma_f32_16x16x32_bf16 v[86:89], v[138:141], v[196:199], v[86:89]
	v_mfma_f32_16x16x32_bf16 v[114:117], v[130:133], v[204:207], v[114:117]
	v_mfma_f32_16x16x32_bf16 v[82:85], v[138:141], v[204:207], v[82:85]
	v_mfma_f32_16x16x32_bf16 v[126:129], v[134:137], v[184:187], v[126:129]
	v_mfma_f32_16x16x32_bf16 v[94:97], v[142:145], v[184:187], v[94:97]
	v_mfma_f32_16x16x32_bf16 v[122:125], v[134:137], v[192:195], v[122:125]
	v_mfma_f32_16x16x32_bf16 v[90:93], v[142:145], v[192:195], v[90:93]
	v_mfma_f32_16x16x32_bf16 v[118:121], v[134:137], v[200:203], v[118:121]
	v_mfma_f32_16x16x32_bf16 v[86:89], v[142:145], v[200:203], v[86:89]
	v_mfma_f32_16x16x32_bf16 v[114:117], v[134:137], v[208:211], v[114:117]
	v_mfma_f32_16x16x32_bf16 v[82:85], v[142:145], v[208:211], v[82:85]
	s_setprio 0
	s_setprio 1
	v_mfma_f32_16x16x32_bf16 v[62:65], v[146:149], v[180:183], v[62:65]
	v_mfma_f32_16x16x32_bf16 v[30:33], v[154:157], v[180:183], v[30:33]
	v_mfma_f32_16x16x32_bf16 v[58:61], v[146:149], v[188:191], v[58:61]
	v_mfma_f32_16x16x32_bf16 v[26:29], v[154:157], v[188:191], v[26:29]
	v_mfma_f32_16x16x32_bf16 v[54:57], v[146:149], v[196:199], v[54:57]
	v_mfma_f32_16x16x32_bf16 v[22:25], v[154:157], v[196:199], v[22:25]
	v_mfma_f32_16x16x32_bf16 v[50:53], v[146:149], v[204:207], v[50:53]
	v_mfma_f32_16x16x32_bf16 v[18:21], v[154:157], v[204:207], v[18:21]
	v_mfma_f32_16x16x32_bf16 v[62:65], v[150:153], v[184:187], v[62:65]
	v_mfma_f32_16x16x32_bf16 v[30:33], v[158:161], v[184:187], v[30:33]
	v_mfma_f32_16x16x32_bf16 v[58:61], v[150:153], v[192:195], v[58:61]
	v_mfma_f32_16x16x32_bf16 v[26:29], v[158:161], v[192:195], v[26:29]
	v_mfma_f32_16x16x32_bf16 v[54:57], v[150:153], v[200:203], v[54:57]
	v_mfma_f32_16x16x32_bf16 v[22:25], v[158:161], v[200:203], v[22:25]
	v_mfma_f32_16x16x32_bf16 v[50:53], v[150:153], v[208:211], v[50:53]
	v_mfma_f32_16x16x32_bf16 v[18:21], v[158:161], v[208:211], v[18:21]
	s_setprio 0
	s_barrier
	s_add_i32 s4, s65, s21
	s_add_u32 s68, s36, s14
	s_addc_u32 s69, s37, s15
	s_mov_b32 m0, s4
	ds_read_b128 v[180:183], v219 offset:49152
	ds_read_b128 v[184:187], v219 offset:50176
	global_load_lds_dwordx4 v164, s[68:69]
	ds_read_b128 v[188:191], v219 offset:51200
	s_add_i32 m0, s4, 0x2000
	s_add_u32 s4, s36, 0x100080
	s_addc_u32 s5, s37, 0
	s_add_i32 s36, s66, s21
	global_load_lds_dwordx4 v168, s[68:69]
	ds_read_b128 v[192:195], v219 offset:52224
	s_mov_b32 m0, s36
	s_nop 0
	global_load_lds_dwordx4 v164, s[4:5]
	ds_read_b128 v[196:199], v219 offset:53248
	s_add_i32 m0, s36, 0x2000
	s_nop 0
	global_load_lds_dwordx4 v168, s[4:5]
	ds_read_b128 v[200:203], v219 offset:54272
	s_add_u32 s70, s38, s14
	s_addc_u32 s71, s39, s15
	s_mov_b32 m0, s51
	s_nop 0
	global_load_lds_dwordx4 v162, s[70:71]
	ds_read_b128 v[204:207], v219 offset:55296
	s_mov_b32 m0, s52
	s_nop 0
	global_load_lds_dwordx4 v166, s[70:71]
	ds_read_b128 v[208:211], v219 offset:56320
	s_waitcnt vmcnt(8)
	s_waitcnt lgkmcnt(0)
	s_barrier
	s_setprio 1
	s_waitcnt lgkmcnt(0)
	v_mfma_f32_16x16x32_bf16 v[110:113], v[130:133], v[180:183], v[110:113]
	v_mfma_f32_16x16x32_bf16 v[78:81], v[138:141], v[180:183], v[78:81]
	v_mfma_f32_16x16x32_bf16 v[106:109], v[130:133], v[188:191], v[106:109]
	v_mfma_f32_16x16x32_bf16 v[74:77], v[138:141], v[188:191], v[74:77]
	v_mfma_f32_16x16x32_bf16 v[102:105], v[130:133], v[196:199], v[102:105]
	v_mfma_f32_16x16x32_bf16 v[70:73], v[138:141], v[196:199], v[70:73]
	v_mfma_f32_16x16x32_bf16 v[98:101], v[130:133], v[204:207], v[98:101]
	v_mfma_f32_16x16x32_bf16 v[66:69], v[138:141], v[204:207], v[66:69]
	v_mfma_f32_16x16x32_bf16 v[110:113], v[134:137], v[184:187], v[110:113]
	v_mfma_f32_16x16x32_bf16 v[78:81], v[142:145], v[184:187], v[78:81]
	v_mfma_f32_16x16x32_bf16 v[106:109], v[134:137], v[192:195], v[106:109]
	v_mfma_f32_16x16x32_bf16 v[74:77], v[142:145], v[192:195], v[74:77]
	v_mfma_f32_16x16x32_bf16 v[102:105], v[134:137], v[200:203], v[102:105]
	v_mfma_f32_16x16x32_bf16 v[70:73], v[142:145], v[200:203], v[70:73]
	v_mfma_f32_16x16x32_bf16 v[98:101], v[134:137], v[208:211], v[98:101]
	v_mfma_f32_16x16x32_bf16 v[66:69], v[142:145], v[208:211], v[66:69]
	s_setprio 0
	s_setprio 1
	v_mfma_f32_16x16x32_bf16 v[46:49], v[146:149], v[180:183], v[46:49]
	v_mfma_f32_16x16x32_bf16 v[14:17], v[154:157], v[180:183], v[14:17]
	v_mfma_f32_16x16x32_bf16 v[42:45], v[146:149], v[188:191], v[42:45]
	v_mfma_f32_16x16x32_bf16 v[10:13], v[154:157], v[188:191], v[10:13]
	v_mfma_f32_16x16x32_bf16 v[38:41], v[146:149], v[196:199], v[38:41]
	v_mfma_f32_16x16x32_bf16 v[6:9], v[154:157], v[196:199], v[6:9]
	v_mfma_f32_16x16x32_bf16 v[34:37], v[146:149], v[204:207], v[34:37]
	v_mfma_f32_16x16x32_bf16 v[2:5], v[154:157], v[204:207], v[2:5]
	v_mfma_f32_16x16x32_bf16 v[46:49], v[150:153], v[184:187], v[46:49]
	v_mfma_f32_16x16x32_bf16 v[14:17], v[158:161], v[184:187], v[14:17]
	v_mfma_f32_16x16x32_bf16 v[42:45], v[150:153], v[192:195], v[42:45]
	v_mfma_f32_16x16x32_bf16 v[10:13], v[158:161], v[192:195], v[10:13]
	v_mfma_f32_16x16x32_bf16 v[38:41], v[150:153], v[200:203], v[38:41]
	v_mfma_f32_16x16x32_bf16 v[6:9], v[158:161], v[200:203], v[6:9]
	v_mfma_f32_16x16x32_bf16 v[34:37], v[150:153], v[208:211], v[34:37]
	v_mfma_f32_16x16x32_bf16 v[2:5], v[158:161], v[208:211], v[2:5]
	s_setprio 0
	s_add_i32 s64, s64, 2
	s_add_u32 s31, s31, 0x100
	s_addc_u32 s63, s63, 0
	s_cmp_gt_u32 s64, 61
	s_mov_b64 s[4:5], s[34:35]
	s_cbranch_scc0 .Lmy_d199B
	s_barrier

;     __host__ __device__ bool next(int i, Unit& u) const { const bool ok = StaticOrder::next(i >> 1, u); if (i & 1) { u.ka = D_INNER; u.nkt = D_ATT / BK; } else { u.ka = 0; u.nkt = D_INNER / BK; } return ok; }
;     __host__ __device__ bool next(int i, Unit& u) const { const long L = (long)i * G + c; if (L >= (long)nM * nS) return false; u.pm = (int)(L % nM); u.pn = 0; u.ka = (int)(L / nM) * kslab; u.nkt = kslab / BK; return true; }
;     __host__ __device__ bool next(int i, Unit& u) const { if (i > 0) return false; const int x = c & 7, j = c >> 3; u.pm = 16 * s + 4 * (x >> 1) + (j & 3); u.pn = 8 * (x & 1) + (j >> 2); u.ka = 0; u.nkt = nkt; return true; }
; template <class Epi, class Sched, bool ALIGN_EPI, class Hook = NoHook>
; __device__ __forceinline__ void gemm_phase(LAS unsigned char* lds, const Gemm g, const Sched& S, const Epi& E, const Hook& H = Hook()) {
;     ...
;         const bool has_next = S.next(ui + 1, nxt);
;         const char* nA = has_next ? (const char*)g.A + (size_t)nxt.pm * tA + (size_t)nxt.ka * 2 : cA; const char* nB = has_next ? (const char*)g.Bt + (size_t)nxt.pn * 2 * hB + (size_t)nxt.ka * 2 : cB;
;     ...
; #pragma unroll
;         for (int a = 0; a < 2; ++a)
; #pragma unroll
;             for (int b = 0; b < 2; ++b)
; #pragma unroll
;                 for (int m = 0; m < 4; ++m)
; #pragma unroll
;                     for (int n = 0; n < 2; ++n) acc[a][b][m][n] = (f32x4){0.f, 0.f, 0.f, 0.f};
.LBB0_261:
	s_ashr_i32 s11, s10, 31
	v_cmp_lt_i64_e32 vcc, s[14:15], v[140:141]
	s_lshl_b64 s[14:15], s[10:11], 21
	v_readlane_b32 s18, v255, 4
	v_readlane_b32 s19, v255, 5
	s_add_u32 s11, s18, s14
	s_addc_u32 s15, s19, s15
	s_ashr_i32 s13, s12, 31
	s_lshl_b64 s[18:19], s[12:13], 1
	s_add_u32 s14, s11, s18
	s_addc_u32 s15, s15, s19
	s_and_b64 s[24:25], vcc, exec
	s_cselect_b32 s11, s15, s21
	s_cselect_b32 s13, s14, s20
	s_add_u32 s18, s27, s18
	s_addc_u32 s19, s28, s19
	s_and_b64 s[24:25], vcc, exec
	s_cselect_b32 s40, s19, s23
	s_cselect_b32 s41, s18, s22
	s_add_u32 s20, s20, 0x100080
	s_addc_u32 s21, s21, 0
	s_add_u32 s42, s22, 0x100
	v_mov_b32_e32 v2, 0
	s_addc_u32 s43, s23, 0
	s_mov_b32 s50, -2
	v_mov_b32_e32 v3, v2
	v_mov_b32_e32 v4, v2
	v_mov_b32_e32 v5, v2
	v_mov_b32_e32 v6, v2
	v_mov_b32_e32 v7, v2
	v_mov_b32_e32 v8, v2
	v_mov_b32_e32 v9, v2
	v_mov_b32_e32 v10, v2
	v_mov_b32_e32 v11, v2
	v_mov_b32_e32 v12, v2
	v_mov_b32_e32 v13, v2
	v_mov_b32_e32 v14, v2
	v_mov_b32_e32 v15, v2
	v_mov_b32_e32 v16, v2
	v_mov_b32_e32 v17, v2
	v_mov_b32_e32 v26, v2
	v_mov_b32_e32 v27, v2
	v_mov_b32_e32 v28, v2
	v_mov_b32_e32 v29, v2
	v_mov_b32_e32 v30, v2
	v_mov_b32_e32 v31, v2
	v_mov_b32_e32 v32, v2
	v_mov_b32_e32 v33, v2
	v_mov_b32_e32 v42, v2
	v_mov_b32_e32 v43, v2
	v_mov_b32_e32 v44, v2
	v_mov_b32_e32 v45, v2
	v_mov_b32_e32 v46, v2
	v_mov_b32_e32 v47, v2
	v_mov_b32_e32 v48, v2
	v_mov_b32_e32 v49, v2
	v_mov_b32_e32 v18, v2
	v_mov_b32_e32 v19, v2
	v_mov_b32_e32 v20, v2
	v_mov_b32_e32 v21, v2
	v_mov_b32_e32 v22, v2
	v_mov_b32_e32 v23, v2
	v_mov_b32_e32 v24, v2
	v_mov_b32_e32 v25, v2
	v_mov_b32_e32 v34, v2
	v_mov_b32_e32 v35, v2
	v_mov_b32_e32 v36, v2
	v_mov_b32_e32 v37, v2
	v_mov_b32_e32 v38, v2
	v_mov_b32_e32 v39, v2
	v_mov_b32_e32 v40, v2
	v_mov_b32_e32 v41, v2
	v_mov_b32_e32 v50, v2
	v_mov_b32_e32 v51, v2
	v_mov_b32_e32 v52, v2
	v_mov_b32_e32 v53, v2
	v_mov_b32_e32 v54, v2
	v_mov_b32_e32 v55, v2
	v_mov_b32_e32 v56, v2
	v_mov_b32_e32 v57, v2
	v_mov_b32_e32 v58, v2
	v_mov_b32_e32 v59, v2
	v_mov_b32_e32 v60, v2
	v_mov_b32_e32 v61, v2
	v_mov_b32_e32 v62, v2
	v_mov_b32_e32 v63, v2
	v_mov_b32_e32 v64, v2
	v_mov_b32_e32 v65, v2
	v_mov_b32_e32 v66, v2
	v_mov_b32_e32 v67, v2
	v_mov_b32_e32 v68, v2
	v_mov_b32_e32 v69, v2
	v_mov_b32_e32 v70, v2
	v_mov_b32_e32 v71, v2
	v_mov_b32_e32 v72, v2
	v_mov_b32_e32 v73, v2
	v_mov_b32_e32 v74, v2
	v_mov_b32_e32 v75, v2
	v_mov_b32_e32 v76, v2
	v_mov_b32_e32 v77, v2
	v_mov_b32_e32 v78, v2
	v_mov_b32_e32 v79, v2
	v_mov_b32_e32 v80, v2
	v_mov_b32_e32 v81, v2
	v_mov_b32_e32 v86, v2
	v_mov_b32_e32 v87, v2
	v_mov_b32_e32 v88, v2
	v_mov_b32_e32 v89, v2
	v_mov_b32_e32 v94, v2
	v_mov_b32_e32 v95, v2
	v_mov_b32_e32 v96, v2
	v_mov_b32_e32 v97, v2
	v_mov_b32_e32 v102, v2
	v_mov_b32_e32 v103, v2
	v_mov_b32_e32 v104, v2
	v_mov_b32_e32 v105, v2
	v_mov_b32_e32 v110, v2
	v_mov_b32_e32 v111, v2
	v_mov_b32_e32 v112, v2
	v_mov_b32_e32 v113, v2
	v_mov_b32_e32 v82, v2
	v_mov_b32_e32 v83, v2
	v_mov_b32_e32 v84, v2
	v_mov_b32_e32 v85, v2
	v_mov_b32_e32 v90, v2
	v_mov_b32_e32 v91, v2
	v_mov_b32_e32 v92, v2
	v_mov_b32_e32 v93, v2
	v_mov_b32_e32 v98, v2
	v_mov_b32_e32 v99, v2
	v_mov_b32_e32 v100, v2
	v_mov_b32_e32 v101, v2
	v_mov_b32_e32 v106, v2
	v_mov_b32_e32 v107, v2
	v_mov_b32_e32 v108, v2
	v_mov_b32_e32 v109, v2
	v_mov_b32_e32 v114, v2
	v_mov_b32_e32 v115, v2
	v_mov_b32_e32 v116, v2
	v_mov_b32_e32 v117, v2
	v_mov_b32_e32 v118, v2
	v_mov_b32_e32 v119, v2
	v_mov_b32_e32 v120, v2
	v_mov_b32_e32 v121, v2
	v_mov_b32_e32 v122, v2
	v_mov_b32_e32 v123, v2
	v_mov_b32_e32 v124, v2
	v_mov_b32_e32 v125, v2
	v_mov_b32_e32 v126, v2
	v_mov_b32_e32 v127, v2
	v_mov_b32_e32 v128, v2
	v_mov_b32_e32 v129, v2
	s_branch .Lmy_r262E

; #define PG8_STAGE(bufoff, gbase, voff) do { _Pragma("unroll") for (int _i = 0; _i < 2; ++_i) \
;         __builtin_amdgcn_global_load_lds((const unsigned*)((const char*)(gbase) + (voff)[_i]), (LAS unsigned*)(lds + (bufoff) + ldsw + _i * 8192), 16, 0, 0); } while (0)
; #define PG8_LDA(dst, b, h) do { _Pragma("unroll") for (int m = 0; m < 4; ++m) _Pragma("unroll") for (int k = 0; k < 2; ++k) dst[m][k] = *(const LAS bf16x8*)(lds + PG8_SA(b, h) + aoff + m * 2048 + k * 1024); } while (0)
; #define PG8_LDB(dst, b, h) do { _Pragma("unroll") for (int n = 0; n < 2; ++n) _Pragma("unroll") for (int k = 0; k < 2; ++k) dst[n][k] = *(const LAS bf16x8*)(lds + PG8_SB(b, h) + boff + n * 2048 + k * 1024); } while (0)
; #define PG8_MMA(ai, bj, At, Bt) do { __builtin_amdgcn_s_setprio(1); _Pragma("unroll") for (int m = 0; m < 4; ++m) _Pragma("unroll") for (int n = 0; n < 2; ++n) _Pragma("unroll") for (int k = 0; k < 2; ++k) \
;         acc[ai][bj][m][n] = __builtin_amdgcn_mfma_f32_16x16x32_bf16(Bt[n][k], At[m][k], acc[ai][bj][m][n], 0, 0, 0); __builtin_amdgcn_s_setprio(0); } while (0)
; #define PG8_WAIT_V(n) asm volatile("s_waitcnt vmcnt(" #n ")" ::: "memory")
; #define PG8_WAIT_L(n) asm volatile("s_waitcnt lgkmcnt(" #n ")" ::: "memory")
; template <class Epi, class Sched, bool ALIGN_EPI, class Hook = NoHook>
; __device__ __forceinline__ void gemm_phase(LAS unsigned char* lds, const Gemm g, const Sched& S, const Epi& E, const Hook& H = Hook()) {
;     ...
;         for (int t = tb; t < te; t += 2) {
;             const bool last = (t == nt - 2);
;             const char* a1 = cA + (size_t)(t + 1) * kstep;
;             const char* a2 = last ? nA : cA + (size_t)(t + 2) * kstep; const char* b2 = last ? nB : cB + (size_t)(t + 2) * kstep;
;             const char* a3 = a2 + kstep; const char* b3 = b2 + kstep;
;             if (last && has_next) S.a_ready(nxt);
;             PG8_LDB(B0, 0, 0); PG8_LDB(B1, 0, 1); PG8_SCHED; PG8_LDA(At, 0, 0); PG8_STAGE(PG8_SA(1, 1), a1 + hA, voffA);
;             PG8_WAIT_V(8); PG8_WAIT_L(0); PG8_BAR; PG8_MMA(0, 0, At, B0); PG8_MMA(0, 1, At, B1); PG8_BAR; PG8_SCHED;
;             PG8_LDA(At, 0, 1); PG8_STAGE(PG8_SB(0, 0), b2, voffB); PG8_STAGE(PG8_SB(0, 1), b2 + hB, voffB); PG8_STAGE(PG8_SA(0, 0), a2, voffA);
;             PG8_WAIT_V(8); PG8_WAIT_L(0); PG8_BAR; PG8_MMA(1, 0, At, B0); PG8_MMA(1, 1, At, B1); PG8_BAR; PG8_SCHED;
.Lmy_r262E:
	ds_read_b128 v[148:151], v145
	ds_read_b128 v[152:155], v145 offset:1024
	s_add_u32 s22, s20, 0xfff00080
	s_addc_u32 s23, s21, -1
	s_cmp_eq_u32 s50, 4
	s_cselect_b32 s25, s11, s23
	s_cselect_b32 s24, s13, s22
	s_cselect_b32 s23, s40, s43
	s_cselect_b32 s22, s41, s42
	s_add_i32 m0, s5, 0xc000
	s_nop 0
	global_load_lds_dwordx4 v136, s[20:21]
	ds_read_b128 v[156:159], v145 offset:2048
	ds_read_b128 v[160:163], v145 offset:3072
	ds_read_b128 v[164:167], v146
	ds_read_b128 v[168:171], v146 offset:1024
	ds_read_b128 v[172:175], v146 offset:2048
	ds_read_b128 v[176:179], v146 offset:3072
	ds_read_b128 v[180:183], v147
	s_add_i32 m0, s5, 0xe000
	s_nop 0
	global_load_lds_dwordx4 v138, s[20:21]
	ds_read_b128 v[184:187], v147 offset:1024
	ds_read_b128 v[188:191], v147 offset:2048
	ds_read_b128 v[192:195], v147 offset:3072
	ds_read_b128 v[196:199], v147 offset:4096
	ds_read_b128 v[200:203], v147 offset:5120
	ds_read_b128 v[204:207], v147 offset:6144
	ds_read_b128 v[208:211], v147 offset:7168
	s_waitcnt vmcnt(8)
	s_waitcnt lgkmcnt(0)
	s_barrier
	s_setprio 1
	s_waitcnt lgkmcnt(0)
	v_mfma_f32_16x16x32_bf16 v[126:129], v[148:151], v[180:183], v[126:129]
	v_mfma_f32_16x16x32_bf16 v[122:125], v[156:159], v[180:183], v[122:125]
	v_mfma_f32_16x16x32_bf16 v[118:121], v[148:151], v[188:191], v[118:121]
	v_mfma_f32_16x16x32_bf16 v[114:117], v[156:159], v[188:191], v[114:117]
	v_mfma_f32_16x16x32_bf16 v[106:109], v[148:151], v[196:199], v[106:109]
	v_mfma_f32_16x16x32_bf16 v[98:101], v[156:159], v[196:199], v[98:101]
	v_mfma_f32_16x16x32_bf16 v[90:93], v[148:151], v[204:207], v[90:93]
	v_mfma_f32_16x16x32_bf16 v[82:85], v[156:159], v[204:207], v[82:85]
	v_mfma_f32_16x16x32_bf16 v[126:129], v[152:155], v[184:187], v[126:129]
	v_mfma_f32_16x16x32_bf16 v[122:125], v[160:163], v[184:187], v[122:125]
	v_mfma_f32_16x16x32_bf16 v[118:121], v[152:155], v[192:195], v[118:121]
	v_mfma_f32_16x16x32_bf16 v[114:117], v[160:163], v[192:195], v[114:117]
	v_mfma_f32_16x16x32_bf16 v[106:109], v[152:155], v[200:203], v[106:109]
	v_mfma_f32_16x16x32_bf16 v[98:101], v[160:163], v[200:203], v[98:101]
	v_mfma_f32_16x16x32_bf16 v[90:93], v[152:155], v[208:211], v[90:93]
	v_mfma_f32_16x16x32_bf16 v[82:85], v[160:163], v[208:211], v[82:85]
	s_setprio 0
	s_setprio 1
	v_mfma_f32_16x16x32_bf16 v[110:113], v[164:167], v[180:183], v[110:113]
	v_mfma_f32_16x16x32_bf16 v[102:105], v[172:175], v[180:183], v[102:105]
	v_mfma_f32_16x16x32_bf16 v[94:97], v[164:167], v[188:191], v[94:97]
	v_mfma_f32_16x16x32_bf16 v[86:89], v[172:175], v[188:191], v[86:89]
	v_mfma_f32_16x16x32_bf16 v[78:81], v[164:167], v[196:199], v[78:81]
	v_mfma_f32_16x16x32_bf16 v[74:77], v[172:175], v[196:199], v[74:77]
	v_mfma_f32_16x16x32_bf16 v[70:73], v[164:167], v[204:207], v[70:73]
	v_mfma_f32_16x16x32_bf16 v[66:69], v[172:175], v[204:207], v[66:69]
	v_mfma_f32_16x16x32_bf16 v[110:113], v[168:171], v[184:187], v[110:113]
	v_mfma_f32_16x16x32_bf16 v[102:105], v[176:179], v[184:187], v[102:105]
	v_mfma_f32_16x16x32_bf16 v[94:97], v[168:171], v[192:195], v[94:97]
	v_mfma_f32_16x16x32_bf16 v[86:89], v[176:179], v[192:195], v[86:89]
	v_mfma_f32_16x16x32_bf16 v[78:81], v[168:171], v[200:203], v[78:81]
	v_mfma_f32_16x16x32_bf16 v[74:77], v[176:179], v[200:203], v[74:77]
	v_mfma_f32_16x16x32_bf16 v[70:73], v[168:171], v[208:211], v[70:73]
	v_mfma_f32_16x16x32_bf16 v[66:69], v[176:179], v[208:211], v[66:69]
	s_setprio 0
	s_barrier
	s_add_i32 s51, s38, s29
	s_mov_b32 m0, s51
	ds_read_b128 v[180:183], v147 offset:16384
	ds_read_b128 v[184:187], v147 offset:17408
	global_load_lds_dwordx4 v132, s[22:23]
	ds_read_b128 v[188:191], v147 offset:18432
	s_add_i32 m0, s51, 0x2000
	s_add_u32 s52, s22, 0x100000
	s_addc_u32 s53, s23, 0
	s_add_i32 s51, s39, s29
	global_load_lds_dwordx4 v130, s[22:23]
	ds_read_b128 v[192:195], v147 offset:19456
	s_mov_b32 m0, s51
	s_nop 0
	global_load_lds_dwordx4 v132, s[52:53]
	ds_read_b128 v[196:199], v147 offset:20480
	s_add_i32 m0, s51, 0x2000
	s_nop 0
	global_load_lds_dwordx4 v130, s[52:53]
	ds_read_b128 v[200:203], v147 offset:21504
	s_add_u32 s56, s24, s8
	s_addc_u32 s57, s25, s9
	s_mov_b32 m0, s5
	s_nop 0
	global_load_lds_dwordx4 v132, s[24:25]
	ds_read_b128 v[204:207], v147 offset:22528
	s_mov_b32 m0, s7
	s_nop 0
	global_load_lds_dwordx4 v130, s[24:25]
	ds_read_b128 v[208:211], v147 offset:23552
	s_waitcnt vmcnt(8)
	s_waitcnt lgkmcnt(0)
	s_barrier
	s_setprio 1
	s_waitcnt lgkmcnt(0)
	v_mfma_f32_16x16x32_bf16 v[62:65], v[148:151], v[180:183], v[62:65]
	v_mfma_f32_16x16x32_bf16 v[58:61], v[156:159], v[180:183], v[58:61]
	v_mfma_f32_16x16x32_bf16 v[54:57], v[148:151], v[188:191], v[54:57]
	v_mfma_f32_16x16x32_bf16 v[50:53], v[156:159], v[188:191], v[50:53]
	v_mfma_f32_16x16x32_bf16 v[38:41], v[148:151], v[196:199], v[38:41]
	v_mfma_f32_16x16x32_bf16 v[34:37], v[156:159], v[196:199], v[34:37]
	v_mfma_f32_16x16x32_bf16 v[22:25], v[148:151], v[204:207], v[22:25]
	v_mfma_f32_16x16x32_bf16 v[18:21], v[156:159], v[204:207], v[18:21]
	v_mfma_f32_16x16x32_bf16 v[62:65], v[152:155], v[184:187], v[62:65]
	v_mfma_f32_16x16x32_bf16 v[58:61], v[160:163], v[184:187], v[58:61]
	v_mfma_f32_16x16x32_bf16 v[54:57], v[152:155], v[192:195], v[54:57]
	v_mfma_f32_16x16x32_bf16 v[50:53], v[160:163], v[192:195], v[50:53]
	v_mfma_f32_16x16x32_bf16 v[38:41], v[152:155], v[200:203], v[38:41]
	v_mfma_f32_16x16x32_bf16 v[34:37], v[160:163], v[200:203], v[34:37]
	v_mfma_f32_16x16x32_bf16 v[22:25], v[152:155], v[208:211], v[22:25]
	v_mfma_f32_16x16x32_bf16 v[18:21], v[160:163], v[208:211], v[18:21]
	s_setprio 0
	s_setprio 1
	v_mfma_f32_16x16x32_bf16 v[46:49], v[164:167], v[180:183], v[46:49]
	v_mfma_f32_16x16x32_bf16 v[42:45], v[172:175], v[180:183], v[42:45]
	v_mfma_f32_16x16x32_bf16 v[30:33], v[164:167], v[188:191], v[30:33]
	v_mfma_f32_16x16x32_bf16 v[26:29], v[172:175], v[188:191], v[26:29]
	v_mfma_f32_16x16x32_bf16 v[14:17], v[164:167], v[196:199], v[14:17]
	v_mfma_f32_16x16x32_bf16 v[10:13], v[172:175], v[196:199], v[10:13]
	v_mfma_f32_16x16x32_bf16 v[6:9], v[164:167], v[204:207], v[6:9]
	v_mfma_f32_16x16x32_bf16 v[2:5], v[172:175], v[204:207], v[2:5]
	v_mfma_f32_16x16x32_bf16 v[46:49], v[168:171], v[184:187], v[46:49]
	v_mfma_f32_16x16x32_bf16 v[42:45], v[176:179], v[184:187], v[42:45]
	v_mfma_f32_16x16x32_bf16 v[30:33], v[168:171], v[192:195], v[30:33]
	v_mfma_f32_16x16x32_bf16 v[26:29], v[176:179], v[192:195], v[26:29]
	v_mfma_f32_16x16x32_bf16 v[14:17], v[168:171], v[200:203], v[14:17]
	v_mfma_f32_16x16x32_bf16 v[10:13], v[176:179], v[200:203], v[10:13]
	v_mfma_f32_16x16x32_bf16 v[6:9], v[168:171], v[208:211], v[6:9]
	v_mfma_f32_16x16x32_bf16 v[2:5], v[176:179], v[208:211], v[2:5]
	s_setprio 0
	s_barrier
; #define PG8_STAGE(bufoff, gbase, voff) do { _Pragma("unroll") for (int _i = 0; _i < 2; ++_i) \
;         __builtin_amdgcn_global_load_lds((const unsigned*)((const char*)(gbase) + (voff)[_i]), (LAS unsigned*)(lds + (bufoff) + ldsw + _i * 8192), 16, 0, 0); } while (0)
; #define PG8_LDA(dst, b, h) do { _Pragma("unroll") for (int m = 0; m < 4; ++m) _Pragma("unroll") for (int k = 0; k < 2; ++k) dst[m][k] = *(const LAS bf16x8*)(lds + PG8_SA(b, h) + aoff + m * 2048 + k * 1024); } while (0)
; #define PG8_LDB(dst, b, h) do { _Pragma("unroll") for (int n = 0; n < 2; ++n) _Pragma("unroll") for (int k = 0; k < 2; ++k) dst[n][k] = *(const LAS bf16x8*)(lds + PG8_SB(b, h) + boff + n * 2048 + k * 1024); } while (0)
; #define PG8_MMA(ai, bj, At, Bt) do { __builtin_amdgcn_s_setprio(1); _Pragma("unroll") for (int m = 0; m < 4; ++m) _Pragma("unroll") for (int n = 0; n < 2; ++n) _Pragma("unroll") for (int k = 0; k < 2; ++k) \
;         acc[ai][bj][m][n] = __builtin_amdgcn_mfma_f32_16x16x32_bf16(Bt[n][k], At[m][k], acc[ai][bj][m][n], 0, 0, 0); __builtin_amdgcn_s_setprio(0); } while (0)
; #define PG8_WAIT_V(n) asm volatile("s_waitcnt vmcnt(" #n ")" ::: "memory")
; #define PG8_WAIT_L(n) asm volatile("s_waitcnt lgkmcnt(" #n ")" ::: "memory")
; #define PG8_BAR __builtin_amdgcn_s_barrier()
; #define PG8_SCHED __builtin_amdgcn_sched_barrier(0)
; template <class Epi, class Sched, bool ALIGN_EPI, class Hook = NoHook>
; __device__ __forceinline__ void gemm_phase(LAS unsigned char* lds, const Gemm g, const Sched& S, const Epi& E, const Hook& H = Hook()) {
;     ...
;             PG8_LDB(B0, 1, 0); PG8_LDB(B1, 1, 1); PG8_SCHED; PG8_LDA(At, 1, 0); PG8_STAGE(PG8_SA(0, 1), a2 + hA, voffA);
;             PG8_WAIT_V(8); PG8_WAIT_L(0); PG8_BAR; PG8_MMA(0, 0, At, B0); PG8_MMA(0, 1, At, B1); PG8_BAR; PG8_SCHED;
;             PG8_LDA(At, 1, 1); PG8_STAGE(PG8_SB(1, 0), b3, voffB); PG8_STAGE(PG8_SB(1, 1), b3 + hB, voffB); PG8_STAGE(PG8_SA(1, 0), a3, voffA);
;             PG8_WAIT_V(8); PG8_WAIT_L(0); PG8_BAR; PG8_MMA(1, 0, At, B0); PG8_MMA(1, 1, At, B1); PG8_BAR; PG8_SCHED;
	s_add_i32 s51, 0, 0x18000
	s_add_i32 s52, 0, 0x1c000
	v_add_u32_e32 v160, s51, v144
	v_add_u32_e32 v176, s52, v144
	ds_read_b128 v[148:151], v160
	ds_read_b128 v[152:155], v160 offset:1024
	s_add_u32 s24, s24, 0x100000
	s_addc_u32 s25, s25, 0
	s_mov_b32 m0, s30
	s_nop 0
	global_load_lds_dwordx4 v132, s[24:25]
	ds_read_b128 v[156:159], v160 offset:2048
	ds_read_b128 v[160:163], v160 offset:3072
	ds_read_b128 v[164:167], v176
	ds_read_b128 v[168:171], v176 offset:1024
	ds_read_b128 v[172:175], v176 offset:2048
	ds_read_b128 v[176:179], v176 offset:3072
	ds_read_b128 v[180:183], v147 offset:32768
	s_mov_b32 m0, s31
	s_nop 0
	global_load_lds_dwordx4 v130, s[24:25]
	ds_read_b128 v[184:187], v147 offset:33792
	ds_read_b128 v[188:191], v147 offset:34816
	ds_read_b128 v[192:195], v147 offset:35840
	ds_read_b128 v[196:199], v147 offset:36864
	ds_read_b128 v[200:203], v147 offset:37888
	ds_read_b128 v[204:207], v147 offset:38912
	ds_read_b128 v[208:211], v147 offset:39936
	s_waitcnt vmcnt(8)
	s_waitcnt lgkmcnt(0)
	s_barrier
	s_setprio 1
	s_waitcnt lgkmcnt(0)
	v_mfma_f32_16x16x32_bf16 v[126:129], v[148:151], v[180:183], v[126:129]
	v_mfma_f32_16x16x32_bf16 v[122:125], v[156:159], v[180:183], v[122:125]
	v_mfma_f32_16x16x32_bf16 v[118:121], v[148:151], v[188:191], v[118:121]
	v_mfma_f32_16x16x32_bf16 v[114:117], v[156:159], v[188:191], v[114:117]
	v_mfma_f32_16x16x32_bf16 v[106:109], v[148:151], v[196:199], v[106:109]
	v_mfma_f32_16x16x32_bf16 v[98:101], v[156:159], v[196:199], v[98:101]
	v_mfma_f32_16x16x32_bf16 v[90:93], v[148:151], v[204:207], v[90:93]
	v_mfma_f32_16x16x32_bf16 v[82:85], v[156:159], v[204:207], v[82:85]
	v_mfma_f32_16x16x32_bf16 v[126:129], v[152:155], v[184:187], v[126:129]
	v_mfma_f32_16x16x32_bf16 v[122:125], v[160:163], v[184:187], v[122:125]
	v_mfma_f32_16x16x32_bf16 v[118:121], v[152:155], v[192:195], v[118:121]
	v_mfma_f32_16x16x32_bf16 v[114:117], v[160:163], v[192:195], v[114:117]
	v_mfma_f32_16x16x32_bf16 v[106:109], v[152:155], v[200:203], v[106:109]
	v_mfma_f32_16x16x32_bf16 v[98:101], v[160:163], v[200:203], v[98:101]
	v_mfma_f32_16x16x32_bf16 v[90:93], v[152:155], v[208:211], v[90:93]
	v_mfma_f32_16x16x32_bf16 v[82:85], v[160:163], v[208:211], v[82:85]
	s_setprio 0
	s_setprio 1
	v_mfma_f32_16x16x32_bf16 v[110:113], v[164:167], v[180:183], v[110:113]
	v_mfma_f32_16x16x32_bf16 v[102:105], v[172:175], v[180:183], v[102:105]
	v_mfma_f32_16x16x32_bf16 v[94:97], v[164:167], v[188:191], v[94:97]
	v_mfma_f32_16x16x32_bf16 v[86:89], v[172:175], v[188:191], v[86:89]
	v_mfma_f32_16x16x32_bf16 v[78:81], v[164:167], v[196:199], v[78:81]
	v_mfma_f32_16x16x32_bf16 v[74:77], v[172:175], v[196:199], v[74:77]
	v_mfma_f32_16x16x32_bf16 v[70:73], v[164:167], v[204:207], v[70:73]
	v_mfma_f32_16x16x32_bf16 v[66:69], v[172:175], v[204:207], v[66:69]
	v_mfma_f32_16x16x32_bf16 v[110:113], v[168:171], v[184:187], v[110:113]
	v_mfma_f32_16x16x32_bf16 v[102:105], v[176:179], v[184:187], v[102:105]
	v_mfma_f32_16x16x32_bf16 v[94:97], v[168:171], v[192:195], v[94:97]
	v_mfma_f32_16x16x32_bf16 v[86:89], v[176:179], v[192:195], v[86:89]
	v_mfma_f32_16x16x32_bf16 v[78:81], v[168:171], v[200:203], v[78:81]
	v_mfma_f32_16x16x32_bf16 v[74:77], v[176:179], v[200:203], v[74:77]
	v_mfma_f32_16x16x32_bf16 v[70:73], v[168:171], v[208:211], v[70:73]
	v_mfma_f32_16x16x32_bf16 v[66:69], v[176:179], v[208:211], v[66:69]
	s_setprio 0
	s_barrier
	s_add_i32 s24, s51, s29
	s_add_u32 s54, s22, s8
	s_addc_u32 s55, s23, s9
	s_mov_b32 m0, s24
	ds_read_b128 v[180:183], v147 offset:49152
	ds_read_b128 v[184:187], v147 offset:50176
	global_load_lds_dwordx4 v132, s[54:55]
	ds_read_b128 v[188:191], v147 offset:51200
	s_add_i32 m0, s24, 0x2000
	s_add_u32 s22, s22, 0x100080
	s_addc_u32 s23, s23, 0
	s_add_i32 s24, s52, s29
	global_load_lds_dwordx4 v130, s[54:55]
	ds_read_b128 v[192:195], v147 offset:52224
	s_mov_b32 m0, s24
	s_nop 0
	global_load_lds_dwordx4 v132, s[22:23]
	ds_read_b128 v[196:199], v147 offset:53248
	s_add_i32 m0, s24, 0x2000
	s_nop 0
	global_load_lds_dwordx4 v130, s[22:23]
	ds_read_b128 v[200:203], v147 offset:54272
	s_mov_b32 m0, s35
	s_nop 0
	global_load_lds_dwordx4 v132, s[56:57]
	ds_read_b128 v[204:207], v147 offset:55296
	s_mov_b32 m0, s36
	s_nop 0
	global_load_lds_dwordx4 v130, s[56:57]
	ds_read_b128 v[208:211], v147 offset:56320
	s_waitcnt vmcnt(8)
	s_waitcnt lgkmcnt(0)
	s_barrier
; #define PG8_STAGE(bufoff, gbase, voff) do { _Pragma("unroll") for (int _i = 0; _i < 2; ++_i) \
;         __builtin_amdgcn_global_load_lds((const unsigned*)((const char*)(gbase) + (voff)[_i]), (LAS unsigned*)(lds + (bufoff) + ldsw + _i * 8192), 16, 0, 0); } while (0)
; #define PG8_LDA(dst, b, h) do { _Pragma("unroll") for (int m = 0; m < 4; ++m) _Pragma("unroll") for (int k = 0; k < 2; ++k) dst[m][k] = *(const LAS bf16x8*)(lds + PG8_SA(b, h) + aoff + m * 2048 + k * 1024); } while (0)
; #define PG8_LDB(dst, b, h) do { _Pragma("unroll") for (int n = 0; n < 2; ++n) _Pragma("unroll") for (int k = 0; k < 2; ++k) dst[n][k] = *(const LAS bf16x8*)(lds + PG8_SB(b, h) + boff + n * 2048 + k * 1024); } while (0)
; #define PG8_WAIT_V(n) asm volatile("s_waitcnt vmcnt(" #n ")" ::: "memory")
; #define PG8_WAIT_L(n) asm volatile("s_waitcnt lgkmcnt(" #n ")" ::: "memory")
; #define PG8_BAR __builtin_amdgcn_s_barrier()
; #define PG8_SCHED __builtin_amdgcn_sched_barrier(0)
;     __device__ __forceinline__ void operator()(const f32x4 (&acc)[2][2][4][2], const Unit& u, int wr, int wc, int fr, int fq) const {
;         float* base = C + (size_t)(u.ka / kslab) * slab_stride;
;         const int row0 = u.pm * BM + wr * 64 + fr, col0 = wc * 32 + 4 * fq;
; #pragma unroll
;         for (int ai = 0; ai < 2; ++ai)
; #pragma unroll
;             for (int m = 0; m < 4; ++m) { float* rowp = base + (size_t)(row0 + ai * HALF + m * 16) * 256 + col0;
; #pragma unroll
;                 for (int bj = 0; bj < 2; ++bj)
; #pragma unroll
;                     for (int n = 0; n < 2; ++n) *(f32x4*)(rowp + bj * HALF + n * 16) = acc[ai][bj][m][n]; }
; template <class Epi, class Sched, bool ALIGN_EPI, class Hook = NoHook>
; __device__ __forceinline__ void gemm_phase(LAS unsigned char* lds, const Gemm g, const Sched& S, const Epi& E, const Hook& H = Hook()) {
;     ...
;             PG8_LDB(B0, 1, 0); PG8_LDB(B1, 1, 1); PG8_SCHED; PG8_LDA(At, 1, 0); PG8_STAGE(PG8_SA(0, 1), a2 + hA, voffA);
;             PG8_WAIT_V(8); PG8_WAIT_L(0); PG8_BAR; PG8_MMA(0, 0, At, B0); PG8_MMA(0, 1, At, B1); PG8_BAR; PG8_SCHED;
;             PG8_LDA(At, 1, 1); PG8_STAGE(PG8_SB(1, 0), b3, voffB); PG8_STAGE(PG8_SB(1, 1), b3 + hB, voffB); PG8_STAGE(PG8_SA(1, 0), a3, voffA);
;             PG8_WAIT_V(8); PG8_WAIT_L(0); PG8_BAR; PG8_MMA(1, 0, At, B0); PG8_MMA(1, 1, At, B1); PG8_BAR; PG8_SCHED;
;         }
	s_setprio 1
	s_waitcnt lgkmcnt(0)
	v_mfma_f32_16x16x32_bf16 v[62:65], v[148:151], v[180:183], v[62:65]
	v_mfma_f32_16x16x32_bf16 v[58:61], v[156:159], v[180:183], v[58:61]
	v_mfma_f32_16x16x32_bf16 v[54:57], v[148:151], v[188:191], v[54:57]
	v_mfma_f32_16x16x32_bf16 v[50:53], v[156:159], v[188:191], v[50:53]
	v_mfma_f32_16x16x32_bf16 v[38:41], v[148:151], v[196:199], v[38:41]
	v_mfma_f32_16x16x32_bf16 v[34:37], v[156:159], v[196:199], v[34:37]
	v_mfma_f32_16x16x32_bf16 v[22:25], v[148:151], v[204:207], v[22:25]
	v_mfma_f32_16x16x32_bf16 v[18:21], v[156:159], v[204:207], v[18:21]
	v_mfma_f32_16x16x32_bf16 v[62:65], v[152:155], v[184:187], v[62:65]
	v_mfma_f32_16x16x32_bf16 v[58:61], v[160:163], v[184:187], v[58:61]
	v_mfma_f32_16x16x32_bf16 v[54:57], v[152:155], v[192:195], v[54:57]
	v_mfma_f32_16x16x32_bf16 v[50:53], v[160:163], v[192:195], v[50:53]
	v_mfma_f32_16x16x32_bf16 v[38:41], v[152:155], v[200:203], v[38:41]
	v_mfma_f32_16x16x32_bf16 v[34:37], v[160:163], v[200:203], v[34:37]
	v_mfma_f32_16x16x32_bf16 v[22:25], v[152:155], v[208:211], v[22:25]
	v_mfma_f32_16x16x32_bf16 v[18:21], v[160:163], v[208:211], v[18:21]
	s_setprio 0
	s_setprio 1
	v_mfma_f32_16x16x32_bf16 v[46:49], v[164:167], v[180:183], v[46:49]
	v_mfma_f32_16x16x32_bf16 v[42:45], v[172:175], v[180:183], v[42:45]
	v_mfma_f32_16x16x32_bf16 v[30:33], v[164:167], v[188:191], v[30:33]
	v_mfma_f32_16x16x32_bf16 v[26:29], v[172:175], v[188:191], v[26:29]
	v_mfma_f32_16x16x32_bf16 v[14:17], v[164:167], v[196:199], v[14:17]
	v_mfma_f32_16x16x32_bf16 v[10:13], v[172:175], v[196:199], v[10:13]
	v_mfma_f32_16x16x32_bf16 v[6:9], v[164:167], v[204:207], v[6:9]
	v_mfma_f32_16x16x32_bf16 v[2:5], v[172:175], v[204:207], v[2:5]
	v_mfma_f32_16x16x32_bf16 v[46:49], v[168:171], v[184:187], v[46:49]
	v_mfma_f32_16x16x32_bf16 v[42:45], v[176:179], v[184:187], v[42:45]
	v_mfma_f32_16x16x32_bf16 v[30:33], v[168:171], v[192:195], v[30:33]
	v_mfma_f32_16x16x32_bf16 v[26:29], v[176:179], v[192:195], v[26:29]
	v_mfma_f32_16x16x32_bf16 v[14:17], v[168:171], v[200:203], v[14:17]
	v_mfma_f32_16x16x32_bf16 v[10:13], v[176:179], v[200:203], v[10:13]
	v_mfma_f32_16x16x32_bf16 v[6:9], v[168:171], v[208:211], v[6:9]
	v_mfma_f32_16x16x32_bf16 v[2:5], v[176:179], v[208:211], v[2:5]
	s_setprio 0
	s_add_i32 s50, s50, 2
	s_add_u32 s20, s20, 0x100
	s_addc_u32 s21, s21, 0
	s_add_u32 s42, s42, 0x100
	s_addc_u32 s43, s43, 0
	s_cmp_gt_u32 s50, 5
	s_cbranch_scc0 .LBB0_262
	s_barrier
	s_ashr_i32 s11, s6, 31
	s_lshr_b32 s11, s11, 23
	s_add_i32 s6, s6, s11
	s_ashr_i32 s20, s6, 9
	s_ashr_i32 s21, s20, 31
	v_lshl_add_u32 v148, s4, 8, v1
	s_lshl_b64 s[20:21], s[20:21], 23
	v_ashrrev_i32_e32 v149, 31, v148
	v_lshl_add_u64 v[150:151], v[134:135], 0, s[20:21]
	v_lshlrev_b64 v[152:153], 10, v[148:149]
	v_lshl_add_u64 v[152:153], v[150:151], 0, v[152:153]
	global_store_dwordx4 v[152:153], v[126:129], off
	global_store_dwordx4 v[152:153], v[122:125], off offset:64
	global_store_dwordx4 v[152:153], v[110:113], off offset:512
	global_store_dwordx4 v[152:153], v[102:105], off offset:576
	s_mov_b32 s4, 0x20000
	s_mov_b64 s[20:21], 0x20000
	v_or_b32_e32 v102, 16, v148
	v_ashrrev_i32_e32 v103, 31, v102
	v_lshlrev_b64 v[102:103], 10, v[102:103]
	v_lshl_add_u64 v[102:103], v[150:151], 0, v[102:103]
	global_store_dwordx4 v[102:103], v[118:121], off
	global_store_dwordx4 v[102:103], v[114:117], off offset:64
	global_store_dwordx4 v[102:103], v[94:97], off offset:512
	global_store_dwordx4 v[102:103], v[86:89], off offset:576
	s_mov_b32 s6, s12
	s_mov_b64 s[22:23], s[18:19]
	v_or_b32_e32 v86, 32, v148
	v_ashrrev_i32_e32 v87, 31, v86
	v_lshlrev_b64 v[86:87], 10, v[86:87]
	v_lshl_add_u64 v[86:87], v[150:151], 0, v[86:87]
	global_store_dwordx4 v[86:87], v[106:109], off
	global_store_dwordx4 v[86:87], v[98:101], off offset:64
	global_store_dwordx4 v[86:87], v[78:81], off offset:512
	global_store_dwordx4 v[86:87], v[74:77], off offset:576
	s_nop 1
	v_or_b32_e32 v74, 48, v148
	v_ashrrev_i32_e32 v75, 31, v74
	v_lshlrev_b64 v[74:75], 10, v[74:75]
	v_lshl_add_u64 v[74:75], v[150:151], 0, v[74:75]
	global_store_dwordx4 v[74:75], v[90:93], off
	global_store_dwordx4 v[74:75], v[82:85], off offset:64
	global_store_dwordx4 v[74:75], v[70:73], off offset:512
	global_store_dwordx4 v[74:75], v[66:69], off offset:576
	s_nop 1
	v_add_co_u32_e32 v68, vcc, s4, v152
	s_mov_b32 s4, 0x24000
	s_nop 0
	v_addc_co_u32_e32 v69, vcc, 0, v153, vcc
	v_lshl_add_u64 v[66:67], v[152:153], 0, s[20:21]
	global_store_dwordx4 v[68:69], v[62:65], off
	global_store_dwordx4 v[66:67], v[58:61], off offset:64
	global_store_dwordx4 v[66:67], v[46:49], off offset:512
	global_store_dwordx4 v[66:67], v[42:45], off offset:576
	s_mov_b64 s[20:21], 0x24000
	s_nop 0
	v_add_co_u32_e32 v44, vcc, s4, v152
	s_mov_b32 s4, 0x28000
	s_nop 0
	v_addc_co_u32_e32 v45, vcc, 0, v153, vcc
	v_lshl_add_u64 v[42:43], v[152:153], 0, s[20:21]
	global_store_dwordx4 v[44:45], v[54:57], off
	global_store_dwordx4 v[42:43], v[50:53], off offset:64
	global_store_dwordx4 v[42:43], v[30:33], off offset:512
	global_store_dwordx4 v[42:43], v[26:29], off offset:576
	s_mov_b64 s[20:21], 0x28000
	s_nop 0
	v_add_co_u32_e32 v28, vcc, s4, v152
	v_lshl_add_u64 v[26:27], v[152:153], 0, s[20:21]
	s_nop 0
	v_addc_co_u32_e32 v29, vcc, 0, v153, vcc
	global_store_dwordx4 v[28:29], v[38:41], off
	global_store_dwordx4 v[26:27], v[34:37], off offset:64
	global_store_dwordx4 v[26:27], v[14:17], off offset:512
	global_store_dwordx4 v[26:27], v[10:13], off offset:576
	s_mov_b64 s[20:21], 0x2c000
	s_mov_b32 s4, s10
	v_add_co_u32_e32 v12, vcc, 0x2c000, v152
	v_lshl_add_u64 v[10:11], v[152:153], 0, s[20:21]
	s_nop 0
	v_addc_co_u32_e32 v13, vcc, 0, v153, vcc
	s_and_b64 vcc, exec, s[2:3]
	s_mov_b64 s[20:21], s[14:15]
	global_store_dwordx4 v[12:13], v[22:25], off
	global_store_dwordx4 v[10:11], v[18:21], off offset:64
	global_store_dwordx4 v[10:11], v[6:9], off offset:512
	global_store_dwordx4 v[10:11], v[2:5], off offset:576
	s_cbranch_vccz .LBB0_259
	s_waitcnt vmcnt(0)
	s_cmpk_gt_u32 s26, 0xff
	s_cbranch_scc1 .LBB0_266
	s_barrier

; template <class Epi, class Sched, bool ALIGN_EPI, class Hook = NoHook>
; __device__ __forceinline__ void gemm_phase(LAS unsigned char* lds, const Gemm g, const Sched& S, const Epi& E, const Hook& H = Hook()) {
;     ...
;         for (int tb = 0; tb < nt; tb += (Hook::ON ? Hook::SEG : nt)) {
;         const int te = Hook::ON ? tb + Hook::SEG : nt;
;         for (int t = tb; t < te; t += 2) {
.LBB0_782:
	s_add_i32 s66, s65, 16
	s_mov_b64 s[26:27], s[24:25]
	s_mov_b32 s67, s65
	s_branch .Lmy_r783E

; #define PG8_STAGE(bufoff, gbase, voff) do { _Pragma("unroll") for (int _i = 0; _i < 2; ++_i) \
;         __builtin_amdgcn_global_load_lds((const unsigned*)((const char*)(gbase) + (voff)[_i]), (LAS unsigned*)(lds + (bufoff) + ldsw + _i * 8192), 16, 0, 0); } while (0)
; #define PG8_LDA(dst, b, h) do { _Pragma("unroll") for (int m = 0; m < 4; ++m) _Pragma("unroll") for (int k = 0; k < 2; ++k) dst[m][k] = *(const LAS bf16x8*)(lds + PG8_SA(b, h) + aoff + m * 2048 + k * 1024); } while (0)
; #define PG8_LDB(dst, b, h) do { _Pragma("unroll") for (int n = 0; n < 2; ++n) _Pragma("unroll") for (int k = 0; k < 2; ++k) dst[n][k] = *(const LAS bf16x8*)(lds + PG8_SB(b, h) + boff + n * 2048 + k * 1024); } while (0)
; #define PG8_MMA(ai, bj, At, Bt) do { __builtin_amdgcn_s_setprio(1); _Pragma("unroll") for (int m = 0; m < 4; ++m) _Pragma("unroll") for (int n = 0; n < 2; ++n) _Pragma("unroll") for (int k = 0; k < 2; ++k) \
;         acc[ai][bj][m][n] = __builtin_amdgcn_mfma_f32_16x16x32_bf16(Bt[n][k], At[m][k], acc[ai][bj][m][n], 0, 0, 0); __builtin_amdgcn_s_setprio(0); } while (0)
; #define PG8_WAIT_V(n) asm volatile("s_waitcnt vmcnt(" #n ")" ::: "memory")
; #define PG8_WAIT_L(n) asm volatile("s_waitcnt lgkmcnt(" #n ")" ::: "memory")
; template <class Epi, class Sched, bool ALIGN_EPI, class Hook = NoHook>
; __device__ __forceinline__ void gemm_phase(LAS unsigned char* lds, const Gemm g, const Sched& S, const Epi& E, const Hook& H = Hook()) {
;     ...
;         for (int t = tb; t < te; t += 2) {
;             const bool last = (t == nt - 2);
;             const char* a1 = cA + (size_t)(t + 1) * kstep;
;             const char* a2 = last ? nA : cA + (size_t)(t + 2) * kstep; const char* b2 = last ? nB : cB + (size_t)(t + 2) * kstep;
;             const char* a3 = a2 + kstep; const char* b3 = b2 + kstep;
;             if (last && has_next) S.a_ready(nxt);
;             PG8_LDB(B0, 0, 0); PG8_LDB(B1, 0, 1); PG8_SCHED; PG8_LDA(At, 0, 0); PG8_STAGE(PG8_SA(1, 1), a1 + hA, voffA);
;             PG8_WAIT_V(8); PG8_WAIT_L(0); PG8_BAR; PG8_MMA(0, 0, At, B0); PG8_MMA(0, 1, At, B1); PG8_BAR; PG8_SCHED;
;             PG8_LDA(At, 0, 1); PG8_STAGE(PG8_SB(0, 0), b2, voffB); PG8_STAGE(PG8_SB(0, 1), b2 + hB, voffB); PG8_STAGE(PG8_SA(0, 0), a2, voffA);
;             PG8_WAIT_V(8); PG8_WAIT_L(0); PG8_BAR; PG8_MMA(1, 0, At, B0); PG8_MMA(1, 1, At, B1); PG8_BAR; PG8_SCHED;
.Lmy_r783E:
	v_add_u32_e32 v3, s56, v222
	s_add_i32 s67, s67, 2
	ds_read_b128 v[126:129], v3
	ds_read_b128 v[130:133], v3 offset:1024
	ds_read_b128 v[142:145], v3 offset:2048
	ds_read_b128 v[146:149], v3 offset:3072
	v_add_u32_e32 v3, s57, v222
	s_add_u32 s28, s22, s26
	s_addc_u32 s29, s23, s27
	s_add_u32 s28, s28, 0x100
	s_addc_u32 s29, s29, 0
	s_add_u32 s68, s63, s26
	s_addc_u32 s69, s64, s27
	s_cmpk_eq_i32 s26, 0x5f00
	s_cselect_b32 s31, s5, s29
	s_cselect_b32 s30, s4, s28
	s_cselect_b32 s29, s21, s69
	s_cselect_b32 s28, s20, s68
	ds_read_b128 v[150:153], v3
	ds_read_b128 v[154:157], v3 offset:1024
	ds_read_b128 v[158:161], v3 offset:2048
	ds_read_b128 v[162:165], v3 offset:3072
	v_lshl_add_u64 v[4:5], v[182:183], 0, s[26:27]
	s_add_i32 m0, s37, 0xc000
	s_nop 0
	global_load_lds_dwordx4 v[4:5], off
	ds_read_b128 v[186:189], v224
	ds_read_b128 v[190:193], v224 offset:1024
	ds_read_b128 v[194:197], v224 offset:2048
	ds_read_b128 v[198:201], v224 offset:3072
	ds_read_b128 v[202:205], v224 offset:4096
	ds_read_b128 v[206:209], v224 offset:5120
	ds_read_b128 v[210:213], v224 offset:6144
	ds_read_b128 v[214:217], v224 offset:7168
	v_lshl_add_u64 v[4:5], v[184:185], 0, s[26:27]
	s_add_i32 m0, s37, 0xe000
	s_nop 0
	global_load_lds_dwordx4 v[4:5], off
	s_waitcnt vmcnt(8)
	s_waitcnt lgkmcnt(0)
	s_barrier
	s_setprio 1
	s_waitcnt lgkmcnt(0)
	v_mfma_f32_16x16x32_bf16 v[138:141], v[126:129], v[186:189], v[138:141]
	v_mfma_f32_16x16x32_bf16 v[134:137], v[142:145], v[186:189], v[134:137]
	v_mfma_f32_16x16x32_bf16 v[122:125], v[126:129], v[194:197], v[122:125]
	v_mfma_f32_16x16x32_bf16 v[118:121], v[142:145], v[194:197], v[118:121]
	v_mfma_f32_16x16x32_bf16 v[114:117], v[126:129], v[202:205], v[114:117]
	v_mfma_f32_16x16x32_bf16 v[110:113], v[142:145], v[202:205], v[110:113]
	v_mfma_f32_16x16x32_bf16 v[106:109], v[126:129], v[210:213], v[106:109]
	v_mfma_f32_16x16x32_bf16 v[102:105], v[142:145], v[210:213], v[102:105]
	v_mfma_f32_16x16x32_bf16 v[138:141], v[130:133], v[190:193], v[138:141]
	v_mfma_f32_16x16x32_bf16 v[134:137], v[146:149], v[190:193], v[134:137]
	v_mfma_f32_16x16x32_bf16 v[122:125], v[130:133], v[198:201], v[122:125]
	v_mfma_f32_16x16x32_bf16 v[118:121], v[146:149], v[198:201], v[118:121]
	v_mfma_f32_16x16x32_bf16 v[114:117], v[130:133], v[206:209], v[114:117]
	v_mfma_f32_16x16x32_bf16 v[110:113], v[146:149], v[206:209], v[110:113]
	v_mfma_f32_16x16x32_bf16 v[106:109], v[130:133], v[214:217], v[106:109]
	v_mfma_f32_16x16x32_bf16 v[102:105], v[146:149], v[214:217], v[102:105]
	s_setprio 0
	s_setprio 1
	v_mfma_f32_16x16x32_bf16 v[66:69], v[150:153], v[186:189], v[66:69]
	v_mfma_f32_16x16x32_bf16 v[62:65], v[158:161], v[186:189], v[62:65]
	v_mfma_f32_16x16x32_bf16 v[58:61], v[150:153], v[194:197], v[58:61]
	v_mfma_f32_16x16x32_bf16 v[54:57], v[158:161], v[194:197], v[54:57]
	v_mfma_f32_16x16x32_bf16 v[50:53], v[150:153], v[202:205], v[50:53]
	v_mfma_f32_16x16x32_bf16 v[46:49], v[158:161], v[202:205], v[46:49]
	v_mfma_f32_16x16x32_bf16 v[42:45], v[150:153], v[210:213], v[42:45]
	v_mfma_f32_16x16x32_bf16 v[38:41], v[158:161], v[210:213], v[38:41]
	v_mfma_f32_16x16x32_bf16 v[66:69], v[154:157], v[190:193], v[66:69]
	v_mfma_f32_16x16x32_bf16 v[62:65], v[162:165], v[190:193], v[62:65]
	v_mfma_f32_16x16x32_bf16 v[58:61], v[154:157], v[198:201], v[58:61]
	v_mfma_f32_16x16x32_bf16 v[54:57], v[162:165], v[198:201], v[54:57]
	v_mfma_f32_16x16x32_bf16 v[50:53], v[154:157], v[206:209], v[50:53]
	v_mfma_f32_16x16x32_bf16 v[46:49], v[162:165], v[206:209], v[46:49]
	v_mfma_f32_16x16x32_bf16 v[42:45], v[154:157], v[214:217], v[42:45]
	v_mfma_f32_16x16x32_bf16 v[38:41], v[162:165], v[214:217], v[38:41]
	s_setprio 0
	s_barrier
	s_add_i32 s68, s56, s35
	s_mov_b32 m0, s68
	ds_read_b128 v[186:189], v224 offset:16384
	ds_read_b128 v[190:193], v224 offset:17408
	global_load_lds_dwordx4 v168, s[28:29]
	ds_read_b128 v[194:197], v224 offset:18432
	s_add_i32 m0, s68, 0x2000
	s_add_u32 s68, s28, 0x300000
	s_addc_u32 s69, s29, 0
	s_add_i32 s70, s57, s35
	global_load_lds_dwordx4 v172, s[28:29]
	ds_read_b128 v[198:201], v224 offset:19456
	s_mov_b32 m0, s70
	s_add_u32 s74, s30, s14
	s_addc_u32 s75, s31, s15
	global_load_lds_dwordx4 v168, s[68:69]
	ds_read_b128 v[202:205], v224 offset:20480
	s_add_i32 m0, s70, 0x2000
	s_nop 0
	global_load_lds_dwordx4 v172, s[68:69]
	ds_read_b128 v[206:209], v224 offset:21504
	s_mov_b32 m0, s37
	s_nop 0
	global_load_lds_dwordx4 v166, s[30:31]
	ds_read_b128 v[210:213], v224 offset:22528
	s_mov_b32 m0, s38
	s_nop 0
	global_load_lds_dwordx4 v170, s[30:31]
	ds_read_b128 v[214:217], v224 offset:23552
	s_waitcnt vmcnt(8)
	s_waitcnt lgkmcnt(0)
	s_barrier
; #define PG8_STAGE(bufoff, gbase, voff) do { _Pragma("unroll") for (int _i = 0; _i < 2; ++_i) \
;         __builtin_amdgcn_global_load_lds((const unsigned*)((const char*)(gbase) + (voff)[_i]), (LAS unsigned*)(lds + (bufoff) + ldsw + _i * 8192), 16, 0, 0); } while (0)
; #define PG8_LDA(dst, b, h) do { _Pragma("unroll") for (int m = 0; m < 4; ++m) _Pragma("unroll") for (int k = 0; k < 2; ++k) dst[m][k] = *(const LAS bf16x8*)(lds + PG8_SA(b, h) + aoff + m * 2048 + k * 1024); } while (0)
; #define PG8_LDB(dst, b, h) do { _Pragma("unroll") for (int n = 0; n < 2; ++n) _Pragma("unroll") for (int k = 0; k < 2; ++k) dst[n][k] = *(const LAS bf16x8*)(lds + PG8_SB(b, h) + boff + n * 2048 + k * 1024); } while (0)
; #define PG8_MMA(ai, bj, At, Bt) do { __builtin_amdgcn_s_setprio(1); _Pragma("unroll") for (int m = 0; m < 4; ++m) _Pragma("unroll") for (int n = 0; n < 2; ++n) _Pragma("unroll") for (int k = 0; k < 2; ++k) \
;         acc[ai][bj][m][n] = __builtin_amdgcn_mfma_f32_16x16x32_bf16(Bt[n][k], At[m][k], acc[ai][bj][m][n], 0, 0, 0); __builtin_amdgcn_s_setprio(0); } while (0)
; #define PG8_WAIT_V(n) asm volatile("s_waitcnt vmcnt(" #n ")" ::: "memory")
; #define PG8_WAIT_L(n) asm volatile("s_waitcnt lgkmcnt(" #n ")" ::: "memory")
; #define PG8_BAR __builtin_amdgcn_s_barrier()
; #define PG8_SCHED __builtin_amdgcn_sched_barrier(0)
; template <class Epi, class Sched, bool ALIGN_EPI, class Hook = NoHook>
; __device__ __forceinline__ void gemm_phase(LAS unsigned char* lds, const Gemm g, const Sched& S, const Epi& E, const Hook& H = Hook()) {
;     ...
;             PG8_LDA(At, 0, 1); PG8_STAGE(PG8_SB(0, 0), b2, voffB); PG8_STAGE(PG8_SB(0, 1), b2 + hB, voffB); PG8_STAGE(PG8_SA(0, 0), a2, voffA);
;             PG8_WAIT_V(8); PG8_WAIT_L(0); PG8_BAR; PG8_MMA(1, 0, At, B0); PG8_MMA(1, 1, At, B1); PG8_BAR; PG8_SCHED;
;             PG8_LDB(B0, 1, 0); PG8_LDB(B1, 1, 1); PG8_SCHED; PG8_LDA(At, 1, 0); PG8_STAGE(PG8_SA(0, 1), a2 + hA, voffA);
;             PG8_WAIT_V(8); PG8_WAIT_L(0); PG8_BAR; PG8_MMA(0, 0, At, B0); PG8_MMA(0, 1, At, B1); PG8_BAR; PG8_SCHED;
;             PG8_LDA(At, 1, 1); PG8_STAGE(PG8_SB(1, 0), b3, voffB); PG8_STAGE(PG8_SB(1, 1), b3 + hB, voffB); PG8_STAGE(PG8_SA(1, 0), a3, voffA);
	s_setprio 1
	s_waitcnt lgkmcnt(0)
	v_mfma_f32_16x16x32_bf16 v[98:101], v[126:129], v[186:189], v[98:101]
	v_mfma_f32_16x16x32_bf16 v[94:97], v[142:145], v[186:189], v[94:97]
	v_mfma_f32_16x16x32_bf16 v[90:93], v[126:129], v[194:197], v[90:93]
	v_mfma_f32_16x16x32_bf16 v[86:89], v[142:145], v[194:197], v[86:89]
	v_mfma_f32_16x16x32_bf16 v[82:85], v[126:129], v[202:205], v[82:85]
	v_mfma_f32_16x16x32_bf16 v[78:81], v[142:145], v[202:205], v[78:81]
	v_mfma_f32_16x16x32_bf16 v[74:77], v[126:129], v[210:213], v[74:77]
	v_mfma_f32_16x16x32_bf16 v[70:73], v[142:145], v[210:213], v[70:73]
	v_mfma_f32_16x16x32_bf16 v[98:101], v[130:133], v[190:193], v[98:101]
	v_mfma_f32_16x16x32_bf16 v[94:97], v[146:149], v[190:193], v[94:97]
	v_mfma_f32_16x16x32_bf16 v[90:93], v[130:133], v[198:201], v[90:93]
	v_mfma_f32_16x16x32_bf16 v[86:89], v[146:149], v[198:201], v[86:89]
	v_mfma_f32_16x16x32_bf16 v[82:85], v[130:133], v[206:209], v[82:85]
	v_mfma_f32_16x16x32_bf16 v[78:81], v[146:149], v[206:209], v[78:81]
	v_mfma_f32_16x16x32_bf16 v[74:77], v[130:133], v[214:217], v[74:77]
	v_mfma_f32_16x16x32_bf16 v[70:73], v[146:149], v[214:217], v[70:73]
	s_setprio 0
	s_setprio 1
	v_mfma_f32_16x16x32_bf16 v[34:37], v[150:153], v[186:189], v[34:37]
	v_mfma_f32_16x16x32_bf16 v[30:33], v[158:161], v[186:189], v[30:33]
	v_mfma_f32_16x16x32_bf16 v[26:29], v[150:153], v[194:197], v[26:29]
	v_mfma_f32_16x16x32_bf16 v[22:25], v[158:161], v[194:197], v[22:25]
	v_mfma_f32_16x16x32_bf16 v[18:21], v[150:153], v[202:205], v[18:21]
	v_mfma_f32_16x16x32_bf16 v[14:17], v[158:161], v[202:205], v[14:17]
	v_mfma_f32_16x16x32_bf16 v[10:13], v[150:153], v[210:213], v[10:13]
	v_mfma_f32_16x16x32_bf16 v[4:7], v[158:161], v[210:213], v[6:9]
	v_mfma_f32_16x16x32_bf16 v[34:37], v[154:157], v[190:193], v[34:37]
	v_mfma_f32_16x16x32_bf16 v[30:33], v[162:165], v[190:193], v[30:33]
	v_mfma_f32_16x16x32_bf16 v[26:29], v[154:157], v[198:201], v[26:29]
	v_mfma_f32_16x16x32_bf16 v[22:25], v[162:165], v[198:201], v[22:25]
	v_mfma_f32_16x16x32_bf16 v[18:21], v[154:157], v[206:209], v[18:21]
	v_mfma_f32_16x16x32_bf16 v[14:17], v[162:165], v[206:209], v[14:17]
	v_mfma_f32_16x16x32_bf16 v[10:13], v[154:157], v[214:217], v[10:13]
	v_mfma_f32_16x16x32_bf16 v[4:7], v[162:165], v[214:217], v[4:7]
	s_setprio 0
	s_barrier
	s_add_i32 s68, 0, 0x18000
	v_add_u32_e32 v3, s68, v222
	s_add_i32 s69, 0, 0x1c000
	ds_read_b128 v[126:129], v3
	ds_read_b128 v[130:133], v3 offset:1024
	ds_read_b128 v[142:145], v3 offset:2048
	ds_read_b128 v[146:149], v3 offset:3072
	v_add_u32_e32 v3, s69, v222
	s_add_u32 s30, s30, 0x300000
	s_addc_u32 s31, s31, 0
	s_mov_b32 m0, s39
	s_nop 0
	global_load_lds_dwordx4 v166, s[30:31]
	ds_read_b128 v[150:153], v3
	ds_read_b128 v[154:157], v3 offset:1024
	ds_read_b128 v[158:161], v3 offset:2048
	ds_read_b128 v[162:165], v3 offset:3072
	ds_read_b128 v[186:189], v224 offset:32768
	ds_read_b128 v[190:193], v224 offset:33792
	ds_read_b128 v[194:197], v224 offset:34816
	s_mov_b32 m0, s40
	s_nop 0
	global_load_lds_dwordx4 v170, s[30:31]
	ds_read_b128 v[198:201], v224 offset:35840
	ds_read_b128 v[202:205], v224 offset:36864
	ds_read_b128 v[206:209], v224 offset:37888
	ds_read_b128 v[210:213], v224 offset:38912
	ds_read_b128 v[214:217], v224 offset:39936
	s_waitcnt vmcnt(8)
	s_waitcnt lgkmcnt(0)
	s_barrier
	s_setprio 1
	s_waitcnt lgkmcnt(0)
	v_mfma_f32_16x16x32_bf16 v[138:141], v[126:129], v[186:189], v[138:141]
	v_mfma_f32_16x16x32_bf16 v[134:137], v[142:145], v[186:189], v[134:137]
	v_mfma_f32_16x16x32_bf16 v[122:125], v[126:129], v[194:197], v[122:125]
	v_mfma_f32_16x16x32_bf16 v[118:121], v[142:145], v[194:197], v[118:121]
	v_mfma_f32_16x16x32_bf16 v[114:117], v[126:129], v[202:205], v[114:117]
	v_mfma_f32_16x16x32_bf16 v[110:113], v[142:145], v[202:205], v[110:113]
	v_mfma_f32_16x16x32_bf16 v[106:109], v[126:129], v[210:213], v[106:109]
	v_mfma_f32_16x16x32_bf16 v[102:105], v[142:145], v[210:213], v[102:105]
	v_mfma_f32_16x16x32_bf16 v[138:141], v[130:133], v[190:193], v[138:141]
	v_mfma_f32_16x16x32_bf16 v[134:137], v[146:149], v[190:193], v[134:137]
	v_mfma_f32_16x16x32_bf16 v[122:125], v[130:133], v[198:201], v[122:125]
	v_mfma_f32_16x16x32_bf16 v[118:121], v[146:149], v[198:201], v[118:121]
	v_mfma_f32_16x16x32_bf16 v[114:117], v[130:133], v[206:209], v[114:117]
	v_mfma_f32_16x16x32_bf16 v[110:113], v[146:149], v[206:209], v[110:113]
	v_mfma_f32_16x16x32_bf16 v[106:109], v[130:133], v[214:217], v[106:109]
	v_mfma_f32_16x16x32_bf16 v[102:105], v[146:149], v[214:217], v[102:105]
	s_setprio 0
	s_setprio 1
	v_mfma_f32_16x16x32_bf16 v[66:69], v[150:153], v[186:189], v[66:69]
	v_mfma_f32_16x16x32_bf16 v[62:65], v[158:161], v[186:189], v[62:65]
	v_mfma_f32_16x16x32_bf16 v[58:61], v[150:153], v[194:197], v[58:61]
	v_mfma_f32_16x16x32_bf16 v[54:57], v[158:161], v[194:197], v[54:57]
	v_mfma_f32_16x16x32_bf16 v[50:53], v[150:153], v[202:205], v[50:53]
	v_mfma_f32_16x16x32_bf16 v[46:49], v[158:161], v[202:205], v[46:49]
	v_mfma_f32_16x16x32_bf16 v[42:45], v[150:153], v[210:213], v[42:45]
	v_mfma_f32_16x16x32_bf16 v[38:41], v[158:161], v[210:213], v[38:41]
	v_mfma_f32_16x16x32_bf16 v[66:69], v[154:157], v[190:193], v[66:69]
	v_mfma_f32_16x16x32_bf16 v[62:65], v[162:165], v[190:193], v[62:65]
	v_mfma_f32_16x16x32_bf16 v[58:61], v[154:157], v[198:201], v[58:61]
	v_mfma_f32_16x16x32_bf16 v[54:57], v[162:165], v[198:201], v[54:57]
	v_mfma_f32_16x16x32_bf16 v[50:53], v[154:157], v[206:209], v[50:53]
	v_mfma_f32_16x16x32_bf16 v[46:49], v[162:165], v[206:209], v[46:49]
	v_mfma_f32_16x16x32_bf16 v[42:45], v[154:157], v[214:217], v[42:45]
	v_mfma_f32_16x16x32_bf16 v[38:41], v[162:165], v[214:217], v[38:41]
	s_setprio 0
	s_barrier
; #define PG8_STAGE(bufoff, gbase, voff) do { _Pragma("unroll") for (int _i = 0; _i < 2; ++_i) \
;         __builtin_amdgcn_global_load_lds((const unsigned*)((const char*)(gbase) + (voff)[_i]), (LAS unsigned*)(lds + (bufoff) + ldsw + _i * 8192), 16, 0, 0); } while (0)
; #define PG8_LDA(dst, b, h) do { _Pragma("unroll") for (int m = 0; m < 4; ++m) _Pragma("unroll") for (int k = 0; k < 2; ++k) dst[m][k] = *(const LAS bf16x8*)(lds + PG8_SA(b, h) + aoff + m * 2048 + k * 1024); } while (0)
; #define PG8_MMA(ai, bj, At, Bt) do { __builtin_amdgcn_s_setprio(1); _Pragma("unroll") for (int m = 0; m < 4; ++m) _Pragma("unroll") for (int n = 0; n < 2; ++n) _Pragma("unroll") for (int k = 0; k < 2; ++k) \
;         acc[ai][bj][m][n] = __builtin_amdgcn_mfma_f32_16x16x32_bf16(Bt[n][k], At[m][k], acc[ai][bj][m][n], 0, 0, 0); __builtin_amdgcn_s_setprio(0); } while (0)
; #define PG8_WAIT_V(n) asm volatile("s_waitcnt vmcnt(" #n ")" ::: "memory")
; #define PG8_WAIT_L(n) asm volatile("s_waitcnt lgkmcnt(" #n ")" ::: "memory")
; #define PG8_BAR __builtin_amdgcn_s_barrier()
; #define PG8_SCHED __builtin_amdgcn_sched_barrier(0)
;     __device__ __forceinline__ void after(int te, f32x4 (&acc)[2][2][4][2], const Unit& u, int wr, int wc, int fr, int fq) const {
;         if (te > D_INNER / BK) return;
;         const int g = (te >> 4) - 1;
;         asm volatile("" : "+v"(fr), "+v"(fq));
; #pragma unroll
;         for (int ai = 0; ai < 2; ++ai)
; #pragma unroll
;             for (int m = 0; m < 4; ++m) { const float f = tab[(ai * HALF + wr * 64 + m * 16 + fr) * 8 + g];
; #pragma unroll
;                 for (int bj = 0; bj < 2; ++bj)
; #pragma unroll
;                     for (int n = 0; n < 2; ++n) acc[ai][bj][m][n] *= f; }
; template <class Epi, class Sched, bool ALIGN_EPI, class Hook = NoHook>
; __device__ __forceinline__ void gemm_phase(LAS unsigned char* lds, const Gemm g, const Sched& S, const Epi& E, const Hook& H = Hook()) {
;     ...
;             PG8_LDA(At, 1, 1); PG8_STAGE(PG8_SB(1, 0), b3, voffB); PG8_STAGE(PG8_SB(1, 1), b3 + hB, voffB); PG8_STAGE(PG8_SA(1, 0), a3, voffA);
;             PG8_WAIT_V(8); PG8_WAIT_L(0); PG8_BAR; PG8_MMA(1, 0, At, B0); PG8_MMA(1, 1, At, B1); PG8_BAR; PG8_SCHED;
;         }
	s_add_i32 s30, s68, s35
	s_add_u32 s72, s28, s14
	s_addc_u32 s73, s29, s15
	s_mov_b32 m0, s30
	ds_read_b128 v[186:189], v224 offset:49152
	ds_read_b128 v[190:193], v224 offset:50176
	global_load_lds_dwordx4 v168, s[72:73]
	ds_read_b128 v[194:197], v224 offset:51200
	s_add_i32 m0, s30, 0x2000
	s_add_u32 s28, s28, 0x300080
	s_addc_u32 s29, s29, 0
	s_add_i32 s30, s69, s35
	global_load_lds_dwordx4 v172, s[72:73]
	ds_read_b128 v[198:201], v224 offset:52224
	s_mov_b32 m0, s30
	s_nop 0
	global_load_lds_dwordx4 v168, s[28:29]
	ds_read_b128 v[202:205], v224 offset:53248
	s_add_i32 m0, s30, 0x2000
	s_nop 0
	global_load_lds_dwordx4 v172, s[28:29]
	ds_read_b128 v[206:209], v224 offset:54272
	s_mov_b32 m0, s45
	s_nop 0
	global_load_lds_dwordx4 v166, s[74:75]
	ds_read_b128 v[210:213], v224 offset:55296
	s_mov_b32 m0, s46
	s_nop 0
	global_load_lds_dwordx4 v170, s[74:75]
	ds_read_b128 v[214:217], v224 offset:56320
	s_waitcnt vmcnt(8)
	s_waitcnt lgkmcnt(0)
	s_barrier
	s_setprio 1
	s_waitcnt lgkmcnt(0)
	v_mfma_f32_16x16x32_bf16 v[98:101], v[126:129], v[186:189], v[98:101]
	v_mfma_f32_16x16x32_bf16 v[94:97], v[142:145], v[186:189], v[94:97]
	v_mfma_f32_16x16x32_bf16 v[90:93], v[126:129], v[194:197], v[90:93]
	v_mfma_f32_16x16x32_bf16 v[86:89], v[142:145], v[194:197], v[86:89]
	v_mfma_f32_16x16x32_bf16 v[82:85], v[126:129], v[202:205], v[82:85]
	v_mfma_f32_16x16x32_bf16 v[78:81], v[142:145], v[202:205], v[78:81]
	v_mfma_f32_16x16x32_bf16 v[74:77], v[126:129], v[210:213], v[74:77]
	v_mfma_f32_16x16x32_bf16 v[70:73], v[142:145], v[210:213], v[70:73]
	v_mfma_f32_16x16x32_bf16 v[98:101], v[130:133], v[190:193], v[98:101]
	v_mfma_f32_16x16x32_bf16 v[94:97], v[146:149], v[190:193], v[94:97]
	v_mfma_f32_16x16x32_bf16 v[90:93], v[130:133], v[198:201], v[90:93]
	v_mfma_f32_16x16x32_bf16 v[86:89], v[146:149], v[198:201], v[86:89]
	v_mfma_f32_16x16x32_bf16 v[82:85], v[130:133], v[206:209], v[82:85]
	v_mfma_f32_16x16x32_bf16 v[78:81], v[146:149], v[206:209], v[78:81]
	v_mfma_f32_16x16x32_bf16 v[74:77], v[130:133], v[214:217], v[74:77]
	v_mfma_f32_16x16x32_bf16 v[70:73], v[146:149], v[214:217], v[70:73]
	s_setprio 0
	s_setprio 1
	v_mfma_f32_16x16x32_bf16 v[34:37], v[150:153], v[186:189], v[34:37]
	v_mfma_f32_16x16x32_bf16 v[30:33], v[158:161], v[186:189], v[30:33]
	v_mfma_f32_16x16x32_bf16 v[26:29], v[150:153], v[194:197], v[26:29]
	v_mfma_f32_16x16x32_bf16 v[22:25], v[158:161], v[194:197], v[22:25]
	v_mfma_f32_16x16x32_bf16 v[18:21], v[150:153], v[202:205], v[18:21]
	v_mfma_f32_16x16x32_bf16 v[14:17], v[158:161], v[202:205], v[14:17]
	v_mfma_f32_16x16x32_bf16 v[8:11], v[150:153], v[210:213], v[10:13]
	v_mfma_f32_16x16x32_bf16 v[4:7], v[158:161], v[210:213], v[4:7]
	v_mfma_f32_16x16x32_bf16 v[34:37], v[154:157], v[190:193], v[34:37]
	v_mfma_f32_16x16x32_bf16 v[30:33], v[162:165], v[190:193], v[30:33]
	v_mfma_f32_16x16x32_bf16 v[26:29], v[154:157], v[198:201], v[26:29]
	v_mfma_f32_16x16x32_bf16 v[22:25], v[162:165], v[198:201], v[22:25]
	v_mfma_f32_16x16x32_bf16 v[18:21], v[154:157], v[206:209], v[18:21]
	v_mfma_f32_16x16x32_bf16 v[14:17], v[162:165], v[206:209], v[14:17]
	v_mfma_f32_16x16x32_bf16 v[10:13], v[154:157], v[214:217], v[8:11]
	v_mfma_f32_16x16x32_bf16 v[6:9], v[162:165], v[214:217], v[4:7]
	s_setprio 0
	s_add_u32 s26, s26, 0x100
	s_addc_u32 s27, s27, 0
	s_cmp_ge_u32 s67, s66
	s_cbranch_scc0 .LBB0_783
	s_barrier
	s_cmpk_gt_u32 s65, 0x7f
	s_cbranch_scc1 .LBB0_787
	s_lshr_b32 s26, s66, 4
	s_add_i32 s26, s26, -1
	v_mov_b32_e32 v3, v1
	v_mov_b32_e32 v4, v220
	s_lshl_b32 s27, s26, 2
	s_add_i32 s28, s27, s48
	v_lshlrev_b32_e32 v5, 5, v3
	v_add_u32_e32 v126, s28, v5
	ds_read_b32 v126, v126
	s_add_i32 s28, s27, s49
	s_waitcnt lgkmcnt(0)
	v_pk_mul_f32 v[140:141], v[140:141], v[126:127] op_sel_hi:[1,0]
	v_pk_mul_f32 v[138:139], v[138:139], v[126:127] op_sel_hi:[1,0]
	v_pk_mul_f32 v[136:137], v[136:137], v[126:127] op_sel_hi:[1,0]
	v_pk_mul_f32 v[134:135], v[134:135], v[126:127] op_sel_hi:[1,0]
	v_pk_mul_f32 v[68:69], v[68:69], v[126:127] op_sel_hi:[1,0]
	v_pk_mul_f32 v[66:67], v[66:67], v[126:127] op_sel_hi:[1,0]
	v_pk_mul_f32 v[64:65], v[64:65], v[126:127] op_sel_hi:[1,0]
	v_pk_mul_f32 v[62:63], v[62:63], v[126:127] op_sel_hi:[1,0]
	v_add_u32_e32 v126, s28, v5
	ds_read_b32 v126, v126
	s_add_i32 s28, s27, s50
	s_waitcnt lgkmcnt(0)
	v_pk_mul_f32 v[124:125], v[124:125], v[126:127] op_sel_hi:[1,0]
	v_pk_mul_f32 v[122:123], v[122:123], v[126:127] op_sel_hi:[1,0]
	v_pk_mul_f32 v[120:121], v[120:121], v[126:127] op_sel_hi:[1,0]
	v_pk_mul_f32 v[118:119], v[118:119], v[126:127] op_sel_hi:[1,0]
	v_pk_mul_f32 v[60:61], v[60:61], v[126:127] op_sel_hi:[1,0]
	v_pk_mul_f32 v[58:59], v[58:59], v[126:127] op_sel_hi:[1,0]
	v_pk_mul_f32 v[56:57], v[56:57], v[126:127] op_sel_hi:[1,0]
	v_pk_mul_f32 v[54:55], v[54:55], v[126:127] op_sel_hi:[1,0]
	v_add_u32_e32 v126, s28, v5
	ds_read_b32 v126, v126
	s_add_i32 s28, s27, s51
	s_waitcnt lgkmcnt(0)
	v_pk_mul_f32 v[116:117], v[116:117], v[126:127] op_sel_hi:[1,0]
	v_pk_mul_f32 v[114:115], v[114:115], v[126:127] op_sel_hi:[1,0]
	v_pk_mul_f32 v[112:113], v[112:113], v[126:127] op_sel_hi:[1,0]
	v_pk_mul_f32 v[110:111], v[110:111], v[126:127] op_sel_hi:[1,0]
	v_pk_mul_f32 v[52:53], v[52:53], v[126:127] op_sel_hi:[1,0]
	v_pk_mul_f32 v[50:51], v[50:51], v[126:127] op_sel_hi:[1,0]
	v_pk_mul_f32 v[48:49], v[48:49], v[126:127] op_sel_hi:[1,0]
	v_pk_mul_f32 v[46:47], v[46:47], v[126:127] op_sel_hi:[1,0]
	v_add_u32_e32 v126, s28, v5
	ds_read_b32 v126, v126
	s_add_i32 s28, s27, s52
	s_waitcnt lgkmcnt(0)
;     __device__ __forceinline__ void after(int te, f32x4 (&acc)[2][2][4][2], const Unit& u, int wr, int wc, int fr, int fq) const {
;     ...
;         for (int ai = 0; ai < 2; ++ai)
; #pragma unroll
;             for (int m = 0; m < 4; ++m) { const float f = tab[(ai * HALF + wr * 64 + m * 16 + fr) * 8 + g];
; #pragma unroll
;                 for (int bj = 0; bj < 2; ++bj)
; #pragma unroll
;                     for (int n = 0; n < 2; ++n) acc[ai][bj][m][n] *= f; }
;         if (g == 7) {
;             const int row0 = u.pm * BM + wr * 64 + fr, col0 = u.pn * BM + wc * 32 + 8 * fq;
; #pragma unroll
;             for (int bj = 0; bj < 2; ++bj) { const int c = col0 + bj * HALF;
;                 const f32x4 s0 = *(const f32x4*)(gb + c), s1 = *(const f32x4*)(gb + c + 4), a0 = *(const f32x4*)(gb + D_MODEL + c), a1 = *(const f32x4*)(gb + D_MODEL + c + 4);
; #pragma unroll
;                 for (int ai = 0; ai < 2; ++ai) {
;                     u32x4 gs[4], ga[4];
; #pragma unroll
;                     for (int m = 0; m < 4; ++m) { const size_t r = (size_t)(row0 + ai * HALF + m * 16); gs[m] = *(const u32x4*)(proj + r * LDP + PGS + c); ga[m] = *(const u32x4*)(proj + r * LDP + PGA + c); }
	v_pk_mul_f32 v[108:109], v[108:109], v[126:127] op_sel_hi:[1,0]
	v_pk_mul_f32 v[106:107], v[106:107], v[126:127] op_sel_hi:[1,0]
	v_pk_mul_f32 v[104:105], v[104:105], v[126:127] op_sel_hi:[1,0]
	v_pk_mul_f32 v[102:103], v[102:103], v[126:127] op_sel_hi:[1,0]
	v_pk_mul_f32 v[44:45], v[44:45], v[126:127] op_sel_hi:[1,0]
	v_pk_mul_f32 v[42:43], v[42:43], v[126:127] op_sel_hi:[1,0]
	v_pk_mul_f32 v[40:41], v[40:41], v[126:127] op_sel_hi:[1,0]
	v_pk_mul_f32 v[38:39], v[38:39], v[126:127] op_sel_hi:[1,0]
	v_add_u32_e32 v126, s28, v5
	ds_read_b32 v126, v126
	s_add_i32 s28, s27, s53
	s_waitcnt lgkmcnt(0)
	v_pk_mul_f32 v[100:101], v[100:101], v[126:127] op_sel_hi:[1,0]
	v_pk_mul_f32 v[98:99], v[98:99], v[126:127] op_sel_hi:[1,0]
	v_pk_mul_f32 v[96:97], v[96:97], v[126:127] op_sel_hi:[1,0]
	v_pk_mul_f32 v[94:95], v[94:95], v[126:127] op_sel_hi:[1,0]
	v_pk_mul_f32 v[36:37], v[36:37], v[126:127] op_sel_hi:[1,0]
	v_pk_mul_f32 v[34:35], v[34:35], v[126:127] op_sel_hi:[1,0]
	v_pk_mul_f32 v[32:33], v[32:33], v[126:127] op_sel_hi:[1,0]
	v_pk_mul_f32 v[30:31], v[30:31], v[126:127] op_sel_hi:[1,0]
	v_add_u32_e32 v126, s28, v5
	ds_read_b32 v126, v126
	s_add_i32 s28, s27, s54
	s_add_i32 s27, s27, s55
	s_cmp_lg_u32 s26, 7
	s_waitcnt lgkmcnt(0)
	v_pk_mul_f32 v[92:93], v[92:93], v[126:127] op_sel_hi:[1,0]
	v_pk_mul_f32 v[90:91], v[90:91], v[126:127] op_sel_hi:[1,0]
	v_pk_mul_f32 v[88:89], v[88:89], v[126:127] op_sel_hi:[1,0]
	v_pk_mul_f32 v[86:87], v[86:87], v[126:127] op_sel_hi:[1,0]
	v_pk_mul_f32 v[28:29], v[28:29], v[126:127] op_sel_hi:[1,0]
	v_pk_mul_f32 v[26:27], v[26:27], v[126:127] op_sel_hi:[1,0]
	v_pk_mul_f32 v[24:25], v[24:25], v[126:127] op_sel_hi:[1,0]
	v_pk_mul_f32 v[22:23], v[22:23], v[126:127] op_sel_hi:[1,0]
	v_add_u32_e32 v126, s28, v5
	ds_read_b32 v126, v126
	v_add_u32_e32 v5, s27, v5
	s_waitcnt lgkmcnt(0)
	v_pk_mul_f32 v[84:85], v[84:85], v[126:127] op_sel_hi:[1,0]
	v_pk_mul_f32 v[82:83], v[82:83], v[126:127] op_sel_hi:[1,0]
	v_pk_mul_f32 v[80:81], v[80:81], v[126:127] op_sel_hi:[1,0]
	v_pk_mul_f32 v[78:79], v[78:79], v[126:127] op_sel_hi:[1,0]
	v_pk_mul_f32 v[20:21], v[20:21], v[126:127] op_sel_hi:[1,0]
	v_pk_mul_f32 v[18:19], v[18:19], v[126:127] op_sel_hi:[1,0]
	v_pk_mul_f32 v[16:17], v[16:17], v[126:127] op_sel_hi:[1,0]
	v_pk_mul_f32 v[14:15], v[14:15], v[126:127] op_sel_hi:[1,0]
	ds_read_b32 v126, v5
	s_waitcnt lgkmcnt(0)
	v_pk_mul_f32 v[76:77], v[76:77], v[126:127] op_sel_hi:[1,0]
	v_pk_mul_f32 v[74:75], v[74:75], v[126:127] op_sel_hi:[1,0]
	v_pk_mul_f32 v[72:73], v[72:73], v[126:127] op_sel_hi:[1,0]
	v_pk_mul_f32 v[70:71], v[70:71], v[126:127] op_sel_hi:[1,0]
	v_pk_mul_f32 v[12:13], v[12:13], v[126:127] op_sel_hi:[1,0]
	v_pk_mul_f32 v[10:11], v[10:11], v[126:127] op_sel_hi:[1,0]
	v_pk_mul_f32 v[8:9], v[8:9], v[126:127] op_sel_hi:[1,0]
	v_pk_mul_f32 v[6:7], v[6:7], v[126:127] op_sel_hi:[1,0]
	s_cbranch_scc1 .LBB0_787
	v_add_u32_e32 v126, s62, v3
	v_ashrrev_i32_e32 v127, 31, v126
	v_lshl_add_u32 v4, v4, 3, s61
	v_lshlrev_b64 v[126:127], 14, v[126:127]
	v_ashrrev_i32_e32 v5, 31, v4
	v_lshl_add_u64 v[126:127], s[76:77], 0, v[126:127]
	v_lshl_add_u64 v[192:193], v[4:5], 1, v[126:127]
	v_readlane_b32 s68, v254, 20
	global_load_dwordx4 v[204:207], v[192:193], off
	v_add_co_u32_e32 v126, vcc, s41, v192
	v_lshlrev_b64 v[4:5], 2, v[4:5]
	v_readlane_b32 s70, v254, 22
	v_readlane_b32 s71, v254, 23
	v_addc_co_u32_e32 v127, vcc, 0, v193, vcc
	s_nop 0
	v_lshl_add_u64 v[196:197], s[70:71], 0, v[4:5]
	global_load_dwordx4 v[208:211], v[126:127], off
	global_load_dwordx4 v[142:145], v[196:197], off
	s_nop 0
	global_load_dwordx4 v[126:129], v[196:197], off offset:16
	v_lshl_add_u64 v[198:199], s[12:13], 0, v[4:5]
	global_load_dwordx4 v[146:149], v[198:199], off
	global_load_dwordx4 v[130:133], v[198:199], off offset:16
	s_mov_b64 s[26:27], 0x40000
	v_lshl_add_u64 v[4:5], v[192:193], 0, s[26:27]
	s_mov_b32 s26, 0x40000
	v_add_co_u32_e32 v150, vcc, s26, v192
	s_mov_b64 s[26:27], 0x42000
	s_nop 0
	v_addc_co_u32_e32 v151, vcc, 0, v193, vcc
	v_lshl_add_u64 v[186:187], v[192:193], 0, s[26:27]
	s_mov_b32 s26, 0x42000
	v_add_co_u32_e32 v152, vcc, s26, v192
	s_mov_b64 s[26:27], 0x80000
	s_nop 0
	v_addc_co_u32_e32 v153, vcc, 0, v193, vcc
	v_lshl_add_u64 v[188:189], v[192:193], 0, s[26:27]
	s_mov_b32 s26, 0x80000
	v_add_co_u32_e32 v154, vcc, s26, v192
	s_mov_b64 s[26:27], 0x82000
	s_nop 0
	v_addc_co_u32_e32 v155, vcc, 0, v193, vcc
	v_lshl_add_u64 v[190:191], v[192:193], 0, s[26:27]
	s_mov_b32 s26, 0x82000
	v_add_co_u32_e32 v156, vcc, s26, v192
	s_mov_b64 s[26:27], 0xc0000
	s_nop 0
	v_addc_co_u32_e32 v157, vcc, 0, v193, vcc
	v_lshl_add_u64 v[194:195], v[192:193], 0, s[26:27]
	s_mov_b32 s26, 0xc0000
	v_add_co_u32_e32 v228, vcc, s26, v192
	s_mov_b64 s[26:27], 0xc2000
	s_nop 0
	v_addc_co_u32_e32 v229, vcc, 0, v193, vcc
	v_lshl_add_u64 v[200:201], v[192:193], 0, s[26:27]
	s_mov_b32 s26, 0xc2000
	v_add_co_u32_e32 v230, vcc, s26, v192
	s_mov_b32 s26, 0x200000
	s_nop 0
	v_addc_co_u32_e32 v231, vcc, 0, v193, vcc
	global_load_dwordx4 v[212:215], v[150:151], off
	global_load_dwordx4 v[216:219], v[152:153], off
	global_load_dwordx4 v[162:165], v[154:155], off
	global_load_dwordx4 v[158:161], v[156:157], off
	s_nop 0
	global_load_dwordx4 v[154:157], v[228:229], off
	global_load_dwordx4 v[150:153], v[230:231], off
	v_lshl_add_u64 v[202:203], v[192:193], 0, s[18:19]
	v_readlane_b32 s76, v254, 28
	v_readlane_b32 s77, v254, 29
	v_readlane_b32 s76, v255, 8
	v_readlane_b32 s77, v255, 9
	v_readlane_b32 s69, v254, 21
	v_readlane_b32 s72, v254, 24
	v_readlane_b32 s73, v254, 25
	v_readlane_b32 s74, v254, 26
	v_readlane_b32 s75, v254, 27
	v_readlane_b32 s78, v254, 30
	v_readlane_b32 s79, v254, 31
	v_readlane_b32 s80, v254, 32
	v_readlane_b32 s81, v254, 33
	v_readlane_b32 s82, v254, 34
	v_readlane_b32 s83, v254, 35
	s_waitcnt vmcnt(0)
; __device__ __forceinline__ void unpack8(const u32x4 w, float (&v)[8]) { v[0] = bf_lo(w.x); v[1] = bf_hi(w.x); v[2] = bf_lo(w.y); v[3] = bf_hi(w.y); v[4] = bf_lo(w.z); v[5] = bf_hi(w.z); v[6] = bf_lo(w.w); v[7] = bf_hi(w.w); }
;     __device__ __forceinline__ void after(int te, f32x4 (&acc)[2][2][4][2], const Unit& u, int wr, int wc, int fr, int fq) const {
;     ...
;                     for (int m = 0; m < 4; ++m) { const size_t r = (size_t)(row0 + ai * HALF + m * 16); gs[m] = *(const u32x4*)(proj + r * LDP + PGS + c); ga[m] = *(const u32x4*)(proj + r * LDP + PGA + c); }
; #pragma unroll
;                     for (int m = 0; m < 4; ++m) { float vs[8], va[8]; unpack8(gs[m], vs); unpack8(ga[m], va);
; #pragma unroll
;                         for (int e = 0; e < 4; ++e) {
;                             acc[ai][bj][m][0][e] *= (1.f + __expf(-(va[e] + a0[e]))) * __builtin_amdgcn_rcpf(1.f + __expf(-(vs[e] + s0[e])));
;                             acc[ai][bj][m][1][e] *= (1.f + __expf(-(va[4 + e] + a1[e]))) * __builtin_amdgcn_rcpf(1.f + __expf(-(vs[4 + e] + s1[e]))); } }
	v_lshlrev_b32_e32 v3, 16, v204
	v_and_b32_e32 v204, 0xffff0000, v204
	v_lshlrev_b32_e32 v225, 16, v205
	v_and_b32_e32 v227, 0xffff0000, v205
	v_lshlrev_b32_e32 v205, 16, v206
	v_and_b32_e32 v228, 0xffff0000, v206
	v_lshlrev_b32_e32 v229, 16, v207
	v_and_b32_e32 v233, 0xffff0000, v207
	v_add_f32_e32 v3, v142, v3
	v_add_f32_e32 v204, v143, v204
	v_mul_f32_e32 v3, 0xbfb8aa3b, v3
	v_mul_f32_e32 v204, 0xbfb8aa3b, v204
	v_exp_f32_e32 v3, v3
	v_lshlrev_b32_e32 v230, 16, v209
	v_and_b32_e32 v231, 0xffff0000, v209
	v_exp_f32_e32 v209, v204
	v_lshlrev_b32_e32 v206, 16, v208
	v_and_b32_e32 v207, 0xffff0000, v208
	v_lshlrev_b32_e32 v208, 16, v210
	v_add_f32_e32 v206, v146, v206
	v_add_f32_e32 v208, v130, v208
	v_mul_f32_e32 v206, 0xbfb8aa3b, v206
	v_mul_f32_e32 v208, 0xbfb8aa3b, v208
	v_add_f32_e32 v3, 1.0, v3
	v_exp_f32_e32 v204, v206
	v_exp_f32_e32 v206, v208
	v_rcp_f32_e32 v208, v3
	v_add_f32_e32 v3, 1.0, v209
	v_rcp_f32_e32 v209, v3
	v_add_f32_e32 v3, v127, v228
	v_mul_f32_e32 v3, 0xbfb8aa3b, v3
	v_exp_f32_e32 v3, v3
	v_lshlrev_b32_e32 v234, 16, v211
	v_and_b32_e32 v235, 0xffff0000, v211
	v_add_f32_e32 v205, v126, v205
	v_add_f32_e32 v3, 1.0, v3
	v_rcp_f32_e32 v211, v3
	v_add_f32_e32 v3, v144, v225
	v_mul_f32_e32 v3, 0xbfb8aa3b, v3
	v_exp_f32_e32 v3, v3
	v_mul_f32_e32 v205, 0xbfb8aa3b, v205
	v_exp_f32_e32 v205, v205
	v_add_f32_e32 v225, v148, v230
	v_add_f32_e32 v3, 1.0, v3
	v_rcp_f32_e32 v230, v3
	v_add_f32_e32 v3, v128, v229
	v_mul_f32_e32 v3, 0xbfb8aa3b, v3
	v_add_f32_e32 v227, v145, v227
	v_mul_f32_e32 v225, 0xbfb8aa3b, v225
	v_exp_f32_e32 v3, v3
	v_mul_f32_e32 v227, 0xbfb8aa3b, v227
	v_add_f32_e32 v207, v147, v207
	v_exp_f32_e32 v228, v225
	v_add_f32_e32 v225, v132, v234
	v_exp_f32_e32 v227, v227
	v_and_b32_e32 v232, 0xffff0000, v210
	v_mul_f32_e32 v207, 0xbfb8aa3b, v207
	v_add_f32_e32 v205, 1.0, v205
	v_mul_f32_e32 v225, 0xbfb8aa3b, v225
	v_rcp_f32_e32 v210, v205
	v_exp_f32_e32 v205, v207
	v_add_f32_e32 v207, v131, v232
	v_exp_f32_e32 v232, v225
	v_add_f32_e32 v225, v149, v231
	v_add_f32_e32 v3, 1.0, v3
	v_mul_f32_e32 v225, 0xbfb8aa3b, v225
	v_exp_f32_e32 v229, v225
	v_rcp_f32_e32 v234, v3
	v_add_f32_e32 v3, 1.0, v227
	v_rcp_f32_e32 v231, v3
	v_pk_add_f32 v[228:229], v[228:229], 1.0 op_sel_hi:[1,0]
	v_pk_add_f32 v[204:205], v[204:205], 1.0 op_sel_hi:[1,0]
	v_add_f32_e32 v3, v133, v235
	v_pk_mul_f32 v[204:205], v[204:205], v[208:209]
	v_pk_mul_f32 v[208:209], v[228:229], v[230:231]
	v_mul_f32_e32 v3, 0xbfb8aa3b, v3
	v_pk_mul_f32 v[140:141], v[140:141], v[208:209]
	v_add_f32_e32 v208, v129, v233
	v_mul_f32_e32 v208, 0xbfb8aa3b, v208
	v_exp_f32_e32 v208, v208
	v_exp_f32_e32 v233, v3
	v_mul_f32_e32 v207, 0xbfb8aa3b, v207
	v_exp_f32_e32 v207, v207
	v_add_f32_e32 v3, 1.0, v208
	v_rcp_f32_e32 v235, v3
	v_lshlrev_b32_e32 v3, 16, v212
	v_add_f32_e32 v3, v142, v3
	v_mul_f32_e32 v3, 0xbfb8aa3b, v3
	v_exp_f32_e32 v3, v3
	v_pk_add_f32 v[206:207], v[206:207], 1.0 op_sel_hi:[1,0]
	v_pk_mul_f32 v[138:139], v[138:139], v[204:205]
	v_pk_mul_f32 v[206:207], v[206:207], v[210:211]
	v_add_f32_e32 v3, 1.0, v3
	v_pk_mul_f32 v[134:135], v[134:135], v[206:207]
	v_lshlrev_b32_e32 v207, 16, v214
	v_rcp_f32_e32 v206, v3
	v_add_f32_e32 v3, v126, v207
	v_mul_f32_e32 v3, 0xbfb8aa3b, v3
	v_exp_f32_e32 v3, v3
	v_pk_add_f32 v[204:205], v[232:233], 1.0 op_sel_hi:[1,0]
	v_lshlrev_b32_e32 v208, 16, v218
	v_pk_mul_f32 v[204:205], v[204:205], v[234:235]
	v_add_f32_e32 v3, 1.0, v3
	v_pk_mul_f32 v[136:137], v[136:137], v[204:205]
	v_and_b32_e32 v205, 0xffff0000, v212
	v_rcp_f32_e32 v210, v3
	v_add_f32_e32 v3, v143, v205
	v_mul_f32_e32 v3, 0xbfb8aa3b, v3
	v_exp_f32_e32 v3, v3
	v_add_f32_e32 v207, v130, v208
	v_and_b32_e32 v209, 0xffff0000, v214
	v_mul_f32_e32 v207, 0xbfb8aa3b, v207
	v_add_f32_e32 v3, 1.0, v3
	v_exp_f32_e32 v208, v207
	v_rcp_f32_e32 v207, v3
	v_add_f32_e32 v3, v127, v209
	v_mul_f32_e32 v3, 0xbfb8aa3b, v3
	v_exp_f32_e32 v3, v3
	v_lshlrev_b32_e32 v212, 16, v213
	v_and_b32_e32 v211, 0xffff0000, v216
	v_add_f32_e32 v205, v147, v211
	v_add_f32_e32 v3, 1.0, v3
	v_rcp_f32_e32 v211, v3
	v_add_f32_e32 v3, v144, v212
	v_mul_f32_e32 v3, 0xbfb8aa3b, v3
	v_exp_f32_e32 v3, v3
	v_lshlrev_b32_e32 v225, 16, v215
	v_lshlrev_b32_e32 v214, 16, v217
	v_and_b32_e32 v213, 0xffff0000, v213
	v_add_f32_e32 v3, 1.0, v3
	v_add_f32_e32 v212, v148, v214
	v_rcp_f32_e32 v214, v3
	v_add_f32_e32 v3, v128, v225
	v_mul_f32_e32 v3, 0xbfb8aa3b, v3
	v_add_f32_e32 v213, v145, v213
	v_and_b32_e32 v227, 0xffff0000, v215
	v_lshlrev_b32_e32 v204, 16, v216
	v_and_b32_e32 v215, 0xffff0000, v217
	v_and_b32_e32 v216, 0xffff0000, v218
	v_lshlrev_b32_e32 v217, 16, v219
	v_exp_f32_e32 v3, v3
	v_mul_f32_e32 v213, 0xbfb8aa3b, v213
	v_add_f32_e32 v209, v131, v216
	v_add_f32_e32 v216, v132, v217
	v_exp_f32_e32 v217, v213
	v_add_f32_e32 v204, v146, v204
	v_add_f32_e32 v215, v149, v215
	v_mul_f32_e32 v204, 0xbfb8aa3b, v204
	v_mul_f32_e32 v205, 0xbfb8aa3b, v205
	v_mul_f32_e32 v212, 0xbfb8aa3b, v212
	v_add_f32_e32 v3, 1.0, v3
	v_mul_f32_e32 v213, 0xbfb8aa3b, v215
	v_exp_f32_e32 v204, v204
	v_exp_f32_e32 v205, v205
	v_exp_f32_e32 v212, v212
	v_exp_f32_e32 v213, v213
	v_rcp_f32_e32 v218, v3
	v_add_f32_e32 v3, 1.0, v217
	v_rcp_f32_e32 v215, v3
	v_pk_add_f32 v[212:213], v[212:213], 1.0 op_sel_hi:[1,0]
	v_pk_add_f32 v[204:205], v[204:205], 1.0 op_sel_hi:[1,0]
	v_and_b32_e32 v219, 0xffff0000, v219
	v_pk_mul_f32 v[204:205], v[204:205], v[206:207]
	v_pk_mul_f32 v[206:207], v[212:213], v[214:215]
	v_add_f32_e32 v3, v133, v219
	v_pk_mul_f32 v[124:125], v[124:125], v[206:207]
	v_add_f32_e32 v206, v129, v227
	v_mul_f32_e32 v206, 0xbfb8aa3b, v206
	v_exp_f32_e32 v206, v206
	v_mul_f32_e32 v3, 0xbfb8aa3b, v3
	v_exp_f32_e32 v217, v3
; __device__ __forceinline__ void unpack8(const u32x4 w, float (&v)[8]) { v[0] = bf_lo(w.x); v[1] = bf_hi(w.x); v[2] = bf_lo(w.y); v[3] = bf_hi(w.y); v[4] = bf_lo(w.z); v[5] = bf_hi(w.z); v[6] = bf_lo(w.w); v[7] = bf_hi(w.w); }
;     __device__ __forceinline__ void after(int te, f32x4 (&acc)[2][2][4][2], const Unit& u, int wr, int wc, int fr, int fq) const {
;     ...
;                     for (int m = 0; m < 4; ++m) { float vs[8], va[8]; unpack8(gs[m], vs); unpack8(ga[m], va);
; #pragma unroll
;                         for (int e = 0; e < 4; ++e) {
;                             acc[ai][bj][m][0][e] *= (1.f + __expf(-(va[e] + a0[e]))) * __builtin_amdgcn_rcpf(1.f + __expf(-(vs[e] + s0[e])));
;                             acc[ai][bj][m][1][e] *= (1.f + __expf(-(va[4 + e] + a1[e]))) * __builtin_amdgcn_rcpf(1.f + __expf(-(vs[4 + e] + s1[e]))); } }
	v_mul_f32_e32 v216, 0xbfb8aa3b, v216
	v_add_f32_e32 v3, 1.0, v206
	v_rcp_f32_e32 v219, v3
	v_lshlrev_b32_e32 v3, 16, v162
	v_mul_f32_e32 v209, 0xbfb8aa3b, v209
	v_exp_f32_e32 v216, v216
	v_add_f32_e32 v3, v142, v3
	v_exp_f32_e32 v209, v209
	v_mul_f32_e32 v3, 0xbfb8aa3b, v3
	v_exp_f32_e32 v3, v3
	v_pk_mul_f32 v[122:123], v[122:123], v[204:205]
	v_pk_add_f32 v[204:205], v[216:217], 1.0 op_sel_hi:[1,0]
	v_pk_add_f32 v[206:207], v[208:209], 1.0 op_sel_hi:[1,0]
	v_pk_mul_f32 v[204:205], v[204:205], v[218:219]
	v_pk_mul_f32 v[206:207], v[206:207], v[210:211]
	v_pk_mul_f32 v[120:121], v[120:121], v[204:205]
	v_and_b32_e32 v204, 0xffff0000, v162
	v_lshlrev_b32_e32 v162, 16, v164
	v_add_f32_e32 v3, 1.0, v3
	v_pk_mul_f32 v[118:119], v[118:119], v[206:207]
	v_lshlrev_b32_e32 v206, 16, v159
	v_and_b32_e32 v210, 0xffff0000, v159
	v_lshlrev_b32_e32 v159, 16, v160
	v_and_b32_e32 v211, 0xffff0000, v160
	v_rcp_f32_e32 v160, v3
	v_add_f32_e32 v3, v126, v162
	v_mul_f32_e32 v3, 0xbfb8aa3b, v3
	v_exp_f32_e32 v3, v3
	v_lshlrev_b32_e32 v205, 16, v163
	v_and_b32_e32 v207, 0xffff0000, v163
	v_and_b32_e32 v163, 0xffff0000, v164
	v_lshlrev_b32_e32 v164, 16, v158
	v_add_f32_e32 v3, 1.0, v3
	v_lshlrev_b32_e32 v208, 16, v165
	v_and_b32_e32 v209, 0xffff0000, v165
	v_and_b32_e32 v165, 0xffff0000, v158
	v_add_f32_e32 v158, v146, v164
	v_rcp_f32_e32 v164, v3
	v_add_f32_e32 v3, v143, v204
	v_mul_f32_e32 v3, 0xbfb8aa3b, v3
	v_exp_f32_e32 v3, v3
	v_lshlrev_b32_e32 v212, 16, v161
	v_and_b32_e32 v213, 0xffff0000, v161
	v_add_f32_e32 v159, v130, v159
	v_add_f32_e32 v3, 1.0, v3
	v_rcp_f32_e32 v161, v3
	v_add_f32_e32 v3, v127, v163
	v_mul_f32_e32 v3, 0xbfb8aa3b, v3
	v_exp_f32_e32 v3, v3
	v_mul_f32_e32 v159, 0xbfb8aa3b, v159
	v_exp_f32_e32 v162, v159
	v_add_f32_e32 v159, v147, v165
	v_add_f32_e32 v3, 1.0, v3
	v_rcp_f32_e32 v165, v3
	v_add_f32_e32 v3, v144, v205
	v_mul_f32_e32 v3, 0xbfb8aa3b, v3
	v_exp_f32_e32 v3, v3
	v_add_f32_e32 v204, v148, v206
	v_add_f32_e32 v207, v145, v207
	v_mul_f32_e32 v207, 0xbfb8aa3b, v207
	v_add_f32_e32 v3, 1.0, v3
	v_rcp_f32_e32 v206, v3
	v_add_f32_e32 v3, v128, v208
	v_mul_f32_e32 v3, 0xbfb8aa3b, v3
	v_exp_f32_e32 v3, v3
	v_add_f32_e32 v205, v132, v212
	v_exp_f32_e32 v207, v207
	v_mul_f32_e32 v205, 0xbfb8aa3b, v205
	v_exp_f32_e32 v208, v205
	v_add_f32_e32 v205, v149, v210
	v_mul_f32_e32 v158, 0xbfb8aa3b, v158
	v_mul_f32_e32 v159, 0xbfb8aa3b, v159
	v_mul_f32_e32 v204, 0xbfb8aa3b, v204
	v_add_f32_e32 v3, 1.0, v3
	v_mul_f32_e32 v205, 0xbfb8aa3b, v205
	v_exp_f32_e32 v158, v158
	v_exp_f32_e32 v159, v159
	v_exp_f32_e32 v204, v204
	v_exp_f32_e32 v205, v205
	v_rcp_f32_e32 v210, v3
	v_add_f32_e32 v3, 1.0, v207
	v_rcp_f32_e32 v207, v3
	v_pk_add_f32 v[204:205], v[204:205], 1.0 op_sel_hi:[1,0]
	v_pk_add_f32 v[158:159], v[158:159], 1.0 op_sel_hi:[1,0]
	v_add_f32_e32 v3, v133, v213
	v_pk_mul_f32 v[158:159], v[158:159], v[160:161]
	v_pk_mul_f32 v[160:161], v[204:205], v[206:207]
	v_mul_f32_e32 v3, 0xbfb8aa3b, v3
	v_pk_mul_f32 v[116:117], v[116:117], v[160:161]
	v_add_f32_e32 v160, v129, v209
	v_mul_f32_e32 v160, 0xbfb8aa3b, v160
	v_exp_f32_e32 v160, v160
	v_exp_f32_e32 v209, v3
	v_add_f32_e32 v163, v131, v211
	v_mul_f32_e32 v163, 0xbfb8aa3b, v163
	v_add_f32_e32 v3, 1.0, v160
	v_rcp_f32_e32 v211, v3
	v_lshlrev_b32_e32 v3, 16, v154
	v_add_f32_e32 v3, v142, v3
	v_exp_f32_e32 v163, v163
	v_mul_f32_e32 v3, 0xbfb8aa3b, v3
	v_exp_f32_e32 v3, v3
	v_pk_mul_f32 v[114:115], v[114:115], v[158:159]
	v_pk_add_f32 v[158:159], v[208:209], 1.0 op_sel_hi:[1,0]
	v_pk_add_f32 v[160:161], v[162:163], 1.0 op_sel_hi:[1,0]
	v_pk_mul_f32 v[158:159], v[158:159], v[210:211]
	v_pk_mul_f32 v[160:161], v[160:161], v[164:165]
	v_pk_mul_f32 v[112:113], v[112:113], v[158:159]
	v_and_b32_e32 v158, 0xffff0000, v154
	v_lshlrev_b32_e32 v154, 16, v156
	v_add_f32_e32 v3, 1.0, v3
	v_pk_mul_f32 v[110:111], v[110:111], v[160:161]
	v_lshlrev_b32_e32 v160, 16, v151
	v_and_b32_e32 v204, 0xffff0000, v151
	v_lshlrev_b32_e32 v151, 16, v152
	v_and_b32_e32 v162, 0xffff0000, v152
	v_rcp_f32_e32 v152, v3
	v_add_f32_e32 v3, v126, v154
	v_mul_f32_e32 v3, 0xbfb8aa3b, v3
	v_exp_f32_e32 v3, v3
	v_lshlrev_b32_e32 v159, 16, v155
	v_and_b32_e32 v161, 0xffff0000, v155
	v_and_b32_e32 v155, 0xffff0000, v156
	v_lshlrev_b32_e32 v156, 16, v150
	v_add_f32_e32 v3, 1.0, v3
	v_lshlrev_b32_e32 v164, 16, v157
	v_and_b32_e32 v165, 0xffff0000, v157
	v_and_b32_e32 v157, 0xffff0000, v150
	v_add_f32_e32 v150, v146, v156
	v_rcp_f32_e32 v156, v3
	v_add_f32_e32 v3, v143, v158
	v_mul_f32_e32 v3, 0xbfb8aa3b, v3
	v_exp_f32_e32 v3, v3
	v_lshlrev_b32_e32 v205, 16, v153
	v_and_b32_e32 v206, 0xffff0000, v153
	v_add_f32_e32 v151, v130, v151
	v_add_f32_e32 v3, 1.0, v3
	v_rcp_f32_e32 v153, v3
	v_add_f32_e32 v3, v127, v155
	v_add_f32_e32 v155, v131, v162
	v_add_co_u32_e32 v162, vcc, s26, v192
	v_mul_f32_e32 v3, 0xbfb8aa3b, v3
	s_nop 0
	v_addc_co_u32_e32 v163, vcc, 0, v193, vcc
	global_load_dwordx4 v[228:231], v[162:163], off
	v_exp_f32_e32 v3, v3
	v_mul_f32_e32 v151, 0xbfb8aa3b, v151
	s_mov_b32 s26, 0x202000
	v_exp_f32_e32 v154, v151
	v_add_f32_e32 v3, 1.0, v3
	v_add_f32_e32 v151, v147, v157
	v_rcp_f32_e32 v157, v3
	v_add_f32_e32 v3, v144, v159
	v_add_co_u32_e32 v162, vcc, s26, v192
	v_mul_f32_e32 v3, 0xbfb8aa3b, v3
	s_nop 0
	v_addc_co_u32_e32 v163, vcc, 0, v193, vcc
	v_exp_f32_e32 v3, v3
	global_load_dwordx4 v[232:235], v[162:163], off
	v_add_f32_e32 v158, v148, v160
	v_add_f32_e32 v161, v145, v161
	v_add_f32_e32 v3, 1.0, v3
	v_rcp_f32_e32 v160, v3
	v_add_f32_e32 v3, v128, v164
	v_mul_f32_e32 v3, 0xbfb8aa3b, v3
	v_exp_f32_e32 v3, v3
	v_mul_f32_e32 v161, 0xbfb8aa3b, v161
	v_add_f32_e32 v159, v132, v205
	v_exp_f32_e32 v161, v161
	v_mul_f32_e32 v159, 0xbfb8aa3b, v159
; __device__ __forceinline__ void unpack8(const u32x4 w, float (&v)[8]) { v[0] = bf_lo(w.x); v[1] = bf_hi(w.x); v[2] = bf_lo(w.y); v[3] = bf_hi(w.y); v[4] = bf_lo(w.z); v[5] = bf_hi(w.z); v[6] = bf_lo(w.w); v[7] = bf_hi(w.w); }
;     __device__ __forceinline__ void after(int te, f32x4 (&acc)[2][2][4][2], const Unit& u, int wr, int wc, int fr, int fq) const {
;     ...
;                     for (int m = 0; m < 4; ++m) { float vs[8], va[8]; unpack8(gs[m], vs); unpack8(ga[m], va);
; #pragma unroll
;                         for (int e = 0; e < 4; ++e) {
;                             acc[ai][bj][m][0][e] *= (1.f + __expf(-(va[e] + a0[e]))) * __builtin_amdgcn_rcpf(1.f + __expf(-(vs[e] + s0[e])));
;                             acc[ai][bj][m][1][e] *= (1.f + __expf(-(va[4 + e] + a1[e]))) * __builtin_amdgcn_rcpf(1.f + __expf(-(vs[4 + e] + s1[e]))); } }
	v_exp_f32_e32 v162, v159
	v_add_f32_e32 v159, v149, v204
	v_mul_f32_e32 v150, 0xbfb8aa3b, v150
	v_mul_f32_e32 v151, 0xbfb8aa3b, v151
	v_mul_f32_e32 v158, 0xbfb8aa3b, v158
	v_add_f32_e32 v3, 1.0, v3
	v_mul_f32_e32 v159, 0xbfb8aa3b, v159
	v_exp_f32_e32 v150, v150
	v_exp_f32_e32 v151, v151
	v_exp_f32_e32 v158, v158
	v_exp_f32_e32 v159, v159
	v_rcp_f32_e32 v164, v3
	v_add_f32_e32 v3, 1.0, v161
	v_rcp_f32_e32 v161, v3
	v_pk_add_f32 v[158:159], v[158:159], 1.0 op_sel_hi:[1,0]
	v_pk_add_f32 v[150:151], v[150:151], 1.0 op_sel_hi:[1,0]
	v_add_f32_e32 v3, v133, v206
	v_pk_mul_f32 v[150:151], v[150:151], v[152:153]
	v_pk_mul_f32 v[152:153], v[158:159], v[160:161]
	v_mul_f32_e32 v3, 0xbfb8aa3b, v3
	v_pk_mul_f32 v[108:109], v[108:109], v[152:153]
	v_add_f32_e32 v152, v129, v165
	v_mul_f32_e32 v152, 0xbfb8aa3b, v152
	v_exp_f32_e32 v152, v152
	v_exp_f32_e32 v163, v3
	v_mul_f32_e32 v155, 0xbfb8aa3b, v155
	v_exp_f32_e32 v155, v155
	v_add_f32_e32 v3, 1.0, v152
	v_rcp_f32_e32 v165, v3
	s_mov_b64 s[26:27], 0x200000
	v_lshl_add_u64 v[218:219], v[192:193], 0, s[26:27]
	s_mov_b64 s[26:27], 0x202000
	v_pk_mul_f32 v[106:107], v[106:107], v[150:151]
	v_pk_add_f32 v[150:151], v[162:163], 1.0 op_sel_hi:[1,0]
	v_lshl_add_u64 v[216:217], v[192:193], 0, s[26:27]
	s_mov_b64 s[26:27], 0x240000
	v_pk_mul_f32 v[150:151], v[150:151], v[164:165]
	v_lshl_add_u64 v[204:205], v[192:193], 0, s[26:27]
	s_mov_b32 s26, 0x240000
	v_pk_add_f32 v[152:153], v[154:155], 1.0 op_sel_hi:[1,0]
	v_pk_mul_f32 v[104:105], v[104:105], v[150:151]
	v_add_co_u32_e32 v150, vcc, s26, v192
	s_mov_b64 s[26:27], 0x242000
	v_pk_mul_f32 v[152:153], v[152:153], v[156:157]
	v_addc_co_u32_e32 v151, vcc, 0, v193, vcc
	v_lshl_add_u64 v[206:207], v[192:193], 0, s[26:27]
	s_mov_b32 s26, 0x242000
	v_pk_mul_f32 v[102:103], v[102:103], v[152:153]
	v_add_co_u32_e32 v152, vcc, s26, v192
	s_mov_b64 s[26:27], 0x280000
	s_nop 0
	v_addc_co_u32_e32 v153, vcc, 0, v193, vcc
	global_load_dwordx4 v[236:239], v[150:151], off
	global_load_dwordx4 v[240:243], v[152:153], off
	s_waitcnt vmcnt(3)
	v_lshlrev_b32_e32 v3, 16, v228
	v_add_f32_e32 v3, v142, v3
	v_mul_f32_e32 v3, 0xbfb8aa3b, v3
	v_exp_f32_e32 v3, v3
	v_lshlrev_b32_e32 v227, 16, v229
	v_and_b32_e32 v245, 0xffff0000, v229
	v_lshlrev_b32_e32 v229, 16, v230
	v_add_f32_e32 v3, 1.0, v3
	v_and_b32_e32 v246, 0xffff0000, v230
	v_rcp_f32_e32 v230, v3
	v_add_f32_e32 v3, v126, v229
	v_mul_f32_e32 v3, 0xbfb8aa3b, v3
	v_exp_f32_e32 v3, v3
	v_lshl_add_u64 v[208:209], v[192:193], 0, s[26:27]
	s_mov_b32 s26, 0x280000
	v_add_co_u32_e32 v150, vcc, s26, v192
	s_mov_b64 s[26:27], 0x282000
	s_nop 0
	v_addc_co_u32_e32 v151, vcc, 0, v193, vcc
	v_lshl_add_u64 v[210:211], v[192:193], 0, s[26:27]
	s_mov_b32 s26, 0x282000
	v_add_co_u32_e32 v152, vcc, s26, v192
	v_and_b32_e32 v225, 0xffff0000, v228
	v_add_f32_e32 v3, 1.0, v3
	v_addc_co_u32_e32 v153, vcc, 0, v193, vcc
	global_load_dwordx4 v[162:165], v[150:151], off
	global_load_dwordx4 v[158:161], v[152:153], off
	v_lshlrev_b32_e32 v247, 16, v231
	v_and_b32_e32 v251, 0xffff0000, v231
	s_waitcnt vmcnt(4)
	v_lshlrev_b32_e32 v228, 16, v232
	v_and_b32_e32 v231, 0xffff0000, v232
	v_lshlrev_b32_e32 v248, 16, v233
	v_and_b32_e32 v249, 0xffff0000, v233
	v_lshlrev_b32_e32 v232, 16, v234
	v_and_b32_e32 v233, 0xffff0000, v234
	v_rcp_f32_e32 v234, v3
	v_add_f32_e32 v3, v143, v225
	v_mul_f32_e32 v3, 0xbfb8aa3b, v3
	v_exp_f32_e32 v3, v3
	v_add_f32_e32 v225, v147, v231
	v_lshlrev_b32_e32 v250, 16, v235
	v_and_b32_e32 v253, 0xffff0000, v235
	v_add_f32_e32 v3, 1.0, v3
	v_rcp_f32_e32 v231, v3
	v_add_f32_e32 v3, v127, v246
	v_mul_f32_e32 v3, 0xbfb8aa3b, v3
	v_exp_f32_e32 v3, v3
	v_add_f32_e32 v229, v130, v232
	v_mul_f32_e32 v229, 0xbfb8aa3b, v229
	v_mul_f32_e32 v225, 0xbfb8aa3b, v225
	v_add_f32_e32 v3, 1.0, v3
	v_rcp_f32_e32 v235, v3
	v_add_f32_e32 v3, v144, v227
	v_mul_f32_e32 v3, 0xbfb8aa3b, v3
	v_exp_f32_e32 v3, v3
	v_exp_f32_e32 v232, v229
	v_exp_f32_e32 v229, v225
	v_add_f32_e32 v225, v131, v233
	v_mul_f32_e32 v225, 0xbfb8aa3b, v225
	v_exp_f32_e32 v233, v225
	v_add_f32_e32 v225, v148, v248
	v_mul_f32_e32 v225, 0xbfb8aa3b, v225
	v_add_f32_e32 v3, 1.0, v3
	v_exp_f32_e32 v246, v225
	v_rcp_f32_e32 v248, v3
	v_add_f32_e32 v3, v128, v247
	v_add_f32_e32 v225, v132, v250
	v_mul_f32_e32 v3, 0xbfb8aa3b, v3
	v_mul_f32_e32 v225, 0xbfb8aa3b, v225
	v_add_f32_e32 v227, v145, v245
	v_exp_f32_e32 v3, v3
	v_exp_f32_e32 v250, v225
	v_add_f32_e32 v225, v149, v249
	v_mul_f32_e32 v227, 0xbfb8aa3b, v227
	v_exp_f32_e32 v227, v227
	v_mul_f32_e32 v225, 0xbfb8aa3b, v225
	v_exp_f32_e32 v247, v225
	v_add_f32_e32 v225, v129, v251
	v_mul_f32_e32 v225, 0xbfb8aa3b, v225
	v_add_f32_e32 v3, 1.0, v3
	v_exp_f32_e32 v225, v225
	v_rcp_f32_e32 v252, v3
	v_add_f32_e32 v3, 1.0, v227
	v_add_f32_e32 v228, v146, v228
	v_rcp_f32_e32 v249, v3
	v_add_f32_e32 v3, v133, v253
	v_mul_f32_e32 v228, 0xbfb8aa3b, v228
	v_mul_f32_e32 v3, 0xbfb8aa3b, v3
	v_exp_f32_e32 v228, v228
	v_exp_f32_e32 v251, v3
	v_add_f32_e32 v3, 1.0, v225
	v_rcp_f32_e32 v253, v3
	s_waitcnt vmcnt(3)
; __device__ __forceinline__ void unpack8(const u32x4 w, float (&v)[8]) { v[0] = bf_lo(w.x); v[1] = bf_hi(w.x); v[2] = bf_lo(w.y); v[3] = bf_hi(w.y); v[4] = bf_lo(w.z); v[5] = bf_hi(w.z); v[6] = bf_lo(w.w); v[7] = bf_hi(w.w); }
;     __device__ __forceinline__ void after(int te, f32x4 (&acc)[2][2][4][2], const Unit& u, int wr, int wc, int fr, int fq) const {
;     ...
;                     for (int m = 0; m < 4; ++m) { float vs[8], va[8]; unpack8(gs[m], vs); unpack8(ga[m], va);
; #pragma unroll
;                         for (int e = 0; e < 4; ++e) {
;                             acc[ai][bj][m][0][e] *= (1.f + __expf(-(va[e] + a0[e]))) * __builtin_amdgcn_rcpf(1.f + __expf(-(vs[e] + s0[e])));
;                             acc[ai][bj][m][1][e] *= (1.f + __expf(-(va[4 + e] + a1[e]))) * __builtin_amdgcn_rcpf(1.f + __expf(-(vs[4 + e] + s1[e]))); } }
	v_lshlrev_b32_e32 v3, 16, v236
	v_add_f32_e32 v3, v142, v3
	v_mul_f32_e32 v3, 0xbfb8aa3b, v3
	v_pk_add_f32 v[228:229], v[228:229], 1.0 op_sel_hi:[1,0]
	v_exp_f32_e32 v3, v3
	v_pk_add_f32 v[246:247], v[246:247], 1.0 op_sel_hi:[1,0]
	v_pk_mul_f32 v[228:229], v[228:229], v[230:231]
	v_pk_mul_f32 v[230:231], v[246:247], v[248:249]
	v_pk_mul_f32 v[98:99], v[98:99], v[228:229]
	v_pk_add_f32 v[228:229], v[250:251], 1.0 op_sel_hi:[1,0]
	v_pk_mul_f32 v[100:101], v[100:101], v[230:231]
	v_pk_add_f32 v[230:231], v[232:233], 1.0 op_sel_hi:[1,0]
	v_pk_mul_f32 v[228:229], v[228:229], v[252:253]
	v_pk_mul_f32 v[230:231], v[230:231], v[234:235]
	v_pk_mul_f32 v[96:97], v[96:97], v[228:229]
	v_lshlrev_b32_e32 v229, 16, v238
	v_add_f32_e32 v3, 1.0, v3
	v_pk_mul_f32 v[94:95], v[94:95], v[230:231]
	v_rcp_f32_e32 v230, v3
	v_add_f32_e32 v3, v126, v229
	v_mul_f32_e32 v3, 0xbfb8aa3b, v3
	v_exp_f32_e32 v3, v3
	v_and_b32_e32 v225, 0xffff0000, v236
	s_mov_b64 s[26:27], 0x2c0000
	v_lshl_add_u64 v[212:213], v[192:193], 0, s[26:27]
	v_add_f32_e32 v3, 1.0, v3
	v_rcp_f32_e32 v234, v3
	v_add_f32_e32 v3, v143, v225
	v_mul_f32_e32 v3, 0xbfb8aa3b, v3
	v_exp_f32_e32 v3, v3
	s_mov_b32 s26, 0x2c0000
	v_add_co_u32_e32 v150, vcc, s26, v192
	s_mov_b64 s[26:27], 0x2c2000
	s_nop 0
	v_addc_co_u32_e32 v151, vcc, 0, v193, vcc
	v_lshl_add_u64 v[214:215], v[192:193], 0, s[26:27]
	s_mov_b32 s26, 0x2c2000
	v_and_b32_e32 v233, 0xffff0000, v238
	s_waitcnt vmcnt(2)
	v_and_b32_e32 v231, 0xffff0000, v240
	v_add_f32_e32 v3, 1.0, v3
	v_add_co_u32_e32 v152, vcc, s26, v192
	v_add_f32_e32 v225, v147, v231
	v_rcp_f32_e32 v231, v3
	v_add_f32_e32 v3, v127, v233
	v_addc_co_u32_e32 v153, vcc, 0, v193, vcc
	v_mul_f32_e32 v3, 0xbfb8aa3b, v3
	global_load_dwordx4 v[154:157], v[150:151], off
	s_nop 0
	global_load_dwordx4 v[150:153], v[152:153], off
	v_exp_f32_e32 v3, v3
	v_lshlrev_b32_e32 v232, 16, v242
	v_add_f32_e32 v229, v130, v232
	v_lshlrev_b32_e32 v227, 16, v237
	v_and_b32_e32 v235, 0xffff0000, v242
	v_mul_f32_e32 v229, 0xbfb8aa3b, v229
	v_mul_f32_e32 v225, 0xbfb8aa3b, v225
	v_add_f32_e32 v3, 1.0, v3
	v_exp_f32_e32 v232, v229
	v_exp_f32_e32 v229, v225
	v_add_f32_e32 v225, v131, v235
	v_rcp_f32_e32 v235, v3
	v_add_f32_e32 v3, v144, v227
	v_mul_f32_e32 v3, 0xbfb8aa3b, v3
	v_exp_f32_e32 v3, v3
	v_lshlrev_b32_e32 v236, 16, v241
	v_mul_f32_e32 v225, 0xbfb8aa3b, v225
	v_exp_f32_e32 v233, v225
	v_add_f32_e32 v225, v148, v236
	v_lshlrev_b32_e32 v245, 16, v239
	v_lshlrev_b32_e32 v228, 16, v240
	v_lshlrev_b32_e32 v240, 16, v243
	v_mul_f32_e32 v225, 0xbfb8aa3b, v225
	v_add_f32_e32 v3, 1.0, v3
	v_and_b32_e32 v237, 0xffff0000, v237
	v_exp_f32_e32 v236, v225
	v_rcp_f32_e32 v238, v3
	v_add_f32_e32 v3, v128, v245
	v_add_f32_e32 v225, v132, v240
	v_and_b32_e32 v246, 0xffff0000, v239
	v_and_b32_e32 v239, 0xffff0000, v241
	v_mul_f32_e32 v3, 0xbfb8aa3b, v3
	v_mul_f32_e32 v225, 0xbfb8aa3b, v225
	v_add_f32_e32 v227, v145, v237
	v_exp_f32_e32 v3, v3
	v_exp_f32_e32 v240, v225
	v_add_f32_e32 v225, v149, v239
	v_mul_f32_e32 v227, 0xbfb8aa3b, v227
	v_exp_f32_e32 v227, v227
	v_mul_f32_e32 v225, 0xbfb8aa3b, v225
	v_exp_f32_e32 v237, v225
	v_add_f32_e32 v225, v129, v246
	v_mul_f32_e32 v225, 0xbfb8aa3b, v225
	v_add_f32_e32 v3, 1.0, v3
	v_exp_f32_e32 v225, v225
	v_and_b32_e32 v241, 0xffff0000, v243
	v_rcp_f32_e32 v242, v3
	v_add_f32_e32 v3, 1.0, v227
	v_rcp_f32_e32 v239, v3
	v_add_f32_e32 v3, v133, v241
	v_add_f32_e32 v228, v146, v228
	v_mul_f32_e32 v3, 0xbfb8aa3b, v3
	v_mul_f32_e32 v228, 0xbfb8aa3b, v228
	v_exp_f32_e32 v241, v3
	v_add_f32_e32 v3, 1.0, v225
	v_exp_f32_e32 v228, v228
	v_rcp_f32_e32 v243, v3
	s_waitcnt vmcnt(3)
	v_lshlrev_b32_e32 v3, 16, v162
	v_add_f32_e32 v3, v142, v3
	v_mul_f32_e32 v3, 0xbfb8aa3b, v3
	v_exp_f32_e32 v3, v3
	v_pk_add_f32 v[236:237], v[236:237], 1.0 op_sel_hi:[1,0]
	v_pk_add_f32 v[228:229], v[228:229], 1.0 op_sel_hi:[1,0]
	v_and_b32_e32 v225, 0xffff0000, v162
	v_pk_mul_f32 v[228:229], v[228:229], v[230:231]
	v_pk_mul_f32 v[230:231], v[236:237], v[238:239]
	v_pk_mul_f32 v[90:91], v[90:91], v[228:229]
	v_pk_mul_f32 v[92:93], v[92:93], v[230:231]
	v_pk_add_f32 v[228:229], v[240:241], 1.0 op_sel_hi:[1,0]
	v_pk_add_f32 v[230:231], v[232:233], 1.0 op_sel_hi:[1,0]
	v_pk_mul_f32 v[228:229], v[228:229], v[242:243]
	v_pk_mul_f32 v[230:231], v[230:231], v[234:235]
	v_lshlrev_b32_e32 v162, 16, v164
	v_add_f32_e32 v3, 1.0, v3
	v_pk_mul_f32 v[88:89], v[88:89], v[228:229]
	v_pk_mul_f32 v[86:87], v[86:87], v[230:231]
	s_waitcnt vmcnt(2)
; __device__ __forceinline__ void unpack8(const u32x4 w, float (&v)[8]) { v[0] = bf_lo(w.x); v[1] = bf_hi(w.x); v[2] = bf_lo(w.y); v[3] = bf_hi(w.y); v[4] = bf_lo(w.z); v[5] = bf_hi(w.z); v[6] = bf_lo(w.w); v[7] = bf_hi(w.w); }
;     __device__ __forceinline__ void after(int te, f32x4 (&acc)[2][2][4][2], const Unit& u, int wr, int wc, int fr, int fq) const {
;     ...
;                     for (int m = 0; m < 4; ++m) { const size_t r = (size_t)(row0 + ai * HALF + m * 16); gs[m] = *(const u32x4*)(proj + r * LDP + PGS + c); ga[m] = *(const u32x4*)(proj + r * LDP + PGA + c); }
; #pragma unroll
;                     for (int m = 0; m < 4; ++m) { float vs[8], va[8]; unpack8(gs[m], vs); unpack8(ga[m], va);
; #pragma unroll
;                         for (int e = 0; e < 4; ++e) {
;                             acc[ai][bj][m][0][e] *= (1.f + __expf(-(va[e] + a0[e]))) * __builtin_amdgcn_rcpf(1.f + __expf(-(vs[e] + s0[e])));
;                             acc[ai][bj][m][1][e] *= (1.f + __expf(-(va[4 + e] + a1[e]))) * __builtin_amdgcn_rcpf(1.f + __expf(-(vs[4 + e] + s1[e]))); } }
	v_lshlrev_b32_e32 v228, 16, v159
	v_and_b32_e32 v234, 0xffff0000, v159
	v_lshlrev_b32_e32 v159, 16, v160
	v_and_b32_e32 v230, 0xffff0000, v160
	v_rcp_f32_e32 v160, v3
	v_add_f32_e32 v3, v126, v162
	v_mul_f32_e32 v3, 0xbfb8aa3b, v3
	v_exp_f32_e32 v3, v3
	v_lshlrev_b32_e32 v227, 16, v163
	v_and_b32_e32 v229, 0xffff0000, v163
	v_and_b32_e32 v163, 0xffff0000, v164
	v_lshlrev_b32_e32 v164, 16, v158
	v_add_f32_e32 v3, 1.0, v3
	v_lshlrev_b32_e32 v231, 16, v165
	v_and_b32_e32 v233, 0xffff0000, v165
	v_and_b32_e32 v165, 0xffff0000, v158
	v_add_f32_e32 v158, v146, v164
	v_rcp_f32_e32 v164, v3
	v_add_f32_e32 v3, v143, v225
	v_mul_f32_e32 v3, 0xbfb8aa3b, v3
	v_exp_f32_e32 v3, v3
	v_lshlrev_b32_e32 v232, 16, v161
	v_and_b32_e32 v235, 0xffff0000, v161
	v_add_f32_e32 v159, v130, v159
	v_add_f32_e32 v3, 1.0, v3
	v_rcp_f32_e32 v161, v3
	v_add_f32_e32 v3, v127, v163
	v_mul_f32_e32 v3, 0xbfb8aa3b, v3
	v_exp_f32_e32 v3, v3
	v_mul_f32_e32 v159, 0xbfb8aa3b, v159
	v_exp_f32_e32 v162, v159
	v_add_f32_e32 v159, v147, v165
	v_add_f32_e32 v3, 1.0, v3
	v_rcp_f32_e32 v165, v3
	v_add_f32_e32 v3, v144, v227
	v_mul_f32_e32 v3, 0xbfb8aa3b, v3
	v_exp_f32_e32 v3, v3
	v_add_f32_e32 v163, v131, v230
	v_add_f32_e32 v225, v148, v228
	v_add_f32_e32 v227, v145, v229
	v_add_f32_e32 v3, 1.0, v3
	v_rcp_f32_e32 v230, v3
	v_add_f32_e32 v3, v128, v231
	v_mul_f32_e32 v3, 0xbfb8aa3b, v3
	v_mul_f32_e32 v225, 0xbfb8aa3b, v225
	v_exp_f32_e32 v3, v3
	v_mul_f32_e32 v227, 0xbfb8aa3b, v227
	v_exp_f32_e32 v228, v225
	v_add_f32_e32 v225, v132, v232
	v_exp_f32_e32 v227, v227
	v_mul_f32_e32 v225, 0xbfb8aa3b, v225
	v_exp_f32_e32 v232, v225
	v_add_f32_e32 v225, v149, v234
	v_mul_f32_e32 v158, 0xbfb8aa3b, v158
	v_mul_f32_e32 v159, 0xbfb8aa3b, v159
	v_add_f32_e32 v3, 1.0, v3
	v_mul_f32_e32 v225, 0xbfb8aa3b, v225
	v_exp_f32_e32 v158, v158
	v_exp_f32_e32 v159, v159
	v_exp_f32_e32 v229, v225
	v_rcp_f32_e32 v234, v3
	v_add_f32_e32 v3, 1.0, v227
	v_rcp_f32_e32 v231, v3
	v_pk_add_f32 v[228:229], v[228:229], 1.0 op_sel_hi:[1,0]
	v_pk_add_f32 v[158:159], v[158:159], 1.0 op_sel_hi:[1,0]
	v_add_f32_e32 v3, v133, v235
	v_pk_mul_f32 v[158:159], v[158:159], v[160:161]
	v_pk_mul_f32 v[160:161], v[228:229], v[230:231]
	v_mul_f32_e32 v3, 0xbfb8aa3b, v3
	v_pk_mul_f32 v[84:85], v[84:85], v[160:161]
	v_add_f32_e32 v160, v129, v233
	v_mul_f32_e32 v160, 0xbfb8aa3b, v160
	v_exp_f32_e32 v160, v160
	v_exp_f32_e32 v233, v3
	s_waitcnt vmcnt(1)
	v_lshlrev_b32_e32 v225, 16, v155
	v_and_b32_e32 v227, 0xffff0000, v155
	v_add_f32_e32 v3, 1.0, v160
	v_rcp_f32_e32 v235, v3
	v_lshlrev_b32_e32 v3, 16, v154
	v_add_f32_e32 v3, v142, v3
	v_mul_f32_e32 v3, 0xbfb8aa3b, v3
	v_exp_f32_e32 v3, v3
	v_lshlrev_b32_e32 v155, 16, v156
	v_and_b32_e32 v236, 0xffff0000, v156
	s_waitcnt vmcnt(0)
	v_lshlrev_b32_e32 v156, 16, v150
	v_add_f32_e32 v3, 1.0, v3
	v_mul_f32_e32 v163, 0xbfb8aa3b, v163
	v_add_f32_e32 v142, v146, v156
	v_rcp_f32_e32 v146, v3
	v_add_f32_e32 v3, v126, v155
	v_exp_f32_e32 v163, v163
	v_mul_f32_e32 v3, 0xbfb8aa3b, v3
	v_exp_f32_e32 v3, v3
	v_pk_mul_f32 v[82:83], v[82:83], v[158:159]
	v_pk_add_f32 v[158:159], v[232:233], 1.0 op_sel_hi:[1,0]
	v_pk_add_f32 v[160:161], v[162:163], 1.0 op_sel_hi:[1,0]
	v_pk_mul_f32 v[158:159], v[158:159], v[234:235]
	v_pk_mul_f32 v[160:161], v[160:161], v[164:165]
	v_and_b32_e32 v150, 0xffff0000, v150
	v_lshlrev_b32_e32 v239, 16, v151
	v_and_b32_e32 v240, 0xffff0000, v151
	v_lshlrev_b32_e32 v151, 16, v152
	global_load_dwordx4 v[228:231], v[192:193], off offset:256
	global_load_dwordx4 v[232:235], v[202:203], off offset:256
	v_add_f32_e32 v3, 1.0, v3
	v_pk_mul_f32 v[80:81], v[80:81], v[158:159]
	v_pk_mul_f32 v[78:79], v[78:79], v[160:161]
	v_and_b32_e32 v241, 0xffff0000, v152
	v_lshlrev_b32_e32 v242, 16, v153
	v_and_b32_e32 v243, 0xffff0000, v153
	v_add_f32_e32 v126, v130, v151
	v_rcp_f32_e32 v130, v3
	v_add_f32_e32 v3, v147, v150
	global_load_dwordx4 v[150:153], v[196:197], off offset:528
	global_load_dwordx4 v[158:161], v[196:197], off offset:512
	v_and_b32_e32 v154, 0xffff0000, v154
	v_lshlrev_b32_e32 v237, 16, v157
	v_and_b32_e32 v238, 0xffff0000, v157
	v_add_f32_e32 v143, v143, v154
	global_load_dwordx4 v[154:157], v[198:199], off offset:528
	global_load_dwordx4 v[162:165], v[198:199], off offset:512
	v_mul_f32_e32 v143, 0xbfb8aa3b, v143
	v_exp_f32_e32 v147, v143
	v_mul_f32_e32 v3, 0xbfb8aa3b, v3
	v_exp_f32_e32 v143, v3
	v_add_f32_e32 v145, v145, v227
	v_add_f32_e32 v3, 1.0, v147
	v_rcp_f32_e32 v147, v3
	v_add_f32_e32 v3, v127, v236
	v_mul_f32_e32 v3, 0xbfb8aa3b, v3
	v_exp_f32_e32 v3, v3
	v_add_f32_e32 v127, v131, v241
	v_mul_f32_e32 v145, 0xbfb8aa3b, v145
	v_add_f32_e32 v129, v129, v238
	v_add_f32_e32 v3, 1.0, v3
	v_rcp_f32_e32 v131, v3
	v_add_f32_e32 v3, v144, v225
	v_mul_f32_e32 v3, 0xbfb8aa3b, v3
	v_exp_f32_e32 v3, v3
	v_add_f32_e32 v144, v148, v239
	v_mul_f32_e32 v129, 0xbfb8aa3b, v129
	v_mul_f32_e32 v142, 0xbfb8aa3b, v142
	v_add_f32_e32 v3, 1.0, v3
	v_rcp_f32_e32 v148, v3
	v_add_f32_e32 v3, v128, v237
	v_mul_f32_e32 v3, 0xbfb8aa3b, v3
	v_exp_f32_e32 v3, v3
	v_add_f32_e32 v128, v132, v242
	v_add_f32_e32 v132, v149, v240
	v_exp_f32_e32 v149, v145
	v_add_f32_e32 v3, 1.0, v3
	v_mul_f32_e32 v132, 0xbfb8aa3b, v132
	v_exp_f32_e32 v145, v132
	v_rcp_f32_e32 v132, v3
	v_add_f32_e32 v3, 1.0, v149
	v_rcp_f32_e32 v149, v3
	v_add_f32_e32 v3, v133, v243
	v_exp_f32_e32 v133, v129
	v_mul_f32_e32 v126, 0xbfb8aa3b, v126
	v_mul_f32_e32 v127, 0xbfb8aa3b, v127
	v_mul_f32_e32 v144, 0xbfb8aa3b, v144
	v_mul_f32_e32 v128, 0xbfb8aa3b, v128
	v_mul_f32_e32 v3, 0xbfb8aa3b, v3
	v_exp_f32_e32 v142, v142
	v_exp_f32_e32 v126, v126
	v_exp_f32_e32 v127, v127
	v_exp_f32_e32 v144, v144
	v_exp_f32_e32 v128, v128
	v_exp_f32_e32 v129, v3
	v_add_f32_e32 v3, 1.0, v133
	v_rcp_f32_e32 v133, v3
	v_pk_add_f32 v[144:145], v[144:145], 1.0 op_sel_hi:[1,0]
	v_pk_add_f32 v[142:143], v[142:143], 1.0 op_sel_hi:[1,0]
	v_pk_add_f32 v[128:129], v[128:129], 1.0 op_sel_hi:[1,0]
	v_pk_add_f32 v[126:127], v[126:127], 1.0 op_sel_hi:[1,0]
	v_pk_mul_f32 v[142:143], v[142:143], v[146:147]
	v_pk_mul_f32 v[144:145], v[144:145], v[148:149]
	v_pk_mul_f32 v[126:127], v[126:127], v[130:131]
	v_pk_mul_f32 v[128:129], v[128:129], v[132:133]
	v_pk_mul_f32 v[76:77], v[76:77], v[144:145]
	v_pk_mul_f32 v[74:75], v[74:75], v[142:143]
	v_pk_mul_f32 v[72:73], v[72:73], v[128:129]
	v_pk_mul_f32 v[70:71], v[70:71], v[126:127]
	global_load_dwordx4 v[196:199], v[4:5], off offset:256
	global_load_dwordx4 v[236:239], v[186:187], off offset:256
	global_load_dwordx4 v[146:149], v[188:189], off offset:256
	global_load_dwordx4 v[142:145], v[190:191], off offset:256
	global_load_dwordx4 v[130:133], v[194:195], off offset:256
	global_load_dwordx4 v[126:129], v[200:201], off offset:256
	s_waitcnt vmcnt(11)
; __device__ __forceinline__ void unpack8(const u32x4 w, float (&v)[8]) { v[0] = bf_lo(w.x); v[1] = bf_hi(w.x); v[2] = bf_lo(w.y); v[3] = bf_hi(w.y); v[4] = bf_lo(w.z); v[5] = bf_hi(w.z); v[6] = bf_lo(w.w); v[7] = bf_hi(w.w); }
;     __device__ __forceinline__ void after(int te, f32x4 (&acc)[2][2][4][2], const Unit& u, int wr, int wc, int fr, int fq) const {
;     ...
;                 const f32x4 s0 = *(const f32x4*)(gb + c), s1 = *(const f32x4*)(gb + c + 4), a0 = *(const f32x4*)(gb + D_MODEL + c), a1 = *(const f32x4*)(gb + D_MODEL + c + 4);
; #pragma unroll
;                 for (int ai = 0; ai < 2; ++ai) {
;                     u32x4 gs[4], ga[4];
; #pragma unroll
;                     for (int m = 0; m < 4; ++m) { const size_t r = (size_t)(row0 + ai * HALF + m * 16); gs[m] = *(const u32x4*)(proj + r * LDP + PGS + c); ga[m] = *(const u32x4*)(proj + r * LDP + PGA + c); }
; #pragma unroll
;                     for (int m = 0; m < 4; ++m) { float vs[8], va[8]; unpack8(gs[m], vs); unpack8(ga[m], va);
; #pragma unroll
;                         for (int e = 0; e < 4; ++e) {
;                             acc[ai][bj][m][0][e] *= (1.f + __expf(-(va[e] + a0[e]))) * __builtin_amdgcn_rcpf(1.f + __expf(-(vs[e] + s0[e])));
;                             acc[ai][bj][m][1][e] *= (1.f + __expf(-(va[4 + e] + a1[e]))) * __builtin_amdgcn_rcpf(1.f + __expf(-(vs[4 + e] + s1[e]))); } }
	v_lshlrev_b32_e32 v3, 16, v228
	v_lshlrev_b32_e32 v187, 16, v230
	v_and_b32_e32 v5, 0xffff0000, v228
	s_waitcnt vmcnt(10)
	v_lshlrev_b32_e32 v188, 16, v234
	v_and_b32_e32 v189, 0xffff0000, v230
	v_lshlrev_b32_e32 v192, 16, v229
	v_and_b32_e32 v191, 0xffff0000, v232
	v_lshlrev_b32_e32 v195, 16, v231
	v_lshlrev_b32_e32 v194, 16, v233
	v_and_b32_e32 v193, 0xffff0000, v229
	v_lshlrev_b32_e32 v203, 16, v235
	s_waitcnt vmcnt(8)
	v_add_f32_e32 v3, v158, v3
	v_mul_f32_e32 v3, 0xbfb8aa3b, v3
	v_exp_f32_e32 v3, v3
	v_add_f32_e32 v193, v161, v193
	v_mul_f32_e32 v193, 0xbfb8aa3b, v193
	v_lshlrev_b32_e32 v4, 16, v232
	v_add_f32_e32 v3, 1.0, v3
	v_rcp_f32_e32 v186, v3
	v_add_f32_e32 v3, v150, v187
	v_mul_f32_e32 v3, 0xbfb8aa3b, v3
	v_exp_f32_e32 v3, v3
	s_waitcnt vmcnt(7)
	v_add_f32_e32 v187, v154, v188
	v_mul_f32_e32 v187, 0xbfb8aa3b, v187
	v_exp_f32_e32 v188, v187
	v_add_f32_e32 v3, 1.0, v3
	v_rcp_f32_e32 v190, v3
	v_add_f32_e32 v3, v159, v5
	v_mul_f32_e32 v3, 0xbfb8aa3b, v3
	v_exp_f32_e32 v3, v3
	s_waitcnt vmcnt(6)
	v_add_f32_e32 v5, v163, v191
	v_and_b32_e32 v202, 0xffff0000, v233
	v_and_b32_e32 v200, 0xffff0000, v234
	v_add_f32_e32 v3, 1.0, v3
	v_rcp_f32_e32 v187, v3
	v_add_f32_e32 v3, v151, v189
	v_mul_f32_e32 v3, 0xbfb8aa3b, v3
	v_exp_f32_e32 v3, v3
	v_add_f32_e32 v4, v162, v4
	v_add_f32_e32 v189, v155, v200
	v_mul_f32_e32 v4, 0xbfb8aa3b, v4
	v_add_f32_e32 v3, 1.0, v3
	v_rcp_f32_e32 v191, v3
	v_add_f32_e32 v3, v160, v192
	v_mul_f32_e32 v3, 0xbfb8aa3b, v3
	v_exp_f32_e32 v3, v3
	v_add_f32_e32 v192, v164, v194
	v_mul_f32_e32 v5, 0xbfb8aa3b, v5
	v_mul_f32_e32 v192, 0xbfb8aa3b, v192
	v_add_f32_e32 v3, 1.0, v3
	v_rcp_f32_e32 v194, v3
	v_add_f32_e32 v3, v152, v195
	v_mul_f32_e32 v3, 0xbfb8aa3b, v3
	v_exp_f32_e32 v3, v3
	v_add_f32_e32 v195, v156, v203
	v_exp_f32_e32 v203, v193
	v_mul_f32_e32 v195, 0xbfb8aa3b, v195
	v_exp_f32_e32 v200, v195
	v_add_f32_e32 v195, v165, v202
	v_add_f32_e32 v3, 1.0, v3
	v_mul_f32_e32 v193, 0xbfb8aa3b, v195
	v_exp_f32_e32 v4, v4
	v_exp_f32_e32 v5, v5
	v_exp_f32_e32 v192, v192
	v_exp_f32_e32 v193, v193
	v_rcp_f32_e32 v202, v3
	v_add_f32_e32 v3, 1.0, v203
	v_rcp_f32_e32 v195, v3
	v_pk_add_f32 v[192:193], v[192:193], 1.0 op_sel_hi:[1,0]
	v_pk_add_f32 v[4:5], v[4:5], 1.0 op_sel_hi:[1,0]
	v_and_b32_e32 v201, 0xffff0000, v231
	v_pk_mul_f32 v[4:5], v[4:5], v[186:187]
	v_pk_mul_f32 v[186:187], v[192:193], v[194:195]
	v_and_b32_e32 v225, 0xffff0000, v235
	v_pk_mul_f32 v[68:69], v[68:69], v[186:187]
	v_add_f32_e32 v186, v153, v201
	v_mul_f32_e32 v186, 0xbfb8aa3b, v186
	v_exp_f32_e32 v186, v186
	v_add_f32_e32 v3, v157, v225
	v_mul_f32_e32 v3, 0xbfb8aa3b, v3
	v_exp_f32_e32 v201, v3
	v_add_f32_e32 v3, 1.0, v186
	v_mul_f32_e32 v189, 0xbfb8aa3b, v189
	v_rcp_f32_e32 v203, v3
	s_waitcnt vmcnt(5)
	v_lshlrev_b32_e32 v3, 16, v196
	v_exp_f32_e32 v189, v189
	v_add_f32_e32 v3, v158, v3
	v_mul_f32_e32 v3, 0xbfb8aa3b, v3
	v_exp_f32_e32 v3, v3
	v_pk_add_f32 v[186:187], v[188:189], 1.0 op_sel_hi:[1,0]
	v_pk_mul_f32 v[66:67], v[66:67], v[4:5]
	v_pk_mul_f32 v[186:187], v[186:187], v[190:191]
	v_add_f32_e32 v3, 1.0, v3
	v_pk_mul_f32 v[62:63], v[62:63], v[186:187]
	v_lshlrev_b32_e32 v187, 16, v198
	v_rcp_f32_e32 v186, v3
	v_add_f32_e32 v3, v150, v187
	v_mul_f32_e32 v3, 0xbfb8aa3b, v3
	v_exp_f32_e32 v3, v3
	v_pk_add_f32 v[4:5], v[200:201], 1.0 op_sel_hi:[1,0]
	s_waitcnt vmcnt(4)
	v_lshlrev_b32_e32 v188, 16, v238
	v_pk_mul_f32 v[4:5], v[4:5], v[202:203]
	v_add_f32_e32 v3, 1.0, v3
	v_pk_mul_f32 v[64:65], v[64:65], v[4:5]
	v_and_b32_e32 v5, 0xffff0000, v196
	v_rcp_f32_e32 v190, v3
	v_add_f32_e32 v3, v159, v5
	v_mul_f32_e32 v3, 0xbfb8aa3b, v3
	v_exp_f32_e32 v3, v3
	v_add_f32_e32 v187, v154, v188
	v_and_b32_e32 v189, 0xffff0000, v198
	v_mul_f32_e32 v187, 0xbfb8aa3b, v187
	v_add_f32_e32 v3, 1.0, v3
	v_exp_f32_e32 v188, v187
	v_rcp_f32_e32 v187, v3
	v_add_f32_e32 v3, v151, v189
	v_mul_f32_e32 v3, 0xbfb8aa3b, v3
	v_exp_f32_e32 v3, v3
	v_lshlrev_b32_e32 v192, 16, v197
	v_and_b32_e32 v191, 0xffff0000, v236
	v_add_f32_e32 v5, v163, v191
	v_add_f32_e32 v3, 1.0, v3
	v_rcp_f32_e32 v191, v3
	v_add_f32_e32 v3, v160, v192
	v_mul_f32_e32 v3, 0xbfb8aa3b, v3
	v_exp_f32_e32 v3, v3
	v_lshlrev_b32_e32 v195, 16, v199
	v_lshlrev_b32_e32 v194, 16, v237
	v_and_b32_e32 v193, 0xffff0000, v197
	v_add_f32_e32 v3, 1.0, v3
	v_add_f32_e32 v192, v164, v194
	v_rcp_f32_e32 v194, v3
	v_add_f32_e32 v3, v152, v195
	v_mul_f32_e32 v3, 0xbfb8aa3b, v3
	v_add_f32_e32 v193, v161, v193
	v_and_b32_e32 v197, 0xffff0000, v199
	v_lshlrev_b32_e32 v199, 16, v239
	v_exp_f32_e32 v3, v3
	v_mul_f32_e32 v193, 0xbfb8aa3b, v193
	v_add_f32_e32 v195, v156, v199
	v_exp_f32_e32 v199, v193
	v_lshlrev_b32_e32 v4, 16, v236
	v_and_b32_e32 v198, 0xffff0000, v237
	v_and_b32_e32 v196, 0xffff0000, v238
	v_mul_f32_e32 v195, 0xbfb8aa3b, v195
	v_add_f32_e32 v4, v162, v4
	v_add_f32_e32 v189, v155, v196
	v_exp_f32_e32 v196, v195
	v_add_f32_e32 v195, v165, v198
	v_mul_f32_e32 v4, 0xbfb8aa3b, v4
	v_mul_f32_e32 v5, 0xbfb8aa3b, v5
	v_mul_f32_e32 v192, 0xbfb8aa3b, v192
	v_add_f32_e32 v3, 1.0, v3
	v_mul_f32_e32 v193, 0xbfb8aa3b, v195
	v_exp_f32_e32 v4, v4
	v_exp_f32_e32 v5, v5
	v_exp_f32_e32 v192, v192
	v_exp_f32_e32 v193, v193
	v_rcp_f32_e32 v198, v3
	v_add_f32_e32 v3, 1.0, v199
	v_rcp_f32_e32 v195, v3
	v_pk_add_f32 v[192:193], v[192:193], 1.0 op_sel_hi:[1,0]
	v_pk_add_f32 v[4:5], v[4:5], 1.0 op_sel_hi:[1,0]
	v_and_b32_e32 v200, 0xffff0000, v239
	v_pk_mul_f32 v[4:5], v[4:5], v[186:187]
	v_pk_mul_f32 v[186:187], v[192:193], v[194:195]
	v_add_f32_e32 v3, v157, v200
	v_pk_mul_f32 v[60:61], v[60:61], v[186:187]
	v_add_f32_e32 v186, v153, v197
	v_mul_f32_e32 v186, 0xbfb8aa3b, v186
	v_exp_f32_e32 v186, v186
	v_mul_f32_e32 v3, 0xbfb8aa3b, v3
	v_exp_f32_e32 v197, v3
	v_mul_f32_e32 v189, 0xbfb8aa3b, v189
	v_add_f32_e32 v3, 1.0, v186
	v_rcp_f32_e32 v199, v3
	s_waitcnt vmcnt(3)
; __device__ __forceinline__ void unpack8(const u32x4 w, float (&v)[8]) { v[0] = bf_lo(w.x); v[1] = bf_hi(w.x); v[2] = bf_lo(w.y); v[3] = bf_hi(w.y); v[4] = bf_lo(w.z); v[5] = bf_hi(w.z); v[6] = bf_lo(w.w); v[7] = bf_hi(w.w); }
;     __device__ __forceinline__ void after(int te, f32x4 (&acc)[2][2][4][2], const Unit& u, int wr, int wc, int fr, int fq) const {
;     ...
;                 const f32x4 s0 = *(const f32x4*)(gb + c), s1 = *(const f32x4*)(gb + c + 4), a0 = *(const f32x4*)(gb + D_MODEL + c), a1 = *(const f32x4*)(gb + D_MODEL + c + 4);
; #pragma unroll
;                 for (int ai = 0; ai < 2; ++ai) {
;                     u32x4 gs[4], ga[4];
; #pragma unroll
;                     for (int m = 0; m < 4; ++m) { const size_t r = (size_t)(row0 + ai * HALF + m * 16); gs[m] = *(const u32x4*)(proj + r * LDP + PGS + c); ga[m] = *(const u32x4*)(proj + r * LDP + PGA + c); }
; #pragma unroll
;                     for (int m = 0; m < 4; ++m) { float vs[8], va[8]; unpack8(gs[m], vs); unpack8(ga[m], va);
; #pragma unroll
;                         for (int e = 0; e < 4; ++e) {
;                             acc[ai][bj][m][0][e] *= (1.f + __expf(-(va[e] + a0[e]))) * __builtin_amdgcn_rcpf(1.f + __expf(-(vs[e] + s0[e])));
;                             acc[ai][bj][m][1][e] *= (1.f + __expf(-(va[4 + e] + a1[e]))) * __builtin_amdgcn_rcpf(1.f + __expf(-(vs[4 + e] + s1[e]))); } }
	v_lshlrev_b32_e32 v3, 16, v146
	v_add_f32_e32 v3, v158, v3
	v_exp_f32_e32 v189, v189
	v_mul_f32_e32 v3, 0xbfb8aa3b, v3
	v_exp_f32_e32 v3, v3
	v_pk_mul_f32 v[58:59], v[58:59], v[4:5]
	v_pk_add_f32 v[4:5], v[196:197], 1.0 op_sel_hi:[1,0]
	v_pk_add_f32 v[186:187], v[188:189], 1.0 op_sel_hi:[1,0]
	v_pk_mul_f32 v[4:5], v[4:5], v[198:199]
	v_pk_mul_f32 v[186:187], v[186:187], v[190:191]
	v_pk_mul_f32 v[56:57], v[56:57], v[4:5]
	v_and_b32_e32 v5, 0xffff0000, v146
	v_lshlrev_b32_e32 v146, 16, v148
	v_add_f32_e32 v3, 1.0, v3
	v_pk_mul_f32 v[54:55], v[54:55], v[186:187]
	v_lshlrev_b32_e32 v186, 16, v147
	v_and_b32_e32 v187, 0xffff0000, v147
	v_and_b32_e32 v147, 0xffff0000, v148
	s_waitcnt vmcnt(2)
	v_lshlrev_b32_e32 v4, 16, v142
	v_and_b32_e32 v148, 0xffff0000, v142
	v_rcp_f32_e32 v142, v3
	v_add_f32_e32 v3, v150, v146
	v_mul_f32_e32 v3, 0xbfb8aa3b, v3
	v_exp_f32_e32 v3, v3
	v_lshlrev_b32_e32 v188, 16, v149
	v_and_b32_e32 v189, 0xffff0000, v149
	v_lshlrev_b32_e32 v149, 16, v143
	v_add_f32_e32 v3, 1.0, v3
	v_rcp_f32_e32 v146, v3
	v_add_f32_e32 v3, v159, v5
	v_mul_f32_e32 v3, 0xbfb8aa3b, v3
	v_exp_f32_e32 v3, v3
	v_and_b32_e32 v190, 0xffff0000, v143
	v_lshlrev_b32_e32 v143, 16, v144
	v_add_f32_e32 v143, v154, v143
	v_mul_f32_e32 v143, 0xbfb8aa3b, v143
	v_add_f32_e32 v3, 1.0, v3
	v_and_b32_e32 v191, 0xffff0000, v144
	v_exp_f32_e32 v144, v143
	v_rcp_f32_e32 v143, v3
	v_add_f32_e32 v3, v151, v147
	v_mul_f32_e32 v3, 0xbfb8aa3b, v3
	v_exp_f32_e32 v3, v3
	v_add_f32_e32 v187, v161, v187
	v_lshlrev_b32_e32 v192, 16, v145
	v_mul_f32_e32 v187, 0xbfb8aa3b, v187
	v_add_f32_e32 v3, 1.0, v3
	v_rcp_f32_e32 v147, v3
	v_add_f32_e32 v3, v160, v186
	v_mul_f32_e32 v3, 0xbfb8aa3b, v3
	v_exp_f32_e32 v3, v3
	v_add_f32_e32 v5, v163, v148
	v_add_f32_e32 v148, v164, v149
	v_add_f32_e32 v149, v156, v192
	v_add_f32_e32 v3, 1.0, v3
	v_rcp_f32_e32 v186, v3
	v_add_f32_e32 v3, v152, v188
	v_mul_f32_e32 v3, 0xbfb8aa3b, v3
	v_exp_f32_e32 v3, v3
	v_exp_f32_e32 v187, v187
	v_mul_f32_e32 v149, 0xbfb8aa3b, v149
	v_add_f32_e32 v4, v162, v4
	v_exp_f32_e32 v188, v149
	v_add_f32_e32 v149, v165, v190
	v_mul_f32_e32 v4, 0xbfb8aa3b, v4
	v_mul_f32_e32 v5, 0xbfb8aa3b, v5
	v_mul_f32_e32 v148, 0xbfb8aa3b, v148
	v_add_f32_e32 v3, 1.0, v3
	v_mul_f32_e32 v149, 0xbfb8aa3b, v149
	v_exp_f32_e32 v4, v4
	v_exp_f32_e32 v5, v5
	v_exp_f32_e32 v148, v148
	v_exp_f32_e32 v149, v149
	v_rcp_f32_e32 v190, v3
	v_add_f32_e32 v3, 1.0, v187
	v_rcp_f32_e32 v187, v3
	v_pk_add_f32 v[148:149], v[148:149], 1.0 op_sel_hi:[1,0]
	v_pk_add_f32 v[4:5], v[4:5], 1.0 op_sel_hi:[1,0]
	v_and_b32_e32 v193, 0xffff0000, v145
	v_pk_mul_f32 v[4:5], v[4:5], v[142:143]
	v_pk_mul_f32 v[142:143], v[148:149], v[186:187]
	v_add_f32_e32 v3, v157, v193
	v_pk_mul_f32 v[52:53], v[52:53], v[142:143]
	v_add_f32_e32 v142, v153, v189
	v_mul_f32_e32 v142, 0xbfb8aa3b, v142
	v_mul_f32_e32 v3, 0xbfb8aa3b, v3
	v_exp_f32_e32 v142, v142
	v_exp_f32_e32 v189, v3
	v_pk_mul_f32 v[50:51], v[50:51], v[4:5]
	v_add_f32_e32 v3, 1.0, v142
	v_pk_add_f32 v[4:5], v[188:189], 1.0 op_sel_hi:[1,0]
	global_load_dwordx4 v[186:189], v[218:219], off offset:256
	v_add_f32_e32 v145, v155, v191
	v_rcp_f32_e32 v191, v3
	s_waitcnt vmcnt(2)
	v_lshlrev_b32_e32 v3, 16, v130
	v_mul_f32_e32 v145, 0xbfb8aa3b, v145
	v_add_f32_e32 v3, v158, v3
	v_exp_f32_e32 v145, v145
	v_mul_f32_e32 v3, 0xbfb8aa3b, v3
	v_exp_f32_e32 v3, v3
	v_pk_mul_f32 v[4:5], v[4:5], v[190:191]
	v_pk_add_f32 v[142:143], v[144:145], 1.0 op_sel_hi:[1,0]
	v_pk_mul_f32 v[48:49], v[48:49], v[4:5]
	v_pk_mul_f32 v[142:143], v[142:143], v[146:147]
	v_and_b32_e32 v5, 0xffff0000, v130
	v_lshlrev_b32_e32 v130, 16, v132
	v_add_f32_e32 v3, 1.0, v3
	v_pk_mul_f32 v[46:47], v[46:47], v[142:143]
	v_lshlrev_b32_e32 v142, 16, v131
	v_and_b32_e32 v143, 0xffff0000, v131
	v_and_b32_e32 v131, 0xffff0000, v132
	s_waitcnt vmcnt(1)
	v_lshlrev_b32_e32 v4, 16, v126
	v_and_b32_e32 v132, 0xffff0000, v126
	v_rcp_f32_e32 v126, v3
	v_add_f32_e32 v3, v150, v130
	v_mul_f32_e32 v3, 0xbfb8aa3b, v3
	v_exp_f32_e32 v3, v3
	global_load_dwordx4 v[190:193], v[216:217], off offset:256
	v_lshlrev_b32_e32 v144, 16, v133
	v_and_b32_e32 v145, 0xffff0000, v133
	v_add_f32_e32 v3, 1.0, v3
	v_rcp_f32_e32 v130, v3
	v_add_f32_e32 v3, v159, v5
	v_mul_f32_e32 v3, 0xbfb8aa3b, v3
	v_exp_f32_e32 v3, v3
	v_lshlrev_b32_e32 v133, 16, v127
	v_and_b32_e32 v146, 0xffff0000, v127
	v_lshlrev_b32_e32 v127, 16, v128
	v_add_f32_e32 v127, v154, v127
	v_mul_f32_e32 v127, 0xbfb8aa3b, v127
	v_add_f32_e32 v3, 1.0, v3
	v_and_b32_e32 v147, 0xffff0000, v128
	v_exp_f32_e32 v128, v127
	v_rcp_f32_e32 v127, v3
	v_add_f32_e32 v3, v151, v131
	v_mul_f32_e32 v3, 0xbfb8aa3b, v3
	v_exp_f32_e32 v3, v3
	v_add_f32_e32 v143, v161, v143
	v_lshlrev_b32_e32 v148, 16, v129
	v_mul_f32_e32 v143, 0xbfb8aa3b, v143
	v_add_f32_e32 v3, 1.0, v3
	v_rcp_f32_e32 v131, v3
	v_add_f32_e32 v3, v160, v142
	v_mul_f32_e32 v3, 0xbfb8aa3b, v3
	v_exp_f32_e32 v3, v3
	v_add_f32_e32 v5, v163, v132
	v_add_f32_e32 v132, v164, v133
	v_add_f32_e32 v133, v156, v148
	v_add_f32_e32 v3, 1.0, v3
	v_rcp_f32_e32 v142, v3
	v_add_f32_e32 v3, v152, v144
	v_mul_f32_e32 v3, 0xbfb8aa3b, v3
	v_exp_f32_e32 v3, v3
	v_exp_f32_e32 v143, v143
	v_mul_f32_e32 v133, 0xbfb8aa3b, v133
	v_add_f32_e32 v4, v162, v4
	v_exp_f32_e32 v144, v133
	v_add_f32_e32 v133, v165, v146
	v_mul_f32_e32 v4, 0xbfb8aa3b, v4
	v_mul_f32_e32 v5, 0xbfb8aa3b, v5
	v_mul_f32_e32 v132, 0xbfb8aa3b, v132
	v_add_f32_e32 v3, 1.0, v3
	v_mul_f32_e32 v133, 0xbfb8aa3b, v133
	v_exp_f32_e32 v4, v4
	v_exp_f32_e32 v5, v5
	v_exp_f32_e32 v132, v132
	v_exp_f32_e32 v133, v133
	v_rcp_f32_e32 v146, v3
	v_add_f32_e32 v3, 1.0, v143
	v_rcp_f32_e32 v143, v3
	v_pk_add_f32 v[132:133], v[132:133], 1.0 op_sel_hi:[1,0]
	v_pk_add_f32 v[4:5], v[4:5], 1.0 op_sel_hi:[1,0]
	v_and_b32_e32 v149, 0xffff0000, v129
	v_pk_mul_f32 v[4:5], v[4:5], v[126:127]
	v_pk_mul_f32 v[126:127], v[132:133], v[142:143]
	v_add_f32_e32 v129, v155, v147
	v_pk_mul_f32 v[44:45], v[44:45], v[126:127]
	v_add_f32_e32 v126, v153, v145
	v_mul_f32_e32 v126, 0xbfb8aa3b, v126
	v_exp_f32_e32 v126, v126
	v_mul_f32_e32 v129, 0xbfb8aa3b, v129
	v_add_f32_e32 v3, v157, v149
	v_exp_f32_e32 v129, v129
	v_mul_f32_e32 v3, 0xbfb8aa3b, v3
	v_exp_f32_e32 v145, v3
	v_add_f32_e32 v3, 1.0, v126
	v_rcp_f32_e32 v147, v3
	v_pk_add_f32 v[126:127], v[128:129], 1.0 op_sel_hi:[1,0]
	v_pk_mul_f32 v[42:43], v[42:43], v[4:5]
	v_pk_add_f32 v[4:5], v[144:145], 1.0 op_sel_hi:[1,0]
	v_pk_mul_f32 v[126:127], v[126:127], v[130:131]
	v_pk_mul_f32 v[4:5], v[4:5], v[146:147]
	v_pk_mul_f32 v[38:39], v[38:39], v[126:127]
	global_load_dwordx4 v[194:197], v[204:205], off offset:256
	global_load_dwordx4 v[198:201], v[206:207], off offset:256
	global_load_dwordx4 v[146:149], v[208:209], off offset:256
	global_load_dwordx4 v[142:145], v[210:211], off offset:256
	global_load_dwordx4 v[130:133], v[212:213], off offset:256
	global_load_dwordx4 v[126:129], v[214:215], off offset:256
	s_waitcnt vmcnt(7)
; __device__ __forceinline__ void unpack8(const u32x4 w, float (&v)[8]) { v[0] = bf_lo(w.x); v[1] = bf_hi(w.x); v[2] = bf_lo(w.y); v[3] = bf_hi(w.y); v[4] = bf_lo(w.z); v[5] = bf_hi(w.z); v[6] = bf_lo(w.w); v[7] = bf_hi(w.w); }
;     __device__ __forceinline__ void after(int te, f32x4 (&acc)[2][2][4][2], const Unit& u, int wr, int wc, int fr, int fq) const {
;     ...
;                 const f32x4 s0 = *(const f32x4*)(gb + c), s1 = *(const f32x4*)(gb + c + 4), a0 = *(const f32x4*)(gb + D_MODEL + c), a1 = *(const f32x4*)(gb + D_MODEL + c + 4);
; #pragma unroll
;                 for (int ai = 0; ai < 2; ++ai) {
;                     u32x4 gs[4], ga[4];
; #pragma unroll
;                     for (int m = 0; m < 4; ++m) { const size_t r = (size_t)(row0 + ai * HALF + m * 16); gs[m] = *(const u32x4*)(proj + r * LDP + PGS + c); ga[m] = *(const u32x4*)(proj + r * LDP + PGA + c); }
; #pragma unroll
;                     for (int m = 0; m < 4; ++m) { float vs[8], va[8]; unpack8(gs[m], vs); unpack8(ga[m], va);
; #pragma unroll
;                         for (int e = 0; e < 4; ++e) {
;                             acc[ai][bj][m][0][e] *= (1.f + __expf(-(va[e] + a0[e]))) * __builtin_amdgcn_rcpf(1.f + __expf(-(vs[e] + s0[e])));
;                             acc[ai][bj][m][1][e] *= (1.f + __expf(-(va[4 + e] + a1[e]))) * __builtin_amdgcn_rcpf(1.f + __expf(-(vs[4 + e] + s1[e]))); } }
	v_lshlrev_b32_e32 v3, 16, v186
	v_add_f32_e32 v3, v158, v3
	v_mul_f32_e32 v3, 0xbfb8aa3b, v3
	v_exp_f32_e32 v3, v3
	v_lshlrev_b32_e32 v202, 16, v187
	v_and_b32_e32 v203, 0xffff0000, v187
	v_lshlrev_b32_e32 v187, 16, v188
	v_add_f32_e32 v3, 1.0, v3
	v_pk_mul_f32 v[40:41], v[40:41], v[4:5]
	v_and_b32_e32 v5, 0xffff0000, v186
	v_rcp_f32_e32 v186, v3
	v_add_f32_e32 v3, v150, v187
	v_mul_f32_e32 v3, 0xbfb8aa3b, v3
	v_exp_f32_e32 v3, v3
	v_lshlrev_b32_e32 v205, 16, v189
	v_and_b32_e32 v207, 0xffff0000, v189
	s_waitcnt vmcnt(6)
	v_lshlrev_b32_e32 v4, 16, v190
	v_add_f32_e32 v3, 1.0, v3
	v_and_b32_e32 v189, 0xffff0000, v190
	v_rcp_f32_e32 v190, v3
	v_add_f32_e32 v3, v159, v5
	v_mul_f32_e32 v3, 0xbfb8aa3b, v3
	v_exp_f32_e32 v3, v3
	v_and_b32_e32 v204, 0xffff0000, v188
	v_lshlrev_b32_e32 v188, 16, v192
	v_add_f32_e32 v187, v154, v188
	v_mul_f32_e32 v187, 0xbfb8aa3b, v187
	v_add_f32_e32 v3, 1.0, v3
	v_exp_f32_e32 v188, v187
	v_rcp_f32_e32 v187, v3
	v_add_f32_e32 v3, v151, v204
	v_mul_f32_e32 v3, 0xbfb8aa3b, v3
	v_exp_f32_e32 v3, v3
	v_lshlrev_b32_e32 v206, 16, v191
	v_and_b32_e32 v208, 0xffff0000, v191
	v_and_b32_e32 v191, 0xffff0000, v192
	v_add_f32_e32 v3, 1.0, v3
	v_add_f32_e32 v5, v163, v189
	v_add_f32_e32 v189, v155, v191
	v_rcp_f32_e32 v191, v3
	v_add_f32_e32 v3, v160, v202
	v_mul_f32_e32 v3, 0xbfb8aa3b, v3
	v_exp_f32_e32 v3, v3
	v_add_f32_e32 v203, v161, v203
	v_lshlrev_b32_e32 v209, 16, v193
	v_mul_f32_e32 v203, 0xbfb8aa3b, v203
	v_add_f32_e32 v3, 1.0, v3
	v_rcp_f32_e32 v202, v3
	v_add_f32_e32 v3, v152, v205
	v_mul_f32_e32 v3, 0xbfb8aa3b, v3
	v_exp_f32_e32 v3, v3
	v_and_b32_e32 v210, 0xffff0000, v193
	v_add_f32_e32 v193, v156, v209
	v_exp_f32_e32 v203, v203
	v_mul_f32_e32 v193, 0xbfb8aa3b, v193
	v_add_f32_e32 v4, v162, v4
	v_add_f32_e32 v192, v164, v206
	v_exp_f32_e32 v204, v193
	v_add_f32_e32 v193, v165, v208
	v_mul_f32_e32 v4, 0xbfb8aa3b, v4
	v_mul_f32_e32 v5, 0xbfb8aa3b, v5
	v_mul_f32_e32 v192, 0xbfb8aa3b, v192
	v_add_f32_e32 v3, 1.0, v3
	v_mul_f32_e32 v193, 0xbfb8aa3b, v193
	v_exp_f32_e32 v4, v4
	v_exp_f32_e32 v5, v5
	v_exp_f32_e32 v192, v192
	v_exp_f32_e32 v193, v193
	v_rcp_f32_e32 v206, v3
	v_add_f32_e32 v3, 1.0, v203
	v_rcp_f32_e32 v203, v3
	v_pk_add_f32 v[192:193], v[192:193], 1.0 op_sel_hi:[1,0]
	v_pk_add_f32 v[4:5], v[4:5], 1.0 op_sel_hi:[1,0]
	v_add_f32_e32 v3, v157, v210
	v_pk_mul_f32 v[4:5], v[4:5], v[186:187]
	v_pk_mul_f32 v[186:187], v[192:193], v[202:203]
	v_mul_f32_e32 v3, 0xbfb8aa3b, v3
	v_pk_mul_f32 v[36:37], v[36:37], v[186:187]
	v_add_f32_e32 v186, v153, v207
	v_mul_f32_e32 v186, 0xbfb8aa3b, v186
	v_exp_f32_e32 v186, v186
	v_exp_f32_e32 v205, v3
	v_mul_f32_e32 v189, 0xbfb8aa3b, v189
	v_exp_f32_e32 v189, v189
	v_add_f32_e32 v3, 1.0, v186
	v_rcp_f32_e32 v207, v3
	s_waitcnt vmcnt(5)
	v_lshlrev_b32_e32 v3, 16, v194
	v_add_f32_e32 v3, v158, v3
	v_mul_f32_e32 v3, 0xbfb8aa3b, v3
	v_exp_f32_e32 v3, v3
	v_pk_add_f32 v[186:187], v[188:189], 1.0 op_sel_hi:[1,0]
	v_pk_mul_f32 v[34:35], v[34:35], v[4:5]
	v_pk_mul_f32 v[186:187], v[186:187], v[190:191]
	v_add_f32_e32 v3, 1.0, v3
	v_pk_mul_f32 v[30:31], v[30:31], v[186:187]
	v_lshlrev_b32_e32 v187, 16, v196
	v_rcp_f32_e32 v186, v3
	v_add_f32_e32 v3, v150, v187
	v_mul_f32_e32 v3, 0xbfb8aa3b, v3
	v_exp_f32_e32 v3, v3
	v_pk_add_f32 v[4:5], v[204:205], 1.0 op_sel_hi:[1,0]
	s_waitcnt vmcnt(4)
	v_lshlrev_b32_e32 v188, 16, v200
	v_pk_mul_f32 v[4:5], v[4:5], v[206:207]
	v_add_f32_e32 v3, 1.0, v3
	v_pk_mul_f32 v[32:33], v[32:33], v[4:5]
	v_and_b32_e32 v5, 0xffff0000, v194
	v_rcp_f32_e32 v190, v3
	v_add_f32_e32 v3, v159, v5
	v_mul_f32_e32 v3, 0xbfb8aa3b, v3
	v_exp_f32_e32 v3, v3
	v_add_f32_e32 v187, v154, v188
	v_and_b32_e32 v189, 0xffff0000, v196
	v_mul_f32_e32 v187, 0xbfb8aa3b, v187
	v_add_f32_e32 v3, 1.0, v3
	v_exp_f32_e32 v188, v187
	v_rcp_f32_e32 v187, v3
	v_add_f32_e32 v3, v151, v189
	v_mul_f32_e32 v3, 0xbfb8aa3b, v3
	v_exp_f32_e32 v3, v3
	v_lshlrev_b32_e32 v192, 16, v195
	v_and_b32_e32 v191, 0xffff0000, v198
	v_add_f32_e32 v5, v163, v191
	v_add_f32_e32 v3, 1.0, v3
	v_rcp_f32_e32 v191, v3
	v_add_f32_e32 v3, v160, v192
	v_mul_f32_e32 v3, 0xbfb8aa3b, v3
	v_exp_f32_e32 v3, v3
	v_and_b32_e32 v193, 0xffff0000, v195
	v_lshlrev_b32_e32 v195, 16, v197
	v_lshlrev_b32_e32 v194, 16, v199
	v_add_f32_e32 v3, 1.0, v3
	v_add_f32_e32 v192, v164, v194
	v_rcp_f32_e32 v194, v3
	v_add_f32_e32 v3, v152, v195
	v_mul_f32_e32 v3, 0xbfb8aa3b, v3
	v_add_f32_e32 v193, v161, v193
	v_lshlrev_b32_e32 v4, 16, v198
	v_and_b32_e32 v198, 0xffff0000, v199
	v_lshlrev_b32_e32 v199, 16, v201
	v_exp_f32_e32 v3, v3
	v_mul_f32_e32 v193, 0xbfb8aa3b, v193
	v_add_f32_e32 v195, v156, v199
	v_exp_f32_e32 v199, v193
	v_and_b32_e32 v196, 0xffff0000, v200
	v_mul_f32_e32 v195, 0xbfb8aa3b, v195
	v_add_f32_e32 v4, v162, v4
	v_add_f32_e32 v189, v155, v196
	v_exp_f32_e32 v196, v195
	v_add_f32_e32 v195, v165, v198
	v_mul_f32_e32 v4, 0xbfb8aa3b, v4
	v_mul_f32_e32 v5, 0xbfb8aa3b, v5
	v_mul_f32_e32 v192, 0xbfb8aa3b, v192
	v_add_f32_e32 v3, 1.0, v3
	v_mul_f32_e32 v193, 0xbfb8aa3b, v195
	v_exp_f32_e32 v4, v4
	v_exp_f32_e32 v5, v5
	v_exp_f32_e32 v192, v192
	v_exp_f32_e32 v193, v193
	v_rcp_f32_e32 v198, v3
	v_add_f32_e32 v3, 1.0, v199
	v_rcp_f32_e32 v195, v3
	v_pk_add_f32 v[192:193], v[192:193], 1.0 op_sel_hi:[1,0]
	v_pk_add_f32 v[4:5], v[4:5], 1.0 op_sel_hi:[1,0]
	v_and_b32_e32 v197, 0xffff0000, v197
	v_pk_mul_f32 v[4:5], v[4:5], v[186:187]
	v_pk_mul_f32 v[186:187], v[192:193], v[194:195]
	v_and_b32_e32 v200, 0xffff0000, v201
	v_pk_mul_f32 v[28:29], v[28:29], v[186:187]
	v_add_f32_e32 v186, v153, v197
	v_mul_f32_e32 v186, 0xbfb8aa3b, v186
	v_exp_f32_e32 v186, v186
	v_add_f32_e32 v3, v157, v200
	v_mul_f32_e32 v3, 0xbfb8aa3b, v3
	v_exp_f32_e32 v197, v3
	v_add_f32_e32 v3, 1.0, v186
	v_rcp_f32_e32 v199, v3
	s_waitcnt vmcnt(3)
; __device__ __forceinline__ void unpack8(const u32x4 w, float (&v)[8]) { v[0] = bf_lo(w.x); v[1] = bf_hi(w.x); v[2] = bf_lo(w.y); v[3] = bf_hi(w.y); v[4] = bf_lo(w.z); v[5] = bf_hi(w.z); v[6] = bf_lo(w.w); v[7] = bf_hi(w.w); }
;     __device__ __forceinline__ void after(int te, f32x4 (&acc)[2][2][4][2], const Unit& u, int wr, int wc, int fr, int fq) const {
;     ...
;                 const f32x4 s0 = *(const f32x4*)(gb + c), s1 = *(const f32x4*)(gb + c + 4), a0 = *(const f32x4*)(gb + D_MODEL + c), a1 = *(const f32x4*)(gb + D_MODEL + c + 4);
; #pragma unroll
;                 for (int ai = 0; ai < 2; ++ai) {
;                     u32x4 gs[4], ga[4];
; #pragma unroll
;                     for (int m = 0; m < 4; ++m) { const size_t r = (size_t)(row0 + ai * HALF + m * 16); gs[m] = *(const u32x4*)(proj + r * LDP + PGS + c); ga[m] = *(const u32x4*)(proj + r * LDP + PGA + c); }
; #pragma unroll
;                     for (int m = 0; m < 4; ++m) { float vs[8], va[8]; unpack8(gs[m], vs); unpack8(ga[m], va);
; #pragma unroll
;                         for (int e = 0; e < 4; ++e) {
;                             acc[ai][bj][m][0][e] *= (1.f + __expf(-(va[e] + a0[e]))) * __builtin_amdgcn_rcpf(1.f + __expf(-(vs[e] + s0[e])));
;                             acc[ai][bj][m][1][e] *= (1.f + __expf(-(va[4 + e] + a1[e]))) * __builtin_amdgcn_rcpf(1.f + __expf(-(vs[4 + e] + s1[e]))); } }
	v_lshlrev_b32_e32 v3, 16, v146
	v_mul_f32_e32 v189, 0xbfb8aa3b, v189
	v_add_f32_e32 v3, v158, v3
	v_exp_f32_e32 v189, v189
	v_mul_f32_e32 v3, 0xbfb8aa3b, v3
	v_exp_f32_e32 v3, v3
	v_pk_mul_f32 v[26:27], v[26:27], v[4:5]
	v_pk_add_f32 v[4:5], v[196:197], 1.0 op_sel_hi:[1,0]
	v_pk_add_f32 v[186:187], v[188:189], 1.0 op_sel_hi:[1,0]
	v_pk_mul_f32 v[4:5], v[4:5], v[198:199]
	v_pk_mul_f32 v[186:187], v[186:187], v[190:191]
	v_pk_mul_f32 v[24:25], v[24:25], v[4:5]
	v_and_b32_e32 v5, 0xffff0000, v146
	v_lshlrev_b32_e32 v146, 16, v148
	v_add_f32_e32 v3, 1.0, v3
	v_pk_mul_f32 v[22:23], v[22:23], v[186:187]
	v_lshlrev_b32_e32 v186, 16, v147
	v_and_b32_e32 v187, 0xffff0000, v147
	v_and_b32_e32 v147, 0xffff0000, v148
	s_waitcnt vmcnt(2)
	v_lshlrev_b32_e32 v4, 16, v142
	v_and_b32_e32 v148, 0xffff0000, v142
	v_rcp_f32_e32 v142, v3
	v_add_f32_e32 v3, v150, v146
	v_mul_f32_e32 v3, 0xbfb8aa3b, v3
	v_exp_f32_e32 v3, v3
	v_lshlrev_b32_e32 v188, 16, v149
	v_and_b32_e32 v189, 0xffff0000, v149
	v_lshlrev_b32_e32 v149, 16, v143
	v_add_f32_e32 v3, 1.0, v3
	v_rcp_f32_e32 v146, v3
	v_add_f32_e32 v3, v159, v5
	v_mul_f32_e32 v3, 0xbfb8aa3b, v3
	v_exp_f32_e32 v3, v3
	v_and_b32_e32 v190, 0xffff0000, v143
	v_lshlrev_b32_e32 v143, 16, v144
	v_add_f32_e32 v143, v154, v143
	v_mul_f32_e32 v143, 0xbfb8aa3b, v143
	v_add_f32_e32 v3, 1.0, v3
	v_and_b32_e32 v191, 0xffff0000, v144
	v_exp_f32_e32 v144, v143
	v_rcp_f32_e32 v143, v3
	v_add_f32_e32 v3, v151, v147
	v_mul_f32_e32 v3, 0xbfb8aa3b, v3
	v_exp_f32_e32 v3, v3
	v_add_f32_e32 v187, v161, v187
	v_lshlrev_b32_e32 v192, 16, v145
	v_mul_f32_e32 v187, 0xbfb8aa3b, v187
	v_add_f32_e32 v3, 1.0, v3
	v_rcp_f32_e32 v147, v3
	v_add_f32_e32 v3, v160, v186
	v_mul_f32_e32 v3, 0xbfb8aa3b, v3
	v_exp_f32_e32 v3, v3
	v_add_f32_e32 v5, v163, v148
	v_add_f32_e32 v148, v164, v149
	v_add_f32_e32 v149, v156, v192
	v_add_f32_e32 v3, 1.0, v3
	v_rcp_f32_e32 v186, v3
	v_add_f32_e32 v3, v152, v188
	v_mul_f32_e32 v3, 0xbfb8aa3b, v3
	v_exp_f32_e32 v3, v3
	v_exp_f32_e32 v187, v187
	v_mul_f32_e32 v149, 0xbfb8aa3b, v149
	v_add_f32_e32 v4, v162, v4
	v_exp_f32_e32 v188, v149
	v_add_f32_e32 v149, v165, v190
	v_mul_f32_e32 v4, 0xbfb8aa3b, v4
	v_mul_f32_e32 v5, 0xbfb8aa3b, v5
	v_mul_f32_e32 v148, 0xbfb8aa3b, v148
	v_add_f32_e32 v3, 1.0, v3
	v_mul_f32_e32 v149, 0xbfb8aa3b, v149
	v_exp_f32_e32 v4, v4
	v_exp_f32_e32 v5, v5
	v_exp_f32_e32 v148, v148
	v_exp_f32_e32 v149, v149
	v_rcp_f32_e32 v190, v3
	v_add_f32_e32 v3, 1.0, v187
	v_rcp_f32_e32 v187, v3
	v_pk_add_f32 v[148:149], v[148:149], 1.0 op_sel_hi:[1,0]
	v_pk_add_f32 v[4:5], v[4:5], 1.0 op_sel_hi:[1,0]
	v_and_b32_e32 v193, 0xffff0000, v145
	v_pk_mul_f32 v[4:5], v[4:5], v[142:143]
	v_pk_mul_f32 v[142:143], v[148:149], v[186:187]
	v_add_f32_e32 v3, v157, v193
	v_pk_mul_f32 v[20:21], v[20:21], v[142:143]
	v_add_f32_e32 v142, v153, v189
	v_mul_f32_e32 v142, 0xbfb8aa3b, v142
	v_exp_f32_e32 v142, v142
	v_mul_f32_e32 v3, 0xbfb8aa3b, v3
	v_exp_f32_e32 v189, v3
	v_add_f32_e32 v145, v155, v191
	v_add_f32_e32 v3, 1.0, v142
	v_rcp_f32_e32 v191, v3
	s_waitcnt vmcnt(1)
	v_lshlrev_b32_e32 v3, 16, v130
	v_mul_f32_e32 v145, 0xbfb8aa3b, v145
	v_add_f32_e32 v3, v158, v3
	v_exp_f32_e32 v145, v145
	v_mul_f32_e32 v3, 0xbfb8aa3b, v3
	v_exp_f32_e32 v3, v3
	v_pk_mul_f32 v[18:19], v[18:19], v[4:5]
	v_pk_add_f32 v[4:5], v[188:189], 1.0 op_sel_hi:[1,0]
	v_pk_add_f32 v[142:143], v[144:145], 1.0 op_sel_hi:[1,0]
	v_pk_mul_f32 v[4:5], v[4:5], v[190:191]
	v_pk_mul_f32 v[142:143], v[142:143], v[146:147]
	v_pk_mul_f32 v[16:17], v[16:17], v[4:5]
	v_and_b32_e32 v5, 0xffff0000, v130
	v_lshlrev_b32_e32 v130, 16, v132
	v_add_f32_e32 v3, 1.0, v3
	v_pk_mul_f32 v[14:15], v[14:15], v[142:143]
	v_lshlrev_b32_e32 v142, 16, v131
	v_and_b32_e32 v143, 0xffff0000, v131
	v_and_b32_e32 v131, 0xffff0000, v132
	s_waitcnt vmcnt(0)
	v_lshlrev_b32_e32 v4, 16, v126
	v_and_b32_e32 v132, 0xffff0000, v126
	v_rcp_f32_e32 v126, v3
	v_add_f32_e32 v3, v150, v130
	v_mul_f32_e32 v3, 0xbfb8aa3b, v3
	v_exp_f32_e32 v3, v3
	v_lshlrev_b32_e32 v144, 16, v133
	v_and_b32_e32 v145, 0xffff0000, v133
	v_lshlrev_b32_e32 v133, 16, v127
	v_add_f32_e32 v3, 1.0, v3
	v_rcp_f32_e32 v130, v3
	v_add_f32_e32 v3, v159, v5
	v_mul_f32_e32 v3, 0xbfb8aa3b, v3
	v_exp_f32_e32 v3, v3
	v_and_b32_e32 v146, 0xffff0000, v127
	v_lshlrev_b32_e32 v127, 16, v128
	v_add_f32_e32 v127, v154, v127
	v_mul_f32_e32 v127, 0xbfb8aa3b, v127
	v_add_f32_e32 v3, 1.0, v3
	v_and_b32_e32 v147, 0xffff0000, v128
	v_exp_f32_e32 v128, v127
	v_rcp_f32_e32 v127, v3
	v_add_f32_e32 v3, v151, v131
	v_mul_f32_e32 v3, 0xbfb8aa3b, v3
	v_exp_f32_e32 v3, v3
	v_add_f32_e32 v143, v161, v143
	v_lshlrev_b32_e32 v148, 16, v129
	v_mul_f32_e32 v143, 0xbfb8aa3b, v143
	v_add_f32_e32 v3, 1.0, v3
	v_rcp_f32_e32 v131, v3
	v_add_f32_e32 v3, v160, v142
	v_mul_f32_e32 v3, 0xbfb8aa3b, v3
	v_exp_f32_e32 v3, v3
	v_add_f32_e32 v5, v163, v132
	v_add_f32_e32 v132, v164, v133
	v_add_f32_e32 v133, v156, v148
	v_add_f32_e32 v3, 1.0, v3
	v_rcp_f32_e32 v142, v3
	v_add_f32_e32 v3, v152, v144
	v_mul_f32_e32 v3, 0xbfb8aa3b, v3
	v_exp_f32_e32 v3, v3
	v_exp_f32_e32 v143, v143
	v_mul_f32_e32 v133, 0xbfb8aa3b, v133
	v_add_f32_e32 v4, v162, v4
	v_exp_f32_e32 v144, v133
	v_add_f32_e32 v133, v165, v146
	v_mul_f32_e32 v4, 0xbfb8aa3b, v4
	v_mul_f32_e32 v5, 0xbfb8aa3b, v5
	v_mul_f32_e32 v132, 0xbfb8aa3b, v132
	v_add_f32_e32 v3, 1.0, v3
	v_mul_f32_e32 v133, 0xbfb8aa3b, v133
	v_exp_f32_e32 v4, v4
	v_exp_f32_e32 v5, v5
	v_exp_f32_e32 v132, v132
	v_exp_f32_e32 v133, v133
	v_rcp_f32_e32 v146, v3
	v_add_f32_e32 v3, 1.0, v143
	v_rcp_f32_e32 v143, v3
	v_pk_add_f32 v[132:133], v[132:133], 1.0 op_sel_hi:[1,0]
	v_pk_add_f32 v[4:5], v[4:5], 1.0 op_sel_hi:[1,0]
	v_and_b32_e32 v149, 0xffff0000, v129
	v_pk_mul_f32 v[4:5], v[4:5], v[126:127]
	v_pk_mul_f32 v[126:127], v[132:133], v[142:143]
	v_add_f32_e32 v129, v155, v147
	v_pk_mul_f32 v[12:13], v[12:13], v[126:127]
	v_add_f32_e32 v126, v153, v145
	v_mul_f32_e32 v126, 0xbfb8aa3b, v126
	v_exp_f32_e32 v126, v126
	v_add_f32_e32 v3, v157, v149
	v_mul_f32_e32 v129, 0xbfb8aa3b, v129
	v_mul_f32_e32 v3, 0xbfb8aa3b, v3
	v_exp_f32_e32 v129, v129
	v_exp_f32_e32 v145, v3
	v_add_f32_e32 v3, 1.0, v126
	v_rcp_f32_e32 v147, v3
	v_pk_mul_f32 v[10:11], v[10:11], v[4:5]
	v_pk_add_f32 v[4:5], v[144:145], 1.0 op_sel_hi:[1,0]
	v_pk_add_f32 v[126:127], v[128:129], 1.0 op_sel_hi:[1,0]
	v_pk_mul_f32 v[4:5], v[4:5], v[146:147]
	v_pk_mul_f32 v[126:127], v[126:127], v[130:131]
	v_pk_mul_f32 v[8:9], v[8:9], v[4:5]
	v_pk_mul_f32 v[6:7], v[6:7], v[126:127]

;     __host__ __device__ bool next(int i, Unit& u) const { const bool ok = StaticOrder::next(i >> 1, u); if (i & 1) { u.ka = D_INNER; u.nkt = D_ATT / BK; } else { u.ka = 0; u.nkt = D_INNER / BK; } return ok; }
; #define PG8_BAR __builtin_amdgcn_s_barrier()
; template <class Epi, class Sched, bool ALIGN_EPI, class Hook = NoHook>
; __device__ __forceinline__ void gemm_phase(LAS unsigned char* lds, const Gemm g, const Sched& S, const Epi& E, const Hook& H = Hook()) {
;     ...
;     const int tid = tid_, wid = __builtin_amdgcn_readfirstlane(tid >> 6), lane = tid & 63, wr = wid >> 2, wc = wid & 3, fr = lane & 15, fq = lane >> 4;
;     unsigned voffA[2], voffB[2];
; #pragma unroll
;     for (int i = 0; i < 2; ++i) { int R, C; stage_rc(tid * 16 + i * 8192, R, C); const int Rb = Epi::PERM ? ((R & ~31) + perm32(R & 31)) : R;
;         const int Ra = Epi::APERM ? (8 * (16 * (R >> 6) + (R & 15)) + ((R >> 4) & 3)) : R;
;         voffA[i] = (unsigned)(Ra * g.lda + C) * 2u; voffB[i] = (unsigned)(Rb * g.ldb + C) * 2u; }
;     const size_t kstep = (size_t)(BK * 2);
;     const size_t hA = (size_t)(Epi::APERM ? 4 : HALF) * g.lda * 2, hB = (size_t)HALF * g.ldb * 2;
;     const size_t tA = (size_t)BM * g.lda * 2;
;     const unsigned ldsw = (unsigned)wid * 1024u;
;     const int aoff = lds_byte(wr * 64 + fr, fq * 8), boff = lds_byte(wc * 32 + fr, fq * 8);
;     ...
;     Unit cur, nxt; int ui = 0;
;     if (!S.next(0, cur)) return;
;     f32x4 acc[2][2][4][2];
; #pragma unroll
;     for (int a = 0; a < 2; ++a)
; #pragma unroll
;         for (int b = 0; b < 2; ++b)
; #pragma unroll
;             for (int m = 0; m < 4; ++m)
; #pragma unroll
;                 for (int n = 0; n < 2; ++n) acc[a][b][m][n] = (f32x4){0.f, 0.f, 0.f, 0.f};
;     bf16x8 At[4][2], B0[2][2], B1[2][2];
;     const char* cA = (const char*)g.A + (size_t)cur.pm * tA + (size_t)cur.ka * 2; const char* cB = (const char*)g.Bt + (size_t)cur.pn * 2 * hB + (size_t)cur.ka * 2;
;     S.a_ready(cur);
;     if constexpr (Hook::ON) H.unit_start(cur);
;     PG8_STAGE(PG8_SB(0, 0), cB, voffB); PG8_STAGE(PG8_SB(0, 1), cB + hB, voffB); PG8_STAGE(PG8_SA(0, 0), cA, voffA); PG8_STAGE(PG8_SA(0, 1), cA + hA, voffA);
;     if (wr == 1) PG8_BAR;
;     PG8_WAIT_V(2); PG8_BAR;
;     PG8_STAGE(PG8_SB(1, 0), cB + kstep, voffB); PG8_STAGE(PG8_SA(1, 0), cA + kstep, voffA); PG8_STAGE(PG8_SB(1, 1), cB + hB + kstep, voffB);
;     PG8_WAIT_V(6); PG8_BAR;
.LBB0_849:
	v_and_b32_e32 v181, 15, v180
	v_and_b32_e32 v15, 48, v180
	v_lshlrev_b32_e32 v16, 2, v180
	s_and_b32 s27, s24, 3
	s_lshl_b32 s4, s25, 13
	v_lshl_or_b32 v15, v181, 6, v15
	v_and_b32_e32 v16, 32, v16
	v_bitop3_b32 v17, v15, s4, v16 bitop3:0xde
	s_lshl_b32 s4, s27, 12
	v_bitop3_b32 v15, v15, s4, v16 bitop3:0xde
	s_mov_b64 s[4:5], 0x80
	s_add_i32 m0, s28, 0x18000
	v_lshl_add_u64 v[8:9], v[8:9], 0, s[4:5]
	s_waitcnt vmcnt(2)
	s_barrier
	global_load_lds_dwordx4 v[8:9], off
	v_lshl_add_u64 v[6:7], v[6:7], 0, s[4:5]
	s_add_i32 m0, s28, 0x1a000
	s_add_i32 s40, s28, 0x8000
	s_add_i32 s41, s28, 0xa000
	global_load_lds_dwordx4 v[6:7], off
	v_lshl_add_u64 v[4:5], v[4:5], 0, s[4:5]
	s_mov_b32 m0, s40
	s_add_u32 s18, s14, 0x100080
	global_load_lds_dwordx4 v[4:5], off
	v_lshl_add_u64 v[2:3], v[2:3], 0, s[4:5]
	s_mov_b32 m0, s41
	s_addc_u32 s19, s15, 0
	global_load_lds_dwordx4 v[2:3], off
	s_add_i32 m0, s28, 0x1c000
	v_lshl_add_u64 v[2:3], s[18:19], 0, v[132:133]
	global_load_lds_dwordx4 v[2:3], off
	v_lshl_add_u64 v[2:3], s[18:19], 0, v[136:137]
	s_add_i32 m0, s28, 0x1e000
	s_lshl_b32 s6, s88, 22
	global_load_lds_dwordx4 v[2:3], off
	v_lshlrev_b32_e32 v2, 16, v1
	v_and_b32_e32 v2, 0xfffe0000, v2
	v_lshl_add_u32 v2, v10, 13, v2
	v_and_b32_e32 v1, 1, v1
	s_and_b32 s6, s6, 0x1800000
	s_lshl_b32 s7, s33, 21
	v_lshl_or_b32 v1, v1, 6, v2
	s_or_b32 s6, s6, s7
	v_lshl_add_u32 v2, v11, 1, v1
	s_add_u32 s6, s96, s6
	v_lshlrev_b32_e32 v1, 16, v12
	v_mov_b32_e32 v3, v133
	s_addc_u32 s7, s97, 0
	v_and_b32_e32 v1, 0xfffe0000, v1
	v_lshl_add_u64 v[138:139], s[6:7], 0, v[2:3]
	v_lshl_add_u32 v1, v13, 13, v1
	v_and_b32_e32 v2, 1, v12
	s_waitcnt vmcnt(6)
	v_lshl_or_b32 v1, v2, 6, v1
	s_add_i32 s34, 0, 0x10000
	s_add_i32 s35, 0, 0x14000
	s_add_i32 s36, 0, 0x18000
	s_add_i32 s37, 0, 0x1c000
	v_lshl_add_u32 v2, v14, 1, v1
	s_add_i32 s45, s34, s20
	s_add_i32 s47, s35, s20
	s_add_i32 s49, s36, s20
	s_add_i32 s51, s37, s20
	v_lshl_or_b32 v185, s25, 6, v181
	v_lshl_add_u64 v[140:141], s[6:7], 0, v[2:3]
	s_mov_b32 s42, -2
	s_mov_b64 s[6:7], 0x78400080
	v_add_u32_e32 v1, s34, v15
	v_add_u32_e32 v142, s35, v15
	v_add_u32_e32 v143, 0, v17
	s_add_i32 s43, s28, 0xc000
	s_add_i32 s44, s28, 0xe000
	s_add_i32 s46, s45, 0x2000
	s_add_i32 s48, s47, 0x2000
	v_add_u32_e32 v144, s36, v15
	v_add_u32_e32 v145, s37, v15
	s_add_i32 s50, s49, 0x2000
	s_add_i32 s52, s51, 0x2000
	v_mov_b32_e32 v114, v133
	v_mov_b32_e32 v115, v133
	v_mov_b32_e32 v116, v133
	v_mov_b32_e32 v117, v133
	v_mov_b32_e32 v118, v133
	v_mov_b32_e32 v119, v133
	v_mov_b32_e32 v120, v133
	v_mov_b32_e32 v121, v133
	v_mov_b32_e32 v82, v133
	v_mov_b32_e32 v83, v133
	v_mov_b32_e32 v84, v133
	v_mov_b32_e32 v85, v133
	v_mov_b32_e32 v90, v133
	v_mov_b32_e32 v91, v133
	v_mov_b32_e32 v92, v133
	v_mov_b32_e32 v93, v133
	v_mov_b32_e32 v66, v133
	v_mov_b32_e32 v67, v133
	v_mov_b32_e32 v68, v133
	v_mov_b32_e32 v69, v133
	v_mov_b32_e32 v74, v133
	v_mov_b32_e32 v75, v133
	v_mov_b32_e32 v76, v133
	v_mov_b32_e32 v77, v133
	v_mov_b32_e32 v46, v133
	v_mov_b32_e32 v47, v133
	v_mov_b32_e32 v48, v133
	v_mov_b32_e32 v49, v133
	v_mov_b32_e32 v58, v133
	v_mov_b32_e32 v59, v133
	v_mov_b32_e32 v60, v133
	v_mov_b32_e32 v61, v133
	v_mov_b32_e32 v122, v133
	v_mov_b32_e32 v123, v133
	v_mov_b32_e32 v124, v133
	v_mov_b32_e32 v125, v133
	v_mov_b32_e32 v126, v133
	v_mov_b32_e32 v127, v133
	v_mov_b32_e32 v128, v133
	v_mov_b32_e32 v129, v133
	v_mov_b32_e32 v106, v133
	v_mov_b32_e32 v107, v133
	v_mov_b32_e32 v108, v133
	v_mov_b32_e32 v109, v133
	v_mov_b32_e32 v110, v133
	v_mov_b32_e32 v111, v133
	v_mov_b32_e32 v112, v133
	v_mov_b32_e32 v113, v133
	v_mov_b32_e32 v98, v133
	v_mov_b32_e32 v99, v133
	v_mov_b32_e32 v100, v133
	v_mov_b32_e32 v101, v133
	v_mov_b32_e32 v102, v133
	v_mov_b32_e32 v103, v133
	v_mov_b32_e32 v104, v133
	v_mov_b32_e32 v105, v133
	v_mov_b32_e32 v86, v133
	v_mov_b32_e32 v87, v133
	v_mov_b32_e32 v88, v133
	v_mov_b32_e32 v89, v133
	v_mov_b32_e32 v94, v133
	v_mov_b32_e32 v95, v133
	v_mov_b32_e32 v96, v133
	v_mov_b32_e32 v97, v133
	v_mov_b32_e32 v26, v133
	v_mov_b32_e32 v27, v133
	v_mov_b32_e32 v28, v133
	v_mov_b32_e32 v29, v133
	v_mov_b32_e32 v38, v133
	v_mov_b32_e32 v39, v133
	v_mov_b32_e32 v40, v133
	v_mov_b32_e32 v41, v133
	v_mov_b32_e32 v18, v133
	v_mov_b32_e32 v19, v133
	v_mov_b32_e32 v20, v133
	v_mov_b32_e32 v21, v133
	v_mov_b32_e32 v22, v133
	v_mov_b32_e32 v23, v133
	v_mov_b32_e32 v24, v133
	v_mov_b32_e32 v25, v133
	v_mov_b32_e32 v6, v133
	v_mov_b32_e32 v7, v133
	v_mov_b32_e32 v8, v133
	v_mov_b32_e32 v9, v133
	v_mov_b32_e32 v14, v133
	v_mov_b32_e32 v15, v133
	v_mov_b32_e32 v16, v133
	v_mov_b32_e32 v17, v133
	v_mov_b32_e32 v2, v133
	v_mov_b32_e32 v4, v133
	v_mov_b32_e32 v5, v133
	v_mov_b32_e32 v10, v133
	v_mov_b32_e32 v11, v133
	v_mov_b32_e32 v12, v133
	v_mov_b32_e32 v13, v133
	v_mov_b32_e32 v70, v133
	v_mov_b32_e32 v71, v133
	v_mov_b32_e32 v72, v133
	v_mov_b32_e32 v73, v133
	v_mov_b32_e32 v78, v133
	v_mov_b32_e32 v79, v133
	v_mov_b32_e32 v80, v133
	v_mov_b32_e32 v81, v133
	v_mov_b32_e32 v50, v133
	v_mov_b32_e32 v51, v133
	v_mov_b32_e32 v52, v133
	v_mov_b32_e32 v53, v133
	v_mov_b32_e32 v62, v133
	v_mov_b32_e32 v63, v133
	v_mov_b32_e32 v64, v133
	v_mov_b32_e32 v65, v133
	v_mov_b32_e32 v30, v133
	v_mov_b32_e32 v31, v133
	v_mov_b32_e32 v32, v133
	v_mov_b32_e32 v33, v133
	v_mov_b32_e32 v42, v133
	v_mov_b32_e32 v43, v133
	v_mov_b32_e32 v44, v133
	v_mov_b32_e32 v45, v133
	v_mov_b32_e32 v34, v133
	v_mov_b32_e32 v35, v133
	v_mov_b32_e32 v36, v133
	v_mov_b32_e32 v37, v133
	v_mov_b32_e32 v54, v133
	v_mov_b32_e32 v55, v133
	v_mov_b32_e32 v56, v133
	v_mov_b32_e32 v57, v133
	s_barrier
	s_branch .Lmy_r850E

; #define PG8_STAGE(bufoff, gbase, voff) do { _Pragma("unroll") for (int _i = 0; _i < 2; ++_i) \
;         __builtin_amdgcn_global_load_lds((const unsigned*)((const char*)(gbase) + (voff)[_i]), (LAS unsigned*)(lds + (bufoff) + ldsw + _i * 8192), 16, 0, 0); } while (0)
; #define PG8_LDA(dst, b, h) do { _Pragma("unroll") for (int m = 0; m < 4; ++m) _Pragma("unroll") for (int k = 0; k < 2; ++k) dst[m][k] = *(const LAS bf16x8*)(lds + PG8_SA(b, h) + aoff + m * 2048 + k * 1024); } while (0)
; #define PG8_LDB(dst, b, h) do { _Pragma("unroll") for (int n = 0; n < 2; ++n) _Pragma("unroll") for (int k = 0; k < 2; ++k) dst[n][k] = *(const LAS bf16x8*)(lds + PG8_SB(b, h) + boff + n * 2048 + k * 1024); } while (0)
; #define PG8_MMA(ai, bj, At, Bt) do { __builtin_amdgcn_s_setprio(1); _Pragma("unroll") for (int m = 0; m < 4; ++m) _Pragma("unroll") for (int n = 0; n < 2; ++n) _Pragma("unroll") for (int k = 0; k < 2; ++k) \
;         acc[ai][bj][m][n] = __builtin_amdgcn_mfma_f32_16x16x32_bf16(Bt[n][k], At[m][k], acc[ai][bj][m][n], 0, 0, 0); __builtin_amdgcn_s_setprio(0); } while (0)
; #define PG8_WAIT_V(n) asm volatile("s_waitcnt vmcnt(" #n ")" ::: "memory")
; #define PG8_WAIT_L(n) asm volatile("s_waitcnt lgkmcnt(" #n ")" ::: "memory")
; #define PG8_BAR __builtin_amdgcn_s_barrier()
; #define PG8_SCHED __builtin_amdgcn_sched_barrier(0)
; template <class Epi, class Sched, bool ALIGN_EPI, class Hook = NoHook>
; __device__ __forceinline__ void gemm_phase(LAS unsigned char* lds, const Gemm g, const Sched& S, const Epi& E, const Hook& H = Hook()) {
;     ...
;             PG8_LDB(B0, 0, 0); PG8_LDB(B1, 0, 1); PG8_SCHED; PG8_LDA(At, 0, 0); PG8_STAGE(PG8_SA(1, 1), a1 + hA, voffA);
;             PG8_WAIT_V(8); PG8_WAIT_L(0); PG8_BAR; PG8_MMA(0, 0, At, B0); PG8_MMA(0, 1, At, B1); PG8_BAR; PG8_SCHED;
;             PG8_LDA(At, 0, 1); PG8_STAGE(PG8_SB(0, 0), b2, voffB); PG8_STAGE(PG8_SB(0, 1), b2 + hB, voffB); PG8_STAGE(PG8_SA(0, 0), a2, voffA);
;             PG8_WAIT_V(8); PG8_WAIT_L(0); PG8_BAR; PG8_MMA(1, 0, At, B0); PG8_MMA(1, 1, At, B1); PG8_BAR; PG8_SCHED;
.Lmy_r850E:
	ds_read_b128 v[146:149], v1
	ds_read_b128 v[150:153], v1 offset:1024
	s_add_u32 s20, s6, 0x87c00080
	s_addc_u32 s21, s7, -1
	s_cmp_lg_u32 s42, 60
	s_cselect_b32 s20, s20, 0
	s_cselect_b32 s21, s21, 0
	s_add_u32 s22, s2, s20
	s_addc_u32 s23, s3, s21
	s_add_u32 s20, s14, s20
	s_addc_u32 s21, s15, s21
	s_mov_b32 m0, s43
	ds_read_b128 v[154:157], v1 offset:2048
	ds_read_b128 v[158:161], v1 offset:3072
	ds_read_b128 v[162:165], v142
	ds_read_b128 v[166:169], v142 offset:1024
	ds_read_b128 v[170:173], v142 offset:2048
	ds_read_b128 v[174:177], v142 offset:3072
	v_lshl_add_u64 v[178:179], v[138:139], 0, s[6:7]
	global_load_lds_dwordx4 v[178:179], off
	ds_read_b128 v[186:189], v143
	ds_read_b128 v[190:193], v143 offset:1024
	ds_read_b128 v[194:197], v143 offset:2048
	ds_read_b128 v[198:201], v143 offset:3072
	ds_read_b128 v[202:205], v143 offset:4096
	ds_read_b128 v[206:209], v143 offset:5120
	ds_read_b128 v[210:213], v143 offset:6144
	ds_read_b128 v[214:217], v143 offset:7168
	v_lshl_add_u64 v[178:179], v[140:141], 0, s[6:7]
	s_mov_b32 m0, s44
	s_nop 0
	global_load_lds_dwordx4 v[178:179], off
	s_waitcnt vmcnt(8)
	s_waitcnt lgkmcnt(0)
	s_barrier
	s_setprio 1
	s_waitcnt lgkmcnt(0)
	v_mfma_f32_16x16x32_bf16 v[54:57], v[146:149], v[186:189], v[54:57]
	v_mfma_f32_16x16x32_bf16 v[34:37], v[154:157], v[186:189], v[34:37]
	v_mfma_f32_16x16x32_bf16 v[42:45], v[146:149], v[194:197], v[42:45]
	v_mfma_f32_16x16x32_bf16 v[30:33], v[154:157], v[194:197], v[30:33]
	v_mfma_f32_16x16x32_bf16 v[62:65], v[146:149], v[202:205], v[62:65]
	v_mfma_f32_16x16x32_bf16 v[50:53], v[154:157], v[202:205], v[50:53]
	v_mfma_f32_16x16x32_bf16 v[78:81], v[146:149], v[210:213], v[78:81]
	v_mfma_f32_16x16x32_bf16 v[70:73], v[154:157], v[210:213], v[70:73]
	v_mfma_f32_16x16x32_bf16 v[54:57], v[150:153], v[190:193], v[54:57]
	v_mfma_f32_16x16x32_bf16 v[34:37], v[158:161], v[190:193], v[34:37]
	v_mfma_f32_16x16x32_bf16 v[42:45], v[150:153], v[198:201], v[42:45]
	v_mfma_f32_16x16x32_bf16 v[30:33], v[158:161], v[198:201], v[30:33]
	v_mfma_f32_16x16x32_bf16 v[62:65], v[150:153], v[206:209], v[62:65]
	v_mfma_f32_16x16x32_bf16 v[50:53], v[158:161], v[206:209], v[50:53]
	v_mfma_f32_16x16x32_bf16 v[78:81], v[150:153], v[214:217], v[78:81]
	v_mfma_f32_16x16x32_bf16 v[70:73], v[158:161], v[214:217], v[70:73]
	s_setprio 0
	s_setprio 1
	v_mfma_f32_16x16x32_bf16 v[10:13], v[162:165], v[186:189], v[10:13]
	v_mfma_f32_16x16x32_bf16 v[2:5], v[170:173], v[186:189], v[2:5]
	v_mfma_f32_16x16x32_bf16 v[14:17], v[162:165], v[194:197], v[14:17]
	v_mfma_f32_16x16x32_bf16 v[6:9], v[170:173], v[194:197], v[6:9]
	v_mfma_f32_16x16x32_bf16 v[22:25], v[162:165], v[202:205], v[22:25]
	v_mfma_f32_16x16x32_bf16 v[18:21], v[170:173], v[202:205], v[18:21]
	v_mfma_f32_16x16x32_bf16 v[38:41], v[162:165], v[210:213], v[38:41]
	v_mfma_f32_16x16x32_bf16 v[26:29], v[170:173], v[210:213], v[26:29]
	v_mfma_f32_16x16x32_bf16 v[10:13], v[166:169], v[190:193], v[10:13]
	v_mfma_f32_16x16x32_bf16 v[2:5], v[174:177], v[190:193], v[2:5]
	v_mfma_f32_16x16x32_bf16 v[14:17], v[166:169], v[198:201], v[14:17]
	v_mfma_f32_16x16x32_bf16 v[6:9], v[174:177], v[198:201], v[6:9]
	v_mfma_f32_16x16x32_bf16 v[22:25], v[166:169], v[206:209], v[22:25]
	v_mfma_f32_16x16x32_bf16 v[18:21], v[174:177], v[206:209], v[18:21]
	v_mfma_f32_16x16x32_bf16 v[38:41], v[166:169], v[214:217], v[38:41]
	v_mfma_f32_16x16x32_bf16 v[26:29], v[174:177], v[214:217], v[26:29]
	s_setprio 0
	s_barrier
	s_mov_b32 m0, s45
	s_add_u32 s54, s20, 0x100000
	ds_read_b128 v[186:189], v143 offset:16384
	ds_read_b128 v[190:193], v143 offset:17408
	global_load_lds_dwordx4 v132, s[20:21]
	ds_read_b128 v[194:197], v143 offset:18432
	s_mov_b32 m0, s46
	s_addc_u32 s55, s21, 0
	global_load_lds_dwordx4 v136, s[20:21]
	ds_read_b128 v[198:201], v143 offset:19456
	s_mov_b32 m0, s47
	s_nop 0
	global_load_lds_dwordx4 v132, s[54:55]
	ds_read_b128 v[202:205], v143 offset:20480
	s_mov_b32 m0, s48
	s_nop 0
	global_load_lds_dwordx4 v136, s[54:55]
	ds_read_b128 v[206:209], v143 offset:21504
	s_add_u32 s58, s22, s4
	s_addc_u32 s59, s23, s5
	s_mov_b32 m0, s28
	s_nop 0
	global_load_lds_dwordx4 v130, s[22:23]
	ds_read_b128 v[210:213], v143 offset:22528
	s_mov_b32 m0, s29
	s_nop 0
	global_load_lds_dwordx4 v134, s[22:23]
	ds_read_b128 v[214:217], v143 offset:23552
	s_waitcnt vmcnt(8)
	s_waitcnt lgkmcnt(0)
	s_barrier
	s_setprio 1
	s_waitcnt lgkmcnt(0)
	v_mfma_f32_16x16x32_bf16 v[94:97], v[146:149], v[186:189], v[94:97]
	v_mfma_f32_16x16x32_bf16 v[86:89], v[154:157], v[186:189], v[86:89]
	v_mfma_f32_16x16x32_bf16 v[102:105], v[146:149], v[194:197], v[102:105]
	v_mfma_f32_16x16x32_bf16 v[98:101], v[154:157], v[194:197], v[98:101]
	v_mfma_f32_16x16x32_bf16 v[110:113], v[146:149], v[202:205], v[110:113]
	v_mfma_f32_16x16x32_bf16 v[106:109], v[154:157], v[202:205], v[106:109]
	v_mfma_f32_16x16x32_bf16 v[126:129], v[146:149], v[210:213], v[126:129]
	v_mfma_f32_16x16x32_bf16 v[122:125], v[154:157], v[210:213], v[122:125]
	v_mfma_f32_16x16x32_bf16 v[94:97], v[150:153], v[190:193], v[94:97]
	v_mfma_f32_16x16x32_bf16 v[86:89], v[158:161], v[190:193], v[86:89]
	v_mfma_f32_16x16x32_bf16 v[102:105], v[150:153], v[198:201], v[102:105]
	v_mfma_f32_16x16x32_bf16 v[98:101], v[158:161], v[198:201], v[98:101]
	v_mfma_f32_16x16x32_bf16 v[110:113], v[150:153], v[206:209], v[110:113]
	v_mfma_f32_16x16x32_bf16 v[106:109], v[158:161], v[206:209], v[106:109]
	v_mfma_f32_16x16x32_bf16 v[126:129], v[150:153], v[214:217], v[126:129]
	v_mfma_f32_16x16x32_bf16 v[122:125], v[158:161], v[214:217], v[122:125]
	s_setprio 0
	s_setprio 1
	v_mfma_f32_16x16x32_bf16 v[58:61], v[162:165], v[186:189], v[58:61]
	v_mfma_f32_16x16x32_bf16 v[46:49], v[170:173], v[186:189], v[46:49]
	v_mfma_f32_16x16x32_bf16 v[74:77], v[162:165], v[194:197], v[74:77]
	v_mfma_f32_16x16x32_bf16 v[66:69], v[170:173], v[194:197], v[66:69]
	v_mfma_f32_16x16x32_bf16 v[90:93], v[162:165], v[202:205], v[90:93]
	v_mfma_f32_16x16x32_bf16 v[82:85], v[170:173], v[202:205], v[82:85]
	v_mfma_f32_16x16x32_bf16 v[118:121], v[162:165], v[210:213], v[118:121]
	v_mfma_f32_16x16x32_bf16 v[114:117], v[170:173], v[210:213], v[114:117]
	v_mfma_f32_16x16x32_bf16 v[58:61], v[166:169], v[190:193], v[58:61]
	v_mfma_f32_16x16x32_bf16 v[46:49], v[174:177], v[190:193], v[46:49]
	v_mfma_f32_16x16x32_bf16 v[74:77], v[166:169], v[198:201], v[74:77]
	v_mfma_f32_16x16x32_bf16 v[66:69], v[174:177], v[198:201], v[66:69]
	v_mfma_f32_16x16x32_bf16 v[90:93], v[166:169], v[206:209], v[90:93]
	v_mfma_f32_16x16x32_bf16 v[82:85], v[174:177], v[206:209], v[82:85]
	v_mfma_f32_16x16x32_bf16 v[118:121], v[166:169], v[214:217], v[118:121]
	v_mfma_f32_16x16x32_bf16 v[114:117], v[174:177], v[214:217], v[114:117]
	s_setprio 0
	s_barrier
; #define PG8_STAGE(bufoff, gbase, voff) do { _Pragma("unroll") for (int _i = 0; _i < 2; ++_i) \
;         __builtin_amdgcn_global_load_lds((const unsigned*)((const char*)(gbase) + (voff)[_i]), (LAS unsigned*)(lds + (bufoff) + ldsw + _i * 8192), 16, 0, 0); } while (0)
; #define PG8_LDA(dst, b, h) do { _Pragma("unroll") for (int m = 0; m < 4; ++m) _Pragma("unroll") for (int k = 0; k < 2; ++k) dst[m][k] = *(const LAS bf16x8*)(lds + PG8_SA(b, h) + aoff + m * 2048 + k * 1024); } while (0)
; #define PG8_LDB(dst, b, h) do { _Pragma("unroll") for (int n = 0; n < 2; ++n) _Pragma("unroll") for (int k = 0; k < 2; ++k) dst[n][k] = *(const LAS bf16x8*)(lds + PG8_SB(b, h) + boff + n * 2048 + k * 1024); } while (0)
; #define PG8_MMA(ai, bj, At, Bt) do { __builtin_amdgcn_s_setprio(1); _Pragma("unroll") for (int m = 0; m < 4; ++m) _Pragma("unroll") for (int n = 0; n < 2; ++n) _Pragma("unroll") for (int k = 0; k < 2; ++k) \
;         acc[ai][bj][m][n] = __builtin_amdgcn_mfma_f32_16x16x32_bf16(Bt[n][k], At[m][k], acc[ai][bj][m][n], 0, 0, 0); __builtin_amdgcn_s_setprio(0); } while (0)
; #define PG8_WAIT_V(n) asm volatile("s_waitcnt vmcnt(" #n ")" ::: "memory")
; #define PG8_WAIT_L(n) asm volatile("s_waitcnt lgkmcnt(" #n ")" ::: "memory")
; #define PG8_BAR __builtin_amdgcn_s_barrier()
; #define PG8_SCHED __builtin_amdgcn_sched_barrier(0)
; template <class Epi, class Sched, bool ALIGN_EPI, class Hook = NoHook>
; __device__ __forceinline__ void gemm_phase(LAS unsigned char* lds, const Gemm g, const Sched& S, const Epi& E, const Hook& H = Hook()) {
;     ...
;         for (int t = tb; t < te; t += 2) {
;             const bool last = (t == nt - 2);
;     ...
;             PG8_LDB(B0, 1, 0); PG8_LDB(B1, 1, 1); PG8_SCHED; PG8_LDA(At, 1, 0); PG8_STAGE(PG8_SA(0, 1), a2 + hA, voffA);
;             PG8_WAIT_V(8); PG8_WAIT_L(0); PG8_BAR; PG8_MMA(0, 0, At, B0); PG8_MMA(0, 1, At, B1); PG8_BAR; PG8_SCHED;
;             PG8_LDA(At, 1, 1); PG8_STAGE(PG8_SB(1, 0), b3, voffB); PG8_STAGE(PG8_SB(1, 1), b3 + hB, voffB); PG8_STAGE(PG8_SA(1, 0), a3, voffA);
;             PG8_WAIT_V(8); PG8_WAIT_L(0); PG8_BAR; PG8_MMA(1, 0, At, B0); PG8_MMA(1, 1, At, B1); PG8_BAR; PG8_SCHED;
	ds_read_b128 v[146:149], v144
	ds_read_b128 v[150:153], v144 offset:1024
	s_add_u32 s22, s22, 0x100000
	s_addc_u32 s23, s23, 0
	s_mov_b32 m0, s38
	s_nop 0
	global_load_lds_dwordx4 v130, s[22:23]
	ds_read_b128 v[154:157], v144 offset:2048
	ds_read_b128 v[158:161], v144 offset:3072
	ds_read_b128 v[162:165], v145
	ds_read_b128 v[166:169], v145 offset:1024
	ds_read_b128 v[170:173], v145 offset:2048
	ds_read_b128 v[174:177], v145 offset:3072
	ds_read_b128 v[186:189], v143 offset:32768
	s_mov_b32 m0, s39
	s_nop 0
	global_load_lds_dwordx4 v134, s[22:23]
	ds_read_b128 v[190:193], v143 offset:33792
	ds_read_b128 v[194:197], v143 offset:34816
	ds_read_b128 v[198:201], v143 offset:35840
	ds_read_b128 v[202:205], v143 offset:36864
	ds_read_b128 v[206:209], v143 offset:37888
	ds_read_b128 v[210:213], v143 offset:38912
	ds_read_b128 v[214:217], v143 offset:39936
	s_waitcnt vmcnt(8)
	s_waitcnt lgkmcnt(0)
	s_barrier
	s_setprio 1
	s_waitcnt lgkmcnt(0)
	v_mfma_f32_16x16x32_bf16 v[54:57], v[146:149], v[186:189], v[54:57]
	v_mfma_f32_16x16x32_bf16 v[34:37], v[154:157], v[186:189], v[34:37]
	v_mfma_f32_16x16x32_bf16 v[42:45], v[146:149], v[194:197], v[42:45]
	v_mfma_f32_16x16x32_bf16 v[30:33], v[154:157], v[194:197], v[30:33]
	v_mfma_f32_16x16x32_bf16 v[62:65], v[146:149], v[202:205], v[62:65]
	v_mfma_f32_16x16x32_bf16 v[50:53], v[154:157], v[202:205], v[50:53]
	v_mfma_f32_16x16x32_bf16 v[78:81], v[146:149], v[210:213], v[78:81]
	v_mfma_f32_16x16x32_bf16 v[70:73], v[154:157], v[210:213], v[70:73]
	v_mfma_f32_16x16x32_bf16 v[54:57], v[150:153], v[190:193], v[54:57]
	v_mfma_f32_16x16x32_bf16 v[34:37], v[158:161], v[190:193], v[34:37]
	v_mfma_f32_16x16x32_bf16 v[42:45], v[150:153], v[198:201], v[42:45]
	v_mfma_f32_16x16x32_bf16 v[30:33], v[158:161], v[198:201], v[30:33]
	v_mfma_f32_16x16x32_bf16 v[62:65], v[150:153], v[206:209], v[62:65]
	v_mfma_f32_16x16x32_bf16 v[50:53], v[158:161], v[206:209], v[50:53]
	v_mfma_f32_16x16x32_bf16 v[78:81], v[150:153], v[214:217], v[78:81]
	v_mfma_f32_16x16x32_bf16 v[70:73], v[158:161], v[214:217], v[70:73]
	s_setprio 0
	s_setprio 1
	v_mfma_f32_16x16x32_bf16 v[10:13], v[162:165], v[186:189], v[10:13]
	v_mfma_f32_16x16x32_bf16 v[2:5], v[170:173], v[186:189], v[2:5]
	v_mfma_f32_16x16x32_bf16 v[14:17], v[162:165], v[194:197], v[14:17]
	v_mfma_f32_16x16x32_bf16 v[6:9], v[170:173], v[194:197], v[6:9]
	v_mfma_f32_16x16x32_bf16 v[22:25], v[162:165], v[202:205], v[22:25]
	v_mfma_f32_16x16x32_bf16 v[18:21], v[170:173], v[202:205], v[18:21]
	v_mfma_f32_16x16x32_bf16 v[38:41], v[162:165], v[210:213], v[38:41]
	v_mfma_f32_16x16x32_bf16 v[26:29], v[170:173], v[210:213], v[26:29]
	v_mfma_f32_16x16x32_bf16 v[10:13], v[166:169], v[190:193], v[10:13]
	v_mfma_f32_16x16x32_bf16 v[2:5], v[174:177], v[190:193], v[2:5]
	v_mfma_f32_16x16x32_bf16 v[14:17], v[166:169], v[198:201], v[14:17]
	v_mfma_f32_16x16x32_bf16 v[6:9], v[174:177], v[198:201], v[6:9]
	v_mfma_f32_16x16x32_bf16 v[22:25], v[166:169], v[206:209], v[22:25]
	v_mfma_f32_16x16x32_bf16 v[18:21], v[174:177], v[206:209], v[18:21]
	v_mfma_f32_16x16x32_bf16 v[38:41], v[166:169], v[214:217], v[38:41]
	v_mfma_f32_16x16x32_bf16 v[26:29], v[174:177], v[214:217], v[26:29]
	s_setprio 0
	s_barrier
	s_mov_b32 m0, s49
	s_add_u32 s56, s20, s4
	s_addc_u32 s57, s21, s5
	s_add_u32 s20, s20, 0x100080
	ds_read_b128 v[186:189], v143 offset:49152
	ds_read_b128 v[190:193], v143 offset:50176
	global_load_lds_dwordx4 v132, s[56:57]
	ds_read_b128 v[194:197], v143 offset:51200
	s_mov_b32 m0, s50
	s_addc_u32 s21, s21, 0
	global_load_lds_dwordx4 v136, s[56:57]
	ds_read_b128 v[198:201], v143 offset:52224
	s_mov_b32 m0, s51
	s_nop 0
	global_load_lds_dwordx4 v132, s[20:21]
	ds_read_b128 v[202:205], v143 offset:53248
	s_mov_b32 m0, s52
	s_nop 0
	global_load_lds_dwordx4 v136, s[20:21]
	ds_read_b128 v[206:209], v143 offset:54272
	s_mov_b32 m0, s40
	s_nop 0
	global_load_lds_dwordx4 v130, s[58:59]
	ds_read_b128 v[210:213], v143 offset:55296
	s_mov_b32 m0, s41
	s_nop 0
	global_load_lds_dwordx4 v134, s[58:59]
	ds_read_b128 v[214:217], v143 offset:56320
	s_waitcnt vmcnt(8)
	s_waitcnt lgkmcnt(0)
	s_barrier
	s_setprio 1
	s_waitcnt lgkmcnt(0)
	v_mfma_f32_16x16x32_bf16 v[94:97], v[146:149], v[186:189], v[94:97]
	v_mfma_f32_16x16x32_bf16 v[86:89], v[154:157], v[186:189], v[86:89]
	v_mfma_f32_16x16x32_bf16 v[102:105], v[146:149], v[194:197], v[102:105]
	v_mfma_f32_16x16x32_bf16 v[98:101], v[154:157], v[194:197], v[98:101]
	v_mfma_f32_16x16x32_bf16 v[110:113], v[146:149], v[202:205], v[110:113]
	v_mfma_f32_16x16x32_bf16 v[106:109], v[154:157], v[202:205], v[106:109]
	v_mfma_f32_16x16x32_bf16 v[126:129], v[146:149], v[210:213], v[126:129]
	v_mfma_f32_16x16x32_bf16 v[122:125], v[154:157], v[210:213], v[122:125]
	v_mfma_f32_16x16x32_bf16 v[94:97], v[150:153], v[190:193], v[94:97]
	v_mfma_f32_16x16x32_bf16 v[86:89], v[158:161], v[190:193], v[86:89]
	v_mfma_f32_16x16x32_bf16 v[102:105], v[150:153], v[198:201], v[102:105]
	v_mfma_f32_16x16x32_bf16 v[98:101], v[158:161], v[198:201], v[98:101]
	v_mfma_f32_16x16x32_bf16 v[110:113], v[150:153], v[206:209], v[110:113]
	v_mfma_f32_16x16x32_bf16 v[106:109], v[158:161], v[206:209], v[106:109]
	v_mfma_f32_16x16x32_bf16 v[126:129], v[150:153], v[214:217], v[126:129]
	v_mfma_f32_16x16x32_bf16 v[122:125], v[158:161], v[214:217], v[122:125]
	s_setprio 0
	s_setprio 1
	v_mfma_f32_16x16x32_bf16 v[58:61], v[162:165], v[186:189], v[58:61]
	v_mfma_f32_16x16x32_bf16 v[46:49], v[170:173], v[186:189], v[46:49]
	v_mfma_f32_16x16x32_bf16 v[74:77], v[162:165], v[194:197], v[74:77]
	v_mfma_f32_16x16x32_bf16 v[66:69], v[170:173], v[194:197], v[66:69]
	v_mfma_f32_16x16x32_bf16 v[90:93], v[162:165], v[202:205], v[90:93]
	v_mfma_f32_16x16x32_bf16 v[82:85], v[170:173], v[202:205], v[82:85]
	v_mfma_f32_16x16x32_bf16 v[118:121], v[162:165], v[210:213], v[118:121]
	v_mfma_f32_16x16x32_bf16 v[114:117], v[170:173], v[210:213], v[114:117]
	v_mfma_f32_16x16x32_bf16 v[58:61], v[166:169], v[190:193], v[58:61]
	v_mfma_f32_16x16x32_bf16 v[46:49], v[174:177], v[190:193], v[46:49]
	v_mfma_f32_16x16x32_bf16 v[74:77], v[166:169], v[198:201], v[74:77]
	v_mfma_f32_16x16x32_bf16 v[66:69], v[174:177], v[198:201], v[66:69]
	v_mfma_f32_16x16x32_bf16 v[90:93], v[166:169], v[206:209], v[90:93]
	v_mfma_f32_16x16x32_bf16 v[82:85], v[174:177], v[206:209], v[82:85]
	v_mfma_f32_16x16x32_bf16 v[118:121], v[166:169], v[214:217], v[118:121]
	v_mfma_f32_16x16x32_bf16 v[114:117], v[174:177], v[214:217], v[114:117]
	s_setprio 0
	s_add_i32 s42, s42, 2
	s_add_u32 s6, s6, 0x100
	s_addc_u32 s7, s7, 0
	s_cmp_gt_u32 s42, 61
	s_cbranch_scc0 .LBB0_850
	s_barrier
	s_cmpk_lt_u32 s26, 0x100
	s_cbranch_scc0 .LBB0_853
	s_barrier

;     __host__ __device__ bool next(int i, Unit& u) const { const bool ok = StaticOrder::next(i >> 1, u); if (i & 1) { u.ka = D_INNER; u.nkt = D_ATT / BK; } else { u.ka = 0; u.nkt = D_INNER / BK; } return ok; }
; #define PG8_BAR __builtin_amdgcn_s_barrier()
; template <class Epi, class Sched, bool ALIGN_EPI, class Hook = NoHook>
; __device__ __forceinline__ void gemm_phase(LAS unsigned char* lds, const Gemm g, const Sched& S, const Epi& E, const Hook& H = Hook()) {
;     ...
;     const int tid = tid_, wid = __builtin_amdgcn_readfirstlane(tid >> 6), lane = tid & 63, wr = wid >> 2, wc = wid & 3, fr = lane & 15, fq = lane >> 4;
;     unsigned voffA[2], voffB[2];
; #pragma unroll
;     for (int i = 0; i < 2; ++i) { int R, C; stage_rc(tid * 16 + i * 8192, R, C); const int Rb = Epi::PERM ? ((R & ~31) + perm32(R & 31)) : R;
;         const int Ra = Epi::APERM ? (8 * (16 * (R >> 6) + (R & 15)) + ((R >> 4) & 3)) : R;
;         voffA[i] = (unsigned)(Ra * g.lda + C) * 2u; voffB[i] = (unsigned)(Rb * g.ldb + C) * 2u; }
;     const size_t kstep = (size_t)(BK * 2);
;     const size_t hA = (size_t)(Epi::APERM ? 4 : HALF) * g.lda * 2, hB = (size_t)HALF * g.ldb * 2;
;     const size_t tA = (size_t)BM * g.lda * 2;
;     const unsigned ldsw = (unsigned)wid * 1024u;
;     const int aoff = lds_byte(wr * 64 + fr, fq * 8), boff = lds_byte(wc * 32 + fr, fq * 8);
;     ...
;     Unit cur, nxt; int ui = 0;
;     if (!S.next(0, cur)) return;
;     f32x4 acc[2][2][4][2];
; #pragma unroll
;     for (int a = 0; a < 2; ++a)
; #pragma unroll
;         for (int b = 0; b < 2; ++b)
; #pragma unroll
;             for (int m = 0; m < 4; ++m)
; #pragma unroll
;                 for (int n = 0; n < 2; ++n) acc[a][b][m][n] = (f32x4){0.f, 0.f, 0.f, 0.f};
;     bf16x8 At[4][2], B0[2][2], B1[2][2];
;     const char* cA = (const char*)g.A + (size_t)cur.pm * tA + (size_t)cur.ka * 2; const char* cB = (const char*)g.Bt + (size_t)cur.pn * 2 * hB + (size_t)cur.ka * 2;
;     S.a_ready(cur);
;     if constexpr (Hook::ON) H.unit_start(cur);
;     PG8_STAGE(PG8_SB(0, 0), cB, voffB); PG8_STAGE(PG8_SB(0, 1), cB + hB, voffB); PG8_STAGE(PG8_SA(0, 0), cA, voffA); PG8_STAGE(PG8_SA(0, 1), cA + hA, voffA);
;     if (wr == 1) PG8_BAR;
;     PG8_WAIT_V(2); PG8_BAR;
;     PG8_STAGE(PG8_SB(1, 0), cB + kstep, voffB); PG8_STAGE(PG8_SA(1, 0), cA + kstep, voffA); PG8_STAGE(PG8_SB(1, 1), cB + hB + kstep, voffB);
;     PG8_WAIT_V(6); PG8_BAR;
.LBB0_895:
	v_and_b32_e32 v183, 15, v182
	v_and_b32_e32 v16, 48, v182
	v_lshlrev_b32_e32 v17, 2, v182
	s_and_b32 s25, s23, 3
	s_lshl_b32 s4, s24, 13
	v_lshl_or_b32 v16, v183, 6, v16
	v_and_b32_e32 v17, 32, v17
	v_bitop3_b32 v18, v16, s4, v17 bitop3:0xde
	s_lshl_b32 s4, s25, 12
	v_bitop3_b32 v16, v16, s4, v17 bitop3:0xde
	s_mov_b64 s[4:5], 0x80
	s_add_i32 m0, s27, 0x18000
	v_lshl_add_u64 v[8:9], v[8:9], 0, s[4:5]
	s_waitcnt vmcnt(2)
	s_barrier
	global_load_lds_dwordx4 v[8:9], off
	v_lshl_add_u64 v[6:7], v[6:7], 0, s[4:5]
	s_add_i32 m0, s27, 0x1a000
	s_add_i32 s40, s27, 0x8000
	global_load_lds_dwordx4 v[6:7], off
	v_lshl_add_u64 v[4:5], v[4:5], 0, s[4:5]
	s_mov_b32 m0, s40
	s_add_i32 s41, s27, 0xa000
	global_load_lds_dwordx4 v[4:5], off
	v_lshl_add_u64 v[2:3], v[2:3], 0, s[4:5]
	s_mov_b32 m0, s41
	s_add_i32 s31, s31, s33
	global_load_lds_dwordx4 v[2:3], off
	s_add_i32 m0, s27, 0x1c000
	v_lshl_add_u64 v[2:3], s[18:19], 0, v[180:181]
	global_load_lds_dwordx4 v[2:3], off
	v_lshl_add_u64 v[2:3], s[18:19], 0, v[134:135]
	s_add_i32 m0, s27, 0x1e000
	s_lshl_b32 s6, s31, 21
	global_load_lds_dwordx4 v[2:3], off
	v_lshlrev_b32_e32 v2, 16, v10
	v_and_b32_e32 v2, 0xfffe0000, v2
	s_add_i32 s6, s6, 0x2000000
	v_lshl_add_u32 v2, v11, 13, v2
	v_and_b32_e32 v3, 1, v10
	v_lshl_or_b32 v2, v3, 6, v2
	s_add_u32 s6, s96, s6
	v_lshl_add_u32 v2, v12, 1, v2
	v_mov_b32_e32 v3, v181
	s_addc_u32 s7, s97, 0
	v_lshl_add_u64 v[136:137], s[6:7], 0, v[2:3]
	v_lshlrev_b32_e32 v2, 16, v13
	v_and_b32_e32 v2, 0xfffe0000, v2
	v_lshl_add_u32 v2, v14, 13, v2
	v_and_b32_e32 v3, 1, v13
	s_waitcnt vmcnt(6)
	v_lshl_or_b32 v2, v3, 6, v2
	v_lshl_add_u32 v2, v15, 1, v2
	v_mov_b32_e32 v3, v181
	v_add_u32_e32 v141, s35, v16
	s_add_i32 s33, s34, s44
	s_add_i32 s35, s35, s44
	v_add_u32_e32 v143, s36, v16
	v_add_u32_e32 v144, s37, v16
	s_add_i32 s36, s36, s44
	s_add_i32 s37, s37, s44
	v_lshl_or_b32 v185, s24, 6, v183
	v_lshl_add_u64 v[138:139], s[6:7], 0, v[2:3]
	s_mov_b32 s18, -2
	s_mov_b64 s[6:7], 0x78400080
	v_add_u32_e32 v140, s34, v16
	v_add_u32_e32 v142, 0, v18
	s_add_i32 s19, s27, 0xc000
	s_add_i32 s31, s27, 0xe000
	s_add_i32 s34, s33, 0x2000
	s_add_i32 s42, s35, 0x2000
	s_add_i32 s43, s36, 0x2000
	s_add_i32 s44, s37, 0x2000
	v_mov_b32_e32 v114, v181
	v_mov_b32_e32 v115, v181
	v_mov_b32_e32 v116, v181
	v_mov_b32_e32 v117, v181
	v_mov_b32_e32 v118, v181
	v_mov_b32_e32 v119, v181
	v_mov_b32_e32 v120, v181
	v_mov_b32_e32 v121, v181
	v_mov_b32_e32 v82, v181
	v_mov_b32_e32 v83, v181
	v_mov_b32_e32 v84, v181
	v_mov_b32_e32 v85, v181
	v_mov_b32_e32 v90, v181
	v_mov_b32_e32 v91, v181
	v_mov_b32_e32 v92, v181
	v_mov_b32_e32 v93, v181
	v_mov_b32_e32 v66, v181
	v_mov_b32_e32 v67, v181
	v_mov_b32_e32 v68, v181
	v_mov_b32_e32 v69, v181
	v_mov_b32_e32 v74, v181
	v_mov_b32_e32 v75, v181
	v_mov_b32_e32 v76, v181
	v_mov_b32_e32 v77, v181
	v_mov_b32_e32 v46, v181
	v_mov_b32_e32 v47, v181
	v_mov_b32_e32 v48, v181
	v_mov_b32_e32 v49, v181
	v_mov_b32_e32 v58, v181
	v_mov_b32_e32 v59, v181
	v_mov_b32_e32 v60, v181
	v_mov_b32_e32 v61, v181
	v_mov_b32_e32 v122, v181
	v_mov_b32_e32 v123, v181
	v_mov_b32_e32 v124, v181
	v_mov_b32_e32 v125, v181
	v_mov_b32_e32 v126, v181
	v_mov_b32_e32 v127, v181
	v_mov_b32_e32 v128, v181
	v_mov_b32_e32 v129, v181
	v_mov_b32_e32 v106, v181
	v_mov_b32_e32 v107, v181
	v_mov_b32_e32 v108, v181
	v_mov_b32_e32 v109, v181
	v_mov_b32_e32 v110, v181
	v_mov_b32_e32 v111, v181
	v_mov_b32_e32 v112, v181
	v_mov_b32_e32 v113, v181
	v_mov_b32_e32 v98, v181
	v_mov_b32_e32 v99, v181
	v_mov_b32_e32 v100, v181
	v_mov_b32_e32 v101, v181
	v_mov_b32_e32 v102, v181
	v_mov_b32_e32 v103, v181
	v_mov_b32_e32 v104, v181
	v_mov_b32_e32 v105, v181
	v_mov_b32_e32 v86, v181
	v_mov_b32_e32 v87, v181
	v_mov_b32_e32 v88, v181
	v_mov_b32_e32 v89, v181
	v_mov_b32_e32 v94, v181
	v_mov_b32_e32 v95, v181
	v_mov_b32_e32 v96, v181
	v_mov_b32_e32 v97, v181
	v_mov_b32_e32 v26, v181
	v_mov_b32_e32 v27, v181
	v_mov_b32_e32 v28, v181
	v_mov_b32_e32 v29, v181
	v_mov_b32_e32 v38, v181
	v_mov_b32_e32 v39, v181
	v_mov_b32_e32 v40, v181
	v_mov_b32_e32 v41, v181
	v_mov_b32_e32 v18, v181
	v_mov_b32_e32 v19, v181
	v_mov_b32_e32 v20, v181
	v_mov_b32_e32 v21, v181
	v_mov_b32_e32 v22, v181
	v_mov_b32_e32 v23, v181
	v_mov_b32_e32 v24, v181
	v_mov_b32_e32 v25, v181
	v_mov_b32_e32 v6, v181
	v_mov_b32_e32 v7, v181
	v_mov_b32_e32 v8, v181
	v_mov_b32_e32 v9, v181
	v_mov_b32_e32 v14, v181
	v_mov_b32_e32 v15, v181
	v_mov_b32_e32 v16, v181
	v_mov_b32_e32 v17, v181
	v_mov_b32_e32 v2, v181
	v_mov_b32_e32 v4, v181
	v_mov_b32_e32 v5, v181
	v_mov_b32_e32 v10, v181
	v_mov_b32_e32 v11, v181
	v_mov_b32_e32 v12, v181
	v_mov_b32_e32 v13, v181
	v_mov_b32_e32 v70, v181
	v_mov_b32_e32 v71, v181
	v_mov_b32_e32 v72, v181
	v_mov_b32_e32 v73, v181
	v_mov_b32_e32 v78, v181
	v_mov_b32_e32 v79, v181
	v_mov_b32_e32 v80, v181
	v_mov_b32_e32 v81, v181
	v_mov_b32_e32 v50, v181
	v_mov_b32_e32 v51, v181
	v_mov_b32_e32 v52, v181
	v_mov_b32_e32 v53, v181
	v_mov_b32_e32 v62, v181
	v_mov_b32_e32 v63, v181
	v_mov_b32_e32 v64, v181
	v_mov_b32_e32 v65, v181
	v_mov_b32_e32 v30, v181
	v_mov_b32_e32 v31, v181
	v_mov_b32_e32 v32, v181
	v_mov_b32_e32 v33, v181
	v_mov_b32_e32 v42, v181
	v_mov_b32_e32 v43, v181
	v_mov_b32_e32 v44, v181
	v_mov_b32_e32 v45, v181
	v_mov_b32_e32 v34, v181
	v_mov_b32_e32 v35, v181
	v_mov_b32_e32 v36, v181
	v_mov_b32_e32 v37, v181
	v_mov_b32_e32 v54, v181
	v_mov_b32_e32 v55, v181
	v_mov_b32_e32 v56, v181
	v_mov_b32_e32 v57, v181
	s_barrier
	s_branch .Lmy_r896E

; #define PG8_STAGE(bufoff, gbase, voff) do { _Pragma("unroll") for (int _i = 0; _i < 2; ++_i) \
;         __builtin_amdgcn_global_load_lds((const unsigned*)((const char*)(gbase) + (voff)[_i]), (LAS unsigned*)(lds + (bufoff) + ldsw + _i * 8192), 16, 0, 0); } while (0)
; #define PG8_LDA(dst, b, h) do { _Pragma("unroll") for (int m = 0; m < 4; ++m) _Pragma("unroll") for (int k = 0; k < 2; ++k) dst[m][k] = *(const LAS bf16x8*)(lds + PG8_SA(b, h) + aoff + m * 2048 + k * 1024); } while (0)
; #define PG8_LDB(dst, b, h) do { _Pragma("unroll") for (int n = 0; n < 2; ++n) _Pragma("unroll") for (int k = 0; k < 2; ++k) dst[n][k] = *(const LAS bf16x8*)(lds + PG8_SB(b, h) + boff + n * 2048 + k * 1024); } while (0)
; #define PG8_MMA(ai, bj, At, Bt) do { __builtin_amdgcn_s_setprio(1); _Pragma("unroll") for (int m = 0; m < 4; ++m) _Pragma("unroll") for (int n = 0; n < 2; ++n) _Pragma("unroll") for (int k = 0; k < 2; ++k) \
;         acc[ai][bj][m][n] = __builtin_amdgcn_mfma_f32_16x16x32_bf16(Bt[n][k], At[m][k], acc[ai][bj][m][n], 0, 0, 0); __builtin_amdgcn_s_setprio(0); } while (0)
; #define PG8_WAIT_V(n) asm volatile("s_waitcnt vmcnt(" #n ")" ::: "memory")
; #define PG8_WAIT_L(n) asm volatile("s_waitcnt lgkmcnt(" #n ")" ::: "memory")
; #define PG8_BAR __builtin_amdgcn_s_barrier()
; #define PG8_SCHED __builtin_amdgcn_sched_barrier(0)
; template <class Epi, class Sched, bool ALIGN_EPI, class Hook = NoHook>
; __device__ __forceinline__ void gemm_phase(LAS unsigned char* lds, const Gemm g, const Sched& S, const Epi& E, const Hook& H = Hook()) {
;     ...
;             PG8_LDB(B0, 0, 0); PG8_LDB(B1, 0, 1); PG8_SCHED; PG8_LDA(At, 0, 0); PG8_STAGE(PG8_SA(1, 1), a1 + hA, voffA);
;             PG8_WAIT_V(8); PG8_WAIT_L(0); PG8_BAR; PG8_MMA(0, 0, At, B0); PG8_MMA(0, 1, At, B1); PG8_BAR; PG8_SCHED;
;             PG8_LDA(At, 0, 1); PG8_STAGE(PG8_SB(0, 0), b2, voffB); PG8_STAGE(PG8_SB(0, 1), b2 + hB, voffB); PG8_STAGE(PG8_SA(0, 0), a2, voffA);
;             PG8_WAIT_V(8); PG8_WAIT_L(0); PG8_BAR; PG8_MMA(1, 0, At, B0); PG8_MMA(1, 1, At, B1); PG8_BAR; PG8_SCHED;
.Lmy_r896E:
	ds_read_b128 v[146:149], v140
	ds_read_b128 v[150:153], v140 offset:1024
	s_add_u32 s10, s6, 0x87c00080
	s_addc_u32 s11, s7, -1
	s_cmp_lg_u32 s18, 60
	s_cselect_b32 s10, s10, 0
	s_cselect_b32 s11, s11, 0
	s_add_u32 s16, s2, s10
	s_addc_u32 s17, s3, s11
	s_add_u32 s10, s14, s10
	s_addc_u32 s11, s15, s11
	s_mov_b32 m0, s19
	ds_read_b128 v[154:157], v140 offset:2048
	ds_read_b128 v[158:161], v140 offset:3072
	ds_read_b128 v[162:165], v141
	ds_read_b128 v[166:169], v141 offset:1024
	ds_read_b128 v[170:173], v141 offset:2048
	ds_read_b128 v[174:177], v141 offset:3072
	v_lshl_add_u64 v[178:179], v[136:137], 0, s[6:7]
	global_load_lds_dwordx4 v[178:179], off
	ds_read_b128 v[186:189], v142
	ds_read_b128 v[190:193], v142 offset:1024
	ds_read_b128 v[194:197], v142 offset:2048
	ds_read_b128 v[198:201], v142 offset:3072
	ds_read_b128 v[202:205], v142 offset:4096
	ds_read_b128 v[206:209], v142 offset:5120
	ds_read_b128 v[210:213], v142 offset:6144
	ds_read_b128 v[214:217], v142 offset:7168
	v_lshl_add_u64 v[178:179], v[138:139], 0, s[6:7]
	s_mov_b32 m0, s31
	s_nop 0
	global_load_lds_dwordx4 v[178:179], off
	s_waitcnt vmcnt(8)
	s_waitcnt lgkmcnt(0)
	s_barrier
	s_setprio 1
	s_waitcnt lgkmcnt(0)
	v_mfma_f32_16x16x32_bf16 v[54:57], v[146:149], v[186:189], v[54:57]
	v_mfma_f32_16x16x32_bf16 v[34:37], v[154:157], v[186:189], v[34:37]
	v_mfma_f32_16x16x32_bf16 v[42:45], v[146:149], v[194:197], v[42:45]
	v_mfma_f32_16x16x32_bf16 v[30:33], v[154:157], v[194:197], v[30:33]
	v_mfma_f32_16x16x32_bf16 v[62:65], v[146:149], v[202:205], v[62:65]
	v_mfma_f32_16x16x32_bf16 v[50:53], v[154:157], v[202:205], v[50:53]
	v_mfma_f32_16x16x32_bf16 v[78:81], v[146:149], v[210:213], v[78:81]
	v_mfma_f32_16x16x32_bf16 v[70:73], v[154:157], v[210:213], v[70:73]
	v_mfma_f32_16x16x32_bf16 v[54:57], v[150:153], v[190:193], v[54:57]
	v_mfma_f32_16x16x32_bf16 v[34:37], v[158:161], v[190:193], v[34:37]
	v_mfma_f32_16x16x32_bf16 v[42:45], v[150:153], v[198:201], v[42:45]
	v_mfma_f32_16x16x32_bf16 v[30:33], v[158:161], v[198:201], v[30:33]
	v_mfma_f32_16x16x32_bf16 v[62:65], v[150:153], v[206:209], v[62:65]
	v_mfma_f32_16x16x32_bf16 v[50:53], v[158:161], v[206:209], v[50:53]
	v_mfma_f32_16x16x32_bf16 v[78:81], v[150:153], v[214:217], v[78:81]
	v_mfma_f32_16x16x32_bf16 v[70:73], v[158:161], v[214:217], v[70:73]
	s_setprio 0
	s_setprio 1
	v_mfma_f32_16x16x32_bf16 v[10:13], v[162:165], v[186:189], v[10:13]
	v_mfma_f32_16x16x32_bf16 v[2:5], v[170:173], v[186:189], v[2:5]
	v_mfma_f32_16x16x32_bf16 v[14:17], v[162:165], v[194:197], v[14:17]
	v_mfma_f32_16x16x32_bf16 v[6:9], v[170:173], v[194:197], v[6:9]
	v_mfma_f32_16x16x32_bf16 v[22:25], v[162:165], v[202:205], v[22:25]
	v_mfma_f32_16x16x32_bf16 v[18:21], v[170:173], v[202:205], v[18:21]
	v_mfma_f32_16x16x32_bf16 v[38:41], v[162:165], v[210:213], v[38:41]
	v_mfma_f32_16x16x32_bf16 v[26:29], v[170:173], v[210:213], v[26:29]
	v_mfma_f32_16x16x32_bf16 v[10:13], v[166:169], v[190:193], v[10:13]
	v_mfma_f32_16x16x32_bf16 v[2:5], v[174:177], v[190:193], v[2:5]
	v_mfma_f32_16x16x32_bf16 v[14:17], v[166:169], v[198:201], v[14:17]
	v_mfma_f32_16x16x32_bf16 v[6:9], v[174:177], v[198:201], v[6:9]
	v_mfma_f32_16x16x32_bf16 v[22:25], v[166:169], v[206:209], v[22:25]
	v_mfma_f32_16x16x32_bf16 v[18:21], v[174:177], v[206:209], v[18:21]
	v_mfma_f32_16x16x32_bf16 v[38:41], v[166:169], v[214:217], v[38:41]
	v_mfma_f32_16x16x32_bf16 v[26:29], v[174:177], v[214:217], v[26:29]
	s_setprio 0
	s_barrier
	s_mov_b32 m0, s33
	s_add_u32 s46, s10, 0x100000
	ds_read_b128 v[186:189], v142 offset:16384
	ds_read_b128 v[190:193], v142 offset:17408
	global_load_lds_dwordx4 v180, s[10:11]
	ds_read_b128 v[194:197], v142 offset:18432
	s_mov_b32 m0, s34
	s_addc_u32 s47, s11, 0
	global_load_lds_dwordx4 v134, s[10:11]
	ds_read_b128 v[198:201], v142 offset:19456
	s_mov_b32 m0, s35
	s_nop 0
	global_load_lds_dwordx4 v180, s[46:47]
	ds_read_b128 v[202:205], v142 offset:20480
	s_mov_b32 m0, s42
	s_nop 0
	global_load_lds_dwordx4 v134, s[46:47]
	ds_read_b128 v[206:209], v142 offset:21504
	s_add_u32 s50, s16, s4
	s_addc_u32 s51, s17, s5
	s_mov_b32 m0, s27
	s_nop 0
	global_load_lds_dwordx4 v130, s[16:17]
	ds_read_b128 v[210:213], v142 offset:22528
	s_mov_b32 m0, s28
	s_nop 0
	global_load_lds_dwordx4 v132, s[16:17]
	ds_read_b128 v[214:217], v142 offset:23552
	s_waitcnt vmcnt(8)
	s_waitcnt lgkmcnt(0)
	s_barrier
	s_setprio 1
	s_waitcnt lgkmcnt(0)
	v_mfma_f32_16x16x32_bf16 v[94:97], v[146:149], v[186:189], v[94:97]
	v_mfma_f32_16x16x32_bf16 v[86:89], v[154:157], v[186:189], v[86:89]
	v_mfma_f32_16x16x32_bf16 v[102:105], v[146:149], v[194:197], v[102:105]
	v_mfma_f32_16x16x32_bf16 v[98:101], v[154:157], v[194:197], v[98:101]
	v_mfma_f32_16x16x32_bf16 v[110:113], v[146:149], v[202:205], v[110:113]
	v_mfma_f32_16x16x32_bf16 v[106:109], v[154:157], v[202:205], v[106:109]
	v_mfma_f32_16x16x32_bf16 v[126:129], v[146:149], v[210:213], v[126:129]
	v_mfma_f32_16x16x32_bf16 v[122:125], v[154:157], v[210:213], v[122:125]
	v_mfma_f32_16x16x32_bf16 v[94:97], v[150:153], v[190:193], v[94:97]
	v_mfma_f32_16x16x32_bf16 v[86:89], v[158:161], v[190:193], v[86:89]
	v_mfma_f32_16x16x32_bf16 v[102:105], v[150:153], v[198:201], v[102:105]
	v_mfma_f32_16x16x32_bf16 v[98:101], v[158:161], v[198:201], v[98:101]
	v_mfma_f32_16x16x32_bf16 v[110:113], v[150:153], v[206:209], v[110:113]
	v_mfma_f32_16x16x32_bf16 v[106:109], v[158:161], v[206:209], v[106:109]
	v_mfma_f32_16x16x32_bf16 v[126:129], v[150:153], v[214:217], v[126:129]
	v_mfma_f32_16x16x32_bf16 v[122:125], v[158:161], v[214:217], v[122:125]
	s_setprio 0
	s_setprio 1
	v_mfma_f32_16x16x32_bf16 v[58:61], v[162:165], v[186:189], v[58:61]
	v_mfma_f32_16x16x32_bf16 v[46:49], v[170:173], v[186:189], v[46:49]
	v_mfma_f32_16x16x32_bf16 v[74:77], v[162:165], v[194:197], v[74:77]
	v_mfma_f32_16x16x32_bf16 v[66:69], v[170:173], v[194:197], v[66:69]
	v_mfma_f32_16x16x32_bf16 v[90:93], v[162:165], v[202:205], v[90:93]
	v_mfma_f32_16x16x32_bf16 v[82:85], v[170:173], v[202:205], v[82:85]
	v_mfma_f32_16x16x32_bf16 v[118:121], v[162:165], v[210:213], v[118:121]
	v_mfma_f32_16x16x32_bf16 v[114:117], v[170:173], v[210:213], v[114:117]
	v_mfma_f32_16x16x32_bf16 v[58:61], v[166:169], v[190:193], v[58:61]
	v_mfma_f32_16x16x32_bf16 v[46:49], v[174:177], v[190:193], v[46:49]
	v_mfma_f32_16x16x32_bf16 v[74:77], v[166:169], v[198:201], v[74:77]
	v_mfma_f32_16x16x32_bf16 v[66:69], v[174:177], v[198:201], v[66:69]
	v_mfma_f32_16x16x32_bf16 v[90:93], v[166:169], v[206:209], v[90:93]
	v_mfma_f32_16x16x32_bf16 v[82:85], v[174:177], v[206:209], v[82:85]
	v_mfma_f32_16x16x32_bf16 v[118:121], v[166:169], v[214:217], v[118:121]
	v_mfma_f32_16x16x32_bf16 v[114:117], v[174:177], v[214:217], v[114:117]
	s_setprio 0
	s_barrier
; #define PG8_STAGE(bufoff, gbase, voff) do { _Pragma("unroll") for (int _i = 0; _i < 2; ++_i) \
;         __builtin_amdgcn_global_load_lds((const unsigned*)((const char*)(gbase) + (voff)[_i]), (LAS unsigned*)(lds + (bufoff) + ldsw + _i * 8192), 16, 0, 0); } while (0)
; #define PG8_LDA(dst, b, h) do { _Pragma("unroll") for (int m = 0; m < 4; ++m) _Pragma("unroll") for (int k = 0; k < 2; ++k) dst[m][k] = *(const LAS bf16x8*)(lds + PG8_SA(b, h) + aoff + m * 2048 + k * 1024); } while (0)
; #define PG8_LDB(dst, b, h) do { _Pragma("unroll") for (int n = 0; n < 2; ++n) _Pragma("unroll") for (int k = 0; k < 2; ++k) dst[n][k] = *(const LAS bf16x8*)(lds + PG8_SB(b, h) + boff + n * 2048 + k * 1024); } while (0)
; #define PG8_MMA(ai, bj, At, Bt) do { __builtin_amdgcn_s_setprio(1); _Pragma("unroll") for (int m = 0; m < 4; ++m) _Pragma("unroll") for (int n = 0; n < 2; ++n) _Pragma("unroll") for (int k = 0; k < 2; ++k) \
;         acc[ai][bj][m][n] = __builtin_amdgcn_mfma_f32_16x16x32_bf16(Bt[n][k], At[m][k], acc[ai][bj][m][n], 0, 0, 0); __builtin_amdgcn_s_setprio(0); } while (0)
; #define PG8_WAIT_V(n) asm volatile("s_waitcnt vmcnt(" #n ")" ::: "memory")
; #define PG8_WAIT_L(n) asm volatile("s_waitcnt lgkmcnt(" #n ")" ::: "memory")
; #define PG8_BAR __builtin_amdgcn_s_barrier()
; #define PG8_SCHED __builtin_amdgcn_sched_barrier(0)
; template <class Epi, class Sched, bool ALIGN_EPI, class Hook = NoHook>
; __device__ __forceinline__ void gemm_phase(LAS unsigned char* lds, const Gemm g, const Sched& S, const Epi& E, const Hook& H = Hook()) {
;     ...
;         for (int t = tb; t < te; t += 2) {
;             const bool last = (t == nt - 2);
;     ...
;             PG8_LDB(B0, 1, 0); PG8_LDB(B1, 1, 1); PG8_SCHED; PG8_LDA(At, 1, 0); PG8_STAGE(PG8_SA(0, 1), a2 + hA, voffA);
;             PG8_WAIT_V(8); PG8_WAIT_L(0); PG8_BAR; PG8_MMA(0, 0, At, B0); PG8_MMA(0, 1, At, B1); PG8_BAR; PG8_SCHED;
;             PG8_LDA(At, 1, 1); PG8_STAGE(PG8_SB(1, 0), b3, voffB); PG8_STAGE(PG8_SB(1, 1), b3 + hB, voffB); PG8_STAGE(PG8_SA(1, 0), a3, voffA);
;             PG8_WAIT_V(8); PG8_WAIT_L(0); PG8_BAR; PG8_MMA(1, 0, At, B0); PG8_MMA(1, 1, At, B1); PG8_BAR; PG8_SCHED;
	ds_read_b128 v[146:149], v143
	ds_read_b128 v[150:153], v143 offset:1024
	s_add_u32 s16, s16, 0x100000
	s_addc_u32 s17, s17, 0
	s_mov_b32 m0, s29
	s_nop 0
	global_load_lds_dwordx4 v130, s[16:17]
	ds_read_b128 v[154:157], v143 offset:2048
	ds_read_b128 v[158:161], v143 offset:3072
	ds_read_b128 v[162:165], v144
	ds_read_b128 v[166:169], v144 offset:1024
	ds_read_b128 v[170:173], v144 offset:2048
	ds_read_b128 v[174:177], v144 offset:3072
	ds_read_b128 v[186:189], v142 offset:32768
	s_mov_b32 m0, s39
	s_nop 0
	global_load_lds_dwordx4 v132, s[16:17]
	ds_read_b128 v[190:193], v142 offset:33792
	ds_read_b128 v[194:197], v142 offset:34816
	ds_read_b128 v[198:201], v142 offset:35840
	ds_read_b128 v[202:205], v142 offset:36864
	ds_read_b128 v[206:209], v142 offset:37888
	ds_read_b128 v[210:213], v142 offset:38912
	ds_read_b128 v[214:217], v142 offset:39936
	s_waitcnt vmcnt(8)
	s_waitcnt lgkmcnt(0)
	s_barrier
	s_setprio 1
	s_waitcnt lgkmcnt(0)
	v_mfma_f32_16x16x32_bf16 v[54:57], v[146:149], v[186:189], v[54:57]
	v_mfma_f32_16x16x32_bf16 v[34:37], v[154:157], v[186:189], v[34:37]
	v_mfma_f32_16x16x32_bf16 v[42:45], v[146:149], v[194:197], v[42:45]
	v_mfma_f32_16x16x32_bf16 v[30:33], v[154:157], v[194:197], v[30:33]
	v_mfma_f32_16x16x32_bf16 v[62:65], v[146:149], v[202:205], v[62:65]
	v_mfma_f32_16x16x32_bf16 v[50:53], v[154:157], v[202:205], v[50:53]
	v_mfma_f32_16x16x32_bf16 v[78:81], v[146:149], v[210:213], v[78:81]
	v_mfma_f32_16x16x32_bf16 v[70:73], v[154:157], v[210:213], v[70:73]
	v_mfma_f32_16x16x32_bf16 v[54:57], v[150:153], v[190:193], v[54:57]
	v_mfma_f32_16x16x32_bf16 v[34:37], v[158:161], v[190:193], v[34:37]
	v_mfma_f32_16x16x32_bf16 v[42:45], v[150:153], v[198:201], v[42:45]
	v_mfma_f32_16x16x32_bf16 v[30:33], v[158:161], v[198:201], v[30:33]
	v_mfma_f32_16x16x32_bf16 v[62:65], v[150:153], v[206:209], v[62:65]
	v_mfma_f32_16x16x32_bf16 v[50:53], v[158:161], v[206:209], v[50:53]
	v_mfma_f32_16x16x32_bf16 v[78:81], v[150:153], v[214:217], v[78:81]
	v_mfma_f32_16x16x32_bf16 v[70:73], v[158:161], v[214:217], v[70:73]
	s_setprio 0
	s_setprio 1
	v_mfma_f32_16x16x32_bf16 v[10:13], v[162:165], v[186:189], v[10:13]
	v_mfma_f32_16x16x32_bf16 v[2:5], v[170:173], v[186:189], v[2:5]
	v_mfma_f32_16x16x32_bf16 v[14:17], v[162:165], v[194:197], v[14:17]
	v_mfma_f32_16x16x32_bf16 v[6:9], v[170:173], v[194:197], v[6:9]
	v_mfma_f32_16x16x32_bf16 v[22:25], v[162:165], v[202:205], v[22:25]
	v_mfma_f32_16x16x32_bf16 v[18:21], v[170:173], v[202:205], v[18:21]
	v_mfma_f32_16x16x32_bf16 v[38:41], v[162:165], v[210:213], v[38:41]
	v_mfma_f32_16x16x32_bf16 v[26:29], v[170:173], v[210:213], v[26:29]
	v_mfma_f32_16x16x32_bf16 v[10:13], v[166:169], v[190:193], v[10:13]
	v_mfma_f32_16x16x32_bf16 v[2:5], v[174:177], v[190:193], v[2:5]
	v_mfma_f32_16x16x32_bf16 v[14:17], v[166:169], v[198:201], v[14:17]
	v_mfma_f32_16x16x32_bf16 v[6:9], v[174:177], v[198:201], v[6:9]
	v_mfma_f32_16x16x32_bf16 v[22:25], v[166:169], v[206:209], v[22:25]
	v_mfma_f32_16x16x32_bf16 v[18:21], v[174:177], v[206:209], v[18:21]
	v_mfma_f32_16x16x32_bf16 v[38:41], v[166:169], v[214:217], v[38:41]
	v_mfma_f32_16x16x32_bf16 v[26:29], v[174:177], v[214:217], v[26:29]
	s_setprio 0
	s_barrier
	s_mov_b32 m0, s36
	s_add_u32 s48, s10, s4
	s_addc_u32 s49, s11, s5
	s_add_u32 s10, s10, 0x100080
	ds_read_b128 v[186:189], v142 offset:49152
	ds_read_b128 v[190:193], v142 offset:50176
	global_load_lds_dwordx4 v180, s[48:49]
	ds_read_b128 v[194:197], v142 offset:51200
	s_mov_b32 m0, s43
	s_addc_u32 s11, s11, 0
	global_load_lds_dwordx4 v134, s[48:49]
	ds_read_b128 v[198:201], v142 offset:52224
	s_mov_b32 m0, s37
	s_nop 0
	global_load_lds_dwordx4 v180, s[10:11]
	ds_read_b128 v[202:205], v142 offset:53248
	s_mov_b32 m0, s44
	s_nop 0
	global_load_lds_dwordx4 v134, s[10:11]
	ds_read_b128 v[206:209], v142 offset:54272
	s_mov_b32 m0, s40
	s_nop 0
	global_load_lds_dwordx4 v130, s[50:51]
	ds_read_b128 v[210:213], v142 offset:55296
	s_mov_b32 m0, s41
	s_nop 0
	global_load_lds_dwordx4 v132, s[50:51]
	ds_read_b128 v[214:217], v142 offset:56320
	s_waitcnt vmcnt(8)
	s_waitcnt lgkmcnt(0)
	s_barrier
	s_setprio 1
	s_waitcnt lgkmcnt(0)
	v_mfma_f32_16x16x32_bf16 v[94:97], v[146:149], v[186:189], v[94:97]
	v_mfma_f32_16x16x32_bf16 v[86:89], v[154:157], v[186:189], v[86:89]
	v_mfma_f32_16x16x32_bf16 v[102:105], v[146:149], v[194:197], v[102:105]
	v_mfma_f32_16x16x32_bf16 v[98:101], v[154:157], v[194:197], v[98:101]
	v_mfma_f32_16x16x32_bf16 v[110:113], v[146:149], v[202:205], v[110:113]
	v_mfma_f32_16x16x32_bf16 v[106:109], v[154:157], v[202:205], v[106:109]
	v_mfma_f32_16x16x32_bf16 v[126:129], v[146:149], v[210:213], v[126:129]
	v_mfma_f32_16x16x32_bf16 v[122:125], v[154:157], v[210:213], v[122:125]
	v_mfma_f32_16x16x32_bf16 v[94:97], v[150:153], v[190:193], v[94:97]
	v_mfma_f32_16x16x32_bf16 v[86:89], v[158:161], v[190:193], v[86:89]
	v_mfma_f32_16x16x32_bf16 v[102:105], v[150:153], v[198:201], v[102:105]
	v_mfma_f32_16x16x32_bf16 v[98:101], v[158:161], v[198:201], v[98:101]
	v_mfma_f32_16x16x32_bf16 v[110:113], v[150:153], v[206:209], v[110:113]
	v_mfma_f32_16x16x32_bf16 v[106:109], v[158:161], v[206:209], v[106:109]
	v_mfma_f32_16x16x32_bf16 v[126:129], v[150:153], v[214:217], v[126:129]
	v_mfma_f32_16x16x32_bf16 v[122:125], v[158:161], v[214:217], v[122:125]
	s_setprio 0
	s_setprio 1
	v_mfma_f32_16x16x32_bf16 v[58:61], v[162:165], v[186:189], v[58:61]
	v_mfma_f32_16x16x32_bf16 v[46:49], v[170:173], v[186:189], v[46:49]
	v_mfma_f32_16x16x32_bf16 v[74:77], v[162:165], v[194:197], v[74:77]
	v_mfma_f32_16x16x32_bf16 v[66:69], v[170:173], v[194:197], v[66:69]
	v_mfma_f32_16x16x32_bf16 v[90:93], v[162:165], v[202:205], v[90:93]
	v_mfma_f32_16x16x32_bf16 v[82:85], v[170:173], v[202:205], v[82:85]
	v_mfma_f32_16x16x32_bf16 v[118:121], v[162:165], v[210:213], v[118:121]
	v_mfma_f32_16x16x32_bf16 v[114:117], v[170:173], v[210:213], v[114:117]
	v_mfma_f32_16x16x32_bf16 v[58:61], v[166:169], v[190:193], v[58:61]
	v_mfma_f32_16x16x32_bf16 v[46:49], v[174:177], v[190:193], v[46:49]
	v_mfma_f32_16x16x32_bf16 v[74:77], v[166:169], v[198:201], v[74:77]
	v_mfma_f32_16x16x32_bf16 v[66:69], v[174:177], v[198:201], v[66:69]
	v_mfma_f32_16x16x32_bf16 v[90:93], v[166:169], v[206:209], v[90:93]
	v_mfma_f32_16x16x32_bf16 v[82:85], v[174:177], v[206:209], v[82:85]
	v_mfma_f32_16x16x32_bf16 v[118:121], v[166:169], v[214:217], v[118:121]
	v_mfma_f32_16x16x32_bf16 v[114:117], v[174:177], v[214:217], v[114:117]
	s_setprio 0
	s_add_i32 s18, s18, 2
	s_add_u32 s6, s6, 0x100
	s_addc_u32 s7, s7, 0
	s_cmp_gt_u32 s18, 61
	s_cbranch_scc0 .LBB0_896
	s_barrier
	s_cmpk_lt_u32 s22, 0x100
	s_cbranch_scc0 .LBB0_899
	s_barrier

;     __host__ __device__ bool next(int i, Unit& u) const { const bool ok = StaticOrder::next(i >> 1, u); if (i & 1) { u.ka = D_INNER; u.nkt = D_ATT / BK; } else { u.ka = 0; u.nkt = D_INNER / BK; } return ok; }
;     __host__ __device__ bool next(int i, Unit& u) const { const long L = (long)i * G + c; if (L >= (long)nM * nS) return false; u.pm = (int)(L % nM); u.pn = 0; u.ka = (int)(L / nM) * kslab; u.nkt = kslab / BK; return true; }
;     __host__ __device__ bool next(int i, Unit& u) const { if (i > 0) return false; const int x = c & 7, j = c >> 3; u.pm = 16 * s + 4 * (x >> 1) + (j & 3); u.pn = 8 * (x & 1) + (j >> 2); u.ka = 0; u.nkt = nkt; return true; }
; template <class Epi, class Sched, bool ALIGN_EPI, class Hook = NoHook>
; __device__ __forceinline__ void gemm_phase(LAS unsigned char* lds, const Gemm g, const Sched& S, const Epi& E, const Hook& H = Hook()) {
;     ...
;         const bool has_next = S.next(ui + 1, nxt);
;         const char* nA = has_next ? (const char*)g.A + (size_t)nxt.pm * tA + (size_t)nxt.ka * 2 : cA; const char* nB = has_next ? (const char*)g.Bt + (size_t)nxt.pn * 2 * hB + (size_t)nxt.ka * 2 : cB;
;         const int nt = cur.nkt;
;         for (int tb = 0; tb < nt; tb += (Hook::ON ? Hook::SEG : nt)) {
;         const int te = Hook::ON ? tb + Hook::SEG : nt;
;     ...
; #pragma unroll
;         for (int a = 0; a < 2; ++a)
; #pragma unroll
;             for (int b = 0; b < 2; ++b)
; #pragma unroll
;                 for (int m = 0; m < 4; ++m)
; #pragma unroll
;                     for (int n = 0; n < 2; ++n) acc[a][b][m][n] = (f32x4){0.f, 0.f, 0.f, 0.f};
;         cur = nxt; cA = nA; cB = nB; ++ui;
.LBB0_1000:
	s_ashr_i32 s35, s34, 31
	s_lshl_b64 s[36:37], s[34:35], 21
	s_add_u32 s36, s8, s36
	s_addc_u32 s37, s9, s37
	s_and_b64 s[38:39], s[4:5], exec
	s_cselect_b32 s35, s37, s7
	s_cselect_b32 s66, s36, s6
	s_ashr_i32 s31, s30, 31
	s_lshl_b64 s[38:39], s[30:31], 21
	v_readlane_b32 s31, v254, 52
	s_add_u32 s38, s31, s38
	v_readlane_b32 s31, v254, 53
	s_addc_u32 s39, s31, s39
	s_and_b64 s[44:45], s[4:5], exec
	s_cselect_b32 s31, s39, s43
	s_cselect_b32 s67, s38, s42
	s_add_u32 s68, s42, 0x100
	v_mov_b32_e32 v178, 0
	s_addc_u32 s69, s43, 0
	s_mov_b32 s70, -2
	v_mov_b32_e32 v179, v178
	v_mov_b32_e32 v180, v178
	v_mov_b32_e32 v181, v178
	v_mov_b32_e32 v98, v178
	v_mov_b32_e32 v99, v178
	v_mov_b32_e32 v100, v178
	v_mov_b32_e32 v101, v178
	v_mov_b32_e32 v174, v178
	v_mov_b32_e32 v175, v178
	v_mov_b32_e32 v176, v178
	v_mov_b32_e32 v177, v178
	v_mov_b32_e32 v94, v178
	v_mov_b32_e32 v95, v178
	v_mov_b32_e32 v96, v178
	v_mov_b32_e32 v97, v178
	v_mov_b32_e32 v10, v178
	v_mov_b32_e32 v11, v178
	v_mov_b32_e32 v12, v178
	v_mov_b32_e32 v13, v178
	v_mov_b32_e32 v14, v178
	v_mov_b32_e32 v15, v178
	v_mov_b32_e32 v16, v178
	v_mov_b32_e32 v17, v178
	v_mov_b32_e32 v2, v178
	v_mov_b32_e32 v3, v178
	v_mov_b32_e32 v4, v178
	v_mov_b32_e32 v5, v178
	v_mov_b32_e32 v6, v178
	v_mov_b32_e32 v7, v178
	v_mov_b32_e32 v8, v178
	v_mov_b32_e32 v9, v178
	v_mov_b32_e32 v26, v178
	v_mov_b32_e32 v27, v178
	v_mov_b32_e32 v28, v178
	v_mov_b32_e32 v29, v178
	v_mov_b32_e32 v30, v178
	v_mov_b32_e32 v31, v178
	v_mov_b32_e32 v32, v178
	v_mov_b32_e32 v33, v178
	v_mov_b32_e32 v18, v178
	v_mov_b32_e32 v19, v178
	v_mov_b32_e32 v20, v178
	v_mov_b32_e32 v21, v178
	v_mov_b32_e32 v34, v178
	v_mov_b32_e32 v35, v178
	v_mov_b32_e32 v36, v178
	v_mov_b32_e32 v37, v178
	v_mov_b32_e32 v50, v178
	v_mov_b32_e32 v51, v178
	v_mov_b32_e32 v52, v178
	v_mov_b32_e32 v53, v178
	v_mov_b32_e32 v58, v178
	v_mov_b32_e32 v59, v178
	v_mov_b32_e32 v60, v178
	v_mov_b32_e32 v61, v178
	v_mov_b32_e32 v38, v178
	v_mov_b32_e32 v39, v178
	v_mov_b32_e32 v40, v178
	v_mov_b32_e32 v41, v178
	v_mov_b32_e32 v42, v178
	v_mov_b32_e32 v43, v178
	v_mov_b32_e32 v44, v178
	v_mov_b32_e32 v45, v178
	v_mov_b32_e32 v22, v178
	v_mov_b32_e32 v23, v178
	v_mov_b32_e32 v24, v178
	v_mov_b32_e32 v25, v178
	v_mov_b32_e32 v46, v178
	v_mov_b32_e32 v47, v178
	v_mov_b32_e32 v48, v178
	v_mov_b32_e32 v49, v178
	v_mov_b32_e32 v54, v178
	v_mov_b32_e32 v55, v178
	v_mov_b32_e32 v56, v178
	v_mov_b32_e32 v57, v178
	v_mov_b32_e32 v62, v178
	v_mov_b32_e32 v63, v178
	v_mov_b32_e32 v64, v178
	v_mov_b32_e32 v65, v178
	v_mov_b32_e32 v66, v178
	v_mov_b32_e32 v67, v178
	v_mov_b32_e32 v68, v178
	v_mov_b32_e32 v69, v178
	v_mov_b32_e32 v74, v178
	v_mov_b32_e32 v75, v178
	v_mov_b32_e32 v76, v178
	v_mov_b32_e32 v77, v178
	v_mov_b32_e32 v82, v178
	v_mov_b32_e32 v83, v178
	v_mov_b32_e32 v84, v178
	v_mov_b32_e32 v85, v178
	v_mov_b32_e32 v90, v178
	v_mov_b32_e32 v91, v178
	v_mov_b32_e32 v92, v178
	v_mov_b32_e32 v93, v178
	v_mov_b32_e32 v166, v178
	v_mov_b32_e32 v167, v178
	v_mov_b32_e32 v168, v178
	v_mov_b32_e32 v169, v178
	v_mov_b32_e32 v186, v178
	v_mov_b32_e32 v187, v178
	v_mov_b32_e32 v188, v178
	v_mov_b32_e32 v189, v178
	v_mov_b32_e32 v70, v178
	v_mov_b32_e32 v71, v178
	v_mov_b32_e32 v72, v178
	v_mov_b32_e32 v73, v178
	v_mov_b32_e32 v78, v178
	v_mov_b32_e32 v79, v178
	v_mov_b32_e32 v80, v178
	v_mov_b32_e32 v81, v178
	v_mov_b32_e32 v86, v178
	v_mov_b32_e32 v87, v178
	v_mov_b32_e32 v88, v178
	v_mov_b32_e32 v89, v178
	v_mov_b32_e32 v102, v178
	v_mov_b32_e32 v103, v178
	v_mov_b32_e32 v104, v178
	v_mov_b32_e32 v105, v178
	v_mov_b32_e32 v182, v178
	v_mov_b32_e32 v183, v178
	v_mov_b32_e32 v184, v178
	v_mov_b32_e32 v185, v178
	v_mov_b32_e32 v190, v178
	v_mov_b32_e32 v191, v178
	v_mov_b32_e32 v192, v178
	v_mov_b32_e32 v193, v178
	s_branch .Lmy_r1001E

; #define PG8_STAGE(bufoff, gbase, voff) do { _Pragma("unroll") for (int _i = 0; _i < 2; ++_i) \
;         __builtin_amdgcn_global_load_lds((const unsigned*)((const char*)(gbase) + (voff)[_i]), (LAS unsigned*)(lds + (bufoff) + ldsw + _i * 8192), 16, 0, 0); } while (0)
; #define PG8_LDA(dst, b, h) do { _Pragma("unroll") for (int m = 0; m < 4; ++m) _Pragma("unroll") for (int k = 0; k < 2; ++k) dst[m][k] = *(const LAS bf16x8*)(lds + PG8_SA(b, h) + aoff + m * 2048 + k * 1024); } while (0)
; #define PG8_LDB(dst, b, h) do { _Pragma("unroll") for (int n = 0; n < 2; ++n) _Pragma("unroll") for (int k = 0; k < 2; ++k) dst[n][k] = *(const LAS bf16x8*)(lds + PG8_SB(b, h) + boff + n * 2048 + k * 1024); } while (0)
; #define PG8_MMA(ai, bj, At, Bt) do { __builtin_amdgcn_s_setprio(1); _Pragma("unroll") for (int m = 0; m < 4; ++m) _Pragma("unroll") for (int n = 0; n < 2; ++n) _Pragma("unroll") for (int k = 0; k < 2; ++k) \
;         acc[ai][bj][m][n] = __builtin_amdgcn_mfma_f32_16x16x32_bf16(Bt[n][k], At[m][k], acc[ai][bj][m][n], 0, 0, 0); __builtin_amdgcn_s_setprio(0); } while (0)
; #define PG8_WAIT_V(n) asm volatile("s_waitcnt vmcnt(" #n ")" ::: "memory")
; #define PG8_WAIT_L(n) asm volatile("s_waitcnt lgkmcnt(" #n ")" ::: "memory")
; #define PG8_BAR __builtin_amdgcn_s_barrier()
; #define PG8_SCHED __builtin_amdgcn_sched_barrier(0)
; template <class Epi, class Sched, bool ALIGN_EPI, class Hook = NoHook>
; __device__ __forceinline__ void gemm_phase(LAS unsigned char* lds, const Gemm g, const Sched& S, const Epi& E, const Hook& H = Hook()) {
;     ...
;             const char* a1 = cA + (size_t)(t + 1) * kstep;
;             const char* a2 = last ? nA : cA + (size_t)(t + 2) * kstep; const char* b2 = last ? nB : cB + (size_t)(t + 2) * kstep;
;             const char* a3 = a2 + kstep; const char* b3 = b2 + kstep;
;             if (last && has_next) S.a_ready(nxt);
;             PG8_LDB(B0, 0, 0); PG8_LDB(B1, 0, 1); PG8_SCHED; PG8_LDA(At, 0, 0); PG8_STAGE(PG8_SA(1, 1), a1 + hA, voffA);
;             PG8_WAIT_V(8); PG8_WAIT_L(0); PG8_BAR; PG8_MMA(0, 0, At, B0); PG8_MMA(0, 1, At, B1); PG8_BAR; PG8_SCHED;
;             PG8_LDA(At, 0, 1); PG8_STAGE(PG8_SB(0, 0), b2, voffB); PG8_STAGE(PG8_SB(0, 1), b2 + hB, voffB); PG8_STAGE(PG8_SA(0, 0), a2, voffA);
;             PG8_WAIT_V(8); PG8_WAIT_L(0); PG8_BAR; PG8_MMA(1, 0, At, B0); PG8_MMA(1, 1, At, B1); PG8_BAR; PG8_SCHED;
.Lmy_r1001E:
	ds_read_b128 v[106:109], v246
	ds_read_b128 v[110:113], v246 offset:1024
	s_add_u32 s42, s6, 0x100
	s_addc_u32 s43, s7, 0
	s_cmp_eq_u32 s70, 60
	s_cselect_b32 s47, s35, s43
	s_cselect_b32 s46, s66, s42
	s_cselect_b32 s45, s31, s69
	s_cselect_b32 s44, s67, s68
	s_add_i32 m0, s51, 0xc000
	s_nop 0
	global_load_lds_dwordx4 v236, s[6:7]
	ds_read_b128 v[114:117], v246 offset:2048
	ds_read_b128 v[118:121], v246 offset:3072
	ds_read_b128 v[122:125], v247
	ds_read_b128 v[126:129], v247 offset:1024
	ds_read_b128 v[130:133], v247 offset:2048
	ds_read_b128 v[134:137], v247 offset:3072
	ds_read_b128 v[138:141], v248
	s_add_i32 m0, s51, 0xe000
	s_nop 0
	global_load_lds_dwordx4 v238, s[6:7]
	ds_read_b128 v[142:145], v248 offset:1024
	ds_read_b128 v[146:149], v248 offset:2048
	ds_read_b128 v[150:153], v248 offset:3072
	ds_read_b128 v[154:157], v248 offset:4096
	ds_read_b128 v[158:161], v248 offset:5120
	ds_read_b128 v[162:165], v248 offset:6144
	ds_read_b128 v[170:173], v248 offset:7168
	s_waitcnt vmcnt(8)
	s_waitcnt lgkmcnt(0)
	s_barrier
	s_setprio 1
	s_waitcnt lgkmcnt(0)
	v_mfma_f32_16x16x32_bf16 v[190:193], v[106:109], v[138:141], v[190:193]
	v_mfma_f32_16x16x32_bf16 v[178:181], v[114:117], v[138:141], v[178:181]
	v_mfma_f32_16x16x32_bf16 v[182:185], v[106:109], v[146:149], v[182:185]
	v_mfma_f32_16x16x32_bf16 v[98:101], v[114:117], v[146:149], v[98:101]
	v_mfma_f32_16x16x32_bf16 v[102:105], v[106:109], v[154:157], v[102:105]
	v_mfma_f32_16x16x32_bf16 v[86:89], v[114:117], v[154:157], v[86:89]
	v_mfma_f32_16x16x32_bf16 v[78:81], v[106:109], v[162:165], v[78:81]
	v_mfma_f32_16x16x32_bf16 v[70:73], v[114:117], v[162:165], v[70:73]
	v_mfma_f32_16x16x32_bf16 v[190:193], v[110:113], v[142:145], v[190:193]
	v_mfma_f32_16x16x32_bf16 v[178:181], v[118:121], v[142:145], v[178:181]
	v_mfma_f32_16x16x32_bf16 v[182:185], v[110:113], v[150:153], v[182:185]
	v_mfma_f32_16x16x32_bf16 v[98:101], v[118:121], v[150:153], v[98:101]
	v_mfma_f32_16x16x32_bf16 v[102:105], v[110:113], v[158:161], v[102:105]
	v_mfma_f32_16x16x32_bf16 v[86:89], v[118:121], v[158:161], v[86:89]
	v_mfma_f32_16x16x32_bf16 v[78:81], v[110:113], v[170:173], v[78:81]
	v_mfma_f32_16x16x32_bf16 v[70:73], v[118:121], v[170:173], v[70:73]
	s_setprio 0
	s_setprio 1
	v_mfma_f32_16x16x32_bf16 v[186:189], v[122:125], v[138:141], v[186:189]
	v_mfma_f32_16x16x32_bf16 v[138:141], v[130:133], v[138:141], v[174:177]
	v_mfma_f32_16x16x32_bf16 v[94:97], v[130:133], v[146:149], v[94:97]
	v_mfma_f32_16x16x32_bf16 v[90:93], v[122:125], v[154:157], v[90:93]
	v_mfma_f32_16x16x32_bf16 v[82:85], v[130:133], v[154:157], v[82:85]
	v_mfma_f32_16x16x32_bf16 v[74:77], v[122:125], v[162:165], v[74:77]
	v_mfma_f32_16x16x32_bf16 v[66:69], v[130:133], v[162:165], v[66:69]
	v_mfma_f32_16x16x32_bf16 v[186:189], v[126:129], v[142:145], v[186:189]
	v_mfma_f32_16x16x32_bf16 v[138:141], v[134:137], v[142:145], v[138:141]
	v_mfma_f32_16x16x32_bf16 v[142:145], v[122:125], v[146:149], v[166:169]
	v_mfma_f32_16x16x32_bf16 v[94:97], v[134:137], v[150:153], v[94:97]
	v_mfma_f32_16x16x32_bf16 v[90:93], v[126:129], v[158:161], v[90:93]
	v_mfma_f32_16x16x32_bf16 v[82:85], v[134:137], v[158:161], v[82:85]
	v_mfma_f32_16x16x32_bf16 v[74:77], v[126:129], v[170:173], v[74:77]
	v_mfma_f32_16x16x32_bf16 v[66:69], v[134:137], v[170:173], v[66:69]
	v_mfma_f32_16x16x32_bf16 v[142:145], v[126:129], v[150:153], v[142:145]
	s_setprio 0
	s_barrier
	s_add_i32 s6, s63, s29
	s_mov_b32 m0, s6
	ds_read_b128 v[146:149], v248 offset:16384
	ds_read_b128 v[150:153], v248 offset:17408
	global_load_lds_dwordx4 v232, s[44:45]
	ds_read_b128 v[154:157], v248 offset:18432
	s_add_i32 m0, s6, 0x2000
	s_add_u32 s6, s44, 0x100000
	s_addc_u32 s7, s45, 0
	s_add_i32 s71, s64, s29
	global_load_lds_dwordx4 v228, s[44:45]
	ds_read_b128 v[158:161], v248 offset:19456
	s_mov_b32 m0, s71
	s_nop 0
	global_load_lds_dwordx4 v232, s[6:7]
	ds_read_b128 v[162:165], v248 offset:20480
	s_add_i32 m0, s71, 0x2000
	s_nop 0
	global_load_lds_dwordx4 v228, s[6:7]
	ds_read_b128 v[166:169], v248 offset:21504
	s_mov_b32 m0, s51
	s_nop 0
	global_load_lds_dwordx4 v234, s[46:47]
	ds_read_b128 v[170:173], v248 offset:22528
	s_mov_b32 m0, s52
	s_nop 0
	global_load_lds_dwordx4 v230, s[46:47]
	ds_read_b128 v[174:177], v248 offset:23552
	s_waitcnt vmcnt(8)
	s_waitcnt lgkmcnt(0)
	s_barrier
	s_setprio 1
	s_waitcnt lgkmcnt(0)
	v_mfma_f32_16x16x32_bf16 v[62:65], v[106:109], v[146:149], v[62:65]
	v_mfma_f32_16x16x32_bf16 v[54:57], v[114:117], v[146:149], v[54:57]
	v_mfma_f32_16x16x32_bf16 v[46:49], v[106:109], v[154:157], v[46:49]
	v_mfma_f32_16x16x32_bf16 v[22:25], v[114:117], v[154:157], v[22:25]
	v_mfma_f32_16x16x32_bf16 v[42:45], v[106:109], v[162:165], v[42:45]
	v_mfma_f32_16x16x32_bf16 v[10:13], v[114:117], v[162:165], v[10:13]
	v_mfma_f32_16x16x32_bf16 v[38:41], v[106:109], v[170:173], v[38:41]
	v_mfma_f32_16x16x32_bf16 v[14:17], v[114:117], v[170:173], v[14:17]
	v_mfma_f32_16x16x32_bf16 v[62:65], v[110:113], v[150:153], v[62:65]
	v_mfma_f32_16x16x32_bf16 v[54:57], v[118:121], v[150:153], v[54:57]
	v_mfma_f32_16x16x32_bf16 v[46:49], v[110:113], v[158:161], v[46:49]
	v_mfma_f32_16x16x32_bf16 v[22:25], v[118:121], v[158:161], v[22:25]
	v_mfma_f32_16x16x32_bf16 v[42:45], v[110:113], v[166:169], v[42:45]
	v_mfma_f32_16x16x32_bf16 v[10:13], v[118:121], v[166:169], v[10:13]
	v_mfma_f32_16x16x32_bf16 v[38:41], v[110:113], v[174:177], v[38:41]
	v_mfma_f32_16x16x32_bf16 v[14:17], v[118:121], v[174:177], v[14:17]
	s_setprio 0
	s_setprio 1
	v_mfma_f32_16x16x32_bf16 v[58:61], v[122:125], v[146:149], v[58:61]
	v_mfma_f32_16x16x32_bf16 v[50:53], v[130:133], v[146:149], v[50:53]
	v_mfma_f32_16x16x32_bf16 v[34:37], v[122:125], v[154:157], v[34:37]
	v_mfma_f32_16x16x32_bf16 v[18:21], v[130:133], v[154:157], v[18:21]
	v_mfma_f32_16x16x32_bf16 v[30:33], v[122:125], v[162:165], v[30:33]
	v_mfma_f32_16x16x32_bf16 v[2:5], v[130:133], v[162:165], v[2:5]
	v_mfma_f32_16x16x32_bf16 v[26:29], v[122:125], v[170:173], v[26:29]
	v_mfma_f32_16x16x32_bf16 v[6:9], v[130:133], v[170:173], v[6:9]
	v_mfma_f32_16x16x32_bf16 v[58:61], v[126:129], v[150:153], v[58:61]
	v_mfma_f32_16x16x32_bf16 v[50:53], v[134:137], v[150:153], v[50:53]
	v_mfma_f32_16x16x32_bf16 v[34:37], v[126:129], v[158:161], v[34:37]
	v_mfma_f32_16x16x32_bf16 v[18:21], v[134:137], v[158:161], v[18:21]
	v_mfma_f32_16x16x32_bf16 v[30:33], v[126:129], v[166:169], v[30:33]
	v_mfma_f32_16x16x32_bf16 v[2:5], v[134:137], v[166:169], v[2:5]
	v_mfma_f32_16x16x32_bf16 v[26:29], v[126:129], v[174:177], v[26:29]
	v_mfma_f32_16x16x32_bf16 v[6:9], v[134:137], v[174:177], v[6:9]
	s_setprio 0
	s_barrier
; #define PG8_STAGE(bufoff, gbase, voff) do { _Pragma("unroll") for (int _i = 0; _i < 2; ++_i) \
;         __builtin_amdgcn_global_load_lds((const unsigned*)((const char*)(gbase) + (voff)[_i]), (LAS unsigned*)(lds + (bufoff) + ldsw + _i * 8192), 16, 0, 0); } while (0)
; #define PG8_LDA(dst, b, h) do { _Pragma("unroll") for (int m = 0; m < 4; ++m) _Pragma("unroll") for (int k = 0; k < 2; ++k) dst[m][k] = *(const LAS bf16x8*)(lds + PG8_SA(b, h) + aoff + m * 2048 + k * 1024); } while (0)
; #define PG8_LDB(dst, b, h) do { _Pragma("unroll") for (int n = 0; n < 2; ++n) _Pragma("unroll") for (int k = 0; k < 2; ++k) dst[n][k] = *(const LAS bf16x8*)(lds + PG8_SB(b, h) + boff + n * 2048 + k * 1024); } while (0)
; #define PG8_MMA(ai, bj, At, Bt) do { __builtin_amdgcn_s_setprio(1); _Pragma("unroll") for (int m = 0; m < 4; ++m) _Pragma("unroll") for (int n = 0; n < 2; ++n) _Pragma("unroll") for (int k = 0; k < 2; ++k) \
;         acc[ai][bj][m][n] = __builtin_amdgcn_mfma_f32_16x16x32_bf16(Bt[n][k], At[m][k], acc[ai][bj][m][n], 0, 0, 0); __builtin_amdgcn_s_setprio(0); } while (0)
; #define PG8_WAIT_V(n) asm volatile("s_waitcnt vmcnt(" #n ")" ::: "memory")
; #define PG8_WAIT_L(n) asm volatile("s_waitcnt lgkmcnt(" #n ")" ::: "memory")
; #define PG8_BAR __builtin_amdgcn_s_barrier()
; #define PG8_SCHED __builtin_amdgcn_sched_barrier(0)
; template <class Epi, class Sched, bool ALIGN_EPI, class Hook = NoHook>
; __device__ __forceinline__ void gemm_phase(LAS unsigned char* lds, const Gemm g, const Sched& S, const Epi& E, const Hook& H = Hook()) {
;     ...
;         for (int t = tb; t < te; t += 2) {
;             const bool last = (t == nt - 2);
;     ...
;             PG8_LDB(B0, 1, 0); PG8_LDB(B1, 1, 1); PG8_SCHED; PG8_LDA(At, 1, 0); PG8_STAGE(PG8_SA(0, 1), a2 + hA, voffA);
;             PG8_WAIT_V(8); PG8_WAIT_L(0); PG8_BAR; PG8_MMA(0, 0, At, B0); PG8_MMA(0, 1, At, B1); PG8_BAR; PG8_SCHED;
;             PG8_LDA(At, 1, 1); PG8_STAGE(PG8_SB(1, 0), b3, voffB); PG8_STAGE(PG8_SB(1, 1), b3 + hB, voffB); PG8_STAGE(PG8_SA(1, 0), a3, voffA);
;             PG8_WAIT_V(8); PG8_WAIT_L(0); PG8_BAR; PG8_MMA(1, 0, At, B0); PG8_MMA(1, 1, At, B1); PG8_BAR; PG8_SCHED;
	s_add_i32 s71, 0, 0x18000
	s_add_i32 s72, 0, 0x1c000
	v_add_u32_e32 v118, s71, v245
	v_add_u32_e32 v134, s72, v245
	ds_read_b128 v[106:109], v118
	ds_read_b128 v[110:113], v118 offset:1024
	s_add_u32 s6, s46, 0x8000
	s_addc_u32 s7, s47, 0
	s_mov_b32 m0, s53
	s_nop 0
	global_load_lds_dwordx4 v234, s[6:7]
	ds_read_b128 v[114:117], v118 offset:2048
	ds_read_b128 v[118:121], v118 offset:3072
	ds_read_b128 v[122:125], v134
	ds_read_b128 v[126:129], v134 offset:1024
	ds_read_b128 v[130:133], v134 offset:2048
	ds_read_b128 v[134:137], v134 offset:3072
	ds_read_b128 v[146:149], v248 offset:32768
	s_mov_b32 m0, s54
	s_nop 0
	global_load_lds_dwordx4 v230, s[6:7]
	ds_read_b128 v[150:153], v248 offset:33792
	ds_read_b128 v[154:157], v248 offset:34816
	ds_read_b128 v[158:161], v248 offset:35840
	ds_read_b128 v[162:165], v248 offset:36864
	ds_read_b128 v[170:173], v248 offset:37888
	ds_read_b128 v[194:197], v248 offset:38912
	ds_read_b128 v[198:201], v248 offset:39936
	s_waitcnt vmcnt(8)
	s_waitcnt lgkmcnt(0)
	s_barrier
	s_setprio 1
	s_waitcnt lgkmcnt(0)
	v_mfma_f32_16x16x32_bf16 v[166:169], v[106:109], v[146:149], v[190:193]
	v_mfma_f32_16x16x32_bf16 v[190:193], v[110:113], v[150:153], v[166:169]
	v_mfma_f32_16x16x32_bf16 v[166:169], v[114:117], v[146:149], v[178:181]
	v_mfma_f32_16x16x32_bf16 v[178:181], v[118:121], v[150:153], v[166:169]
	v_mfma_f32_16x16x32_bf16 v[166:169], v[106:109], v[154:157], v[182:185]
	v_mfma_f32_16x16x32_bf16 v[98:101], v[114:117], v[154:157], v[98:101]
	v_mfma_f32_16x16x32_bf16 v[102:105], v[106:109], v[162:165], v[102:105]
	v_mfma_f32_16x16x32_bf16 v[86:89], v[114:117], v[162:165], v[86:89]
	v_mfma_f32_16x16x32_bf16 v[78:81], v[106:109], v[194:197], v[78:81]
	v_mfma_f32_16x16x32_bf16 v[70:73], v[114:117], v[194:197], v[70:73]
	v_mfma_f32_16x16x32_bf16 v[182:185], v[110:113], v[158:161], v[166:169]
	v_mfma_f32_16x16x32_bf16 v[98:101], v[118:121], v[158:161], v[98:101]
	v_mfma_f32_16x16x32_bf16 v[102:105], v[110:113], v[170:173], v[102:105]
	v_mfma_f32_16x16x32_bf16 v[86:89], v[118:121], v[170:173], v[86:89]
	v_mfma_f32_16x16x32_bf16 v[78:81], v[110:113], v[198:201], v[78:81]
	v_mfma_f32_16x16x32_bf16 v[70:73], v[118:121], v[198:201], v[70:73]
	s_setprio 0
	s_setprio 1
	v_mfma_f32_16x16x32_bf16 v[138:141], v[130:133], v[146:149], v[138:141]
	v_mfma_f32_16x16x32_bf16 v[166:169], v[122:125], v[146:149], v[186:189]
	v_mfma_f32_16x16x32_bf16 v[174:177], v[134:137], v[150:153], v[138:141]
	v_mfma_f32_16x16x32_bf16 v[138:141], v[122:125], v[154:157], v[142:145]
	v_mfma_f32_16x16x32_bf16 v[94:97], v[130:133], v[154:157], v[94:97]
	v_mfma_f32_16x16x32_bf16 v[90:93], v[122:125], v[162:165], v[90:93]
	v_mfma_f32_16x16x32_bf16 v[82:85], v[130:133], v[162:165], v[82:85]
	v_mfma_f32_16x16x32_bf16 v[74:77], v[122:125], v[194:197], v[74:77]
	v_mfma_f32_16x16x32_bf16 v[66:69], v[130:133], v[194:197], v[66:69]
	v_mfma_f32_16x16x32_bf16 v[186:189], v[126:129], v[150:153], v[166:169]
	v_mfma_f32_16x16x32_bf16 v[166:169], v[126:129], v[158:161], v[138:141]
	v_mfma_f32_16x16x32_bf16 v[94:97], v[134:137], v[158:161], v[94:97]
	v_mfma_f32_16x16x32_bf16 v[90:93], v[126:129], v[170:173], v[90:93]
	v_mfma_f32_16x16x32_bf16 v[82:85], v[134:137], v[170:173], v[82:85]
	v_mfma_f32_16x16x32_bf16 v[74:77], v[126:129], v[198:201], v[74:77]
	v_mfma_f32_16x16x32_bf16 v[66:69], v[134:137], v[198:201], v[66:69]
	s_setprio 0
	s_barrier
	s_add_i32 s6, s71, s29
	s_add_u32 s74, s44, s14
	s_addc_u32 s75, s45, s15
	s_mov_b32 m0, s6
	ds_read_b128 v[138:141], v248 offset:49152
	ds_read_b128 v[142:145], v248 offset:50176
	global_load_lds_dwordx4 v232, s[74:75]
	ds_read_b128 v[146:149], v248 offset:51200
	s_add_i32 m0, s6, 0x2000
	s_add_u32 s6, s44, 0x100080
	s_addc_u32 s7, s45, 0
	s_add_i32 s44, s72, s29
	global_load_lds_dwordx4 v228, s[74:75]
	ds_read_b128 v[150:153], v248 offset:52224
	s_mov_b32 m0, s44
	s_nop 0
	global_load_lds_dwordx4 v232, s[6:7]
	ds_read_b128 v[154:157], v248 offset:53248
	s_add_i32 m0, s44, 0x2000
	s_nop 0
	global_load_lds_dwordx4 v228, s[6:7]
	ds_read_b128 v[158:161], v248 offset:54272
	s_add_u32 s78, s46, s14
	s_addc_u32 s79, s47, s15
	s_mov_b32 m0, s57
	s_nop 0
	global_load_lds_dwordx4 v234, s[78:79]
	ds_read_b128 v[162:165], v248 offset:55296
	s_mov_b32 m0, s58
	s_nop 0
	global_load_lds_dwordx4 v230, s[78:79]
	ds_read_b128 v[170:173], v248 offset:56320
	s_waitcnt vmcnt(8)
	s_waitcnt lgkmcnt(0)
	s_barrier
	s_setprio 1
	s_waitcnt lgkmcnt(0)
	v_mfma_f32_16x16x32_bf16 v[62:65], v[106:109], v[138:141], v[62:65]
	v_mfma_f32_16x16x32_bf16 v[54:57], v[114:117], v[138:141], v[54:57]
	v_mfma_f32_16x16x32_bf16 v[46:49], v[106:109], v[146:149], v[46:49]
	v_mfma_f32_16x16x32_bf16 v[22:25], v[114:117], v[146:149], v[22:25]
	v_mfma_f32_16x16x32_bf16 v[42:45], v[106:109], v[154:157], v[42:45]
	v_mfma_f32_16x16x32_bf16 v[10:13], v[114:117], v[154:157], v[10:13]
	v_mfma_f32_16x16x32_bf16 v[38:41], v[106:109], v[162:165], v[38:41]
	v_mfma_f32_16x16x32_bf16 v[14:17], v[114:117], v[162:165], v[14:17]
	v_mfma_f32_16x16x32_bf16 v[62:65], v[110:113], v[142:145], v[62:65]
	v_mfma_f32_16x16x32_bf16 v[54:57], v[118:121], v[142:145], v[54:57]
	v_mfma_f32_16x16x32_bf16 v[46:49], v[110:113], v[150:153], v[46:49]
	v_mfma_f32_16x16x32_bf16 v[22:25], v[118:121], v[150:153], v[22:25]
	v_mfma_f32_16x16x32_bf16 v[42:45], v[110:113], v[158:161], v[42:45]
	v_mfma_f32_16x16x32_bf16 v[10:13], v[118:121], v[158:161], v[10:13]
	v_mfma_f32_16x16x32_bf16 v[38:41], v[110:113], v[170:173], v[38:41]
	v_mfma_f32_16x16x32_bf16 v[14:17], v[118:121], v[170:173], v[14:17]
	s_setprio 0
	s_setprio 1
	v_mfma_f32_16x16x32_bf16 v[58:61], v[122:125], v[138:141], v[58:61]
	v_mfma_f32_16x16x32_bf16 v[50:53], v[130:133], v[138:141], v[50:53]
	v_mfma_f32_16x16x32_bf16 v[34:37], v[122:125], v[146:149], v[34:37]
	v_mfma_f32_16x16x32_bf16 v[18:21], v[130:133], v[146:149], v[18:21]
	v_mfma_f32_16x16x32_bf16 v[30:33], v[122:125], v[154:157], v[30:33]
	v_mfma_f32_16x16x32_bf16 v[2:5], v[130:133], v[154:157], v[2:5]
	v_mfma_f32_16x16x32_bf16 v[26:29], v[122:125], v[162:165], v[26:29]
	v_mfma_f32_16x16x32_bf16 v[6:9], v[130:133], v[162:165], v[6:9]
	v_mfma_f32_16x16x32_bf16 v[58:61], v[126:129], v[142:145], v[58:61]
	v_mfma_f32_16x16x32_bf16 v[50:53], v[134:137], v[142:145], v[50:53]
	v_mfma_f32_16x16x32_bf16 v[34:37], v[126:129], v[150:153], v[34:37]
	v_mfma_f32_16x16x32_bf16 v[18:21], v[134:137], v[150:153], v[18:21]
	v_mfma_f32_16x16x32_bf16 v[30:33], v[126:129], v[158:161], v[30:33]
	v_mfma_f32_16x16x32_bf16 v[2:5], v[134:137], v[158:161], v[2:5]
	v_mfma_f32_16x16x32_bf16 v[26:29], v[126:129], v[170:173], v[26:29]
	v_mfma_f32_16x16x32_bf16 v[6:9], v[134:137], v[170:173], v[6:9]
	s_setprio 0
	s_add_i32 s70, s70, 2
	s_add_u32 s68, s68, 0x100
	s_addc_u32 s69, s69, 0
	s_cmp_gt_u32 s70, 61
	s_mov_b64 s[6:7], s[42:43]
	s_cbranch_scc0 .LBB0_1001
	s_barrier
	s_and_b64 vcc, exec, s[2:3]
	s_cbranch_vccz .LBB0_1004
	s_barrier

;     __host__ __device__ bool next(int i, Unit& u) const { const bool ok = StaticOrder::next(i >> 1, u); if (i & 1) { u.ka = D_INNER; u.nkt = D_ATT / BK; } else { u.ka = 0; u.nkt = D_INNER / BK; } return ok; }
; #define PG8_BAR __builtin_amdgcn_s_barrier()
; template <class Epi, class Sched, bool ALIGN_EPI, class Hook = NoHook>
; __device__ __forceinline__ void gemm_phase(LAS unsigned char* lds, const Gemm g, const Sched& S, const Epi& E, const Hook& H = Hook()) {
;     ...
;     const int tid = tid_, wid = __builtin_amdgcn_readfirstlane(tid >> 6), lane = tid & 63, wr = wid >> 2, wc = wid & 3, fr = lane & 15, fq = lane >> 4;
;     unsigned voffA[2], voffB[2];
; #pragma unroll
;     for (int i = 0; i < 2; ++i) { int R, C; stage_rc(tid * 16 + i * 8192, R, C); const int Rb = Epi::PERM ? ((R & ~31) + perm32(R & 31)) : R;
;         const int Ra = Epi::APERM ? (8 * (16 * (R >> 6) + (R & 15)) + ((R >> 4) & 3)) : R;
;         voffA[i] = (unsigned)(Ra * g.lda + C) * 2u; voffB[i] = (unsigned)(Rb * g.ldb + C) * 2u; }
;     const size_t kstep = (size_t)(BK * 2);
;     const size_t hA = (size_t)(Epi::APERM ? 4 : HALF) * g.lda * 2, hB = (size_t)HALF * g.ldb * 2;
;     const size_t tA = (size_t)BM * g.lda * 2;
;     const unsigned ldsw = (unsigned)wid * 1024u;
;     const int aoff = lds_byte(wr * 64 + fr, fq * 8), boff = lds_byte(wc * 32 + fr, fq * 8);
;     ...
;     Unit cur, nxt; int ui = 0;
;     if (!S.next(0, cur)) return;
;     f32x4 acc[2][2][4][2];
; #pragma unroll
;     for (int a = 0; a < 2; ++a)
; #pragma unroll
;         for (int b = 0; b < 2; ++b)
; #pragma unroll
;             for (int m = 0; m < 4; ++m)
; #pragma unroll
;                 for (int n = 0; n < 2; ++n) acc[a][b][m][n] = (f32x4){0.f, 0.f, 0.f, 0.f};
;     bf16x8 At[4][2], B0[2][2], B1[2][2];
;     const char* cA = (const char*)g.A + (size_t)cur.pm * tA + (size_t)cur.ka * 2; const char* cB = (const char*)g.Bt + (size_t)cur.pn * 2 * hB + (size_t)cur.ka * 2;
;     S.a_ready(cur);
;     if constexpr (Hook::ON) H.unit_start(cur);
;     PG8_STAGE(PG8_SB(0, 0), cB, voffB); PG8_STAGE(PG8_SB(0, 1), cB + hB, voffB); PG8_STAGE(PG8_SA(0, 0), cA, voffA); PG8_STAGE(PG8_SA(0, 1), cA + hA, voffA);
;     if (wr == 1) PG8_BAR;
;     PG8_WAIT_V(2); PG8_BAR;
;     PG8_STAGE(PG8_SB(1, 0), cB + kstep, voffB); PG8_STAGE(PG8_SA(1, 0), cA + kstep, voffA); PG8_STAGE(PG8_SB(1, 1), cB + hB + kstep, voffB);
;     PG8_WAIT_V(6); PG8_BAR;
.LBB0_1359:
	v_and_b32_e32 v163, 15, v162
	v_and_b32_e32 v17, 48, v162
	v_lshlrev_b32_e32 v18, 2, v162
	s_and_b32 s24, s22, 3
	s_lshl_b32 s2, s23, 13
	v_lshl_or_b32 v17, v163, 6, v17
	v_and_b32_e32 v18, 32, v18
	v_bitop3_b32 v19, v17, s2, v18 bitop3:0xde
	s_lshl_b32 s2, s24, 12
	v_bitop3_b32 v17, v17, s2, v18 bitop3:0xde
	s_mov_b64 s[2:3], 0x80
	s_add_i32 m0, s25, 0x18000
	v_lshl_add_u64 v[8:9], v[8:9], 0, s[2:3]
	s_lshl_b32 s29, s23, 6
	s_waitcnt vmcnt(2)
	s_barrier
	global_load_lds_dwordx4 v[8:9], off
	v_lshl_add_u64 v[6:7], v[6:7], 0, s[2:3]
	s_add_i32 m0, s25, 0x1a000
	s_add_i32 s39, s25, 0x8000
	s_add_i32 s40, s25, 0xa000
	global_load_lds_dwordx4 v[6:7], off
	v_lshl_add_u64 v[4:5], v[4:5], 0, s[2:3]
	s_mov_b32 m0, s39
	s_add_u32 s18, s12, 0x2b0080
	global_load_lds_dwordx4 v[4:5], off
	v_lshl_add_u64 v[2:3], v[2:3], 0, s[2:3]
	s_mov_b32 m0, s40
	s_addc_u32 s19, s13, 0
	global_load_lds_dwordx4 v[2:3], off
	s_add_i32 m0, s25, 0x1c000
	v_lshl_add_u64 v[2:3], s[18:19], 0, v[132:133]
	global_load_lds_dwordx4 v[2:3], off
	v_lshl_add_u64 v[2:3], s[18:19], 0, v[136:137]
	s_add_i32 m0, s25, 0x1e000
	v_lshrrev_b32_e32 v1, 1, v1
	global_load_lds_dwordx4 v[2:3], off
	v_mul_lo_u32 v2, v11, s4
	s_mov_b32 s5, 0x2b000
	v_mad_u64_u32 v[2:3], s[20:21], v1, s5, v[2:3]
	s_bfe_u32 s15, s88, 0x20001
	s_mul_i32 s15, s15, 0x1580000
	s_mul_i32 s20, s33, 0x560000
	s_add_i32 s15, s15, s20
	v_or_b32_e32 v1, v2, v10
	s_add_u32 s20, s96, s15
	v_add_lshl_u32 v2, v1, v12, 1
	v_mov_b32_e32 v3, v133
	s_addc_u32 s21, s97, 0
	v_lshl_add_u64 v[138:139], s[20:21], 0, v[2:3]
	v_lshrrev_b32_e32 v1, 1, v13
	v_mul_lo_u32 v2, v14, s4
	v_mad_u64_u32 v[2:3], s[4:5], v1, s5, v[2:3]
	s_waitcnt vmcnt(6)
	v_or_b32_e32 v1, v2, v15
	s_add_i32 s34, 0, 0x10000
	s_add_i32 s35, 0, 0x14000
	s_add_i32 s36, 0, 0x18000
	s_add_i32 s37, 0, 0x1c000
	v_add_lshl_u32 v2, v1, v16, 1
	v_mov_b32_e32 v3, v133
	s_add_i32 s44, s34, s14
	s_add_i32 s46, s35, s14
	s_add_i32 s48, s36, s14
	s_add_i32 s50, s37, s14
	v_or_b32_e32 v169, s29, v163
	v_lshl_add_u64 v[140:141], s[20:21], 0, v[2:3]
	s_mov_b32 s41, -2
	s_mov_b64 s[4:5], 0x44fb0080
	v_add_u32_e32 v1, s34, v17
	v_add_u32_e32 v142, s35, v17
	v_add_u32_e32 v143, 0, v19
	s_add_i32 s42, s25, 0xc000
	s_add_i32 s43, s25, 0xe000
	s_add_i32 s45, s44, 0x2000
	s_add_i32 s47, s46, 0x2000
	v_add_u32_e32 v144, s36, v17
	v_add_u32_e32 v145, s37, v17
	s_add_i32 s49, s48, 0x2000
	s_add_i32 s51, s50, 0x2000
	v_mov_b32_e32 v114, v133
	v_mov_b32_e32 v115, v133
	v_mov_b32_e32 v116, v133
	v_mov_b32_e32 v117, v133
	v_mov_b32_e32 v118, v133
	v_mov_b32_e32 v119, v133
	v_mov_b32_e32 v120, v133
	v_mov_b32_e32 v121, v133
	v_mov_b32_e32 v62, v133
	v_mov_b32_e32 v63, v133
	v_mov_b32_e32 v64, v133
	v_mov_b32_e32 v65, v133
	v_mov_b32_e32 v78, v133
	v_mov_b32_e32 v79, v133
	v_mov_b32_e32 v80, v133
	v_mov_b32_e32 v81, v133
	v_mov_b32_e32 v46, v133
	v_mov_b32_e32 v47, v133
	v_mov_b32_e32 v48, v133
	v_mov_b32_e32 v49, v133
	v_mov_b32_e32 v66, v133
	v_mov_b32_e32 v67, v133
	v_mov_b32_e32 v68, v133
	v_mov_b32_e32 v69, v133
	v_mov_b32_e32 v34, v133
	v_mov_b32_e32 v35, v133
	v_mov_b32_e32 v36, v133
	v_mov_b32_e32 v37, v133
	v_mov_b32_e32 v38, v133
	v_mov_b32_e32 v39, v133
	v_mov_b32_e32 v40, v133
	v_mov_b32_e32 v41, v133
	v_mov_b32_e32 v122, v133
	v_mov_b32_e32 v123, v133
	v_mov_b32_e32 v124, v133
	v_mov_b32_e32 v125, v133
	v_mov_b32_e32 v126, v133
	v_mov_b32_e32 v127, v133
	v_mov_b32_e32 v128, v133
	v_mov_b32_e32 v129, v133
	v_mov_b32_e32 v102, v133
	v_mov_b32_e32 v103, v133
	v_mov_b32_e32 v104, v133
	v_mov_b32_e32 v105, v133
	v_mov_b32_e32 v110, v133
	v_mov_b32_e32 v111, v133
	v_mov_b32_e32 v112, v133
	v_mov_b32_e32 v113, v133
	v_mov_b32_e32 v98, v133
	v_mov_b32_e32 v99, v133
	v_mov_b32_e32 v100, v133
	v_mov_b32_e32 v101, v133
	v_mov_b32_e32 v106, v133
	v_mov_b32_e32 v107, v133
	v_mov_b32_e32 v108, v133
	v_mov_b32_e32 v109, v133
	v_mov_b32_e32 v90, v133
	v_mov_b32_e32 v91, v133
	v_mov_b32_e32 v92, v133
	v_mov_b32_e32 v93, v133
	v_mov_b32_e32 v94, v133
	v_mov_b32_e32 v95, v133
	v_mov_b32_e32 v96, v133
	v_mov_b32_e32 v97, v133
	v_mov_b32_e32 v26, v133
	v_mov_b32_e32 v27, v133
	v_mov_b32_e32 v28, v133
	v_mov_b32_e32 v29, v133
	v_mov_b32_e32 v30, v133
	v_mov_b32_e32 v31, v133
	v_mov_b32_e32 v32, v133
	v_mov_b32_e32 v33, v133
	v_mov_b32_e32 v10, v133
	v_mov_b32_e32 v11, v133
	v_mov_b32_e32 v12, v133
	v_mov_b32_e32 v13, v133
	v_mov_b32_e32 v22, v133
	v_mov_b32_e32 v23, v133
	v_mov_b32_e32 v24, v133
	v_mov_b32_e32 v25, v133
	v_mov_b32_e32 v6, v133
	v_mov_b32_e32 v7, v133
	v_mov_b32_e32 v8, v133
	v_mov_b32_e32 v9, v133
	v_mov_b32_e32 v18, v133
	v_mov_b32_e32 v19, v133
	v_mov_b32_e32 v20, v133
	v_mov_b32_e32 v21, v133
	v_mov_b32_e32 v2, v133
	v_mov_b32_e32 v4, v133
	v_mov_b32_e32 v5, v133
	v_mov_b32_e32 v14, v133
	v_mov_b32_e32 v15, v133
	v_mov_b32_e32 v16, v133
	v_mov_b32_e32 v17, v133
	v_mov_b32_e32 v74, v133
	v_mov_b32_e32 v75, v133
	v_mov_b32_e32 v76, v133
	v_mov_b32_e32 v77, v133
	v_mov_b32_e32 v86, v133
	v_mov_b32_e32 v87, v133
	v_mov_b32_e32 v88, v133
	v_mov_b32_e32 v89, v133
	v_mov_b32_e32 v50, v133
	v_mov_b32_e32 v51, v133
	v_mov_b32_e32 v52, v133
	v_mov_b32_e32 v53, v133
	v_mov_b32_e32 v70, v133
	v_mov_b32_e32 v71, v133
	v_mov_b32_e32 v72, v133
	v_mov_b32_e32 v73, v133
	v_mov_b32_e32 v42, v133
	v_mov_b32_e32 v43, v133
	v_mov_b32_e32 v44, v133
	v_mov_b32_e32 v45, v133
	v_mov_b32_e32 v58, v133
	v_mov_b32_e32 v59, v133
	v_mov_b32_e32 v60, v133
	v_mov_b32_e32 v61, v133
	v_mov_b32_e32 v54, v133
	v_mov_b32_e32 v55, v133
	v_mov_b32_e32 v56, v133
	v_mov_b32_e32 v57, v133
	v_mov_b32_e32 v82, v133
	v_mov_b32_e32 v83, v133
	v_mov_b32_e32 v84, v133
	v_mov_b32_e32 v85, v133
	s_barrier
	s_branch .Lmy_r1360E

; #define PG8_STAGE(bufoff, gbase, voff) do { _Pragma("unroll") for (int _i = 0; _i < 2; ++_i) \
;         __builtin_amdgcn_global_load_lds((const unsigned*)((const char*)(gbase) + (voff)[_i]), (LAS unsigned*)(lds + (bufoff) + ldsw + _i * 8192), 16, 0, 0); } while (0)
; #define PG8_LDA(dst, b, h) do { _Pragma("unroll") for (int m = 0; m < 4; ++m) _Pragma("unroll") for (int k = 0; k < 2; ++k) dst[m][k] = *(const LAS bf16x8*)(lds + PG8_SA(b, h) + aoff + m * 2048 + k * 1024); } while (0)
; #define PG8_LDB(dst, b, h) do { _Pragma("unroll") for (int n = 0; n < 2; ++n) _Pragma("unroll") for (int k = 0; k < 2; ++k) dst[n][k] = *(const LAS bf16x8*)(lds + PG8_SB(b, h) + boff + n * 2048 + k * 1024); } while (0)
; #define PG8_MMA(ai, bj, At, Bt) do { __builtin_amdgcn_s_setprio(1); _Pragma("unroll") for (int m = 0; m < 4; ++m) _Pragma("unroll") for (int n = 0; n < 2; ++n) _Pragma("unroll") for (int k = 0; k < 2; ++k) \
;         acc[ai][bj][m][n] = __builtin_amdgcn_mfma_f32_16x16x32_bf16(Bt[n][k], At[m][k], acc[ai][bj][m][n], 0, 0, 0); __builtin_amdgcn_s_setprio(0); } while (0)
; #define PG8_WAIT_V(n) asm volatile("s_waitcnt vmcnt(" #n ")" ::: "memory")
; #define PG8_WAIT_L(n) asm volatile("s_waitcnt lgkmcnt(" #n ")" ::: "memory")
; #define PG8_BAR __builtin_amdgcn_s_barrier()
; #define PG8_SCHED __builtin_amdgcn_sched_barrier(0)
; template <class Epi, class Sched, bool ALIGN_EPI, class Hook = NoHook>
; __device__ __forceinline__ void gemm_phase(LAS unsigned char* lds, const Gemm g, const Sched& S, const Epi& E, const Hook& H = Hook()) {
;     ...
;             PG8_LDB(B0, 0, 0); PG8_LDB(B1, 0, 1); PG8_SCHED; PG8_LDA(At, 0, 0); PG8_STAGE(PG8_SA(1, 1), a1 + hA, voffA);
;             PG8_WAIT_V(8); PG8_WAIT_L(0); PG8_BAR; PG8_MMA(0, 0, At, B0); PG8_MMA(0, 1, At, B1); PG8_BAR; PG8_SCHED;
;             PG8_LDA(At, 0, 1); PG8_STAGE(PG8_SB(0, 0), b2, voffB); PG8_STAGE(PG8_SB(0, 1), b2 + hB, voffB); PG8_STAGE(PG8_SA(0, 0), a2, voffA);
;             PG8_WAIT_V(8); PG8_WAIT_L(0); PG8_BAR; PG8_MMA(1, 0, At, B0); PG8_MMA(1, 1, At, B1); PG8_BAR; PG8_SCHED;
.Lmy_r1360E:
	ds_read_b128 v[146:149], v1
	ds_read_b128 v[150:153], v1 offset:1024
	s_add_u32 s14, s4, 0xbb050080
	s_addc_u32 s15, s5, -1
	s_cmpk_lg_i32 s41, 0xa8
	s_cselect_b32 s14, s14, 0
	s_cselect_b32 s15, s15, 0
	s_add_u32 s20, s0, s14
	s_addc_u32 s21, s1, s15
	s_add_u32 s14, s12, s14
	s_addc_u32 s15, s13, s15
	s_mov_b32 m0, s42
	ds_read_b128 v[154:157], v1 offset:2048
	ds_read_b128 v[158:161], v1 offset:3072
	ds_read_b128 v[164:167], v142
	ds_read_b128 v[170:173], v142 offset:1024
	ds_read_b128 v[174:177], v142 offset:2048
	ds_read_b128 v[178:181], v142 offset:3072
	v_lshl_add_u64 v[214:215], v[138:139], 0, s[4:5]
	global_load_lds_dwordx4 v[214:215], off
	ds_read_b128 v[182:185], v143
	ds_read_b128 v[186:189], v143 offset:1024
	ds_read_b128 v[190:193], v143 offset:2048
	ds_read_b128 v[194:197], v143 offset:3072
	ds_read_b128 v[198:201], v143 offset:4096
	ds_read_b128 v[202:205], v143 offset:5120
	ds_read_b128 v[206:209], v143 offset:6144
	ds_read_b128 v[210:213], v143 offset:7168
	v_lshl_add_u64 v[214:215], v[140:141], 0, s[4:5]
	s_mov_b32 m0, s43
	s_nop 0
	global_load_lds_dwordx4 v[214:215], off
	s_waitcnt vmcnt(8)
	s_waitcnt lgkmcnt(0)
	s_barrier
	s_setprio 1
	s_waitcnt lgkmcnt(0)
	v_mfma_f32_16x16x32_bf16 v[82:85], v[146:149], v[182:185], v[82:85]
	v_mfma_f32_16x16x32_bf16 v[54:57], v[154:157], v[182:185], v[54:57]
	v_mfma_f32_16x16x32_bf16 v[58:61], v[146:149], v[190:193], v[58:61]
	v_mfma_f32_16x16x32_bf16 v[42:45], v[154:157], v[190:193], v[42:45]
	v_mfma_f32_16x16x32_bf16 v[70:73], v[146:149], v[198:201], v[70:73]
	v_mfma_f32_16x16x32_bf16 v[50:53], v[154:157], v[198:201], v[50:53]
	v_mfma_f32_16x16x32_bf16 v[86:89], v[146:149], v[206:209], v[86:89]
	v_mfma_f32_16x16x32_bf16 v[74:77], v[154:157], v[206:209], v[74:77]
	v_mfma_f32_16x16x32_bf16 v[82:85], v[150:153], v[186:189], v[82:85]
	v_mfma_f32_16x16x32_bf16 v[54:57], v[158:161], v[186:189], v[54:57]
	v_mfma_f32_16x16x32_bf16 v[58:61], v[150:153], v[194:197], v[58:61]
	v_mfma_f32_16x16x32_bf16 v[42:45], v[158:161], v[194:197], v[42:45]
	v_mfma_f32_16x16x32_bf16 v[70:73], v[150:153], v[202:205], v[70:73]
	v_mfma_f32_16x16x32_bf16 v[50:53], v[158:161], v[202:205], v[50:53]
	v_mfma_f32_16x16x32_bf16 v[86:89], v[150:153], v[210:213], v[86:89]
	v_mfma_f32_16x16x32_bf16 v[74:77], v[158:161], v[210:213], v[74:77]
	s_setprio 0
	s_setprio 1
	v_mfma_f32_16x16x32_bf16 v[14:17], v[164:167], v[182:185], v[14:17]
	v_mfma_f32_16x16x32_bf16 v[2:5], v[174:177], v[182:185], v[2:5]
	v_mfma_f32_16x16x32_bf16 v[18:21], v[164:167], v[190:193], v[18:21]
	v_mfma_f32_16x16x32_bf16 v[6:9], v[174:177], v[190:193], v[6:9]
	v_mfma_f32_16x16x32_bf16 v[22:25], v[164:167], v[198:201], v[22:25]
	v_mfma_f32_16x16x32_bf16 v[10:13], v[174:177], v[198:201], v[10:13]
	v_mfma_f32_16x16x32_bf16 v[30:33], v[164:167], v[206:209], v[30:33]
	v_mfma_f32_16x16x32_bf16 v[26:29], v[174:177], v[206:209], v[26:29]
	v_mfma_f32_16x16x32_bf16 v[14:17], v[170:173], v[186:189], v[14:17]
	v_mfma_f32_16x16x32_bf16 v[2:5], v[178:181], v[186:189], v[2:5]
	v_mfma_f32_16x16x32_bf16 v[18:21], v[170:173], v[194:197], v[18:21]
	v_mfma_f32_16x16x32_bf16 v[6:9], v[178:181], v[194:197], v[6:9]
	v_mfma_f32_16x16x32_bf16 v[22:25], v[170:173], v[202:205], v[22:25]
	v_mfma_f32_16x16x32_bf16 v[10:13], v[178:181], v[202:205], v[10:13]
	v_mfma_f32_16x16x32_bf16 v[30:33], v[170:173], v[210:213], v[30:33]
	v_mfma_f32_16x16x32_bf16 v[26:29], v[178:181], v[210:213], v[26:29]
	s_setprio 0
	s_barrier
	s_mov_b32 m0, s44
	s_add_u32 s52, s14, 0x2b0000
	ds_read_b128 v[182:185], v143 offset:16384
	ds_read_b128 v[186:189], v143 offset:17408
	global_load_lds_dwordx4 v132, s[14:15]
	ds_read_b128 v[190:193], v143 offset:18432
	s_mov_b32 m0, s45
	s_addc_u32 s53, s15, 0
	global_load_lds_dwordx4 v136, s[14:15]
	ds_read_b128 v[194:197], v143 offset:19456
	s_mov_b32 m0, s46
	s_nop 0
	global_load_lds_dwordx4 v132, s[52:53]
	ds_read_b128 v[198:201], v143 offset:20480
	s_mov_b32 m0, s47
	s_nop 0
	global_load_lds_dwordx4 v136, s[52:53]
	ds_read_b128 v[202:205], v143 offset:21504
	s_add_u32 s56, s20, s2
	s_addc_u32 s57, s21, s3
	s_mov_b32 m0, s25
	s_nop 0
	global_load_lds_dwordx4 v130, s[20:21]
	ds_read_b128 v[206:209], v143 offset:22528
	s_mov_b32 m0, s27
	s_nop 0
	global_load_lds_dwordx4 v134, s[20:21]
	ds_read_b128 v[210:213], v143 offset:23552
	s_waitcnt vmcnt(8)
	s_waitcnt lgkmcnt(0)
	s_barrier
	s_setprio 1
	s_waitcnt lgkmcnt(0)
	v_mfma_f32_16x16x32_bf16 v[94:97], v[146:149], v[182:185], v[94:97]
	v_mfma_f32_16x16x32_bf16 v[90:93], v[154:157], v[182:185], v[90:93]
	v_mfma_f32_16x16x32_bf16 v[106:109], v[146:149], v[190:193], v[106:109]
	v_mfma_f32_16x16x32_bf16 v[98:101], v[154:157], v[190:193], v[98:101]
	v_mfma_f32_16x16x32_bf16 v[110:113], v[146:149], v[198:201], v[110:113]
	v_mfma_f32_16x16x32_bf16 v[102:105], v[154:157], v[198:201], v[102:105]
	v_mfma_f32_16x16x32_bf16 v[126:129], v[146:149], v[206:209], v[126:129]
	v_mfma_f32_16x16x32_bf16 v[122:125], v[154:157], v[206:209], v[122:125]
	v_mfma_f32_16x16x32_bf16 v[94:97], v[150:153], v[186:189], v[94:97]
	v_mfma_f32_16x16x32_bf16 v[90:93], v[158:161], v[186:189], v[90:93]
	v_mfma_f32_16x16x32_bf16 v[106:109], v[150:153], v[194:197], v[106:109]
	v_mfma_f32_16x16x32_bf16 v[98:101], v[158:161], v[194:197], v[98:101]
	v_mfma_f32_16x16x32_bf16 v[110:113], v[150:153], v[202:205], v[110:113]
	v_mfma_f32_16x16x32_bf16 v[102:105], v[158:161], v[202:205], v[102:105]
	v_mfma_f32_16x16x32_bf16 v[126:129], v[150:153], v[210:213], v[126:129]
	v_mfma_f32_16x16x32_bf16 v[122:125], v[158:161], v[210:213], v[122:125]
	s_setprio 0
	s_setprio 1
	v_mfma_f32_16x16x32_bf16 v[38:41], v[164:167], v[182:185], v[38:41]
	v_mfma_f32_16x16x32_bf16 v[34:37], v[174:177], v[182:185], v[34:37]
	v_mfma_f32_16x16x32_bf16 v[66:69], v[164:167], v[190:193], v[66:69]
	v_mfma_f32_16x16x32_bf16 v[46:49], v[174:177], v[190:193], v[46:49]
	v_mfma_f32_16x16x32_bf16 v[78:81], v[164:167], v[198:201], v[78:81]
	v_mfma_f32_16x16x32_bf16 v[62:65], v[174:177], v[198:201], v[62:65]
	v_mfma_f32_16x16x32_bf16 v[118:121], v[164:167], v[206:209], v[118:121]
	v_mfma_f32_16x16x32_bf16 v[114:117], v[174:177], v[206:209], v[114:117]
	v_mfma_f32_16x16x32_bf16 v[38:41], v[170:173], v[186:189], v[38:41]
	v_mfma_f32_16x16x32_bf16 v[34:37], v[178:181], v[186:189], v[34:37]
	v_mfma_f32_16x16x32_bf16 v[66:69], v[170:173], v[194:197], v[66:69]
	v_mfma_f32_16x16x32_bf16 v[46:49], v[178:181], v[194:197], v[46:49]
	v_mfma_f32_16x16x32_bf16 v[78:81], v[170:173], v[202:205], v[78:81]
	v_mfma_f32_16x16x32_bf16 v[62:65], v[178:181], v[202:205], v[62:65]
	v_mfma_f32_16x16x32_bf16 v[118:121], v[170:173], v[210:213], v[118:121]
	v_mfma_f32_16x16x32_bf16 v[114:117], v[178:181], v[210:213], v[114:117]
	s_setprio 0
	s_barrier
; #define PG8_STAGE(bufoff, gbase, voff) do { _Pragma("unroll") for (int _i = 0; _i < 2; ++_i) \
;         __builtin_amdgcn_global_load_lds((const unsigned*)((const char*)(gbase) + (voff)[_i]), (LAS unsigned*)(lds + (bufoff) + ldsw + _i * 8192), 16, 0, 0); } while (0)
; #define PG8_LDA(dst, b, h) do { _Pragma("unroll") for (int m = 0; m < 4; ++m) _Pragma("unroll") for (int k = 0; k < 2; ++k) dst[m][k] = *(const LAS bf16x8*)(lds + PG8_SA(b, h) + aoff + m * 2048 + k * 1024); } while (0)
; #define PG8_LDB(dst, b, h) do { _Pragma("unroll") for (int n = 0; n < 2; ++n) _Pragma("unroll") for (int k = 0; k < 2; ++k) dst[n][k] = *(const LAS bf16x8*)(lds + PG8_SB(b, h) + boff + n * 2048 + k * 1024); } while (0)
; #define PG8_MMA(ai, bj, At, Bt) do { __builtin_amdgcn_s_setprio(1); _Pragma("unroll") for (int m = 0; m < 4; ++m) _Pragma("unroll") for (int n = 0; n < 2; ++n) _Pragma("unroll") for (int k = 0; k < 2; ++k) \
;         acc[ai][bj][m][n] = __builtin_amdgcn_mfma_f32_16x16x32_bf16(Bt[n][k], At[m][k], acc[ai][bj][m][n], 0, 0, 0); __builtin_amdgcn_s_setprio(0); } while (0)
; #define PG8_WAIT_V(n) asm volatile("s_waitcnt vmcnt(" #n ")" ::: "memory")
; #define PG8_WAIT_L(n) asm volatile("s_waitcnt lgkmcnt(" #n ")" ::: "memory")
; #define PG8_BAR __builtin_amdgcn_s_barrier()
; #define PG8_SCHED __builtin_amdgcn_sched_barrier(0)
; template <class Epi, class Sched, bool ALIGN_EPI, class Hook = NoHook>
; __device__ __forceinline__ void gemm_phase(LAS unsigned char* lds, const Gemm g, const Sched& S, const Epi& E, const Hook& H = Hook()) {
;     ...
;         for (int t = tb; t < te; t += 2) {
;             const bool last = (t == nt - 2);
;     ...
;             PG8_LDB(B0, 1, 0); PG8_LDB(B1, 1, 1); PG8_SCHED; PG8_LDA(At, 1, 0); PG8_STAGE(PG8_SA(0, 1), a2 + hA, voffA);
;             PG8_WAIT_V(8); PG8_WAIT_L(0); PG8_BAR; PG8_MMA(0, 0, At, B0); PG8_MMA(0, 1, At, B1); PG8_BAR; PG8_SCHED;
;             PG8_LDA(At, 1, 1); PG8_STAGE(PG8_SB(1, 0), b3, voffB); PG8_STAGE(PG8_SB(1, 1), b3 + hB, voffB); PG8_STAGE(PG8_SA(1, 0), a3, voffA);
;             PG8_WAIT_V(8); PG8_WAIT_L(0); PG8_BAR; PG8_MMA(1, 0, At, B0); PG8_MMA(1, 1, At, B1); PG8_BAR; PG8_SCHED;
	ds_read_b128 v[146:149], v144
	ds_read_b128 v[150:153], v144 offset:1024
	s_add_u32 s20, s20, 0x2b0000
	s_addc_u32 s21, s21, 0
	s_mov_b32 m0, s28
	s_nop 0
	global_load_lds_dwordx4 v130, s[20:21]
	ds_read_b128 v[154:157], v144 offset:2048
	ds_read_b128 v[158:161], v144 offset:3072
	ds_read_b128 v[164:167], v145
	ds_read_b128 v[170:173], v145 offset:1024
	ds_read_b128 v[174:177], v145 offset:2048
	ds_read_b128 v[178:181], v145 offset:3072
	ds_read_b128 v[182:185], v143 offset:32768
	s_mov_b32 m0, s38
	s_nop 0
	global_load_lds_dwordx4 v134, s[20:21]
	ds_read_b128 v[186:189], v143 offset:33792
	ds_read_b128 v[190:193], v143 offset:34816
	ds_read_b128 v[194:197], v143 offset:35840
	ds_read_b128 v[198:201], v143 offset:36864
	ds_read_b128 v[202:205], v143 offset:37888
	ds_read_b128 v[206:209], v143 offset:38912
	ds_read_b128 v[210:213], v143 offset:39936
	s_waitcnt vmcnt(8)
	s_waitcnt lgkmcnt(0)
	s_barrier
	s_setprio 1
	s_waitcnt lgkmcnt(0)
	v_mfma_f32_16x16x32_bf16 v[82:85], v[146:149], v[182:185], v[82:85]
	v_mfma_f32_16x16x32_bf16 v[54:57], v[154:157], v[182:185], v[54:57]
	v_mfma_f32_16x16x32_bf16 v[58:61], v[146:149], v[190:193], v[58:61]
	v_mfma_f32_16x16x32_bf16 v[42:45], v[154:157], v[190:193], v[42:45]
	v_mfma_f32_16x16x32_bf16 v[70:73], v[146:149], v[198:201], v[70:73]
	v_mfma_f32_16x16x32_bf16 v[50:53], v[154:157], v[198:201], v[50:53]
	v_mfma_f32_16x16x32_bf16 v[86:89], v[146:149], v[206:209], v[86:89]
	v_mfma_f32_16x16x32_bf16 v[74:77], v[154:157], v[206:209], v[74:77]
	v_mfma_f32_16x16x32_bf16 v[82:85], v[150:153], v[186:189], v[82:85]
	v_mfma_f32_16x16x32_bf16 v[54:57], v[158:161], v[186:189], v[54:57]
	v_mfma_f32_16x16x32_bf16 v[58:61], v[150:153], v[194:197], v[58:61]
	v_mfma_f32_16x16x32_bf16 v[42:45], v[158:161], v[194:197], v[42:45]
	v_mfma_f32_16x16x32_bf16 v[70:73], v[150:153], v[202:205], v[70:73]
	v_mfma_f32_16x16x32_bf16 v[50:53], v[158:161], v[202:205], v[50:53]
	v_mfma_f32_16x16x32_bf16 v[86:89], v[150:153], v[210:213], v[86:89]
	v_mfma_f32_16x16x32_bf16 v[74:77], v[158:161], v[210:213], v[74:77]
	s_setprio 0
	s_setprio 1
	v_mfma_f32_16x16x32_bf16 v[14:17], v[164:167], v[182:185], v[14:17]
	v_mfma_f32_16x16x32_bf16 v[2:5], v[174:177], v[182:185], v[2:5]
	v_mfma_f32_16x16x32_bf16 v[18:21], v[164:167], v[190:193], v[18:21]
	v_mfma_f32_16x16x32_bf16 v[6:9], v[174:177], v[190:193], v[6:9]
	v_mfma_f32_16x16x32_bf16 v[22:25], v[164:167], v[198:201], v[22:25]
	v_mfma_f32_16x16x32_bf16 v[10:13], v[174:177], v[198:201], v[10:13]
	v_mfma_f32_16x16x32_bf16 v[30:33], v[164:167], v[206:209], v[30:33]
	v_mfma_f32_16x16x32_bf16 v[26:29], v[174:177], v[206:209], v[26:29]
	v_mfma_f32_16x16x32_bf16 v[14:17], v[170:173], v[186:189], v[14:17]
	v_mfma_f32_16x16x32_bf16 v[2:5], v[178:181], v[186:189], v[2:5]
	v_mfma_f32_16x16x32_bf16 v[18:21], v[170:173], v[194:197], v[18:21]
	v_mfma_f32_16x16x32_bf16 v[6:9], v[178:181], v[194:197], v[6:9]
	v_mfma_f32_16x16x32_bf16 v[22:25], v[170:173], v[202:205], v[22:25]
	v_mfma_f32_16x16x32_bf16 v[10:13], v[178:181], v[202:205], v[10:13]
	v_mfma_f32_16x16x32_bf16 v[30:33], v[170:173], v[210:213], v[30:33]
	v_mfma_f32_16x16x32_bf16 v[26:29], v[178:181], v[210:213], v[26:29]
	s_setprio 0
	s_barrier
	s_mov_b32 m0, s48
	s_add_u32 s54, s14, s2
	s_addc_u32 s55, s15, s3
	s_add_u32 s14, s14, 0x2b0080
	ds_read_b128 v[182:185], v143 offset:49152
	ds_read_b128 v[186:189], v143 offset:50176
	global_load_lds_dwordx4 v132, s[54:55]
	ds_read_b128 v[190:193], v143 offset:51200
	s_mov_b32 m0, s49
	s_addc_u32 s15, s15, 0
	global_load_lds_dwordx4 v136, s[54:55]
	ds_read_b128 v[194:197], v143 offset:52224
	s_mov_b32 m0, s50
	s_nop 0
	global_load_lds_dwordx4 v132, s[14:15]
	ds_read_b128 v[198:201], v143 offset:53248
	s_mov_b32 m0, s51
	s_nop 0
	global_load_lds_dwordx4 v136, s[14:15]
	ds_read_b128 v[202:205], v143 offset:54272
	s_mov_b32 m0, s39
	s_nop 0
	global_load_lds_dwordx4 v130, s[56:57]
	ds_read_b128 v[206:209], v143 offset:55296
	s_mov_b32 m0, s40
	s_nop 0
	global_load_lds_dwordx4 v134, s[56:57]
	ds_read_b128 v[210:213], v143 offset:56320
	s_waitcnt vmcnt(8)
	s_waitcnt lgkmcnt(0)
	s_barrier
	s_setprio 1
	s_waitcnt lgkmcnt(0)
	v_mfma_f32_16x16x32_bf16 v[94:97], v[146:149], v[182:185], v[94:97]
	v_mfma_f32_16x16x32_bf16 v[90:93], v[154:157], v[182:185], v[90:93]
	v_mfma_f32_16x16x32_bf16 v[106:109], v[146:149], v[190:193], v[106:109]
	v_mfma_f32_16x16x32_bf16 v[98:101], v[154:157], v[190:193], v[98:101]
	v_mfma_f32_16x16x32_bf16 v[110:113], v[146:149], v[198:201], v[110:113]
	v_mfma_f32_16x16x32_bf16 v[102:105], v[154:157], v[198:201], v[102:105]
	v_mfma_f32_16x16x32_bf16 v[126:129], v[146:149], v[206:209], v[126:129]
	v_mfma_f32_16x16x32_bf16 v[122:125], v[154:157], v[206:209], v[122:125]
	v_mfma_f32_16x16x32_bf16 v[94:97], v[150:153], v[186:189], v[94:97]
	v_mfma_f32_16x16x32_bf16 v[90:93], v[158:161], v[186:189], v[90:93]
	v_mfma_f32_16x16x32_bf16 v[106:109], v[150:153], v[194:197], v[106:109]
	v_mfma_f32_16x16x32_bf16 v[98:101], v[158:161], v[194:197], v[98:101]
	v_mfma_f32_16x16x32_bf16 v[110:113], v[150:153], v[202:205], v[110:113]
	v_mfma_f32_16x16x32_bf16 v[102:105], v[158:161], v[202:205], v[102:105]
	v_mfma_f32_16x16x32_bf16 v[126:129], v[150:153], v[210:213], v[126:129]
	v_mfma_f32_16x16x32_bf16 v[122:125], v[158:161], v[210:213], v[122:125]
	s_setprio 0
	s_setprio 1
	v_mfma_f32_16x16x32_bf16 v[38:41], v[164:167], v[182:185], v[38:41]
	v_mfma_f32_16x16x32_bf16 v[34:37], v[174:177], v[182:185], v[34:37]
	v_mfma_f32_16x16x32_bf16 v[66:69], v[164:167], v[190:193], v[66:69]
	v_mfma_f32_16x16x32_bf16 v[46:49], v[174:177], v[190:193], v[46:49]
	v_mfma_f32_16x16x32_bf16 v[78:81], v[164:167], v[198:201], v[78:81]
	v_mfma_f32_16x16x32_bf16 v[62:65], v[174:177], v[198:201], v[62:65]
	v_mfma_f32_16x16x32_bf16 v[118:121], v[164:167], v[206:209], v[118:121]
	v_mfma_f32_16x16x32_bf16 v[114:117], v[174:177], v[206:209], v[114:117]
	v_mfma_f32_16x16x32_bf16 v[38:41], v[170:173], v[186:189], v[38:41]
	v_mfma_f32_16x16x32_bf16 v[34:37], v[178:181], v[186:189], v[34:37]
	v_mfma_f32_16x16x32_bf16 v[66:69], v[170:173], v[194:197], v[66:69]
	v_mfma_f32_16x16x32_bf16 v[46:49], v[178:181], v[194:197], v[46:49]
	v_mfma_f32_16x16x32_bf16 v[78:81], v[170:173], v[202:205], v[78:81]
	v_mfma_f32_16x16x32_bf16 v[62:65], v[178:181], v[202:205], v[62:65]
	v_mfma_f32_16x16x32_bf16 v[118:121], v[170:173], v[210:213], v[118:121]
	v_mfma_f32_16x16x32_bf16 v[114:117], v[178:181], v[210:213], v[114:117]
	s_setprio 0
	s_add_i32 s41, s41, 2
	s_add_u32 s4, s4, 0x100
	s_addc_u32 s5, s5, 0
	s_cmpk_gt_u32 s41, 0xa9
	s_cbranch_scc0 .LBB0_1360
	s_barrier
	s_cmpk_lt_u32 s26, 0x100
	s_cbranch_scc0 .LBB0_1363
	s_barrier

;     __host__ __device__ bool next(int i, Unit& u) const { const bool ok = StaticOrder::next(i >> 1, u); if (i & 1) { u.ka = D_INNER; u.nkt = D_ATT / BK; } else { u.ka = 0; u.nkt = D_INNER / BK; } return ok; }
; #define PG8_BAR __builtin_amdgcn_s_barrier()
; template <class Epi, class Sched, bool ALIGN_EPI, class Hook = NoHook>
; __device__ __forceinline__ void gemm_phase(LAS unsigned char* lds, const Gemm g, const Sched& S, const Epi& E, const Hook& H = Hook()) {
;     ...
;     const int tid = tid_, wid = __builtin_amdgcn_readfirstlane(tid >> 6), lane = tid & 63, wr = wid >> 2, wc = wid & 3, fr = lane & 15, fq = lane >> 4;
;     unsigned voffA[2], voffB[2];
; #pragma unroll
;     for (int i = 0; i < 2; ++i) { int R, C; stage_rc(tid * 16 + i * 8192, R, C); const int Rb = Epi::PERM ? ((R & ~31) + perm32(R & 31)) : R;
;         const int Ra = Epi::APERM ? (8 * (16 * (R >> 6) + (R & 15)) + ((R >> 4) & 3)) : R;
;         voffA[i] = (unsigned)(Ra * g.lda + C) * 2u; voffB[i] = (unsigned)(Rb * g.ldb + C) * 2u; }
;     const size_t kstep = (size_t)(BK * 2);
;     const size_t hA = (size_t)(Epi::APERM ? 4 : HALF) * g.lda * 2, hB = (size_t)HALF * g.ldb * 2;
;     const size_t tA = (size_t)BM * g.lda * 2;
;     const unsigned ldsw = (unsigned)wid * 1024u;
;     const int aoff = lds_byte(wr * 64 + fr, fq * 8), boff = lds_byte(wc * 32 + fr, fq * 8);
;     ...
;     Unit cur, nxt; int ui = 0;
;     if (!S.next(0, cur)) return;
;     f32x4 acc[2][2][4][2];
; #pragma unroll
;     for (int a = 0; a < 2; ++a)
; #pragma unroll
;         for (int b = 0; b < 2; ++b)
; #pragma unroll
;             for (int m = 0; m < 4; ++m)
; #pragma unroll
;                 for (int n = 0; n < 2; ++n) acc[a][b][m][n] = (f32x4){0.f, 0.f, 0.f, 0.f};
;     bf16x8 At[4][2], B0[2][2], B1[2][2];
;     const char* cA = (const char*)g.A + (size_t)cur.pm * tA + (size_t)cur.ka * 2; const char* cB = (const char*)g.Bt + (size_t)cur.pn * 2 * hB + (size_t)cur.ka * 2;
;     S.a_ready(cur);
;     if constexpr (Hook::ON) H.unit_start(cur);
;     PG8_STAGE(PG8_SB(0, 0), cB, voffB); PG8_STAGE(PG8_SB(0, 1), cB + hB, voffB); PG8_STAGE(PG8_SA(0, 0), cA, voffA); PG8_STAGE(PG8_SA(0, 1), cA + hA, voffA);
;     if (wr == 1) PG8_BAR;
;     PG8_WAIT_V(2); PG8_BAR;
;     PG8_STAGE(PG8_SB(1, 0), cB + kstep, voffB); PG8_STAGE(PG8_SA(1, 0), cA + kstep, voffA); PG8_STAGE(PG8_SB(1, 1), cB + hB + kstep, voffB);
;     PG8_WAIT_V(6); PG8_BAR;
.LBB0_1405:
	v_and_b32_e32 v164, 15, v0
	v_and_b32_e32 v18, 48, v0
	v_lshlrev_b32_e32 v19, 2, v0
	s_and_b32 s25, s23, 3
	s_lshl_b32 s2, s24, 13
	v_lshl_or_b32 v18, v164, 6, v18
	v_and_b32_e32 v19, 32, v19
	v_bitop3_b32 v20, v18, s2, v19 bitop3:0xde
	s_lshl_b32 s2, s25, 12
	v_bitop3_b32 v18, v18, s2, v19 bitop3:0xde
	s_mov_b64 s[2:3], 0x80
	s_add_i32 m0, s27, 0x18000
	v_lshl_add_u64 v[8:9], v[8:9], 0, s[2:3]
	s_waitcnt vmcnt(2)
	s_barrier
	global_load_lds_dwordx4 v[8:9], off
	v_lshl_add_u64 v[6:7], v[6:7], 0, s[2:3]
	s_add_i32 m0, s27, 0x1a000
	s_add_i32 s41, s27, 0x8000
	global_load_lds_dwordx4 v[6:7], off
	v_lshl_add_u64 v[4:5], v[4:5], 0, s[2:3]
	s_mov_b32 m0, s41
	s_add_i32 s42, s27, 0xa000
	global_load_lds_dwordx4 v[4:5], off
	v_lshl_add_u64 v[2:3], v[2:3], 0, s[2:3]
	s_mov_b32 m0, s42
	s_add_i32 s5, s31, s33
	global_load_lds_dwordx4 v[2:3], off
	s_add_i32 m0, s27, 0x1c000
	v_lshl_add_u64 v[2:3], s[18:19], 0, v[162:163]
	global_load_lds_dwordx4 v[2:3], off
	v_lshl_add_u64 v[2:3], s[18:19], 0, v[134:135]
	s_add_i32 m0, s27, 0x1e000
	s_mul_i32 s5, s5, 0x560000
	global_load_lds_dwordx4 v[2:3], off
	v_lshrrev_b32_e32 v3, 1, v10
	v_mul_lo_u32 v2, v12, s4
	s_mov_b32 s16, 0x2b000
	s_lshl_b32 s40, s24, 6
	s_add_i32 s5, s5, 0x5600000
	v_mad_u64_u32 v[2:3], s[10:11], v3, s16, v[2:3]
	v_or_b32_e32 v2, v2, v11
	s_add_u32 s10, s96, s5
	v_add_lshl_u32 v2, v2, v13, 1
	v_mov_b32_e32 v3, v163
	s_addc_u32 s11, s97, 0
	v_lshl_add_u64 v[136:137], s[10:11], 0, v[2:3]
	v_lshrrev_b32_e32 v3, 1, v14
	v_mul_lo_u32 v2, v15, s4
	v_mad_u64_u32 v[2:3], s[4:5], v3, s16, v[2:3]
	s_waitcnt vmcnt(6)
	v_or_b32_e32 v2, v2, v16
	v_add_lshl_u32 v2, v2, v17, 1
	v_mov_b32_e32 v3, v163
	v_add_u32_e32 v141, s35, v18
	s_add_i32 s33, s34, s45
	s_add_i32 s35, s35, s45
	v_add_u32_e32 v143, s36, v18
	v_add_u32_e32 v144, s37, v18
	s_add_i32 s36, s36, s45
	s_add_i32 s37, s37, s45
	v_or_b32_e32 v166, s40, v164
	v_lshl_add_u64 v[138:139], s[10:11], 0, v[2:3]
	s_mov_b32 s18, -2
	s_mov_b64 s[4:5], 0x44fb0080
	v_add_u32_e32 v140, s34, v18
	v_add_u32_e32 v142, 0, v20
	s_add_i32 s19, s27, 0xc000
	s_add_i32 s31, s27, 0xe000
	s_add_i32 s34, s33, 0x2000
	s_add_i32 s43, s35, 0x2000
	s_add_i32 s44, s36, 0x2000
	s_add_i32 s45, s37, 0x2000
	v_mov_b32_e32 v102, v163
	v_mov_b32_e32 v103, v163
	v_mov_b32_e32 v104, v163
	v_mov_b32_e32 v105, v163
	v_mov_b32_e32 v106, v163
	v_mov_b32_e32 v107, v163
	v_mov_b32_e32 v108, v163
	v_mov_b32_e32 v109, v163
	v_mov_b32_e32 v62, v163
	v_mov_b32_e32 v63, v163
	v_mov_b32_e32 v64, v163
	v_mov_b32_e32 v65, v163
	v_mov_b32_e32 v78, v163
	v_mov_b32_e32 v79, v163
	v_mov_b32_e32 v80, v163
	v_mov_b32_e32 v81, v163
	v_mov_b32_e32 v46, v163
	v_mov_b32_e32 v47, v163
	v_mov_b32_e32 v48, v163
	v_mov_b32_e32 v49, v163
	v_mov_b32_e32 v66, v163
	v_mov_b32_e32 v67, v163
	v_mov_b32_e32 v68, v163
	v_mov_b32_e32 v69, v163
	v_mov_b32_e32 v34, v163
	v_mov_b32_e32 v35, v163
	v_mov_b32_e32 v36, v163
	v_mov_b32_e32 v37, v163
	v_mov_b32_e32 v38, v163
	v_mov_b32_e32 v39, v163
	v_mov_b32_e32 v40, v163
	v_mov_b32_e32 v41, v163
	v_mov_b32_e32 v114, v163
	v_mov_b32_e32 v115, v163
	v_mov_b32_e32 v116, v163
	v_mov_b32_e32 v117, v163
	v_mov_b32_e32 v122, v163
	v_mov_b32_e32 v123, v163
	v_mov_b32_e32 v124, v163
	v_mov_b32_e32 v125, v163
	v_mov_b32_e32 v110, v163
	v_mov_b32_e32 v111, v163
	v_mov_b32_e32 v112, v163
	v_mov_b32_e32 v113, v163
	v_mov_b32_e32 v126, v163
	v_mov_b32_e32 v127, v163
	v_mov_b32_e32 v128, v163
	v_mov_b32_e32 v129, v163
	v_mov_b32_e32 v98, v163
	v_mov_b32_e32 v99, v163
	v_mov_b32_e32 v100, v163
	v_mov_b32_e32 v101, v163
	v_mov_b32_e32 v118, v163
	v_mov_b32_e32 v119, v163
	v_mov_b32_e32 v120, v163
	v_mov_b32_e32 v121, v163
	v_mov_b32_e32 v90, v163
	v_mov_b32_e32 v91, v163
	v_mov_b32_e32 v92, v163
	v_mov_b32_e32 v93, v163
	v_mov_b32_e32 v94, v163
	v_mov_b32_e32 v95, v163
	v_mov_b32_e32 v96, v163
	v_mov_b32_e32 v97, v163
	v_mov_b32_e32 v26, v163
	v_mov_b32_e32 v27, v163
	v_mov_b32_e32 v28, v163
	v_mov_b32_e32 v29, v163
	v_mov_b32_e32 v30, v163
	v_mov_b32_e32 v31, v163
	v_mov_b32_e32 v32, v163
	v_mov_b32_e32 v33, v163
	v_mov_b32_e32 v10, v163
	v_mov_b32_e32 v11, v163
	v_mov_b32_e32 v12, v163
	v_mov_b32_e32 v13, v163
	v_mov_b32_e32 v22, v163
	v_mov_b32_e32 v23, v163
	v_mov_b32_e32 v24, v163
	v_mov_b32_e32 v25, v163
	v_mov_b32_e32 v6, v163
	v_mov_b32_e32 v7, v163
	v_mov_b32_e32 v8, v163
	v_mov_b32_e32 v9, v163
	v_mov_b32_e32 v18, v163
	v_mov_b32_e32 v19, v163
	v_mov_b32_e32 v20, v163
	v_mov_b32_e32 v21, v163
	v_mov_b32_e32 v2, v163
	v_mov_b32_e32 v4, v163
	v_mov_b32_e32 v5, v163
	v_mov_b32_e32 v14, v163
	v_mov_b32_e32 v15, v163
	v_mov_b32_e32 v16, v163
	v_mov_b32_e32 v17, v163
	v_mov_b32_e32 v74, v163
	v_mov_b32_e32 v75, v163
	v_mov_b32_e32 v76, v163
	v_mov_b32_e32 v77, v163
	v_mov_b32_e32 v86, v163
	v_mov_b32_e32 v87, v163
	v_mov_b32_e32 v88, v163
	v_mov_b32_e32 v89, v163
	v_mov_b32_e32 v50, v163
	v_mov_b32_e32 v51, v163
	v_mov_b32_e32 v52, v163
	v_mov_b32_e32 v53, v163
	v_mov_b32_e32 v70, v163
	v_mov_b32_e32 v71, v163
	v_mov_b32_e32 v72, v163
	v_mov_b32_e32 v73, v163
	v_mov_b32_e32 v42, v163
	v_mov_b32_e32 v43, v163
	v_mov_b32_e32 v44, v163
	v_mov_b32_e32 v45, v163
	v_mov_b32_e32 v58, v163
	v_mov_b32_e32 v59, v163
	v_mov_b32_e32 v60, v163
	v_mov_b32_e32 v61, v163
	v_mov_b32_e32 v54, v163
	v_mov_b32_e32 v55, v163
	v_mov_b32_e32 v56, v163
	v_mov_b32_e32 v57, v163
	v_mov_b32_e32 v82, v163
	v_mov_b32_e32 v83, v163
	v_mov_b32_e32 v84, v163
	v_mov_b32_e32 v85, v163
	s_barrier
	s_branch .Lmy_r1406E

; #define PG8_STAGE(bufoff, gbase, voff) do { _Pragma("unroll") for (int _i = 0; _i < 2; ++_i) \
;         __builtin_amdgcn_global_load_lds((const unsigned*)((const char*)(gbase) + (voff)[_i]), (LAS unsigned*)(lds + (bufoff) + ldsw + _i * 8192), 16, 0, 0); } while (0)
; #define PG8_LDA(dst, b, h) do { _Pragma("unroll") for (int m = 0; m < 4; ++m) _Pragma("unroll") for (int k = 0; k < 2; ++k) dst[m][k] = *(const LAS bf16x8*)(lds + PG8_SA(b, h) + aoff + m * 2048 + k * 1024); } while (0)
; #define PG8_LDB(dst, b, h) do { _Pragma("unroll") for (int n = 0; n < 2; ++n) _Pragma("unroll") for (int k = 0; k < 2; ++k) dst[n][k] = *(const LAS bf16x8*)(lds + PG8_SB(b, h) + boff + n * 2048 + k * 1024); } while (0)
; #define PG8_MMA(ai, bj, At, Bt) do { __builtin_amdgcn_s_setprio(1); _Pragma("unroll") for (int m = 0; m < 4; ++m) _Pragma("unroll") for (int n = 0; n < 2; ++n) _Pragma("unroll") for (int k = 0; k < 2; ++k) \
;         acc[ai][bj][m][n] = __builtin_amdgcn_mfma_f32_16x16x32_bf16(Bt[n][k], At[m][k], acc[ai][bj][m][n], 0, 0, 0); __builtin_amdgcn_s_setprio(0); } while (0)
; #define PG8_WAIT_V(n) asm volatile("s_waitcnt vmcnt(" #n ")" ::: "memory")
; #define PG8_WAIT_L(n) asm volatile("s_waitcnt lgkmcnt(" #n ")" ::: "memory")
; #define PG8_BAR __builtin_amdgcn_s_barrier()
; #define PG8_SCHED __builtin_amdgcn_sched_barrier(0)
; template <class Epi, class Sched, bool ALIGN_EPI, class Hook = NoHook>
; __device__ __forceinline__ void gemm_phase(LAS unsigned char* lds, const Gemm g, const Sched& S, const Epi& E, const Hook& H = Hook()) {
;     ...
;             PG8_LDB(B0, 0, 0); PG8_LDB(B1, 0, 1); PG8_SCHED; PG8_LDA(At, 0, 0); PG8_STAGE(PG8_SA(1, 1), a1 + hA, voffA);
;             PG8_WAIT_V(8); PG8_WAIT_L(0); PG8_BAR; PG8_MMA(0, 0, At, B0); PG8_MMA(0, 1, At, B1); PG8_BAR; PG8_SCHED;
;             PG8_LDA(At, 0, 1); PG8_STAGE(PG8_SB(0, 0), b2, voffB); PG8_STAGE(PG8_SB(0, 1), b2 + hB, voffB); PG8_STAGE(PG8_SA(0, 0), a2, voffA);
;             PG8_WAIT_V(8); PG8_WAIT_L(0); PG8_BAR; PG8_MMA(1, 0, At, B0); PG8_MMA(1, 1, At, B1); PG8_BAR; PG8_SCHED;
.Lmy_r1406E:
	ds_read_b128 v[146:149], v140
	ds_read_b128 v[150:153], v140 offset:1024
	s_add_u32 s10, s4, 0xbb050080
	s_addc_u32 s11, s5, -1
	s_cmpk_lg_i32 s18, 0xa8
	s_cselect_b32 s10, s10, 0
	s_cselect_b32 s11, s11, 0
	s_add_u32 s16, s0, s10
	s_addc_u32 s17, s1, s11
	s_add_u32 s10, s12, s10
	s_addc_u32 s11, s13, s11
	s_mov_b32 m0, s19
	ds_read_b128 v[154:157], v140 offset:2048
	ds_read_b128 v[158:161], v140 offset:3072
	ds_read_b128 v[170:173], v141
	ds_read_b128 v[174:177], v141 offset:1024
	ds_read_b128 v[178:181], v141 offset:2048
	ds_read_b128 v[182:185], v141 offset:3072
	v_lshl_add_u64 v[218:219], v[136:137], 0, s[4:5]
	global_load_lds_dwordx4 v[218:219], off
	ds_read_b128 v[186:189], v142
	ds_read_b128 v[190:193], v142 offset:1024
	ds_read_b128 v[194:197], v142 offset:2048
	ds_read_b128 v[198:201], v142 offset:3072
	ds_read_b128 v[202:205], v142 offset:4096
	ds_read_b128 v[206:209], v142 offset:5120
	ds_read_b128 v[210:213], v142 offset:6144
	ds_read_b128 v[214:217], v142 offset:7168
	v_lshl_add_u64 v[218:219], v[138:139], 0, s[4:5]
	s_mov_b32 m0, s31
	s_nop 0
	global_load_lds_dwordx4 v[218:219], off
	s_waitcnt vmcnt(8)
	s_waitcnt lgkmcnt(0)
	s_barrier
	s_setprio 1
	s_waitcnt lgkmcnt(0)
	v_mfma_f32_16x16x32_bf16 v[82:85], v[146:149], v[186:189], v[82:85]
	v_mfma_f32_16x16x32_bf16 v[54:57], v[154:157], v[186:189], v[54:57]
	v_mfma_f32_16x16x32_bf16 v[58:61], v[146:149], v[194:197], v[58:61]
	v_mfma_f32_16x16x32_bf16 v[42:45], v[154:157], v[194:197], v[42:45]
	v_mfma_f32_16x16x32_bf16 v[70:73], v[146:149], v[202:205], v[70:73]
	v_mfma_f32_16x16x32_bf16 v[50:53], v[154:157], v[202:205], v[50:53]
	v_mfma_f32_16x16x32_bf16 v[86:89], v[146:149], v[210:213], v[86:89]
	v_mfma_f32_16x16x32_bf16 v[74:77], v[154:157], v[210:213], v[74:77]
	v_mfma_f32_16x16x32_bf16 v[82:85], v[150:153], v[190:193], v[82:85]
	v_mfma_f32_16x16x32_bf16 v[54:57], v[158:161], v[190:193], v[54:57]
	v_mfma_f32_16x16x32_bf16 v[58:61], v[150:153], v[198:201], v[58:61]
	v_mfma_f32_16x16x32_bf16 v[42:45], v[158:161], v[198:201], v[42:45]
	v_mfma_f32_16x16x32_bf16 v[70:73], v[150:153], v[206:209], v[70:73]
	v_mfma_f32_16x16x32_bf16 v[50:53], v[158:161], v[206:209], v[50:53]
	v_mfma_f32_16x16x32_bf16 v[86:89], v[150:153], v[214:217], v[86:89]
	v_mfma_f32_16x16x32_bf16 v[74:77], v[158:161], v[214:217], v[74:77]
	s_setprio 0
	s_setprio 1
	v_mfma_f32_16x16x32_bf16 v[14:17], v[170:173], v[186:189], v[14:17]
	v_mfma_f32_16x16x32_bf16 v[2:5], v[178:181], v[186:189], v[2:5]
	v_mfma_f32_16x16x32_bf16 v[18:21], v[170:173], v[194:197], v[18:21]
	v_mfma_f32_16x16x32_bf16 v[6:9], v[178:181], v[194:197], v[6:9]
	v_mfma_f32_16x16x32_bf16 v[22:25], v[170:173], v[202:205], v[22:25]
	v_mfma_f32_16x16x32_bf16 v[10:13], v[178:181], v[202:205], v[10:13]
	v_mfma_f32_16x16x32_bf16 v[30:33], v[170:173], v[210:213], v[30:33]
	v_mfma_f32_16x16x32_bf16 v[26:29], v[178:181], v[210:213], v[26:29]
	v_mfma_f32_16x16x32_bf16 v[14:17], v[174:177], v[190:193], v[14:17]
	v_mfma_f32_16x16x32_bf16 v[2:5], v[182:185], v[190:193], v[2:5]
	v_mfma_f32_16x16x32_bf16 v[18:21], v[174:177], v[198:201], v[18:21]
	v_mfma_f32_16x16x32_bf16 v[6:9], v[182:185], v[198:201], v[6:9]
	v_mfma_f32_16x16x32_bf16 v[22:25], v[174:177], v[206:209], v[22:25]
	v_mfma_f32_16x16x32_bf16 v[10:13], v[182:185], v[206:209], v[10:13]
	v_mfma_f32_16x16x32_bf16 v[30:33], v[174:177], v[214:217], v[30:33]
	v_mfma_f32_16x16x32_bf16 v[26:29], v[182:185], v[214:217], v[26:29]
	s_setprio 0
	s_barrier
	s_mov_b32 m0, s33
	s_add_u32 s46, s10, 0x2b0000
	ds_read_b128 v[186:189], v142 offset:16384
	ds_read_b128 v[190:193], v142 offset:17408
	global_load_lds_dwordx4 v162, s[10:11]
	ds_read_b128 v[194:197], v142 offset:18432
	s_mov_b32 m0, s34
	s_addc_u32 s47, s11, 0
	global_load_lds_dwordx4 v134, s[10:11]
	ds_read_b128 v[198:201], v142 offset:19456
	s_mov_b32 m0, s35
	s_nop 0
	global_load_lds_dwordx4 v162, s[46:47]
	ds_read_b128 v[202:205], v142 offset:20480
	s_mov_b32 m0, s43
	s_nop 0
	global_load_lds_dwordx4 v134, s[46:47]
	ds_read_b128 v[206:209], v142 offset:21504
	s_add_u32 s54, s16, s2
	s_addc_u32 s55, s17, s3
	s_mov_b32 m0, s27
	s_nop 0
	global_load_lds_dwordx4 v130, s[16:17]
	ds_read_b128 v[210:213], v142 offset:22528
	s_mov_b32 m0, s28
	s_nop 0
	global_load_lds_dwordx4 v132, s[16:17]
	ds_read_b128 v[214:217], v142 offset:23552
	s_waitcnt vmcnt(8)
	s_waitcnt lgkmcnt(0)
	s_barrier
	s_setprio 1
	s_waitcnt lgkmcnt(0)
	v_mfma_f32_16x16x32_bf16 v[94:97], v[146:149], v[186:189], v[94:97]
	v_mfma_f32_16x16x32_bf16 v[90:93], v[154:157], v[186:189], v[90:93]
	v_mfma_f32_16x16x32_bf16 v[118:121], v[146:149], v[194:197], v[118:121]
	v_mfma_f32_16x16x32_bf16 v[98:101], v[154:157], v[194:197], v[98:101]
	v_mfma_f32_16x16x32_bf16 v[126:129], v[146:149], v[202:205], v[126:129]
	v_mfma_f32_16x16x32_bf16 v[110:113], v[154:157], v[202:205], v[110:113]
	v_mfma_f32_16x16x32_bf16 v[122:125], v[146:149], v[210:213], v[122:125]
	v_mfma_f32_16x16x32_bf16 v[114:117], v[154:157], v[210:213], v[114:117]
	v_mfma_f32_16x16x32_bf16 v[94:97], v[150:153], v[190:193], v[94:97]
	v_mfma_f32_16x16x32_bf16 v[90:93], v[158:161], v[190:193], v[90:93]
	v_mfma_f32_16x16x32_bf16 v[118:121], v[150:153], v[198:201], v[118:121]
	v_mfma_f32_16x16x32_bf16 v[98:101], v[158:161], v[198:201], v[98:101]
	v_mfma_f32_16x16x32_bf16 v[126:129], v[150:153], v[206:209], v[126:129]
	v_mfma_f32_16x16x32_bf16 v[110:113], v[158:161], v[206:209], v[110:113]
	v_mfma_f32_16x16x32_bf16 v[122:125], v[150:153], v[214:217], v[122:125]
	v_mfma_f32_16x16x32_bf16 v[114:117], v[158:161], v[214:217], v[114:117]
	s_setprio 0
	s_setprio 1
	v_mfma_f32_16x16x32_bf16 v[38:41], v[170:173], v[186:189], v[38:41]
	v_mfma_f32_16x16x32_bf16 v[34:37], v[178:181], v[186:189], v[34:37]
	v_mfma_f32_16x16x32_bf16 v[66:69], v[170:173], v[194:197], v[66:69]
	v_mfma_f32_16x16x32_bf16 v[46:49], v[178:181], v[194:197], v[46:49]
	v_mfma_f32_16x16x32_bf16 v[78:81], v[170:173], v[202:205], v[78:81]
	v_mfma_f32_16x16x32_bf16 v[62:65], v[178:181], v[202:205], v[62:65]
	v_mfma_f32_16x16x32_bf16 v[106:109], v[170:173], v[210:213], v[106:109]
	v_mfma_f32_16x16x32_bf16 v[102:105], v[178:181], v[210:213], v[102:105]
	v_mfma_f32_16x16x32_bf16 v[38:41], v[174:177], v[190:193], v[38:41]
	v_mfma_f32_16x16x32_bf16 v[34:37], v[182:185], v[190:193], v[34:37]
	v_mfma_f32_16x16x32_bf16 v[66:69], v[174:177], v[198:201], v[66:69]
	v_mfma_f32_16x16x32_bf16 v[46:49], v[182:185], v[198:201], v[46:49]
	v_mfma_f32_16x16x32_bf16 v[78:81], v[174:177], v[206:209], v[78:81]
	v_mfma_f32_16x16x32_bf16 v[62:65], v[182:185], v[206:209], v[62:65]
	v_mfma_f32_16x16x32_bf16 v[106:109], v[174:177], v[214:217], v[106:109]
	v_mfma_f32_16x16x32_bf16 v[102:105], v[182:185], v[214:217], v[102:105]
	s_setprio 0
	s_barrier
; #define PG8_STAGE(bufoff, gbase, voff) do { _Pragma("unroll") for (int _i = 0; _i < 2; ++_i) \
;         __builtin_amdgcn_global_load_lds((const unsigned*)((const char*)(gbase) + (voff)[_i]), (LAS unsigned*)(lds + (bufoff) + ldsw + _i * 8192), 16, 0, 0); } while (0)
; #define PG8_LDA(dst, b, h) do { _Pragma("unroll") for (int m = 0; m < 4; ++m) _Pragma("unroll") for (int k = 0; k < 2; ++k) dst[m][k] = *(const LAS bf16x8*)(lds + PG8_SA(b, h) + aoff + m * 2048 + k * 1024); } while (0)
; #define PG8_LDB(dst, b, h) do { _Pragma("unroll") for (int n = 0; n < 2; ++n) _Pragma("unroll") for (int k = 0; k < 2; ++k) dst[n][k] = *(const LAS bf16x8*)(lds + PG8_SB(b, h) + boff + n * 2048 + k * 1024); } while (0)
; #define PG8_MMA(ai, bj, At, Bt) do { __builtin_amdgcn_s_setprio(1); _Pragma("unroll") for (int m = 0; m < 4; ++m) _Pragma("unroll") for (int n = 0; n < 2; ++n) _Pragma("unroll") for (int k = 0; k < 2; ++k) \
;         acc[ai][bj][m][n] = __builtin_amdgcn_mfma_f32_16x16x32_bf16(Bt[n][k], At[m][k], acc[ai][bj][m][n], 0, 0, 0); __builtin_amdgcn_s_setprio(0); } while (0)
; #define PG8_WAIT_V(n) asm volatile("s_waitcnt vmcnt(" #n ")" ::: "memory")
; #define PG8_WAIT_L(n) asm volatile("s_waitcnt lgkmcnt(" #n ")" ::: "memory")
; #define PG8_BAR __builtin_amdgcn_s_barrier()
; #define PG8_SCHED __builtin_amdgcn_sched_barrier(0)
; template <class Epi, class Sched, bool ALIGN_EPI, class Hook = NoHook>
; __device__ __forceinline__ void gemm_phase(LAS unsigned char* lds, const Gemm g, const Sched& S, const Epi& E, const Hook& H = Hook()) {
;     ...
;         for (int t = tb; t < te; t += 2) {
;             const bool last = (t == nt - 2);
;     ...
;             PG8_LDB(B0, 1, 0); PG8_LDB(B1, 1, 1); PG8_SCHED; PG8_LDA(At, 1, 0); PG8_STAGE(PG8_SA(0, 1), a2 + hA, voffA);
;             PG8_WAIT_V(8); PG8_WAIT_L(0); PG8_BAR; PG8_MMA(0, 0, At, B0); PG8_MMA(0, 1, At, B1); PG8_BAR; PG8_SCHED;
;             PG8_LDA(At, 1, 1); PG8_STAGE(PG8_SB(1, 0), b3, voffB); PG8_STAGE(PG8_SB(1, 1), b3 + hB, voffB); PG8_STAGE(PG8_SA(1, 0), a3, voffA);
;             PG8_WAIT_V(8); PG8_WAIT_L(0); PG8_BAR; PG8_MMA(1, 0, At, B0); PG8_MMA(1, 1, At, B1); PG8_BAR; PG8_SCHED;
	ds_read_b128 v[146:149], v143
	ds_read_b128 v[150:153], v143 offset:1024
	s_add_u32 s16, s16, 0x2b0000
	s_addc_u32 s17, s17, 0
	s_mov_b32 m0, s29
	s_nop 0
	global_load_lds_dwordx4 v130, s[16:17]
	ds_read_b128 v[154:157], v143 offset:2048
	ds_read_b128 v[158:161], v143 offset:3072
	ds_read_b128 v[170:173], v144
	ds_read_b128 v[174:177], v144 offset:1024
	ds_read_b128 v[178:181], v144 offset:2048
	ds_read_b128 v[182:185], v144 offset:3072
	ds_read_b128 v[186:189], v142 offset:32768
	s_mov_b32 m0, s39
	s_nop 0
	global_load_lds_dwordx4 v132, s[16:17]
	ds_read_b128 v[190:193], v142 offset:33792
	ds_read_b128 v[194:197], v142 offset:34816
	ds_read_b128 v[198:201], v142 offset:35840
	ds_read_b128 v[202:205], v142 offset:36864
	ds_read_b128 v[206:209], v142 offset:37888
	ds_read_b128 v[210:213], v142 offset:38912
	ds_read_b128 v[214:217], v142 offset:39936
	s_waitcnt vmcnt(8)
	s_waitcnt lgkmcnt(0)
	s_barrier
	s_setprio 1
	s_waitcnt lgkmcnt(0)
	v_mfma_f32_16x16x32_bf16 v[82:85], v[146:149], v[186:189], v[82:85]
	v_mfma_f32_16x16x32_bf16 v[54:57], v[154:157], v[186:189], v[54:57]
	v_mfma_f32_16x16x32_bf16 v[58:61], v[146:149], v[194:197], v[58:61]
	v_mfma_f32_16x16x32_bf16 v[42:45], v[154:157], v[194:197], v[42:45]
	v_mfma_f32_16x16x32_bf16 v[70:73], v[146:149], v[202:205], v[70:73]
	v_mfma_f32_16x16x32_bf16 v[50:53], v[154:157], v[202:205], v[50:53]
	v_mfma_f32_16x16x32_bf16 v[86:89], v[146:149], v[210:213], v[86:89]
	v_mfma_f32_16x16x32_bf16 v[74:77], v[154:157], v[210:213], v[74:77]
	v_mfma_f32_16x16x32_bf16 v[82:85], v[150:153], v[190:193], v[82:85]
	v_mfma_f32_16x16x32_bf16 v[54:57], v[158:161], v[190:193], v[54:57]
	v_mfma_f32_16x16x32_bf16 v[58:61], v[150:153], v[198:201], v[58:61]
	v_mfma_f32_16x16x32_bf16 v[42:45], v[158:161], v[198:201], v[42:45]
	v_mfma_f32_16x16x32_bf16 v[70:73], v[150:153], v[206:209], v[70:73]
	v_mfma_f32_16x16x32_bf16 v[50:53], v[158:161], v[206:209], v[50:53]
	v_mfma_f32_16x16x32_bf16 v[86:89], v[150:153], v[214:217], v[86:89]
	v_mfma_f32_16x16x32_bf16 v[74:77], v[158:161], v[214:217], v[74:77]
	s_setprio 0
	s_setprio 1
	v_mfma_f32_16x16x32_bf16 v[14:17], v[170:173], v[186:189], v[14:17]
	v_mfma_f32_16x16x32_bf16 v[2:5], v[178:181], v[186:189], v[2:5]
	v_mfma_f32_16x16x32_bf16 v[18:21], v[170:173], v[194:197], v[18:21]
	v_mfma_f32_16x16x32_bf16 v[6:9], v[178:181], v[194:197], v[6:9]
	v_mfma_f32_16x16x32_bf16 v[22:25], v[170:173], v[202:205], v[22:25]
	v_mfma_f32_16x16x32_bf16 v[10:13], v[178:181], v[202:205], v[10:13]
	v_mfma_f32_16x16x32_bf16 v[30:33], v[170:173], v[210:213], v[30:33]
	v_mfma_f32_16x16x32_bf16 v[26:29], v[178:181], v[210:213], v[26:29]
	v_mfma_f32_16x16x32_bf16 v[14:17], v[174:177], v[190:193], v[14:17]
	v_mfma_f32_16x16x32_bf16 v[2:5], v[182:185], v[190:193], v[2:5]
	v_mfma_f32_16x16x32_bf16 v[18:21], v[174:177], v[198:201], v[18:21]
	v_mfma_f32_16x16x32_bf16 v[6:9], v[182:185], v[198:201], v[6:9]
	v_mfma_f32_16x16x32_bf16 v[22:25], v[174:177], v[206:209], v[22:25]
	v_mfma_f32_16x16x32_bf16 v[10:13], v[182:185], v[206:209], v[10:13]
	v_mfma_f32_16x16x32_bf16 v[30:33], v[174:177], v[214:217], v[30:33]
	v_mfma_f32_16x16x32_bf16 v[26:29], v[182:185], v[214:217], v[26:29]
	s_setprio 0
	s_barrier
	s_mov_b32 m0, s36
	s_add_u32 s52, s10, s2
	s_addc_u32 s53, s11, s3
	s_add_u32 s10, s10, 0x2b0080
	ds_read_b128 v[186:189], v142 offset:49152
	ds_read_b128 v[190:193], v142 offset:50176
	global_load_lds_dwordx4 v162, s[52:53]
	ds_read_b128 v[194:197], v142 offset:51200
	s_mov_b32 m0, s44
	s_addc_u32 s11, s11, 0
	global_load_lds_dwordx4 v134, s[52:53]
	ds_read_b128 v[198:201], v142 offset:52224
	s_mov_b32 m0, s37
	s_nop 0
	global_load_lds_dwordx4 v162, s[10:11]
	ds_read_b128 v[202:205], v142 offset:53248
	s_mov_b32 m0, s45
	s_nop 0
	global_load_lds_dwordx4 v134, s[10:11]
	ds_read_b128 v[206:209], v142 offset:54272
	s_mov_b32 m0, s41
	s_nop 0
	global_load_lds_dwordx4 v130, s[54:55]
	ds_read_b128 v[210:213], v142 offset:55296
	s_mov_b32 m0, s42
	s_nop 0
	global_load_lds_dwordx4 v132, s[54:55]
	ds_read_b128 v[214:217], v142 offset:56320
	s_waitcnt vmcnt(8)
	s_waitcnt lgkmcnt(0)
	s_barrier
	s_setprio 1
	s_waitcnt lgkmcnt(0)
	v_mfma_f32_16x16x32_bf16 v[94:97], v[146:149], v[186:189], v[94:97]
	v_mfma_f32_16x16x32_bf16 v[90:93], v[154:157], v[186:189], v[90:93]
	v_mfma_f32_16x16x32_bf16 v[118:121], v[146:149], v[194:197], v[118:121]
	v_mfma_f32_16x16x32_bf16 v[98:101], v[154:157], v[194:197], v[98:101]
	v_mfma_f32_16x16x32_bf16 v[126:129], v[146:149], v[202:205], v[126:129]
	v_mfma_f32_16x16x32_bf16 v[110:113], v[154:157], v[202:205], v[110:113]
	v_mfma_f32_16x16x32_bf16 v[122:125], v[146:149], v[210:213], v[122:125]
	v_mfma_f32_16x16x32_bf16 v[114:117], v[154:157], v[210:213], v[114:117]
	v_mfma_f32_16x16x32_bf16 v[94:97], v[150:153], v[190:193], v[94:97]
	v_mfma_f32_16x16x32_bf16 v[90:93], v[158:161], v[190:193], v[90:93]
	v_mfma_f32_16x16x32_bf16 v[118:121], v[150:153], v[198:201], v[118:121]
	v_mfma_f32_16x16x32_bf16 v[98:101], v[158:161], v[198:201], v[98:101]
	v_mfma_f32_16x16x32_bf16 v[126:129], v[150:153], v[206:209], v[126:129]
	v_mfma_f32_16x16x32_bf16 v[110:113], v[158:161], v[206:209], v[110:113]
	v_mfma_f32_16x16x32_bf16 v[122:125], v[150:153], v[214:217], v[122:125]
	v_mfma_f32_16x16x32_bf16 v[114:117], v[158:161], v[214:217], v[114:117]
	s_setprio 0
	s_setprio 1
	v_mfma_f32_16x16x32_bf16 v[38:41], v[170:173], v[186:189], v[38:41]
	v_mfma_f32_16x16x32_bf16 v[34:37], v[178:181], v[186:189], v[34:37]
	v_mfma_f32_16x16x32_bf16 v[66:69], v[170:173], v[194:197], v[66:69]
	v_mfma_f32_16x16x32_bf16 v[46:49], v[178:181], v[194:197], v[46:49]
	v_mfma_f32_16x16x32_bf16 v[78:81], v[170:173], v[202:205], v[78:81]
	v_mfma_f32_16x16x32_bf16 v[62:65], v[178:181], v[202:205], v[62:65]
	v_mfma_f32_16x16x32_bf16 v[106:109], v[170:173], v[210:213], v[106:109]
	v_mfma_f32_16x16x32_bf16 v[102:105], v[178:181], v[210:213], v[102:105]
	v_mfma_f32_16x16x32_bf16 v[38:41], v[174:177], v[190:193], v[38:41]
	v_mfma_f32_16x16x32_bf16 v[34:37], v[182:185], v[190:193], v[34:37]
	v_mfma_f32_16x16x32_bf16 v[66:69], v[174:177], v[198:201], v[66:69]
	v_mfma_f32_16x16x32_bf16 v[46:49], v[182:185], v[198:201], v[46:49]
	v_mfma_f32_16x16x32_bf16 v[78:81], v[174:177], v[206:209], v[78:81]
	v_mfma_f32_16x16x32_bf16 v[62:65], v[182:185], v[206:209], v[62:65]
	v_mfma_f32_16x16x32_bf16 v[106:109], v[174:177], v[214:217], v[106:109]
	v_mfma_f32_16x16x32_bf16 v[102:105], v[182:185], v[214:217], v[102:105]
	s_setprio 0
	s_add_i32 s18, s18, 2
	s_add_u32 s4, s4, 0x100
	s_addc_u32 s5, s5, 0
	s_cmpk_gt_u32 s18, 0xa9
	s_cbranch_scc0 .LBB0_1406
	s_barrier
	s_cmpk_lt_u32 s22, 0x100
	s_cbranch_scc0 .LBB0_1409
	s_barrier
